# phase-2 work queue: thread 0 requests the next ticket after the K-tile-11 loads of each projection GEMM unit (late lookahead) so the returning atomic's latency is hidden
# speedup vs baseline: 1.0045x; 1.0045x over previous
.LBB0_265:
	s_add_u32 s34, s46, 0x1000
	v_readlane_b32 s0, v197, 34
	s_addc_u32 s35, s47, 0
	v_readlane_b32 s14, v197, 48
	v_readlane_b32 s15, v197, 49
	s_add_u32 s28, s14, 0x100
	s_addc_u32 s29, s15, 0
	v_readlane_b32 s3, v197, 37
	s_add_u32 s26, s14, 0x2100
	v_writelane_b32 v196, s24, 26
	v_readlane_b32 s2, v197, 36
	s_addc_u32 s27, s15, 0
	s_add_i32 s3, 0, 0x24000
	v_mbcnt_lo_u32_b32 v2, -1, 0
	s_movk_i32 s84, 0xfa00
	v_writelane_b32 v196, s25, 27
	s_mov_b64 s[96:97], 0x100
	s_mov_b32 s67, 0
	v_mov_b32_e32 v99, 0
	v_mov_b32_e32 v1, s3
	s_mov_b64 s[68:69], 0x40000
	s_mov_b32 s37, 0x40000
	s_mov_b64 s[30:31], 0x80000
	s_mov_b32 s65, 0x80000
	s_mov_b64 s[24:25], 0xc0000
	s_mov_b32 s78, 0xc0000
	s_mov_b64 s[80:81], 0x80
	s_mov_b32 s79, 0x1ffffc0
	s_movk_i32 s70, 0x2200
	s_movk_i32 s82, 0x600
	v_mov_b32_e32 v137, 0x358637bd
	v_mov_b32_e32 v148, 1
	v_mov_b32_e32 v149, 0x300
	v_mbcnt_hi_u32_b32 v150, -1, v2
	v_mov_b32_e32 v151, 0x104
	s_mov_b32 s83, 0x800000
	s_mov_b32 s85, -1
	s_mov_b32 s2, 0x3e38aa3b
	s_mov_b32 s36, 0x3b000000
	v_readlane_b32 s1, v197, 35
	v_readlane_b32 s4, v197, 38
	v_readlane_b32 s5, v197, 39
	v_readlane_b32 s6, v197, 40
	v_readlane_b32 s7, v197, 41
	v_readlane_b32 s8, v197, 42
	v_readlane_b32 s9, v197, 43
	v_readlane_b32 s10, v197, 44
	v_readlane_b32 s11, v197, 45
	v_readlane_b32 s12, v197, 46
	v_readlane_b32 s13, v197, 47
	s_mov_b32 s99, 0
	s_branch .LBB0_269

.LBB0_269:
	s_barrier
	s_mov_b64 s[0:1], exec
	v_readlane_b32 s4, v197, 0
	v_readlane_b32 s5, v197, 1
	s_and_b64 s[4:5], s[0:1], s[4:5]
	s_mov_b64 exec, s[4:5]
	s_cbranch_execz .LBB0_273
	s_mov_b64 s[6:7], exec
	v_mbcnt_lo_u32_b32 v2, s6, 0
	v_mbcnt_hi_u32_b32 v2, s7, v2
	v_cmp_eq_u32_e32 vcc, 0, v2
	s_and_saveexec_b64 s[4:5], vcc
	s_cbranch_execz .LBB0_272
	s_bcnt1_i32_b64 s6, s[6:7]
	v_mov_b32_e32 v3, s6
	s_cmp_eq_u32 s99, 1
	s_cbranch_scc1 .Ldq_have
	global_atomic_add v3, v99, v3, s[92:93] offset:8 sc0
	s_branch .LBB0_272
.Ldq_have:
	s_waitcnt vmcnt(0)
	v_mov_b32_e32 v3, v250
	s_mov_b32 s99, 0

.LBB0_303:
	s_cmpk_gt_u32 s4, 0x47f
	s_cbranch_scc0 .LBB0_313
	s_cmpk_gt_u32 s4, 0x57f
	s_cbranch_scc0 .LBB0_310
	s_cmpk_gt_u32 s4, 0x597
	s_cbranch_scc0 .LBB0_307
	s_lshl_b32 s0, s4, 5
	s_and_b32 s0, s0, 0xffffff80
	s_add_i32 s1, s0, 0xffff5300
	v_add_u32_e32 v2, s1, v70
	s_add_i32 s1, s0, 0xffff5340
	v_add_u32_e32 v4, s1, v70
	s_lshl_b32 s1, s58, 8
	s_and_b32 s1, s1, 0x300
	v_mov_b32_e32 v14, v0
	v_add_u32_e32 v6, s1, v70
	v_ashrrev_i32_e32 v3, 31, v2
	v_readfirstlane_b32 s1, v14
	v_readlane_b32 s8, v197, 34
	v_ashrrev_i32_e32 v5, 31, v4
	s_lshl_b32 s1, s1, 4
	v_lshlrev_b64 v[2:3], 11, v[2:3]
	v_readlane_b32 s9, v197, 35
	v_readlane_b32 s10, v197, 36
	v_readlane_b32 s11, v197, 37
	v_readlane_b32 s12, v197, 38
	v_readlane_b32 s13, v197, 39
	v_readlane_b32 s14, v197, 40
	v_readlane_b32 s15, v197, 41
	v_readlane_b32 s16, v197, 42
	v_readlane_b32 s17, v197, 43
	v_readlane_b32 s18, v197, 44
	v_readlane_b32 s19, v197, 45
	v_readlane_b32 s20, v197, 46
	v_readlane_b32 s21, v197, 47
	v_readlane_b32 s22, v197, 48
	v_readlane_b32 s23, v197, 49
	v_lshlrev_b64 v[4:5], 11, v[4:5]
	s_and_b32 s1, s1, 0xfffffc00
	v_lshl_add_u64 v[2:3], s[10:11], 0, v[2:3]
	v_lshlrev_b32_e32 v98, 1, v71
	v_lshl_add_u64 v[4:5], s[10:11], 0, v[4:5]
	v_ashrrev_i32_e32 v7, 31, v6
	v_readlane_b32 s8, v196, 6
	s_add_i32 s56, s1, 0
	v_lshl_add_u64 v[2:3], v[2:3], 0, v[98:99]
	v_lshlrev_b64 v[6:7], 11, v[6:7]
	v_readlane_b32 s10, v196, 8
	v_readlane_b32 s11, v196, 9
	s_mov_b32 m0, s56
	s_add_i32 s1, s56, 0x2000
	v_lshl_add_u64 v[4:5], v[4:5], 0, v[98:99]
	v_readlane_b32 s9, v196, 7
	v_lshl_add_u64 v[6:7], s[10:11], 0, v[6:7]
	global_load_lds_dwordx4 v[2:3], off
	s_mov_b32 m0, s1
	s_add_i32 s5, s56, 0x4000
	v_lshl_add_u64 v[6:7], v[6:7], 0, v[98:99]
	s_mov_b64 s[8:9], 0x20000
	global_load_lds_dwordx4 v[4:5], off
	s_mov_b32 m0, s5
	s_add_i32 s33, s56, 0x6000
	v_lshl_add_u64 v[8:9], v[6:7], 0, s[8:9]
	global_load_lds_dwordx4 v[6:7], off
	s_mov_b32 m0, s33
	s_add_i32 s38, s56, 0x8000
	v_lshl_add_u64 v[10:11], v[6:7], 0, s[68:69]
	s_mov_b64 s[8:9], 0x60000
	global_load_lds_dwordx4 v[8:9], off
	s_mov_b32 m0, s38
	s_add_i32 s39, s56, 0xa000
	v_lshl_add_u64 v[12:13], v[6:7], 0, s[8:9]
	global_load_lds_dwordx4 v[10:11], off
	s_mov_b32 m0, s39
	s_add_i32 s59, s56, 0xc000
	global_load_lds_dwordx4 v[12:13], off
	v_lshl_add_u64 v[8:9], v[2:3], 0, s[80:81]
	s_mov_b32 m0, s59
	s_add_i32 s57, s56, 0xe000
	global_load_lds_dwordx4 v[8:9], off
	v_lshl_add_u64 v[8:9], v[4:5], 0, s[80:81]
	s_mov_b32 m0, s57
	s_add_i32 s60, s56, 0x10000
	global_load_lds_dwordx4 v[8:9], off
	v_lshl_add_u64 v[8:9], v[6:7], 0, s[80:81]
	s_mov_b32 m0, s60
	s_mov_b64 s[8:9], 0x20080
	s_add_i32 s61, s56, 0x12000
	global_load_lds_dwordx4 v[8:9], off
	v_lshl_add_u64 v[8:9], v[6:7], 0, s[8:9]
	s_mov_b32 m0, s61
	s_mov_b64 s[8:9], 0x40080
	s_add_i32 s62, s56, 0x14000
	global_load_lds_dwordx4 v[8:9], off
	v_lshl_add_u64 v[8:9], v[6:7], 0, s[8:9]
	s_mov_b32 m0, s62
	s_mov_b64 s[8:9], 0x60080
	s_add_i32 s71, s56, 0x16000
	global_load_lds_dwordx4 v[8:9], off
	v_lshl_add_u64 v[8:9], v[6:7], 0, s[8:9]
	s_mov_b32 m0, s71
	v_lshrrev_b32_e32 v15, 4, v14
	v_bfe_u32 v16, v14, 4, 2
	v_and_b32_e32 v17, 15, v14
	global_load_lds_dwordx4 v[8:9], off
	v_bfe_u32 v8, v14, 1, 3
	v_lshrrev_b32_e32 v9, 2, v14
	v_and_or_b32 v9, v9, s79, v17
	v_lshlrev_b32_e32 v10, 7, v14
	v_bitop3_b32 v11, v15, v8, 3 bitop3:0x6c
	v_bitop3_b32 v8, v16, v8, 4 bitop3:0x36
	v_lshlrev_b32_e32 v9, 7, v9
	v_and_b32_e32 v60, 0x6780, v10
	v_lshlrev_b32_e32 v11, 4, v11
	v_lshlrev_b32_e32 v61, 4, v8
	v_add_u32_e32 v10, 0x4000, v60
	v_or_b32_e32 v68, v11, v9
	v_or_b32_e32 v80, v61, v9
	v_or_b32_e32 v9, v11, v60
	s_add_i32 s63, s56, 0x18000
	s_waitcnt vmcnt(6)
	s_barrier
	v_or_b32_e32 v69, v11, v10
	v_or_b32_e32 v81, v61, v10
	v_add_u32_e32 v8, 0, v68
	v_add_u32_e32 v9, 0, v9
	v_lshl_add_u64 v[10:11], v[2:3], 0, s[96:97]
	s_mov_b32 m0, s63
	s_add_i32 s64, s56, 0x1a000
	ds_read_b128 v[12:15], v8
	ds_read_b128 v[16:19], v8 offset:2048
	ds_read_b128 v[20:23], v8 offset:4096
	ds_read_b128 v[24:27], v8 offset:6144
	ds_read_b128 v[28:31], v9 offset:22528
	ds_read_b128 v[32:35], v9 offset:20480
	ds_read_b128 v[36:39], v9 offset:18432
	ds_read_b128 v[40:43], v9 offset:16384
	global_load_lds_dwordx4 v[10:11], off
	v_lshl_add_u64 v[10:11], v[4:5], 0, s[96:97]
	s_mov_b32 m0, s64
	s_add_i32 s72, s56, 0x1c000
	global_load_lds_dwordx4 v[10:11], off
	v_lshl_add_u64 v[10:11], v[6:7], 0, s[96:97]
	s_mov_b32 m0, s72
	s_mov_b64 s[8:9], 0x20100
	s_add_i32 s73, s56, 0x1e000
	global_load_lds_dwordx4 v[10:11], off
	v_lshl_add_u64 v[10:11], v[6:7], 0, s[8:9]
	s_mov_b32 m0, s73
	s_mov_b64 s[8:9], 0x40100
	s_add_i32 s74, s56, 0x20000
	global_load_lds_dwordx4 v[10:11], off
	v_lshl_add_u64 v[10:11], v[6:7], 0, s[8:9]
	s_mov_b32 m0, s74
	s_mov_b64 s[8:9], 0x60100
	s_add_i32 s75, s56, 0x22000
	global_load_lds_dwordx4 v[10:11], off
	v_lshl_add_u64 v[10:11], v[6:7], 0, s[8:9]
	s_mov_b32 m0, s75
	v_readlane_b32 s12, v196, 10
	global_load_lds_dwordx4 v[10:11], off
	v_or_b32_e32 v11, v61, v60
	v_add_u32_e32 v10, 0, v80
	v_add_u32_e32 v11, 0, v11
	ds_read_b128 v[44:47], v10
	ds_read_b128 v[48:51], v10 offset:2048
	ds_read_b128 v[52:55], v10 offset:4096
	ds_read_b128 v[56:59], v10 offset:6144
	ds_read_b128 v[60:63], v11 offset:16384
	ds_read_b128 v[64:67], v11 offset:18432
	ds_read_b128 v[72:75], v11 offset:20480
	ds_read_b128 v[76:79], v11 offset:22528
	v_readlane_b32 s13, v196, 11
	v_readlane_b32 s14, v196, 12
	v_readlane_b32 s15, v196, 13
	v_readlane_b32 s16, v196, 14
	v_readlane_b32 s17, v196, 15
	v_readlane_b32 s18, v196, 16
	v_readlane_b32 s19, v196, 17
	v_readlane_b32 s20, v196, 18
	v_readlane_b32 s21, v196, 19
	v_readlane_b32 s22, v196, 20
	v_readlane_b32 s23, v196, 21
	s_waitcnt lgkmcnt(8)
	v_mfma_f32_16x16x32_bf16 v[84:87], v[40:43], v[12:15], 0
	v_mfma_f32_16x16x32_bf16 v[88:91], v[36:39], v[12:15], 0
	v_mfma_f32_16x16x32_bf16 v[92:95], v[32:35], v[12:15], 0
	v_mfma_f32_16x16x32_bf16 v[102:105], v[28:31], v[12:15], 0
	v_mfma_f32_16x16x32_bf16 v[106:109], v[40:43], v[16:19], 0
	v_mfma_f32_16x16x32_bf16 v[112:115], v[36:39], v[16:19], 0
	v_mfma_f32_16x16x32_bf16 v[116:119], v[32:35], v[16:19], 0
	v_mfma_f32_16x16x32_bf16 v[14:17], v[28:31], v[16:19], 0
	v_mfma_f32_16x16x32_bf16 v[120:123], v[40:43], v[20:23], 0
	v_mfma_f32_16x16x32_bf16 v[124:127], v[36:39], v[20:23], 0
	v_mfma_f32_16x16x32_bf16 v[128:131], v[32:35], v[20:23], 0
	v_mfma_f32_16x16x32_bf16 v[18:21], v[28:31], v[20:23], 0
	v_mfma_f32_16x16x32_bf16 v[40:43], v[40:43], v[24:27], 0
	v_mfma_f32_16x16x32_bf16 v[36:39], v[36:39], v[24:27], 0
	v_mfma_f32_16x16x32_bf16 v[32:35], v[32:35], v[24:27], 0
	v_mfma_f32_16x16x32_bf16 v[22:25], v[28:31], v[24:27], 0
	s_add_i32 s76, 0, 0xc000
	s_waitcnt vmcnt(6) lgkmcnt(0)
	s_barrier
	v_add_u32_e32 v12, s76, v69
	ds_read_b128 v[26:29], v8 offset:49152
	ds_read_b128 v[132:135], v8 offset:51200
	ds_read_b128 v[138:141], v8 offset:53248
	ds_read_b128 v[142:145], v8 offset:55296
	ds_read_b128 v[152:155], v12
	ds_read_b128 v[156:159], v12 offset:2048
	ds_read_b128 v[160:163], v12 offset:4096
	ds_read_b128 v[164:167], v12 offset:6144
	v_mfma_f32_16x16x32_bf16 v[84:87], v[60:63], v[44:47], v[84:87]
	v_mfma_f32_16x16x32_bf16 v[88:91], v[64:67], v[44:47], v[88:91]
	v_mfma_f32_16x16x32_bf16 v[92:95], v[72:75], v[44:47], v[92:95]
	v_mfma_f32_16x16x32_bf16 v[44:47], v[76:79], v[44:47], v[102:105]
	v_mfma_f32_16x16x32_bf16 v[102:105], v[60:63], v[48:51], v[106:109]
	v_mfma_f32_16x16x32_bf16 v[106:109], v[64:67], v[48:51], v[112:115]
	v_mfma_f32_16x16x32_bf16 v[112:115], v[72:75], v[48:51], v[116:119]
	v_mfma_f32_16x16x32_bf16 v[14:17], v[76:79], v[48:51], v[14:17]
	v_mfma_f32_16x16x32_bf16 v[48:51], v[60:63], v[52:55], v[120:123]
	v_mfma_f32_16x16x32_bf16 v[116:119], v[64:67], v[52:55], v[124:127]
	v_mfma_f32_16x16x32_bf16 v[120:123], v[72:75], v[52:55], v[128:131]
	v_mfma_f32_16x16x32_bf16 v[18:21], v[76:79], v[52:55], v[18:21]
	v_mfma_f32_16x16x32_bf16 v[40:43], v[60:63], v[56:59], v[40:43]
	v_mfma_f32_16x16x32_bf16 v[36:39], v[64:67], v[56:59], v[36:39]
	v_mfma_f32_16x16x32_bf16 v[30:33], v[72:75], v[56:59], v[32:35]
	v_mfma_f32_16x16x32_bf16 v[22:25], v[76:79], v[56:59], v[22:25]
	s_mov_b64 s[8:9], 0x180
	s_mov_b32 m0, s56
	v_lshl_add_u64 v[34:35], v[2:3], 0, s[8:9]
	global_load_lds_dwordx4 v[34:35], off
	v_lshl_add_u64 v[34:35], v[4:5], 0, s[8:9]
	s_mov_b32 m0, s1
	v_add_u32_e32 v13, s76, v81
	global_load_lds_dwordx4 v[34:35], off
	v_lshl_add_u64 v[34:35], v[6:7], 0, s[8:9]
	s_mov_b32 m0, s5
	s_mov_b64 s[8:9], 0x20180
	global_load_lds_dwordx4 v[34:35], off
	v_lshl_add_u64 v[34:35], v[6:7], 0, s[8:9]
	s_mov_b32 m0, s33
	s_mov_b64 s[8:9], 0x40180
	global_load_lds_dwordx4 v[34:35], off
	v_lshl_add_u64 v[34:35], v[6:7], 0, s[8:9]
	s_mov_b32 m0, s38
	s_mov_b64 s[8:9], 0x60180
	global_load_lds_dwordx4 v[34:35], off
	v_lshl_add_u64 v[34:35], v[6:7], 0, s[8:9]
	s_mov_b32 m0, s39
	s_nop 0
	global_load_lds_dwordx4 v[34:35], off
	ds_read_b128 v[52:55], v10 offset:49152
	ds_read_b128 v[56:59], v10 offset:51200
	ds_read_b128 v[60:63], v10 offset:53248
	ds_read_b128 v[64:67], v10 offset:55296
	ds_read_b128 v[72:75], v13
	ds_read_b128 v[76:79], v13 offset:2048
	ds_read_b128 v[124:127], v13 offset:4096
	ds_read_b128 v[128:131], v13 offset:6144
	s_waitcnt lgkmcnt(8)
	v_mfma_f32_16x16x32_bf16 v[84:87], v[152:155], v[26:29], v[84:87]
	v_mfma_f32_16x16x32_bf16 v[88:91], v[156:159], v[26:29], v[88:91]
	v_mfma_f32_16x16x32_bf16 v[92:95], v[160:163], v[26:29], v[92:95]
	v_mfma_f32_16x16x32_bf16 v[26:29], v[164:167], v[26:29], v[44:47]
	v_mfma_f32_16x16x32_bf16 v[44:47], v[152:155], v[132:135], v[102:105]
	v_mfma_f32_16x16x32_bf16 v[102:105], v[156:159], v[132:135], v[106:109]
	v_mfma_f32_16x16x32_bf16 v[106:109], v[160:163], v[132:135], v[112:115]
	v_mfma_f32_16x16x32_bf16 v[112:115], v[164:167], v[132:135], v[14:17]
	v_mfma_f32_16x16x32_bf16 v[48:51], v[152:155], v[138:141], v[48:51]
	v_mfma_f32_16x16x32_bf16 v[116:119], v[156:159], v[138:141], v[116:119]
	v_mfma_f32_16x16x32_bf16 v[120:123], v[160:163], v[138:141], v[120:123]
	v_mfma_f32_16x16x32_bf16 v[16:19], v[164:167], v[138:141], v[18:21]
	v_mfma_f32_16x16x32_bf16 v[40:43], v[152:155], v[142:145], v[40:43]
	v_mfma_f32_16x16x32_bf16 v[34:37], v[156:159], v[142:145], v[36:39]
	v_mfma_f32_16x16x32_bf16 v[30:33], v[160:163], v[142:145], v[30:33]
	v_mfma_f32_16x16x32_bf16 v[20:23], v[164:167], v[142:145], v[22:25]
	s_add_i32 s76, 0, 0x18000
	s_waitcnt vmcnt(6) lgkmcnt(0)
	s_barrier
	v_add_u32_e32 v14, s76, v68
	v_add_u32_e32 v15, s76, v69
	ds_read_b128 v[132:135], v14
	ds_read_b128 v[138:141], v14 offset:2048
	ds_read_b128 v[142:145], v14 offset:4096
	ds_read_b128 v[152:155], v14 offset:6144
	ds_read_b128 v[156:159], v15
	ds_read_b128 v[160:163], v15 offset:2048
	ds_read_b128 v[164:167], v15 offset:4096
	ds_read_b128 v[168:171], v15 offset:6144
	v_mfma_f32_16x16x32_bf16 v[84:87], v[72:75], v[52:55], v[84:87]
	v_mfma_f32_16x16x32_bf16 v[88:91], v[76:79], v[52:55], v[88:91]
	v_mfma_f32_16x16x32_bf16 v[92:95], v[124:127], v[52:55], v[92:95]
	v_mfma_f32_16x16x32_bf16 v[24:27], v[128:131], v[52:55], v[26:29]
	v_mfma_f32_16x16x32_bf16 v[44:47], v[72:75], v[56:59], v[44:47]
	v_mfma_f32_16x16x32_bf16 v[52:55], v[76:79], v[56:59], v[102:105]
	v_mfma_f32_16x16x32_bf16 v[102:105], v[124:127], v[56:59], v[106:109]
	v_mfma_f32_16x16x32_bf16 v[56:59], v[128:131], v[56:59], v[112:115]
	v_mfma_f32_16x16x32_bf16 v[48:51], v[72:75], v[60:63], v[48:51]
	v_mfma_f32_16x16x32_bf16 v[106:109], v[76:79], v[60:63], v[116:119]
	v_mfma_f32_16x16x32_bf16 v[112:115], v[124:127], v[60:63], v[120:123]
	v_mfma_f32_16x16x32_bf16 v[60:63], v[128:131], v[60:63], v[16:19]
	v_mfma_f32_16x16x32_bf16 v[38:41], v[72:75], v[64:67], v[40:43]
	v_mfma_f32_16x16x32_bf16 v[34:37], v[76:79], v[64:67], v[34:37]
	v_mfma_f32_16x16x32_bf16 v[28:31], v[124:127], v[64:67], v[30:33]
	v_mfma_f32_16x16x32_bf16 v[18:21], v[128:131], v[64:67], v[20:23]
	s_mov_b64 s[8:9], 0x200
	s_mov_b32 m0, s59
	v_lshl_add_u64 v[16:17], v[2:3], 0, s[8:9]
	global_load_lds_dwordx4 v[16:17], off
	v_lshl_add_u64 v[16:17], v[4:5], 0, s[8:9]
	s_mov_b32 m0, s57
	s_nop 0
	global_load_lds_dwordx4 v[16:17], off
	v_lshl_add_u64 v[16:17], v[6:7], 0, s[8:9]
	s_mov_b32 m0, s60
	s_mov_b64 s[8:9], 0x20200
	global_load_lds_dwordx4 v[16:17], off
	v_lshl_add_u64 v[16:17], v[6:7], 0, s[8:9]
	s_mov_b32 m0, s61
	s_mov_b64 s[8:9], 0x40200
	global_load_lds_dwordx4 v[16:17], off
	v_lshl_add_u64 v[16:17], v[6:7], 0, s[8:9]
	s_mov_b32 m0, s62
	s_mov_b64 s[8:9], 0x60200
	global_load_lds_dwordx4 v[16:17], off
	v_lshl_add_u64 v[16:17], v[6:7], 0, s[8:9]
	s_mov_b32 m0, s71
	s_nop 0
	global_load_lds_dwordx4 v[16:17], off
	v_add_u32_e32 v16, s76, v80
	v_add_u32_e32 v17, s76, v81
	ds_read_b128 v[64:67], v16
	ds_read_b128 v[72:75], v16 offset:2048
	ds_read_b128 v[76:79], v16 offset:4096
	ds_read_b128 v[116:119], v16 offset:6144
	ds_read_b128 v[120:123], v17
	ds_read_b128 v[124:127], v17 offset:2048
	ds_read_b128 v[128:131], v17 offset:4096
	ds_read_b128 v[172:175], v17 offset:6144
	s_waitcnt lgkmcnt(8)
	v_mfma_f32_16x16x32_bf16 v[84:87], v[156:159], v[132:135], v[84:87]
	v_mfma_f32_16x16x32_bf16 v[88:91], v[160:163], v[132:135], v[88:91]
	v_mfma_f32_16x16x32_bf16 v[92:95], v[164:167], v[132:135], v[92:95]
	v_mfma_f32_16x16x32_bf16 v[22:25], v[168:171], v[132:135], v[24:27]
	v_mfma_f32_16x16x32_bf16 v[42:45], v[156:159], v[138:141], v[44:47]
	v_mfma_f32_16x16x32_bf16 v[52:55], v[160:163], v[138:141], v[52:55]
	v_mfma_f32_16x16x32_bf16 v[102:105], v[164:167], v[138:141], v[102:105]
	v_mfma_f32_16x16x32_bf16 v[56:59], v[168:171], v[138:141], v[56:59]
	v_mfma_f32_16x16x32_bf16 v[46:49], v[156:159], v[142:145], v[48:51]
	v_mfma_f32_16x16x32_bf16 v[106:109], v[160:163], v[142:145], v[106:109]
	v_mfma_f32_16x16x32_bf16 v[112:115], v[164:167], v[142:145], v[112:115]
	v_mfma_f32_16x16x32_bf16 v[60:63], v[168:171], v[142:145], v[60:63]
	v_mfma_f32_16x16x32_bf16 v[38:41], v[156:159], v[152:155], v[38:41]
	v_mfma_f32_16x16x32_bf16 v[32:35], v[160:163], v[152:155], v[34:37]
	v_mfma_f32_16x16x32_bf16 v[26:29], v[164:167], v[152:155], v[28:31]
	v_mfma_f32_16x16x32_bf16 v[18:21], v[168:171], v[152:155], v[18:21]
	s_waitcnt vmcnt(6) lgkmcnt(0)
	s_barrier
	ds_read_b128 v[132:135], v8
	ds_read_b128 v[138:141], v8 offset:2048
	ds_read_b128 v[142:145], v8 offset:4096
	ds_read_b128 v[152:155], v8 offset:6144
	ds_read_b128 v[156:159], v9 offset:16384
	ds_read_b128 v[160:163], v9 offset:18432
	ds_read_b128 v[164:167], v9 offset:20480
	ds_read_b128 v[168:171], v9 offset:22528
	v_mfma_f32_16x16x32_bf16 v[84:87], v[120:123], v[64:67], v[84:87]
	v_mfma_f32_16x16x32_bf16 v[88:91], v[124:127], v[64:67], v[88:91]
	v_mfma_f32_16x16x32_bf16 v[92:95], v[128:131], v[64:67], v[92:95]
	v_mfma_f32_16x16x32_bf16 v[22:25], v[172:175], v[64:67], v[22:25]
	v_mfma_f32_16x16x32_bf16 v[42:45], v[120:123], v[72:75], v[42:45]
	v_mfma_f32_16x16x32_bf16 v[50:53], v[124:127], v[72:75], v[52:55]
	v_mfma_f32_16x16x32_bf16 v[64:67], v[128:131], v[72:75], v[102:105]
	v_mfma_f32_16x16x32_bf16 v[54:57], v[172:175], v[72:75], v[56:59]
	v_mfma_f32_16x16x32_bf16 v[46:49], v[120:123], v[76:79], v[46:49]
	v_mfma_f32_16x16x32_bf16 v[72:75], v[124:127], v[76:79], v[106:109]
	v_mfma_f32_16x16x32_bf16 v[102:105], v[128:131], v[76:79], v[112:115]
	v_mfma_f32_16x16x32_bf16 v[58:61], v[172:175], v[76:79], v[60:63]
	v_mfma_f32_16x16x32_bf16 v[36:39], v[120:123], v[116:119], v[38:41]
	v_mfma_f32_16x16x32_bf16 v[30:33], v[124:127], v[116:119], v[32:35]
	v_mfma_f32_16x16x32_bf16 v[26:29], v[128:131], v[116:119], v[26:29]
	v_mfma_f32_16x16x32_bf16 v[18:21], v[172:175], v[116:119], v[18:21]
	s_mov_b64 s[8:9], 0x280
	s_mov_b32 m0, s63
	v_lshl_add_u64 v[34:35], v[2:3], 0, s[8:9]
	global_load_lds_dwordx4 v[34:35], off
	v_lshl_add_u64 v[34:35], v[4:5], 0, s[8:9]
	s_mov_b32 m0, s64
	s_nop 0
	global_load_lds_dwordx4 v[34:35], off
	v_lshl_add_u64 v[34:35], v[6:7], 0, s[8:9]
	s_mov_b32 m0, s72
	s_mov_b64 s[8:9], 0x20280
	global_load_lds_dwordx4 v[34:35], off
	v_lshl_add_u64 v[34:35], v[6:7], 0, s[8:9]
	s_mov_b32 m0, s73
	s_mov_b64 s[8:9], 0x40280
	global_load_lds_dwordx4 v[34:35], off
	v_lshl_add_u64 v[34:35], v[6:7], 0, s[8:9]
	s_mov_b32 m0, s74
	s_mov_b64 s[8:9], 0x60280
	global_load_lds_dwordx4 v[34:35], off
	v_lshl_add_u64 v[34:35], v[6:7], 0, s[8:9]
	s_mov_b32 m0, s75
	s_nop 0
	global_load_lds_dwordx4 v[34:35], off
	ds_read_b128 v[76:79], v10
	ds_read_b128 v[106:109], v10 offset:2048
	ds_read_b128 v[112:115], v10 offset:4096
	ds_read_b128 v[116:119], v10 offset:6144
	ds_read_b128 v[120:123], v11 offset:16384
	ds_read_b128 v[124:127], v11 offset:18432
	ds_read_b128 v[128:131], v11 offset:20480
	ds_read_b128 v[172:175], v11 offset:22528
	s_waitcnt lgkmcnt(8)
	v_mfma_f32_16x16x32_bf16 v[84:87], v[156:159], v[132:135], v[84:87]
	v_mfma_f32_16x16x32_bf16 v[88:91], v[160:163], v[132:135], v[88:91]
	v_mfma_f32_16x16x32_bf16 v[92:95], v[164:167], v[132:135], v[92:95]
	v_mfma_f32_16x16x32_bf16 v[22:25], v[168:171], v[132:135], v[22:25]
	v_mfma_f32_16x16x32_bf16 v[40:43], v[156:159], v[138:141], v[42:45]
	v_mfma_f32_16x16x32_bf16 v[50:53], v[160:163], v[138:141], v[50:53]
	v_mfma_f32_16x16x32_bf16 v[62:65], v[164:167], v[138:141], v[64:67]
	v_mfma_f32_16x16x32_bf16 v[54:57], v[168:171], v[138:141], v[54:57]
	v_mfma_f32_16x16x32_bf16 v[44:47], v[156:159], v[142:145], v[46:49]
	v_mfma_f32_16x16x32_bf16 v[66:69], v[160:163], v[142:145], v[72:75]
	v_mfma_f32_16x16x32_bf16 v[72:75], v[164:167], v[142:145], v[102:105]
	v_mfma_f32_16x16x32_bf16 v[58:61], v[168:171], v[142:145], v[58:61]
	v_mfma_f32_16x16x32_bf16 v[34:37], v[156:159], v[152:155], v[36:39]
	v_mfma_f32_16x16x32_bf16 v[30:33], v[160:163], v[152:155], v[30:33]
	v_mfma_f32_16x16x32_bf16 v[26:29], v[164:167], v[152:155], v[26:29]
	v_mfma_f32_16x16x32_bf16 v[18:21], v[168:171], v[152:155], v[18:21]
	s_waitcnt vmcnt(6) lgkmcnt(0)
	s_barrier
	ds_read_b128 v[102:105], v8 offset:49152
	ds_read_b128 v[132:135], v8 offset:51200
	ds_read_b128 v[138:141], v8 offset:53248
	ds_read_b128 v[142:145], v8 offset:55296
	ds_read_b128 v[152:155], v12
	ds_read_b128 v[156:159], v12 offset:2048
	ds_read_b128 v[160:163], v12 offset:4096
	ds_read_b128 v[164:167], v12 offset:6144
	v_mfma_f32_16x16x32_bf16 v[84:87], v[120:123], v[76:79], v[84:87]
	v_mfma_f32_16x16x32_bf16 v[88:91], v[124:127], v[76:79], v[88:91]
	v_mfma_f32_16x16x32_bf16 v[92:95], v[128:131], v[76:79], v[92:95]
	v_mfma_f32_16x16x32_bf16 v[22:25], v[172:175], v[76:79], v[22:25]
	v_mfma_f32_16x16x32_bf16 v[38:41], v[120:123], v[106:109], v[40:43]
	v_mfma_f32_16x16x32_bf16 v[48:51], v[124:127], v[106:109], v[50:53]
	v_mfma_f32_16x16x32_bf16 v[62:65], v[128:131], v[106:109], v[62:65]
	v_mfma_f32_16x16x32_bf16 v[52:55], v[172:175], v[106:109], v[54:57]
	v_mfma_f32_16x16x32_bf16 v[42:45], v[120:123], v[112:115], v[44:47]
	v_mfma_f32_16x16x32_bf16 v[66:69], v[124:127], v[112:115], v[66:69]
	v_mfma_f32_16x16x32_bf16 v[72:75], v[128:131], v[112:115], v[72:75]
	v_mfma_f32_16x16x32_bf16 v[56:59], v[172:175], v[112:115], v[58:61]
	v_mfma_f32_16x16x32_bf16 v[34:37], v[120:123], v[116:119], v[34:37]
	v_mfma_f32_16x16x32_bf16 v[30:33], v[124:127], v[116:119], v[30:33]
	v_mfma_f32_16x16x32_bf16 v[26:29], v[128:131], v[116:119], v[26:29]
	v_mfma_f32_16x16x32_bf16 v[18:21], v[172:175], v[116:119], v[18:21]
	s_mov_b64 s[8:9], 0x300
	s_mov_b32 m0, s56
	v_lshl_add_u64 v[46:47], v[2:3], 0, s[8:9]
	global_load_lds_dwordx4 v[46:47], off
	v_lshl_add_u64 v[46:47], v[4:5], 0, s[8:9]
	s_mov_b32 m0, s1
	s_nop 0
	global_load_lds_dwordx4 v[46:47], off
	v_lshl_add_u64 v[46:47], v[6:7], 0, s[8:9]
	s_mov_b32 m0, s5
	s_mov_b64 s[8:9], 0x20300
	global_load_lds_dwordx4 v[46:47], off
	v_lshl_add_u64 v[46:47], v[6:7], 0, s[8:9]
	s_mov_b32 m0, s33
	s_mov_b64 s[8:9], 0x40300
	global_load_lds_dwordx4 v[46:47], off
	v_lshl_add_u64 v[46:47], v[6:7], 0, s[8:9]
	s_mov_b32 m0, s38
	s_mov_b64 s[8:9], 0x60300
	global_load_lds_dwordx4 v[46:47], off
	v_lshl_add_u64 v[46:47], v[6:7], 0, s[8:9]
	s_mov_b32 m0, s39
	s_nop 0
	global_load_lds_dwordx4 v[46:47], off
	ds_read_b128 v[76:79], v10 offset:49152
	ds_read_b128 v[106:109], v10 offset:51200
	ds_read_b128 v[112:115], v10 offset:53248
	ds_read_b128 v[116:119], v10 offset:55296
	ds_read_b128 v[120:123], v13
	ds_read_b128 v[124:127], v13 offset:2048
	ds_read_b128 v[128:131], v13 offset:4096
	ds_read_b128 v[168:171], v13 offset:6144
	s_waitcnt lgkmcnt(8)
	v_mfma_f32_16x16x32_bf16 v[84:87], v[152:155], v[102:105], v[84:87]
	v_mfma_f32_16x16x32_bf16 v[88:91], v[156:159], v[102:105], v[88:91]
	v_mfma_f32_16x16x32_bf16 v[92:95], v[160:163], v[102:105], v[92:95]
	v_mfma_f32_16x16x32_bf16 v[22:25], v[164:167], v[102:105], v[22:25]
	v_mfma_f32_16x16x32_bf16 v[38:41], v[152:155], v[132:135], v[38:41]
	v_mfma_f32_16x16x32_bf16 v[46:49], v[156:159], v[132:135], v[48:51]
	v_mfma_f32_16x16x32_bf16 v[60:63], v[160:163], v[132:135], v[62:65]
	v_mfma_f32_16x16x32_bf16 v[50:53], v[164:167], v[132:135], v[52:55]
	v_mfma_f32_16x16x32_bf16 v[42:45], v[152:155], v[138:141], v[42:45]
	v_mfma_f32_16x16x32_bf16 v[64:67], v[156:159], v[138:141], v[66:69]
	v_mfma_f32_16x16x32_bf16 v[72:75], v[160:163], v[138:141], v[72:75]
	v_mfma_f32_16x16x32_bf16 v[54:57], v[164:167], v[138:141], v[56:59]
	v_mfma_f32_16x16x32_bf16 v[34:37], v[152:155], v[142:145], v[34:37]
	v_mfma_f32_16x16x32_bf16 v[30:33], v[156:159], v[142:145], v[30:33]
	v_mfma_f32_16x16x32_bf16 v[26:29], v[160:163], v[142:145], v[26:29]
	v_mfma_f32_16x16x32_bf16 v[18:21], v[164:167], v[142:145], v[18:21]
	s_waitcnt vmcnt(6) lgkmcnt(0)
	s_barrier
	ds_read_b128 v[102:105], v14
	ds_read_b128 v[132:135], v14 offset:2048
	ds_read_b128 v[138:141], v14 offset:4096
	ds_read_b128 v[142:145], v14 offset:6144
	ds_read_b128 v[152:155], v15
	ds_read_b128 v[156:159], v15 offset:2048
	ds_read_b128 v[160:163], v15 offset:4096
	ds_read_b128 v[164:167], v15 offset:6144
	v_mfma_f32_16x16x32_bf16 v[84:87], v[120:123], v[76:79], v[84:87]
	v_mfma_f32_16x16x32_bf16 v[88:91], v[124:127], v[76:79], v[88:91]
	v_mfma_f32_16x16x32_bf16 v[92:95], v[128:131], v[76:79], v[92:95]
	v_mfma_f32_16x16x32_bf16 v[22:25], v[168:171], v[76:79], v[22:25]
	v_mfma_f32_16x16x32_bf16 v[38:41], v[120:123], v[106:109], v[38:41]
	v_mfma_f32_16x16x32_bf16 v[46:49], v[124:127], v[106:109], v[46:49]
	v_mfma_f32_16x16x32_bf16 v[58:61], v[128:131], v[106:109], v[60:63]
	v_mfma_f32_16x16x32_bf16 v[50:53], v[168:171], v[106:109], v[50:53]
	v_mfma_f32_16x16x32_bf16 v[42:45], v[120:123], v[112:115], v[42:45]
	v_mfma_f32_16x16x32_bf16 v[62:65], v[124:127], v[112:115], v[64:67]
	v_mfma_f32_16x16x32_bf16 v[66:69], v[128:131], v[112:115], v[72:75]
	v_mfma_f32_16x16x32_bf16 v[54:57], v[168:171], v[112:115], v[54:57]
	v_mfma_f32_16x16x32_bf16 v[34:37], v[120:123], v[116:119], v[34:37]
	v_mfma_f32_16x16x32_bf16 v[30:33], v[124:127], v[116:119], v[30:33]
	v_mfma_f32_16x16x32_bf16 v[26:29], v[128:131], v[116:119], v[26:29]
	v_mfma_f32_16x16x32_bf16 v[18:21], v[168:171], v[116:119], v[18:21]
	s_mov_b64 s[8:9], 0x380
	s_mov_b32 m0, s59
	v_lshl_add_u64 v[72:73], v[2:3], 0, s[8:9]
	global_load_lds_dwordx4 v[72:73], off
	v_lshl_add_u64 v[72:73], v[4:5], 0, s[8:9]
	s_mov_b32 m0, s57
	s_nop 0
	global_load_lds_dwordx4 v[72:73], off
	v_lshl_add_u64 v[72:73], v[6:7], 0, s[8:9]
	s_mov_b32 m0, s60
	s_mov_b64 s[8:9], 0x20380
	global_load_lds_dwordx4 v[72:73], off
	v_lshl_add_u64 v[72:73], v[6:7], 0, s[8:9]
	s_mov_b32 m0, s61
	s_mov_b64 s[8:9], 0x40380
	global_load_lds_dwordx4 v[72:73], off
	v_lshl_add_u64 v[72:73], v[6:7], 0, s[8:9]
	s_mov_b32 m0, s62
	s_mov_b64 s[8:9], 0x60380
	global_load_lds_dwordx4 v[72:73], off
	v_lshl_add_u64 v[72:73], v[6:7], 0, s[8:9]
	s_mov_b32 m0, s71
	s_nop 0
	global_load_lds_dwordx4 v[72:73], off
	ds_read_b128 v[72:75], v16
	ds_read_b128 v[76:79], v16 offset:2048
	ds_read_b128 v[106:109], v16 offset:4096
	ds_read_b128 v[112:115], v16 offset:6144
	ds_read_b128 v[116:119], v17
	ds_read_b128 v[120:123], v17 offset:2048
	ds_read_b128 v[124:127], v17 offset:4096
	ds_read_b128 v[128:131], v17 offset:6144
	s_waitcnt lgkmcnt(8)
	v_mfma_f32_16x16x32_bf16 v[84:87], v[152:155], v[102:105], v[84:87]
	v_mfma_f32_16x16x32_bf16 v[88:91], v[156:159], v[102:105], v[88:91]
	v_mfma_f32_16x16x32_bf16 v[92:95], v[160:163], v[102:105], v[92:95]
	v_mfma_f32_16x16x32_bf16 v[22:25], v[164:167], v[102:105], v[22:25]
	v_mfma_f32_16x16x32_bf16 v[38:41], v[152:155], v[132:135], v[38:41]
	v_mfma_f32_16x16x32_bf16 v[46:49], v[156:159], v[132:135], v[46:49]
	v_mfma_f32_16x16x32_bf16 v[58:61], v[160:163], v[132:135], v[58:61]
	v_mfma_f32_16x16x32_bf16 v[50:53], v[164:167], v[132:135], v[50:53]
	v_mfma_f32_16x16x32_bf16 v[42:45], v[152:155], v[138:141], v[42:45]
	v_mfma_f32_16x16x32_bf16 v[62:65], v[156:159], v[138:141], v[62:65]
	v_mfma_f32_16x16x32_bf16 v[66:69], v[160:163], v[138:141], v[66:69]
	v_mfma_f32_16x16x32_bf16 v[54:57], v[164:167], v[138:141], v[54:57]
	v_mfma_f32_16x16x32_bf16 v[34:37], v[152:155], v[142:145], v[34:37]
	v_mfma_f32_16x16x32_bf16 v[30:33], v[156:159], v[142:145], v[30:33]
	v_mfma_f32_16x16x32_bf16 v[26:29], v[160:163], v[142:145], v[26:29]
	v_mfma_f32_16x16x32_bf16 v[18:21], v[164:167], v[142:145], v[18:21]
	s_waitcnt vmcnt(6) lgkmcnt(0)
	s_barrier
	ds_read_b128 v[102:105], v8
	ds_read_b128 v[132:135], v8 offset:2048
	ds_read_b128 v[138:141], v8 offset:4096
	ds_read_b128 v[142:145], v8 offset:6144
	ds_read_b128 v[152:155], v9 offset:16384
	ds_read_b128 v[156:159], v9 offset:18432
	ds_read_b128 v[160:163], v9 offset:20480
	ds_read_b128 v[164:167], v9 offset:22528
	v_mfma_f32_16x16x32_bf16 v[84:87], v[116:119], v[72:75], v[84:87]
	v_mfma_f32_16x16x32_bf16 v[88:91], v[120:123], v[72:75], v[88:91]
	v_mfma_f32_16x16x32_bf16 v[92:95], v[124:127], v[72:75], v[92:95]
	v_mfma_f32_16x16x32_bf16 v[22:25], v[128:131], v[72:75], v[22:25]
	v_mfma_f32_16x16x32_bf16 v[38:41], v[116:119], v[76:79], v[38:41]
	v_mfma_f32_16x16x32_bf16 v[46:49], v[120:123], v[76:79], v[46:49]
	v_mfma_f32_16x16x32_bf16 v[58:61], v[124:127], v[76:79], v[58:61]
	v_mfma_f32_16x16x32_bf16 v[50:53], v[128:131], v[76:79], v[50:53]
	v_mfma_f32_16x16x32_bf16 v[42:45], v[116:119], v[106:109], v[42:45]
	v_mfma_f32_16x16x32_bf16 v[62:65], v[120:123], v[106:109], v[62:65]
	v_mfma_f32_16x16x32_bf16 v[66:69], v[124:127], v[106:109], v[66:69]
	v_mfma_f32_16x16x32_bf16 v[54:57], v[128:131], v[106:109], v[54:57]
	v_mfma_f32_16x16x32_bf16 v[34:37], v[116:119], v[112:115], v[34:37]
	v_mfma_f32_16x16x32_bf16 v[30:33], v[120:123], v[112:115], v[30:33]
	v_mfma_f32_16x16x32_bf16 v[26:29], v[124:127], v[112:115], v[26:29]
	v_mfma_f32_16x16x32_bf16 v[18:21], v[128:131], v[112:115], v[18:21]
	s_mov_b64 s[8:9], 0x400
	s_mov_b32 m0, s63
	v_lshl_add_u64 v[72:73], v[2:3], 0, s[8:9]
	global_load_lds_dwordx4 v[72:73], off
	v_lshl_add_u64 v[72:73], v[4:5], 0, s[8:9]
	s_mov_b32 m0, s64
	s_nop 0
	global_load_lds_dwordx4 v[72:73], off
	v_lshl_add_u64 v[72:73], v[6:7], 0, s[8:9]
	s_mov_b32 m0, s72
	s_mov_b64 s[8:9], 0x20400
	global_load_lds_dwordx4 v[72:73], off
	v_lshl_add_u64 v[72:73], v[6:7], 0, s[8:9]
	s_mov_b32 m0, s73
	s_mov_b64 s[8:9], 0x40400
	global_load_lds_dwordx4 v[72:73], off
	v_lshl_add_u64 v[72:73], v[6:7], 0, s[8:9]
	s_mov_b32 m0, s74
	s_mov_b64 s[8:9], 0x60400
	global_load_lds_dwordx4 v[72:73], off
	v_lshl_add_u64 v[72:73], v[6:7], 0, s[8:9]
	s_mov_b32 m0, s75
	s_nop 0
	global_load_lds_dwordx4 v[72:73], off
	ds_read_b128 v[72:75], v10
	ds_read_b128 v[76:79], v10 offset:2048
	ds_read_b128 v[106:109], v10 offset:4096
	ds_read_b128 v[112:115], v10 offset:6144
	ds_read_b128 v[116:119], v11 offset:16384
	ds_read_b128 v[120:123], v11 offset:18432
	ds_read_b128 v[124:127], v11 offset:20480
	ds_read_b128 v[128:131], v11 offset:22528
	s_waitcnt lgkmcnt(8)
	v_mfma_f32_16x16x32_bf16 v[84:87], v[152:155], v[102:105], v[84:87]
	v_mfma_f32_16x16x32_bf16 v[88:91], v[156:159], v[102:105], v[88:91]
	v_mfma_f32_16x16x32_bf16 v[92:95], v[160:163], v[102:105], v[92:95]
	v_mfma_f32_16x16x32_bf16 v[22:25], v[164:167], v[102:105], v[22:25]
	v_mfma_f32_16x16x32_bf16 v[38:41], v[152:155], v[132:135], v[38:41]
	v_mfma_f32_16x16x32_bf16 v[46:49], v[156:159], v[132:135], v[46:49]
	v_mfma_f32_16x16x32_bf16 v[58:61], v[160:163], v[132:135], v[58:61]
	v_mfma_f32_16x16x32_bf16 v[50:53], v[164:167], v[132:135], v[50:53]
	v_mfma_f32_16x16x32_bf16 v[42:45], v[152:155], v[138:141], v[42:45]
	v_mfma_f32_16x16x32_bf16 v[62:65], v[156:159], v[138:141], v[62:65]
	v_mfma_f32_16x16x32_bf16 v[66:69], v[160:163], v[138:141], v[66:69]
	v_mfma_f32_16x16x32_bf16 v[54:57], v[164:167], v[138:141], v[54:57]
	v_mfma_f32_16x16x32_bf16 v[34:37], v[152:155], v[142:145], v[34:37]
	v_mfma_f32_16x16x32_bf16 v[30:33], v[156:159], v[142:145], v[30:33]
	v_mfma_f32_16x16x32_bf16 v[26:29], v[160:163], v[142:145], v[26:29]
	v_mfma_f32_16x16x32_bf16 v[18:21], v[164:167], v[142:145], v[18:21]
	s_waitcnt vmcnt(6) lgkmcnt(0)
	s_barrier
	ds_read_b128 v[102:105], v8 offset:49152
	ds_read_b128 v[132:135], v8 offset:51200
	ds_read_b128 v[138:141], v8 offset:53248
	ds_read_b128 v[142:145], v8 offset:55296
	ds_read_b128 v[152:155], v12
	ds_read_b128 v[156:159], v12 offset:2048
	ds_read_b128 v[160:163], v12 offset:4096
	ds_read_b128 v[164:167], v12 offset:6144
	v_mfma_f32_16x16x32_bf16 v[84:87], v[116:119], v[72:75], v[84:87]
	v_mfma_f32_16x16x32_bf16 v[88:91], v[120:123], v[72:75], v[88:91]
	v_mfma_f32_16x16x32_bf16 v[92:95], v[124:127], v[72:75], v[92:95]
	v_mfma_f32_16x16x32_bf16 v[22:25], v[128:131], v[72:75], v[22:25]
	v_mfma_f32_16x16x32_bf16 v[38:41], v[116:119], v[76:79], v[38:41]
	v_mfma_f32_16x16x32_bf16 v[46:49], v[120:123], v[76:79], v[46:49]
	v_mfma_f32_16x16x32_bf16 v[58:61], v[124:127], v[76:79], v[58:61]
	v_mfma_f32_16x16x32_bf16 v[50:53], v[128:131], v[76:79], v[50:53]
	v_mfma_f32_16x16x32_bf16 v[42:45], v[116:119], v[106:109], v[42:45]
	v_mfma_f32_16x16x32_bf16 v[62:65], v[120:123], v[106:109], v[62:65]
	v_mfma_f32_16x16x32_bf16 v[66:69], v[124:127], v[106:109], v[66:69]
	v_mfma_f32_16x16x32_bf16 v[54:57], v[128:131], v[106:109], v[54:57]
	v_mfma_f32_16x16x32_bf16 v[34:37], v[116:119], v[112:115], v[34:37]
	v_mfma_f32_16x16x32_bf16 v[30:33], v[120:123], v[112:115], v[30:33]
	v_mfma_f32_16x16x32_bf16 v[26:29], v[124:127], v[112:115], v[26:29]
	v_mfma_f32_16x16x32_bf16 v[18:21], v[128:131], v[112:115], v[18:21]
	s_mov_b64 s[8:9], 0x480
	s_mov_b32 m0, s56
	v_lshl_add_u64 v[72:73], v[2:3], 0, s[8:9]
	global_load_lds_dwordx4 v[72:73], off
	v_lshl_add_u64 v[72:73], v[4:5], 0, s[8:9]
	s_mov_b32 m0, s1
	s_nop 0
	global_load_lds_dwordx4 v[72:73], off
	v_lshl_add_u64 v[72:73], v[6:7], 0, s[8:9]
	s_mov_b32 m0, s5
	s_mov_b64 s[8:9], 0x20480
	global_load_lds_dwordx4 v[72:73], off
	v_lshl_add_u64 v[72:73], v[6:7], 0, s[8:9]
	s_mov_b32 m0, s33
	s_mov_b64 s[8:9], 0x40480
	global_load_lds_dwordx4 v[72:73], off
	v_lshl_add_u64 v[72:73], v[6:7], 0, s[8:9]
	s_mov_b32 m0, s38
	s_mov_b64 s[8:9], 0x60480
	global_load_lds_dwordx4 v[72:73], off
	v_lshl_add_u64 v[72:73], v[6:7], 0, s[8:9]
	s_mov_b32 m0, s39
	s_nop 0
	global_load_lds_dwordx4 v[72:73], off
	ds_read_b128 v[72:75], v10 offset:49152
	ds_read_b128 v[76:79], v10 offset:51200
	ds_read_b128 v[106:109], v10 offset:53248
	ds_read_b128 v[112:115], v10 offset:55296
	ds_read_b128 v[116:119], v13
	ds_read_b128 v[120:123], v13 offset:2048
	ds_read_b128 v[124:127], v13 offset:4096
	ds_read_b128 v[128:131], v13 offset:6144
	s_waitcnt lgkmcnt(8)
	v_mfma_f32_16x16x32_bf16 v[84:87], v[152:155], v[102:105], v[84:87]
	v_mfma_f32_16x16x32_bf16 v[88:91], v[156:159], v[102:105], v[88:91]
	v_mfma_f32_16x16x32_bf16 v[92:95], v[160:163], v[102:105], v[92:95]
	v_mfma_f32_16x16x32_bf16 v[22:25], v[164:167], v[102:105], v[22:25]
	v_mfma_f32_16x16x32_bf16 v[38:41], v[152:155], v[132:135], v[38:41]
	v_mfma_f32_16x16x32_bf16 v[46:49], v[156:159], v[132:135], v[46:49]
	v_mfma_f32_16x16x32_bf16 v[58:61], v[160:163], v[132:135], v[58:61]
	v_mfma_f32_16x16x32_bf16 v[50:53], v[164:167], v[132:135], v[50:53]
	v_mfma_f32_16x16x32_bf16 v[42:45], v[152:155], v[138:141], v[42:45]
	v_mfma_f32_16x16x32_bf16 v[62:65], v[156:159], v[138:141], v[62:65]
	v_mfma_f32_16x16x32_bf16 v[66:69], v[160:163], v[138:141], v[66:69]
	v_mfma_f32_16x16x32_bf16 v[54:57], v[164:167], v[138:141], v[54:57]
	v_mfma_f32_16x16x32_bf16 v[34:37], v[152:155], v[142:145], v[34:37]
	v_mfma_f32_16x16x32_bf16 v[30:33], v[156:159], v[142:145], v[30:33]
	v_mfma_f32_16x16x32_bf16 v[26:29], v[160:163], v[142:145], v[26:29]
	v_mfma_f32_16x16x32_bf16 v[18:21], v[164:167], v[142:145], v[18:21]
	s_waitcnt vmcnt(6) lgkmcnt(0)
	s_barrier
	ds_read_b128 v[102:105], v14
	ds_read_b128 v[132:135], v14 offset:2048
	ds_read_b128 v[138:141], v14 offset:4096
	ds_read_b128 v[142:145], v14 offset:6144
	ds_read_b128 v[152:155], v15
	ds_read_b128 v[156:159], v15 offset:2048
	ds_read_b128 v[160:163], v15 offset:4096
	ds_read_b128 v[164:167], v15 offset:6144
	v_mfma_f32_16x16x32_bf16 v[84:87], v[116:119], v[72:75], v[84:87]
	v_mfma_f32_16x16x32_bf16 v[88:91], v[120:123], v[72:75], v[88:91]
	v_mfma_f32_16x16x32_bf16 v[92:95], v[124:127], v[72:75], v[92:95]
	v_mfma_f32_16x16x32_bf16 v[22:25], v[128:131], v[72:75], v[22:25]
	v_mfma_f32_16x16x32_bf16 v[38:41], v[116:119], v[76:79], v[38:41]
	v_mfma_f32_16x16x32_bf16 v[46:49], v[120:123], v[76:79], v[46:49]
	v_mfma_f32_16x16x32_bf16 v[58:61], v[124:127], v[76:79], v[58:61]
	v_mfma_f32_16x16x32_bf16 v[50:53], v[128:131], v[76:79], v[50:53]
	v_mfma_f32_16x16x32_bf16 v[42:45], v[116:119], v[106:109], v[42:45]
	v_mfma_f32_16x16x32_bf16 v[62:65], v[120:123], v[106:109], v[62:65]
	v_mfma_f32_16x16x32_bf16 v[66:69], v[124:127], v[106:109], v[66:69]
	v_mfma_f32_16x16x32_bf16 v[54:57], v[128:131], v[106:109], v[54:57]
	v_mfma_f32_16x16x32_bf16 v[34:37], v[116:119], v[112:115], v[34:37]
	v_mfma_f32_16x16x32_bf16 v[30:33], v[120:123], v[112:115], v[30:33]
	v_mfma_f32_16x16x32_bf16 v[26:29], v[124:127], v[112:115], v[26:29]
	v_mfma_f32_16x16x32_bf16 v[18:21], v[128:131], v[112:115], v[18:21]
	s_mov_b64 s[8:9], 0x500
	s_mov_b32 m0, s59
	v_lshl_add_u64 v[72:73], v[2:3], 0, s[8:9]
	global_load_lds_dwordx4 v[72:73], off
	v_lshl_add_u64 v[72:73], v[4:5], 0, s[8:9]
	s_mov_b32 m0, s57
	s_nop 0
	global_load_lds_dwordx4 v[72:73], off
	v_lshl_add_u64 v[72:73], v[6:7], 0, s[8:9]
	s_mov_b32 m0, s60
	s_mov_b64 s[8:9], 0x20500
	global_load_lds_dwordx4 v[72:73], off
	v_lshl_add_u64 v[72:73], v[6:7], 0, s[8:9]
	s_mov_b32 m0, s61
	s_mov_b64 s[8:9], 0x40500
	global_load_lds_dwordx4 v[72:73], off
	v_lshl_add_u64 v[72:73], v[6:7], 0, s[8:9]
	s_mov_b32 m0, s62
	s_mov_b64 s[8:9], 0x60500
	global_load_lds_dwordx4 v[72:73], off
	v_lshl_add_u64 v[72:73], v[6:7], 0, s[8:9]
	s_mov_b32 m0, s71
	s_nop 0
	global_load_lds_dwordx4 v[72:73], off
	ds_read_b128 v[72:75], v16
	ds_read_b128 v[76:79], v16 offset:2048
	ds_read_b128 v[106:109], v16 offset:4096
	ds_read_b128 v[112:115], v16 offset:6144
	ds_read_b128 v[116:119], v17
	ds_read_b128 v[120:123], v17 offset:2048
	ds_read_b128 v[124:127], v17 offset:4096
	ds_read_b128 v[128:131], v17 offset:6144
	s_waitcnt lgkmcnt(8)
	v_mfma_f32_16x16x32_bf16 v[84:87], v[152:155], v[102:105], v[84:87]
	v_mfma_f32_16x16x32_bf16 v[88:91], v[156:159], v[102:105], v[88:91]
	v_mfma_f32_16x16x32_bf16 v[92:95], v[160:163], v[102:105], v[92:95]
	v_mfma_f32_16x16x32_bf16 v[22:25], v[164:167], v[102:105], v[22:25]
	v_mfma_f32_16x16x32_bf16 v[38:41], v[152:155], v[132:135], v[38:41]
	v_mfma_f32_16x16x32_bf16 v[46:49], v[156:159], v[132:135], v[46:49]
	v_mfma_f32_16x16x32_bf16 v[58:61], v[160:163], v[132:135], v[58:61]
	v_mfma_f32_16x16x32_bf16 v[50:53], v[164:167], v[132:135], v[50:53]
	v_mfma_f32_16x16x32_bf16 v[42:45], v[152:155], v[138:141], v[42:45]
	v_mfma_f32_16x16x32_bf16 v[62:65], v[156:159], v[138:141], v[62:65]
	v_mfma_f32_16x16x32_bf16 v[66:69], v[160:163], v[138:141], v[66:69]
	v_mfma_f32_16x16x32_bf16 v[54:57], v[164:167], v[138:141], v[54:57]
	v_mfma_f32_16x16x32_bf16 v[34:37], v[152:155], v[142:145], v[34:37]
	v_mfma_f32_16x16x32_bf16 v[30:33], v[156:159], v[142:145], v[30:33]
	v_mfma_f32_16x16x32_bf16 v[26:29], v[160:163], v[142:145], v[26:29]
	v_mfma_f32_16x16x32_bf16 v[18:21], v[164:167], v[142:145], v[18:21]
	s_waitcnt vmcnt(6) lgkmcnt(0)
	s_barrier
	ds_read_b128 v[102:105], v8
	ds_read_b128 v[132:135], v8 offset:2048
	ds_read_b128 v[138:141], v8 offset:4096
	ds_read_b128 v[142:145], v8 offset:6144
	ds_read_b128 v[152:155], v9 offset:16384
	ds_read_b128 v[156:159], v9 offset:18432
	ds_read_b128 v[160:163], v9 offset:20480
	ds_read_b128 v[164:167], v9 offset:22528
	v_mfma_f32_16x16x32_bf16 v[84:87], v[116:119], v[72:75], v[84:87]
	v_mfma_f32_16x16x32_bf16 v[88:91], v[120:123], v[72:75], v[88:91]
	v_mfma_f32_16x16x32_bf16 v[92:95], v[124:127], v[72:75], v[92:95]
	v_mfma_f32_16x16x32_bf16 v[22:25], v[128:131], v[72:75], v[22:25]
	v_mfma_f32_16x16x32_bf16 v[38:41], v[116:119], v[76:79], v[38:41]
	v_mfma_f32_16x16x32_bf16 v[46:49], v[120:123], v[76:79], v[46:49]
	v_mfma_f32_16x16x32_bf16 v[58:61], v[124:127], v[76:79], v[58:61]
	v_mfma_f32_16x16x32_bf16 v[50:53], v[128:131], v[76:79], v[50:53]
	v_mfma_f32_16x16x32_bf16 v[42:45], v[116:119], v[106:109], v[42:45]
	v_mfma_f32_16x16x32_bf16 v[62:65], v[120:123], v[106:109], v[62:65]
	v_mfma_f32_16x16x32_bf16 v[66:69], v[124:127], v[106:109], v[66:69]
	v_mfma_f32_16x16x32_bf16 v[54:57], v[128:131], v[106:109], v[54:57]
	v_mfma_f32_16x16x32_bf16 v[34:37], v[116:119], v[112:115], v[34:37]
	v_mfma_f32_16x16x32_bf16 v[30:33], v[120:123], v[112:115], v[30:33]
	v_mfma_f32_16x16x32_bf16 v[26:29], v[124:127], v[112:115], v[26:29]
	v_mfma_f32_16x16x32_bf16 v[18:21], v[128:131], v[112:115], v[18:21]
	s_mov_b64 s[8:9], 0x580
	s_mov_b32 m0, s63
	v_lshl_add_u64 v[72:73], v[2:3], 0, s[8:9]
	global_load_lds_dwordx4 v[72:73], off
	v_lshl_add_u64 v[72:73], v[4:5], 0, s[8:9]
	s_mov_b32 m0, s64
	s_nop 0
	global_load_lds_dwordx4 v[72:73], off
	v_lshl_add_u64 v[72:73], v[6:7], 0, s[8:9]
	s_mov_b32 m0, s72
	s_mov_b64 s[8:9], 0x20580
	global_load_lds_dwordx4 v[72:73], off
	v_lshl_add_u64 v[72:73], v[6:7], 0, s[8:9]
	s_mov_b32 m0, s73
	s_mov_b64 s[8:9], 0x40580
	global_load_lds_dwordx4 v[72:73], off
	v_lshl_add_u64 v[72:73], v[6:7], 0, s[8:9]
	s_mov_b32 m0, s74
	s_mov_b64 s[8:9], 0x60580
	global_load_lds_dwordx4 v[72:73], off
	v_lshl_add_u64 v[72:73], v[6:7], 0, s[8:9]
	s_mov_b32 m0, s75
	s_nop 0
	global_load_lds_dwordx4 v[72:73], off
	ds_read_b128 v[72:75], v10
	ds_read_b128 v[76:79], v10 offset:2048
	ds_read_b128 v[106:109], v10 offset:4096
	ds_read_b128 v[112:115], v10 offset:6144
	ds_read_b128 v[116:119], v11 offset:16384
	ds_read_b128 v[120:123], v11 offset:18432
	ds_read_b128 v[124:127], v11 offset:20480
	ds_read_b128 v[128:131], v11 offset:22528
	s_waitcnt lgkmcnt(8)
	v_mfma_f32_16x16x32_bf16 v[84:87], v[152:155], v[102:105], v[84:87]
	v_mfma_f32_16x16x32_bf16 v[88:91], v[156:159], v[102:105], v[88:91]
	v_mfma_f32_16x16x32_bf16 v[92:95], v[160:163], v[102:105], v[92:95]
	v_mfma_f32_16x16x32_bf16 v[22:25], v[164:167], v[102:105], v[22:25]
	v_mfma_f32_16x16x32_bf16 v[38:41], v[152:155], v[132:135], v[38:41]
	v_mfma_f32_16x16x32_bf16 v[46:49], v[156:159], v[132:135], v[46:49]
	v_mfma_f32_16x16x32_bf16 v[58:61], v[160:163], v[132:135], v[58:61]
	v_mfma_f32_16x16x32_bf16 v[50:53], v[164:167], v[132:135], v[50:53]
	v_mfma_f32_16x16x32_bf16 v[42:45], v[152:155], v[138:141], v[42:45]
	v_mfma_f32_16x16x32_bf16 v[62:65], v[156:159], v[138:141], v[62:65]
	v_mfma_f32_16x16x32_bf16 v[66:69], v[160:163], v[138:141], v[66:69]
	v_mfma_f32_16x16x32_bf16 v[54:57], v[164:167], v[138:141], v[54:57]
	v_mfma_f32_16x16x32_bf16 v[34:37], v[152:155], v[142:145], v[34:37]
	v_mfma_f32_16x16x32_bf16 v[30:33], v[156:159], v[142:145], v[30:33]
	v_mfma_f32_16x16x32_bf16 v[26:29], v[160:163], v[142:145], v[26:29]
	v_mfma_f32_16x16x32_bf16 v[18:21], v[164:167], v[142:145], v[18:21]
	s_waitcnt vmcnt(6) lgkmcnt(0)
	s_barrier
	ds_read_b128 v[102:105], v8 offset:49152
	ds_read_b128 v[132:135], v8 offset:51200
	ds_read_b128 v[138:141], v8 offset:53248
	ds_read_b128 v[142:145], v8 offset:55296
	ds_read_b128 v[152:155], v12
	ds_read_b128 v[156:159], v12 offset:2048
	ds_read_b128 v[160:163], v12 offset:4096
	ds_read_b128 v[164:167], v12 offset:6144
	v_mfma_f32_16x16x32_bf16 v[84:87], v[116:119], v[72:75], v[84:87]
	v_mfma_f32_16x16x32_bf16 v[88:91], v[120:123], v[72:75], v[88:91]
	v_mfma_f32_16x16x32_bf16 v[92:95], v[124:127], v[72:75], v[92:95]
	v_mfma_f32_16x16x32_bf16 v[22:25], v[128:131], v[72:75], v[22:25]
	v_mfma_f32_16x16x32_bf16 v[38:41], v[116:119], v[76:79], v[38:41]
	v_mfma_f32_16x16x32_bf16 v[46:49], v[120:123], v[76:79], v[46:49]
	v_mfma_f32_16x16x32_bf16 v[58:61], v[124:127], v[76:79], v[58:61]
	v_mfma_f32_16x16x32_bf16 v[50:53], v[128:131], v[76:79], v[50:53]
	v_mfma_f32_16x16x32_bf16 v[42:45], v[116:119], v[106:109], v[42:45]
	v_mfma_f32_16x16x32_bf16 v[62:65], v[120:123], v[106:109], v[62:65]
	v_mfma_f32_16x16x32_bf16 v[66:69], v[124:127], v[106:109], v[66:69]
	v_mfma_f32_16x16x32_bf16 v[54:57], v[128:131], v[106:109], v[54:57]
	v_mfma_f32_16x16x32_bf16 v[34:37], v[116:119], v[112:115], v[34:37]
	v_mfma_f32_16x16x32_bf16 v[30:33], v[120:123], v[112:115], v[30:33]
	v_mfma_f32_16x16x32_bf16 v[26:29], v[124:127], v[112:115], v[26:29]
	v_mfma_f32_16x16x32_bf16 v[18:21], v[128:131], v[112:115], v[18:21]
	s_mov_b64 s[8:9], 0x600
	s_mov_b32 m0, s56
	v_lshl_add_u64 v[72:73], v[2:3], 0, s[8:9]
	global_load_lds_dwordx4 v[72:73], off
	v_lshl_add_u64 v[72:73], v[4:5], 0, s[8:9]
	s_mov_b32 m0, s1
	s_nop 0
	global_load_lds_dwordx4 v[72:73], off
	v_lshl_add_u64 v[72:73], v[6:7], 0, s[8:9]
	s_mov_b32 m0, s5
	s_mov_b64 s[8:9], 0x20600
	global_load_lds_dwordx4 v[72:73], off
	v_lshl_add_u64 v[72:73], v[6:7], 0, s[8:9]
	s_mov_b32 m0, s33
	s_mov_b64 s[8:9], 0x40600
	global_load_lds_dwordx4 v[72:73], off
	v_lshl_add_u64 v[72:73], v[6:7], 0, s[8:9]
	s_mov_b32 m0, s38
	s_mov_b64 s[8:9], 0x60600
	global_load_lds_dwordx4 v[72:73], off
	v_lshl_add_u64 v[72:73], v[6:7], 0, s[8:9]
	s_mov_b32 m0, s39
	s_nop 0
	global_load_lds_dwordx4 v[72:73], off
	ds_read_b128 v[72:75], v10 offset:49152
	ds_read_b128 v[76:79], v10 offset:51200
	ds_read_b128 v[106:109], v10 offset:53248
	ds_read_b128 v[112:115], v10 offset:55296
	ds_read_b128 v[116:119], v13
	ds_read_b128 v[120:123], v13 offset:2048
	ds_read_b128 v[124:127], v13 offset:4096
	ds_read_b128 v[128:131], v13 offset:6144
	s_waitcnt lgkmcnt(8)
	v_mfma_f32_16x16x32_bf16 v[84:87], v[152:155], v[102:105], v[84:87]
	v_mfma_f32_16x16x32_bf16 v[88:91], v[156:159], v[102:105], v[88:91]
	v_mfma_f32_16x16x32_bf16 v[92:95], v[160:163], v[102:105], v[92:95]
	v_mfma_f32_16x16x32_bf16 v[22:25], v[164:167], v[102:105], v[22:25]
	v_mfma_f32_16x16x32_bf16 v[38:41], v[152:155], v[132:135], v[38:41]
	v_mfma_f32_16x16x32_bf16 v[46:49], v[156:159], v[132:135], v[46:49]
	v_mfma_f32_16x16x32_bf16 v[58:61], v[160:163], v[132:135], v[58:61]
	v_mfma_f32_16x16x32_bf16 v[50:53], v[164:167], v[132:135], v[50:53]
	v_mfma_f32_16x16x32_bf16 v[42:45], v[152:155], v[138:141], v[42:45]
	v_mfma_f32_16x16x32_bf16 v[62:65], v[156:159], v[138:141], v[62:65]
	v_mfma_f32_16x16x32_bf16 v[66:69], v[160:163], v[138:141], v[66:69]
	v_mfma_f32_16x16x32_bf16 v[54:57], v[164:167], v[138:141], v[54:57]
	v_mfma_f32_16x16x32_bf16 v[34:37], v[152:155], v[142:145], v[34:37]
	v_mfma_f32_16x16x32_bf16 v[30:33], v[156:159], v[142:145], v[30:33]
	v_mfma_f32_16x16x32_bf16 v[26:29], v[160:163], v[142:145], v[26:29]
	v_mfma_f32_16x16x32_bf16 v[18:21], v[164:167], v[142:145], v[18:21]
	s_waitcnt vmcnt(6) lgkmcnt(0)
	s_barrier
	ds_read_b128 v[102:105], v14
	ds_read_b128 v[132:135], v14 offset:2048
	ds_read_b128 v[138:141], v14 offset:4096
	ds_read_b128 v[142:145], v14 offset:6144
	ds_read_b128 v[152:155], v15
	ds_read_b128 v[156:159], v15 offset:2048
	ds_read_b128 v[160:163], v15 offset:4096
	ds_read_b128 v[164:167], v15 offset:6144
	v_mfma_f32_16x16x32_bf16 v[84:87], v[116:119], v[72:75], v[84:87]
	v_mfma_f32_16x16x32_bf16 v[88:91], v[120:123], v[72:75], v[88:91]
	v_mfma_f32_16x16x32_bf16 v[92:95], v[124:127], v[72:75], v[92:95]
	v_mfma_f32_16x16x32_bf16 v[22:25], v[128:131], v[72:75], v[22:25]
	v_mfma_f32_16x16x32_bf16 v[38:41], v[116:119], v[76:79], v[38:41]
	v_mfma_f32_16x16x32_bf16 v[46:49], v[120:123], v[76:79], v[46:49]
	v_mfma_f32_16x16x32_bf16 v[58:61], v[124:127], v[76:79], v[58:61]
	v_mfma_f32_16x16x32_bf16 v[50:53], v[128:131], v[76:79], v[50:53]
	v_mfma_f32_16x16x32_bf16 v[42:45], v[116:119], v[106:109], v[42:45]
	v_mfma_f32_16x16x32_bf16 v[62:65], v[120:123], v[106:109], v[62:65]
	v_mfma_f32_16x16x32_bf16 v[66:69], v[124:127], v[106:109], v[66:69]
	v_mfma_f32_16x16x32_bf16 v[54:57], v[128:131], v[106:109], v[54:57]
	v_mfma_f32_16x16x32_bf16 v[34:37], v[116:119], v[112:115], v[34:37]
	v_mfma_f32_16x16x32_bf16 v[30:33], v[120:123], v[112:115], v[30:33]
	v_mfma_f32_16x16x32_bf16 v[26:29], v[124:127], v[112:115], v[26:29]
	v_mfma_f32_16x16x32_bf16 v[18:21], v[128:131], v[112:115], v[18:21]
	s_mov_b64 s[8:9], 0x680
	s_mov_b32 m0, s59
	v_lshl_add_u64 v[72:73], v[2:3], 0, s[8:9]
	global_load_lds_dwordx4 v[72:73], off
	v_lshl_add_u64 v[72:73], v[4:5], 0, s[8:9]
	s_mov_b32 m0, s57
	s_nop 0
	global_load_lds_dwordx4 v[72:73], off
	v_lshl_add_u64 v[72:73], v[6:7], 0, s[8:9]
	s_mov_b32 m0, s60
	s_mov_b64 s[8:9], 0x20680
	global_load_lds_dwordx4 v[72:73], off
	v_lshl_add_u64 v[72:73], v[6:7], 0, s[8:9]
	s_mov_b32 m0, s61
	s_mov_b64 s[8:9], 0x40680
	global_load_lds_dwordx4 v[72:73], off
	v_lshl_add_u64 v[72:73], v[6:7], 0, s[8:9]
	s_mov_b32 m0, s62
	s_mov_b64 s[8:9], 0x60680
	global_load_lds_dwordx4 v[72:73], off
	v_lshl_add_u64 v[72:73], v[6:7], 0, s[8:9]
	s_mov_b32 m0, s71
	s_nop 0
	global_load_lds_dwordx4 v[72:73], off
	s_mov_b64 s[8:9], exec
	v_readlane_b32 s20, v197, 0
	v_readlane_b32 s21, v197, 1
	s_and_b64 s[20:21], s[8:9], s[20:21]
	s_mov_b64 exec, s[20:21]
	s_cbranch_execz .Ldq_skip0
	v_mov_b32_e32 v251, 0
	v_mov_b32_e32 v252, 1
	global_atomic_add v250, v251, v252, s[92:93] offset:8 sc0
.Ldq_skip0:
	s_mov_b64 exec, s[8:9]
	s_mov_b32 s99, 1
	ds_read_b128 v[72:75], v16
	ds_read_b128 v[76:79], v16 offset:2048
	ds_read_b128 v[106:109], v16 offset:4096
	ds_read_b128 v[112:115], v16 offset:6144
	ds_read_b128 v[116:119], v17
	ds_read_b128 v[120:123], v17 offset:2048
	ds_read_b128 v[124:127], v17 offset:4096
	ds_read_b128 v[128:131], v17 offset:6144
	s_waitcnt lgkmcnt(8)
	v_mfma_f32_16x16x32_bf16 v[84:87], v[152:155], v[102:105], v[84:87]
	v_mfma_f32_16x16x32_bf16 v[88:91], v[156:159], v[102:105], v[88:91]
	v_mfma_f32_16x16x32_bf16 v[92:95], v[160:163], v[102:105], v[92:95]
	v_mfma_f32_16x16x32_bf16 v[22:25], v[164:167], v[102:105], v[22:25]
	v_mfma_f32_16x16x32_bf16 v[38:41], v[152:155], v[132:135], v[38:41]
	v_mfma_f32_16x16x32_bf16 v[46:49], v[156:159], v[132:135], v[46:49]
	v_mfma_f32_16x16x32_bf16 v[58:61], v[160:163], v[132:135], v[58:61]
	v_mfma_f32_16x16x32_bf16 v[50:53], v[164:167], v[132:135], v[50:53]
	v_mfma_f32_16x16x32_bf16 v[42:45], v[152:155], v[138:141], v[42:45]
	v_mfma_f32_16x16x32_bf16 v[62:65], v[156:159], v[138:141], v[62:65]
	v_mfma_f32_16x16x32_bf16 v[66:69], v[160:163], v[138:141], v[66:69]
	v_mfma_f32_16x16x32_bf16 v[54:57], v[164:167], v[138:141], v[54:57]
	v_mfma_f32_16x16x32_bf16 v[34:37], v[152:155], v[142:145], v[34:37]
	v_mfma_f32_16x16x32_bf16 v[30:33], v[156:159], v[142:145], v[30:33]
	v_mfma_f32_16x16x32_bf16 v[26:29], v[160:163], v[142:145], v[26:29]
	v_mfma_f32_16x16x32_bf16 v[18:21], v[164:167], v[142:145], v[18:21]
	s_waitcnt vmcnt(6) lgkmcnt(0)
	s_barrier
	ds_read_b128 v[102:105], v8
	ds_read_b128 v[132:135], v8 offset:2048
	ds_read_b128 v[138:141], v8 offset:4096
	ds_read_b128 v[142:145], v8 offset:6144
	ds_read_b128 v[152:155], v9 offset:16384
	ds_read_b128 v[156:159], v9 offset:18432
	ds_read_b128 v[160:163], v9 offset:20480
	ds_read_b128 v[164:167], v9 offset:22528
	v_mfma_f32_16x16x32_bf16 v[84:87], v[116:119], v[72:75], v[84:87]
	v_mfma_f32_16x16x32_bf16 v[88:91], v[120:123], v[72:75], v[88:91]
	v_mfma_f32_16x16x32_bf16 v[92:95], v[124:127], v[72:75], v[92:95]
	v_mfma_f32_16x16x32_bf16 v[22:25], v[128:131], v[72:75], v[22:25]
	v_mfma_f32_16x16x32_bf16 v[38:41], v[116:119], v[76:79], v[38:41]
	v_mfma_f32_16x16x32_bf16 v[46:49], v[120:123], v[76:79], v[46:49]
	v_mfma_f32_16x16x32_bf16 v[58:61], v[124:127], v[76:79], v[58:61]
	v_mfma_f32_16x16x32_bf16 v[50:53], v[128:131], v[76:79], v[50:53]
	v_mfma_f32_16x16x32_bf16 v[42:45], v[116:119], v[106:109], v[42:45]
	v_mfma_f32_16x16x32_bf16 v[62:65], v[120:123], v[106:109], v[62:65]
	v_mfma_f32_16x16x32_bf16 v[66:69], v[124:127], v[106:109], v[66:69]
	v_mfma_f32_16x16x32_bf16 v[54:57], v[128:131], v[106:109], v[54:57]
	v_mfma_f32_16x16x32_bf16 v[34:37], v[116:119], v[112:115], v[34:37]
	v_mfma_f32_16x16x32_bf16 v[30:33], v[120:123], v[112:115], v[30:33]
	v_mfma_f32_16x16x32_bf16 v[26:29], v[124:127], v[112:115], v[26:29]
	v_mfma_f32_16x16x32_bf16 v[18:21], v[128:131], v[112:115], v[18:21]
	s_mov_b64 s[8:9], 0x700
	s_mov_b32 m0, s63
	v_lshl_add_u64 v[72:73], v[2:3], 0, s[8:9]
	global_load_lds_dwordx4 v[72:73], off
	v_lshl_add_u64 v[72:73], v[4:5], 0, s[8:9]
	s_mov_b32 m0, s64
	s_nop 0
	global_load_lds_dwordx4 v[72:73], off
	v_lshl_add_u64 v[72:73], v[6:7], 0, s[8:9]
	s_mov_b32 m0, s72
	s_mov_b64 s[8:9], 0x20700
	global_load_lds_dwordx4 v[72:73], off
	v_lshl_add_u64 v[72:73], v[6:7], 0, s[8:9]
	s_mov_b32 m0, s73
	s_mov_b64 s[8:9], 0x40700
	global_load_lds_dwordx4 v[72:73], off
	v_lshl_add_u64 v[72:73], v[6:7], 0, s[8:9]
	s_mov_b32 m0, s74
	s_mov_b64 s[8:9], 0x60700
	global_load_lds_dwordx4 v[72:73], off
	v_lshl_add_u64 v[72:73], v[6:7], 0, s[8:9]
	s_mov_b32 m0, s75
	s_nop 0
	global_load_lds_dwordx4 v[72:73], off
	ds_read_b128 v[72:75], v10
	ds_read_b128 v[76:79], v10 offset:2048
	ds_read_b128 v[106:109], v10 offset:4096
	ds_read_b128 v[112:115], v10 offset:6144
	ds_read_b128 v[116:119], v11 offset:16384
	ds_read_b128 v[120:123], v11 offset:18432
	ds_read_b128 v[124:127], v11 offset:20480
	ds_read_b128 v[128:131], v11 offset:22528
	s_waitcnt lgkmcnt(8)
	v_mfma_f32_16x16x32_bf16 v[84:87], v[152:155], v[102:105], v[84:87]
	v_mfma_f32_16x16x32_bf16 v[88:91], v[156:159], v[102:105], v[88:91]
	v_mfma_f32_16x16x32_bf16 v[92:95], v[160:163], v[102:105], v[92:95]
	v_mfma_f32_16x16x32_bf16 v[22:25], v[164:167], v[102:105], v[22:25]
	v_mfma_f32_16x16x32_bf16 v[38:41], v[152:155], v[132:135], v[38:41]
	v_mfma_f32_16x16x32_bf16 v[46:49], v[156:159], v[132:135], v[46:49]
	v_mfma_f32_16x16x32_bf16 v[58:61], v[160:163], v[132:135], v[58:61]
	v_mfma_f32_16x16x32_bf16 v[50:53], v[164:167], v[132:135], v[50:53]
	v_mfma_f32_16x16x32_bf16 v[42:45], v[152:155], v[138:141], v[42:45]
	v_mfma_f32_16x16x32_bf16 v[62:65], v[156:159], v[138:141], v[62:65]
	v_mfma_f32_16x16x32_bf16 v[66:69], v[160:163], v[138:141], v[66:69]
	v_mfma_f32_16x16x32_bf16 v[54:57], v[164:167], v[138:141], v[54:57]
	v_mfma_f32_16x16x32_bf16 v[34:37], v[152:155], v[142:145], v[34:37]
	v_mfma_f32_16x16x32_bf16 v[30:33], v[156:159], v[142:145], v[30:33]
	v_mfma_f32_16x16x32_bf16 v[26:29], v[160:163], v[142:145], v[26:29]
	v_mfma_f32_16x16x32_bf16 v[18:21], v[164:167], v[142:145], v[18:21]
	s_waitcnt vmcnt(6) lgkmcnt(0)
	s_barrier
	ds_read_b128 v[102:105], v8 offset:49152
	ds_read_b128 v[132:135], v8 offset:51200
	ds_read_b128 v[138:141], v8 offset:53248
	ds_read_b128 v[142:145], v8 offset:55296
	ds_read_b128 v[152:155], v12
	ds_read_b128 v[156:159], v12 offset:2048
	ds_read_b128 v[160:163], v12 offset:4096
	ds_read_b128 v[164:167], v12 offset:6144
	v_mfma_f32_16x16x32_bf16 v[84:87], v[116:119], v[72:75], v[84:87]
	v_mfma_f32_16x16x32_bf16 v[88:91], v[120:123], v[72:75], v[88:91]
	v_mfma_f32_16x16x32_bf16 v[92:95], v[124:127], v[72:75], v[92:95]
	v_mfma_f32_16x16x32_bf16 v[22:25], v[128:131], v[72:75], v[22:25]
	v_mfma_f32_16x16x32_bf16 v[38:41], v[116:119], v[76:79], v[38:41]
	v_mfma_f32_16x16x32_bf16 v[46:49], v[120:123], v[76:79], v[46:49]
	v_mfma_f32_16x16x32_bf16 v[58:61], v[124:127], v[76:79], v[58:61]
	v_mfma_f32_16x16x32_bf16 v[50:53], v[128:131], v[76:79], v[50:53]
	v_mfma_f32_16x16x32_bf16 v[42:45], v[116:119], v[106:109], v[42:45]
	v_mfma_f32_16x16x32_bf16 v[62:65], v[120:123], v[106:109], v[62:65]
	v_mfma_f32_16x16x32_bf16 v[66:69], v[124:127], v[106:109], v[66:69]
	v_mfma_f32_16x16x32_bf16 v[54:57], v[128:131], v[106:109], v[54:57]
	v_mfma_f32_16x16x32_bf16 v[34:37], v[116:119], v[112:115], v[34:37]
	v_mfma_f32_16x16x32_bf16 v[30:33], v[120:123], v[112:115], v[30:33]
	v_mfma_f32_16x16x32_bf16 v[26:29], v[124:127], v[112:115], v[26:29]
	v_mfma_f32_16x16x32_bf16 v[18:21], v[128:131], v[112:115], v[18:21]
	s_mov_b64 s[8:9], 0x780
	s_mov_b32 m0, s56
	v_lshl_add_u64 v[2:3], v[2:3], 0, s[8:9]
	global_load_lds_dwordx4 v[2:3], off
	v_lshl_add_u64 v[2:3], v[4:5], 0, s[8:9]
	s_mov_b32 m0, s1
	s_nop 0
	global_load_lds_dwordx4 v[2:3], off
	v_lshl_add_u64 v[2:3], v[6:7], 0, s[8:9]
	s_mov_b32 m0, s5
	s_mov_b64 s[8:9], 0x20780
	global_load_lds_dwordx4 v[2:3], off
	v_lshl_add_u64 v[2:3], v[6:7], 0, s[8:9]
	s_mov_b32 m0, s33
	s_mov_b64 s[8:9], 0x40780
	global_load_lds_dwordx4 v[2:3], off
	v_lshl_add_u64 v[2:3], v[6:7], 0, s[8:9]
	s_mov_b32 m0, s38
	s_mov_b64 s[8:9], 0x60780
	global_load_lds_dwordx4 v[2:3], off
	v_lshl_add_u64 v[2:3], v[6:7], 0, s[8:9]
	s_mov_b32 m0, s39
	s_nop 0
	global_load_lds_dwordx4 v[2:3], off
	ds_read_b128 v[2:5], v10 offset:49152
	ds_read_b128 v[72:75], v10 offset:51200
	ds_read_b128 v[76:79], v10 offset:53248
	ds_read_b128 v[106:109], v10 offset:55296
	ds_read_b128 v[112:115], v13
	ds_read_b128 v[116:119], v13 offset:2048
	ds_read_b128 v[120:123], v13 offset:4096
	ds_read_b128 v[124:127], v13 offset:6144
	s_waitcnt lgkmcnt(8)
	v_mfma_f32_16x16x32_bf16 v[84:87], v[152:155], v[102:105], v[84:87]
	v_mfma_f32_16x16x32_bf16 v[88:91], v[156:159], v[102:105], v[88:91]
	v_mfma_f32_16x16x32_bf16 v[92:95], v[160:163], v[102:105], v[92:95]
	v_mfma_f32_16x16x32_bf16 v[22:25], v[164:167], v[102:105], v[22:25]
	v_mfma_f32_16x16x32_bf16 v[38:41], v[152:155], v[132:135], v[38:41]
	v_mfma_f32_16x16x32_bf16 v[46:49], v[156:159], v[132:135], v[46:49]
	v_mfma_f32_16x16x32_bf16 v[58:61], v[160:163], v[132:135], v[58:61]
	v_mfma_f32_16x16x32_bf16 v[50:53], v[164:167], v[132:135], v[50:53]
	v_mfma_f32_16x16x32_bf16 v[42:45], v[152:155], v[138:141], v[42:45]
	v_mfma_f32_16x16x32_bf16 v[62:65], v[156:159], v[138:141], v[62:65]
	v_mfma_f32_16x16x32_bf16 v[66:69], v[160:163], v[138:141], v[66:69]
	v_mfma_f32_16x16x32_bf16 v[54:57], v[164:167], v[138:141], v[54:57]
	v_mfma_f32_16x16x32_bf16 v[34:37], v[152:155], v[142:145], v[34:37]
	v_mfma_f32_16x16x32_bf16 v[30:33], v[156:159], v[142:145], v[30:33]
	v_mfma_f32_16x16x32_bf16 v[26:29], v[160:163], v[142:145], v[26:29]
	v_mfma_f32_16x16x32_bf16 v[18:21], v[164:167], v[142:145], v[18:21]
	s_waitcnt vmcnt(6) lgkmcnt(0)
	s_barrier
	ds_read_b128 v[102:105], v14
	ds_read_b128 v[128:131], v14 offset:2048
	ds_read_b128 v[132:135], v14 offset:4096
	ds_read_b128 v[138:141], v14 offset:6144
	ds_read_b128 v[142:145], v15
	ds_read_b128 v[152:155], v15 offset:2048
	ds_read_b128 v[156:159], v15 offset:4096
	ds_read_b128 v[12:15], v15 offset:6144
	v_mfma_f32_16x16x32_bf16 v[84:87], v[112:115], v[2:5], v[84:87]
	v_mfma_f32_16x16x32_bf16 v[88:91], v[116:119], v[2:5], v[88:91]
	v_mfma_f32_16x16x32_bf16 v[92:95], v[120:123], v[2:5], v[92:95]
	v_mfma_f32_16x16x32_bf16 v[2:5], v[124:127], v[2:5], v[22:25]
	v_mfma_f32_16x16x32_bf16 v[22:25], v[112:115], v[72:75], v[38:41]
	v_mfma_f32_16x16x32_bf16 v[38:41], v[116:119], v[72:75], v[46:49]
	v_mfma_f32_16x16x32_bf16 v[46:49], v[120:123], v[72:75], v[58:61]
	v_mfma_f32_16x16x32_bf16 v[50:53], v[124:127], v[72:75], v[50:53]
	v_mfma_f32_16x16x32_bf16 v[42:45], v[112:115], v[76:79], v[42:45]
	v_mfma_f32_16x16x32_bf16 v[58:61], v[116:119], v[76:79], v[62:65]
	v_mfma_f32_16x16x32_bf16 v[62:65], v[120:123], v[76:79], v[66:69]
	v_mfma_f32_16x16x32_bf16 v[54:57], v[124:127], v[76:79], v[54:57]
	v_mfma_f32_16x16x32_bf16 v[34:37], v[112:115], v[106:109], v[34:37]
	v_mfma_f32_16x16x32_bf16 v[30:33], v[116:119], v[106:109], v[30:33]
	v_mfma_f32_16x16x32_bf16 v[26:29], v[120:123], v[106:109], v[26:29]
	v_mfma_f32_16x16x32_bf16 v[18:21], v[124:127], v[106:109], v[18:21]
	ds_read_b128 v[66:69], v16
	ds_read_b128 v[72:75], v16 offset:2048
	ds_read_b128 v[76:79], v16 offset:4096
	ds_read_b128 v[106:109], v16 offset:6144
	ds_read_b128 v[112:115], v17
	ds_read_b128 v[116:119], v17 offset:2048
	ds_read_b128 v[120:123], v17 offset:4096
	ds_read_b128 v[124:127], v17 offset:6144
	s_waitcnt lgkmcnt(8)
	v_mfma_f32_16x16x32_bf16 v[84:87], v[142:145], v[102:105], v[84:87]
	v_mfma_f32_16x16x32_bf16 v[88:91], v[152:155], v[102:105], v[88:91]
	v_mfma_f32_16x16x32_bf16 v[92:95], v[156:159], v[102:105], v[92:95]
	v_mfma_f32_16x16x32_bf16 v[2:5], v[12:15], v[102:105], v[2:5]
	v_mfma_f32_16x16x32_bf16 v[22:25], v[142:145], v[128:131], v[22:25]
	v_mfma_f32_16x16x32_bf16 v[38:41], v[152:155], v[128:131], v[38:41]
	v_mfma_f32_16x16x32_bf16 v[46:49], v[156:159], v[128:131], v[46:49]
	v_mfma_f32_16x16x32_bf16 v[50:53], v[12:15], v[128:131], v[50:53]
	v_mfma_f32_16x16x32_bf16 v[42:45], v[142:145], v[132:135], v[42:45]
	v_mfma_f32_16x16x32_bf16 v[58:61], v[152:155], v[132:135], v[58:61]
	v_mfma_f32_16x16x32_bf16 v[62:65], v[156:159], v[132:135], v[62:65]
	v_mfma_f32_16x16x32_bf16 v[54:57], v[12:15], v[132:135], v[54:57]
	v_mfma_f32_16x16x32_bf16 v[34:37], v[142:145], v[138:141], v[34:37]
	v_mfma_f32_16x16x32_bf16 v[30:33], v[152:155], v[138:141], v[30:33]
	v_mfma_f32_16x16x32_bf16 v[26:29], v[156:159], v[138:141], v[26:29]
	v_mfma_f32_16x16x32_bf16 v[12:15], v[12:15], v[138:141], v[18:21]
	s_waitcnt vmcnt(0) lgkmcnt(0)
	s_barrier
	s_nop 1
	ds_read_b128 v[16:19], v8
	ds_read_b128 v[102:105], v8 offset:2048
	ds_read_b128 v[128:131], v8 offset:4096
	ds_read_b128 v[132:135], v8 offset:6144
	ds_read_b128 v[138:141], v9 offset:16384
	ds_read_b128 v[142:145], v9 offset:18432
	ds_read_b128 v[152:155], v9 offset:20480
	ds_read_b128 v[6:9], v9 offset:22528
	v_mfma_f32_16x16x32_bf16 v[84:87], v[112:115], v[66:69], v[84:87]
	v_mfma_f32_16x16x32_bf16 v[88:91], v[116:119], v[66:69], v[88:91]
	v_mfma_f32_16x16x32_bf16 v[92:95], v[120:123], v[66:69], v[92:95]
	v_mfma_f32_16x16x32_bf16 v[2:5], v[124:127], v[66:69], v[2:5]
	v_mfma_f32_16x16x32_bf16 v[20:23], v[112:115], v[72:75], v[22:25]
	v_mfma_f32_16x16x32_bf16 v[38:41], v[116:119], v[72:75], v[38:41]
	v_mfma_f32_16x16x32_bf16 v[46:49], v[120:123], v[72:75], v[46:49]
	v_mfma_f32_16x16x32_bf16 v[50:53], v[124:127], v[72:75], v[50:53]
	v_mfma_f32_16x16x32_bf16 v[42:45], v[112:115], v[76:79], v[42:45]
	v_mfma_f32_16x16x32_bf16 v[58:61], v[116:119], v[76:79], v[58:61]
	v_mfma_f32_16x16x32_bf16 v[62:65], v[120:123], v[76:79], v[62:65]
	v_mfma_f32_16x16x32_bf16 v[54:57], v[124:127], v[76:79], v[54:57]
	v_mfma_f32_16x16x32_bf16 v[34:37], v[112:115], v[106:109], v[34:37]
	v_mfma_f32_16x16x32_bf16 v[30:33], v[116:119], v[106:109], v[30:33]
	v_mfma_f32_16x16x32_bf16 v[24:27], v[120:123], v[106:109], v[26:29]
	v_mfma_f32_16x16x32_bf16 v[12:15], v[124:127], v[106:109], v[12:15]
	ds_read_b128 v[66:69], v10
	ds_read_b128 v[72:75], v10 offset:2048
	ds_read_b128 v[76:79], v10 offset:4096
	ds_read_b128 v[106:109], v10 offset:6144
	ds_read_b128 v[112:115], v11 offset:16384
	ds_read_b128 v[116:119], v11 offset:18432
	ds_read_b128 v[120:123], v11 offset:20480
	ds_read_b128 v[124:127], v11 offset:22528
	s_add_i32 s0, s0, 0xffff4d00
	s_waitcnt lgkmcnt(8)
	v_mfma_f32_16x16x32_bf16 v[84:87], v[138:141], v[16:19], v[84:87]
	v_mfma_f32_16x16x32_bf16 v[88:91], v[142:145], v[16:19], v[88:91]
	v_mfma_f32_16x16x32_bf16 v[92:95], v[152:155], v[16:19], v[92:95]
	v_mfma_f32_16x16x32_bf16 v[2:5], v[6:9], v[16:19], v[2:5]
	v_mfma_f32_16x16x32_bf16 v[16:19], v[138:141], v[102:105], v[20:23]
	v_mfma_f32_16x16x32_bf16 v[20:23], v[142:145], v[102:105], v[38:41]
	v_mfma_f32_16x16x32_bf16 v[38:41], v[152:155], v[102:105], v[46:49]
	v_mfma_f32_16x16x32_bf16 v[46:49], v[6:9], v[102:105], v[50:53]
	v_mfma_f32_16x16x32_bf16 v[42:45], v[138:141], v[128:131], v[42:45]
	v_mfma_f32_16x16x32_bf16 v[50:53], v[142:145], v[128:131], v[58:61]
	v_mfma_f32_16x16x32_bf16 v[58:61], v[152:155], v[128:131], v[62:65]
	v_mfma_f32_16x16x32_bf16 v[54:57], v[6:9], v[128:131], v[54:57]
	v_mfma_f32_16x16x32_bf16 v[34:37], v[138:141], v[132:135], v[34:37]
	v_mfma_f32_16x16x32_bf16 v[28:31], v[142:145], v[132:135], v[30:33]
	v_mfma_f32_16x16x32_bf16 v[24:27], v[152:155], v[132:135], v[24:27]
	v_mfma_f32_16x16x32_bf16 v[6:9], v[6:9], v[132:135], v[12:15]
	s_waitcnt vmcnt(0) lgkmcnt(0)
	s_barrier
	v_mfma_f32_16x16x32_bf16 v[10:13], v[112:115], v[66:69], v[84:87]
	v_mfma_f32_16x16x32_bf16 v[62:65], v[116:119], v[66:69], v[88:91]
	v_mfma_f32_16x16x32_bf16 v[84:87], v[120:123], v[66:69], v[92:95]
	v_mfma_f32_16x16x32_bf16 v[2:5], v[124:127], v[66:69], v[2:5]
	v_mfma_f32_16x16x32_bf16 v[14:17], v[112:115], v[72:75], v[16:19]
	v_mfma_f32_16x16x32_bf16 v[18:21], v[116:119], v[72:75], v[20:23]
	v_mfma_f32_16x16x32_bf16 v[38:41], v[120:123], v[72:75], v[38:41]
	v_mfma_f32_16x16x32_bf16 v[46:49], v[124:127], v[72:75], v[46:49]
	v_mfma_f32_16x16x32_bf16 v[42:45], v[112:115], v[76:79], v[42:45]
	v_mfma_f32_16x16x32_bf16 v[50:53], v[116:119], v[76:79], v[50:53]
	v_mfma_f32_16x16x32_bf16 v[58:61], v[120:123], v[76:79], v[58:61]
	v_mfma_f32_16x16x32_bf16 v[54:57], v[124:127], v[76:79], v[54:57]
	v_mfma_f32_16x16x32_bf16 v[32:35], v[112:115], v[106:109], v[34:37]
	v_mfma_f32_16x16x32_bf16 v[28:31], v[116:119], v[106:109], v[28:31]
	v_mfma_f32_16x16x32_bf16 v[22:25], v[120:123], v[106:109], v[24:27]
	v_mfma_f32_16x16x32_bf16 v[6:9], v[124:127], v[106:109], v[6:9]
	s_nop 1
	v_or_b32_e32 v26, s0, v101
	v_lshl_add_u32 v26, v82, 6, v26
	s_and_b32 s0, s58, 3
	v_mul_u32_u24_e32 v98, s0, v149
	v_ashrrev_i32_e32 v27, 31, v26
	v_lshl_add_u64 v[36:37], v[26:27], 0, v[98:99]
	v_mov_b64_e32 v[66:67], s[16:17]
	v_mad_u64_u32 v[68:69], s[0:1], v36, s70, v[66:67]
	v_mad_i32_i24 v69, v37, s70, v69
	s_mov_b64 s[8:9], 0x2000
	v_lshl_add_u64 v[36:37], v[68:69], 0, s[8:9]
	v_lshlrev_b32_e32 v68, 7, v83
	v_mov_b32_e32 v69, v99
	v_lshl_add_u64 v[72:73], v[36:37], 0, v[68:69]
	v_lshlrev_b32_e32 v74, 4, v110
	v_mov_b32_e32 v75, v99
	v_lshl_add_u64 v[72:73], v[72:73], 0, v[74:75]
	v_cvt_pk_bf16_f32 v10, v10, v11
	v_cvt_pk_bf16_f32 v11, v12, v13
	v_cvt_pk_bf16_f32 v12, v62, v63
	v_cvt_pk_bf16_f32 v13, v64, v65
	s_waitcnt lgkmcnt(0)
	s_barrier
	global_store_dwordx4 v[72:73], v[10:13], off
	s_nop 1
	v_cvt_pk_bf16_f32 v12, v2, v3
	v_or_b32_e32 v2, 16, v26
	v_ashrrev_i32_e32 v3, 31, v2
	v_lshl_add_u64 v[2:3], v[2:3], 0, v[98:99]
	v_lshl_add_u64 v[10:11], v[36:37], 0, v[74:75]
	v_or_b32_e32 v36, 64, v68
	v_mov_b32_e32 v37, v99
	v_cvt_pk_bf16_f32 v13, v4, v5
	v_mad_u64_u32 v[4:5], s[0:1], v2, s70, v[66:67]
	v_lshl_add_u64 v[62:63], v[10:11], 0, v[36:37]
	v_cvt_pk_bf16_f32 v10, v84, v85
	v_cvt_pk_bf16_f32 v11, v86, v87
	v_mad_i32_i24 v5, v3, s70, v5
	global_store_dwordx4 v[62:63], v[10:13], off
	s_nop 1
	v_lshl_add_u64 v[10:11], v[4:5], 0, s[8:9]
	v_lshl_add_u64 v[2:3], v[10:11], 0, v[68:69]
	v_lshl_add_u64 v[12:13], v[2:3], 0, v[74:75]
	v_cvt_pk_bf16_f32 v2, v14, v15
	v_cvt_pk_bf16_f32 v3, v16, v17
	v_cvt_pk_bf16_f32 v4, v18, v19
	v_cvt_pk_bf16_f32 v5, v20, v21
	global_store_dwordx4 v[12:13], v[2:5], off
	s_nop 1
	v_lshl_add_u64 v[2:3], v[10:11], 0, v[74:75]
	v_lshl_add_u64 v[10:11], v[2:3], 0, v[36:37]
	v_cvt_pk_bf16_f32 v2, v38, v39
	v_cvt_pk_bf16_f32 v3, v40, v41
	v_cvt_pk_bf16_f32 v4, v46, v47
	v_cvt_pk_bf16_f32 v5, v48, v49
	global_store_dwordx4 v[10:11], v[2:5], off
	s_nop 1
	v_or_b32_e32 v2, 32, v26
	v_ashrrev_i32_e32 v3, 31, v2
	v_lshl_add_u64 v[2:3], v[2:3], 0, v[98:99]
	v_mad_u64_u32 v[4:5], s[0:1], v2, s70, v[66:67]
	v_mad_i32_i24 v5, v3, s70, v5
	v_lshl_add_u64 v[10:11], v[4:5], 0, s[8:9]
	v_lshl_add_u64 v[2:3], v[10:11], 0, v[68:69]
	v_lshl_add_u64 v[12:13], v[2:3], 0, v[74:75]
	v_cvt_pk_bf16_f32 v2, v42, v43
	v_cvt_pk_bf16_f32 v3, v44, v45
	v_cvt_pk_bf16_f32 v4, v50, v51
	v_cvt_pk_bf16_f32 v5, v52, v53
	global_store_dwordx4 v[12:13], v[2:5], off
	s_nop 1
	v_lshl_add_u64 v[2:3], v[10:11], 0, v[74:75]
	v_lshl_add_u64 v[10:11], v[2:3], 0, v[36:37]
	v_cvt_pk_bf16_f32 v2, v58, v59
	v_cvt_pk_bf16_f32 v3, v60, v61
	v_cvt_pk_bf16_f32 v4, v54, v55
	v_cvt_pk_bf16_f32 v5, v56, v57
	global_store_dwordx4 v[10:11], v[2:5], off
	s_nop 1
	v_or_b32_e32 v2, 48, v26
	v_ashrrev_i32_e32 v3, 31, v2
	v_lshl_add_u64 v[2:3], v[2:3], 0, v[98:99]
	v_mad_u64_u32 v[4:5], s[0:1], v2, s70, v[66:67]
	v_mad_i32_i24 v5, v3, s70, v5
	v_lshl_add_u64 v[10:11], v[4:5], 0, s[8:9]
	v_lshl_add_u64 v[2:3], v[10:11], 0, v[68:69]
	v_lshl_add_u64 v[12:13], v[2:3], 0, v[74:75]
	v_cvt_pk_bf16_f32 v2, v32, v33
	v_cvt_pk_bf16_f32 v3, v34, v35
	v_cvt_pk_bf16_f32 v4, v28, v29
	v_cvt_pk_bf16_f32 v5, v30, v31
	global_store_dwordx4 v[12:13], v[2:5], off
	s_mov_b64 s[0:1], 0
	s_nop 0
	v_lshl_add_u64 v[2:3], v[10:11], 0, v[74:75]
	v_lshl_add_u64 v[10:11], v[2:3], 0, v[36:37]
	v_cvt_pk_bf16_f32 v2, v22, v23
	v_cvt_pk_bf16_f32 v3, v24, v25
	v_cvt_pk_bf16_f32 v4, v6, v7
	v_cvt_pk_bf16_f32 v5, v8, v9
	global_store_dwordx4 v[10:11], v[2:5], off
.LBB0_307:
	s_andn2_b64 vcc, exec, s[0:1]
	s_cbranch_vccnz .LBB0_309
	s_xor_b32 s0, s4, 0xff80
	s_and_b32 s1, s0, 0xff
	s_mulk_i32 s1, 0xab
	s_lshr_b32 s1, s1, 9
	s_mul_i32 s5, s1, 3
	s_lshl_b32 s1, s1, 7
	s_sub_i32 s0, s0, s5
	v_add_u32_e32 v4, s1, v70
	v_mov_b32_e32 v14, v0
	s_and_b32 s0, s0, 0xff
	v_ashrrev_i32_e32 v5, 31, v4
	v_lshlrev_b64 v[2:3], 11, v[4:5]
	v_readfirstlane_b32 s5, v14
	v_readlane_b32 s8, v196, 6
	v_add_u32_e32 v4, 64, v4
	v_lshl_add_u32 v6, s0, 8, v70
	s_lshl_b32 s5, s5, 4
	v_readlane_b32 s10, v196, 8
	v_readlane_b32 s11, v196, 9
	v_ashrrev_i32_e32 v5, 31, v4
	v_add_u32_e32 v6, 0x300, v6
	s_and_b32 s5, s5, 0xfffffc00
	v_lshl_add_u64 v[2:3], s[10:11], 0, v[2:3]
	v_lshlrev_b32_e32 v98, 1, v71
	v_lshlrev_b64 v[4:5], 11, v[4:5]
	v_ashrrev_i32_e32 v7, 31, v6
	v_readlane_b32 s72, v197, 34
	s_add_i32 s57, s5, 0
	v_lshl_add_u64 v[2:3], v[2:3], 0, v[98:99]
	v_lshl_add_u64 v[4:5], s[10:11], 0, v[4:5]
	v_lshlrev_b64 v[6:7], 11, v[6:7]
	v_readlane_b32 s74, v197, 36
	v_readlane_b32 s75, v197, 37
	s_mov_b32 m0, s57
	s_add_i32 s5, s57, 0x2000
	v_readlane_b32 s9, v196, 7
	v_lshl_add_u64 v[4:5], v[4:5], 0, v[98:99]
	v_lshl_add_u64 v[6:7], s[74:75], 0, v[6:7]
	global_load_lds_dwordx4 v[2:3], off
	s_mov_b32 m0, s5
	s_add_i32 s33, s57, 0x4000
	v_lshl_add_u64 v[6:7], v[6:7], 0, v[98:99]
	s_mov_b64 s[8:9], 0x20000
	global_load_lds_dwordx4 v[4:5], off
	s_mov_b32 m0, s33
	s_add_i32 s38, s57, 0x6000
	v_lshl_add_u64 v[8:9], v[6:7], 0, s[8:9]
	global_load_lds_dwordx4 v[6:7], off
	s_mov_b32 m0, s38
	s_add_i32 s39, s57, 0x8000
	v_lshl_add_u64 v[10:11], v[6:7], 0, s[68:69]
	s_mov_b64 s[8:9], 0x60000
	global_load_lds_dwordx4 v[8:9], off
	s_mov_b32 m0, s39
	s_add_i32 s56, s57, 0xa000
	s_mov_b64 s[10:11], 0x80
	v_lshl_add_u64 v[12:13], v[6:7], 0, s[8:9]
	global_load_lds_dwordx4 v[10:11], off
	s_mov_b32 m0, s56
	s_add_i32 s60, s57, 0xc000
	global_load_lds_dwordx4 v[12:13], off
	v_lshl_add_u64 v[8:9], v[2:3], 0, s[10:11]
	s_mov_b32 m0, s60
	s_add_i32 s59, s57, 0xe000
	global_load_lds_dwordx4 v[8:9], off
	v_lshl_add_u64 v[8:9], v[4:5], 0, s[10:11]
	s_mov_b32 m0, s59
	s_add_i32 s61, s57, 0x10000
	global_load_lds_dwordx4 v[8:9], off
	v_lshl_add_u64 v[8:9], v[6:7], 0, s[10:11]
	s_mov_b32 m0, s61
	s_mov_b64 s[8:9], 0x20080
	s_add_i32 s62, s57, 0x12000
	global_load_lds_dwordx4 v[8:9], off
	v_lshl_add_u64 v[8:9], v[6:7], 0, s[8:9]
	s_mov_b32 m0, s62
	s_mov_b64 s[8:9], 0x40080
	s_add_i32 s63, s57, 0x14000
	global_load_lds_dwordx4 v[8:9], off
	v_lshl_add_u64 v[8:9], v[6:7], 0, s[8:9]
	s_mov_b32 m0, s63
	s_mov_b64 s[8:9], 0x60080
	s_add_i32 s72, s57, 0x16000
	v_readlane_b32 s12, v196, 10
	global_load_lds_dwordx4 v[8:9], off
	v_lshl_add_u64 v[8:9], v[6:7], 0, s[8:9]
	s_mov_b32 m0, s72
	s_mov_b32 s12, 0x1ffffc0
	v_lshrrev_b32_e32 v15, 4, v14
	v_bfe_u32 v16, v14, 4, 2
	v_and_b32_e32 v17, 15, v14
	global_load_lds_dwordx4 v[8:9], off
	v_bfe_u32 v8, v14, 1, 3
	v_lshrrev_b32_e32 v9, 2, v14
	v_and_or_b32 v9, v9, s12, v17
	v_lshlrev_b32_e32 v10, 7, v14
	v_bitop3_b32 v11, v15, v8, 3 bitop3:0x6c
	v_bitop3_b32 v8, v16, v8, 4 bitop3:0x36
	v_lshlrev_b32_e32 v9, 7, v9
	v_and_b32_e32 v60, 0x6780, v10
	v_lshlrev_b32_e32 v11, 4, v11
	v_lshlrev_b32_e32 v61, 4, v8
	v_add_u32_e32 v10, 0x4000, v60
	v_or_b32_e32 v68, v11, v9
	v_or_b32_e32 v80, v61, v9
	v_or_b32_e32 v9, v11, v60
	s_add_i32 s64, s57, 0x18000
	v_readlane_b32 s73, v197, 35
	s_waitcnt vmcnt(6)
	s_barrier
	v_or_b32_e32 v69, v11, v10
	v_or_b32_e32 v81, v61, v10
	v_add_u32_e32 v8, 0, v68
	v_add_u32_e32 v9, 0, v9
	v_lshl_add_u64 v[10:11], v[2:3], 0, s[96:97]
	s_mov_b32 m0, s64
	s_add_i32 s71, s57, 0x1a000
	ds_read_b128 v[12:15], v8
	ds_read_b128 v[16:19], v8 offset:2048
	ds_read_b128 v[20:23], v8 offset:4096
	ds_read_b128 v[24:27], v8 offset:6144
	ds_read_b128 v[28:31], v9 offset:22528
	ds_read_b128 v[32:35], v9 offset:20480
	ds_read_b128 v[36:39], v9 offset:18432
	ds_read_b128 v[40:43], v9 offset:16384
	global_load_lds_dwordx4 v[10:11], off
	v_lshl_add_u64 v[10:11], v[4:5], 0, s[96:97]
	s_mov_b32 m0, s71
	s_add_i32 s73, s57, 0x1c000
	global_load_lds_dwordx4 v[10:11], off
	v_lshl_add_u64 v[10:11], v[6:7], 0, s[96:97]
	s_mov_b32 m0, s73
	s_mov_b64 s[8:9], 0x20100
	s_add_i32 s74, s57, 0x1e000
	v_readlane_b32 s76, v197, 38
	global_load_lds_dwordx4 v[10:11], off
	v_lshl_add_u64 v[10:11], v[6:7], 0, s[8:9]
	s_mov_b32 m0, s74
	s_mov_b64 s[8:9], 0x40100
	s_add_i32 s75, s57, 0x20000
	global_load_lds_dwordx4 v[10:11], off
	v_lshl_add_u64 v[10:11], v[6:7], 0, s[8:9]
	s_mov_b32 m0, s75
	s_mov_b64 s[8:9], 0x60100
	s_add_i32 s76, s57, 0x22000
	global_load_lds_dwordx4 v[10:11], off
	v_lshl_add_u64 v[10:11], v[6:7], 0, s[8:9]
	s_mov_b32 m0, s76
	v_readlane_b32 s78, v197, 40
	global_load_lds_dwordx4 v[10:11], off
	v_or_b32_e32 v11, v61, v60
	v_add_u32_e32 v10, 0, v80
	v_add_u32_e32 v11, 0, v11
	ds_read_b128 v[44:47], v10
	ds_read_b128 v[48:51], v10 offset:2048
	ds_read_b128 v[52:55], v10 offset:4096
	ds_read_b128 v[56:59], v10 offset:6144
	ds_read_b128 v[60:63], v11 offset:16384
	ds_read_b128 v[64:67], v11 offset:18432
	ds_read_b128 v[72:75], v11 offset:20480
	ds_read_b128 v[76:79], v11 offset:22528
	v_readlane_b32 s79, v197, 41
	v_readlane_b32 s80, v197, 42
	v_readlane_b32 s81, v197, 43
	v_readlane_b32 s82, v197, 44
	v_readlane_b32 s83, v197, 45
	v_readlane_b32 s84, v197, 46
	v_readlane_b32 s85, v197, 47
	v_readlane_b32 s13, v196, 11
	v_readlane_b32 s14, v196, 12
	v_readlane_b32 s15, v196, 13
	v_readlane_b32 s16, v196, 14
	v_readlane_b32 s17, v196, 15
	v_readlane_b32 s18, v196, 16
	v_readlane_b32 s19, v196, 17
	v_readlane_b32 s20, v196, 18
	v_readlane_b32 s21, v196, 19
	v_readlane_b32 s22, v196, 20
	v_readlane_b32 s23, v196, 21
	v_readlane_b32 s77, v197, 39
	v_readlane_b32 s86, v197, 48
	v_readlane_b32 s87, v197, 49
	s_waitcnt lgkmcnt(8)
	v_mfma_f32_16x16x32_bf16 v[84:87], v[40:43], v[12:15], 0
	v_mfma_f32_16x16x32_bf16 v[88:91], v[36:39], v[12:15], 0
	v_mfma_f32_16x16x32_bf16 v[92:95], v[32:35], v[12:15], 0
	v_mfma_f32_16x16x32_bf16 v[102:105], v[28:31], v[12:15], 0
	v_mfma_f32_16x16x32_bf16 v[106:109], v[40:43], v[16:19], 0
	v_mfma_f32_16x16x32_bf16 v[112:115], v[36:39], v[16:19], 0
	v_mfma_f32_16x16x32_bf16 v[116:119], v[32:35], v[16:19], 0
	v_mfma_f32_16x16x32_bf16 v[14:17], v[28:31], v[16:19], 0
	v_mfma_f32_16x16x32_bf16 v[120:123], v[40:43], v[20:23], 0
	v_mfma_f32_16x16x32_bf16 v[124:127], v[36:39], v[20:23], 0
	v_mfma_f32_16x16x32_bf16 v[128:131], v[32:35], v[20:23], 0
	v_mfma_f32_16x16x32_bf16 v[18:21], v[28:31], v[20:23], 0
	v_mfma_f32_16x16x32_bf16 v[40:43], v[40:43], v[24:27], 0
	v_mfma_f32_16x16x32_bf16 v[36:39], v[36:39], v[24:27], 0
	v_mfma_f32_16x16x32_bf16 v[32:35], v[32:35], v[24:27], 0
	v_mfma_f32_16x16x32_bf16 v[22:25], v[28:31], v[24:27], 0
	s_add_i32 s77, 0, 0xc000
	s_waitcnt vmcnt(6) lgkmcnt(0)
	s_barrier
	v_add_u32_e32 v12, s77, v69
	ds_read_b128 v[26:29], v8 offset:49152
	ds_read_b128 v[132:135], v8 offset:51200
	ds_read_b128 v[138:141], v8 offset:53248
	ds_read_b128 v[142:145], v8 offset:55296
	ds_read_b128 v[152:155], v12
	ds_read_b128 v[156:159], v12 offset:2048
	ds_read_b128 v[160:163], v12 offset:4096
	ds_read_b128 v[164:167], v12 offset:6144
	v_mfma_f32_16x16x32_bf16 v[84:87], v[60:63], v[44:47], v[84:87]
	v_mfma_f32_16x16x32_bf16 v[88:91], v[64:67], v[44:47], v[88:91]
	v_mfma_f32_16x16x32_bf16 v[92:95], v[72:75], v[44:47], v[92:95]
	v_mfma_f32_16x16x32_bf16 v[44:47], v[76:79], v[44:47], v[102:105]
	v_mfma_f32_16x16x32_bf16 v[102:105], v[60:63], v[48:51], v[106:109]
	v_mfma_f32_16x16x32_bf16 v[106:109], v[64:67], v[48:51], v[112:115]
	v_mfma_f32_16x16x32_bf16 v[112:115], v[72:75], v[48:51], v[116:119]
	v_mfma_f32_16x16x32_bf16 v[14:17], v[76:79], v[48:51], v[14:17]
	v_mfma_f32_16x16x32_bf16 v[48:51], v[60:63], v[52:55], v[120:123]
	v_mfma_f32_16x16x32_bf16 v[116:119], v[64:67], v[52:55], v[124:127]
	v_mfma_f32_16x16x32_bf16 v[120:123], v[72:75], v[52:55], v[128:131]
	v_mfma_f32_16x16x32_bf16 v[18:21], v[76:79], v[52:55], v[18:21]
	v_mfma_f32_16x16x32_bf16 v[40:43], v[60:63], v[56:59], v[40:43]
	v_mfma_f32_16x16x32_bf16 v[36:39], v[64:67], v[56:59], v[36:39]
	v_mfma_f32_16x16x32_bf16 v[30:33], v[72:75], v[56:59], v[32:35]
	v_mfma_f32_16x16x32_bf16 v[22:25], v[76:79], v[56:59], v[22:25]
	s_mov_b64 s[8:9], 0x180
	s_mov_b32 m0, s57
	v_lshl_add_u64 v[34:35], v[2:3], 0, s[8:9]
	global_load_lds_dwordx4 v[34:35], off
	v_lshl_add_u64 v[34:35], v[4:5], 0, s[8:9]
	s_mov_b32 m0, s5
	v_add_u32_e32 v13, s77, v81
	global_load_lds_dwordx4 v[34:35], off
	v_lshl_add_u64 v[34:35], v[6:7], 0, s[8:9]
	s_mov_b32 m0, s33
	s_mov_b64 s[8:9], 0x20180
	global_load_lds_dwordx4 v[34:35], off
	v_lshl_add_u64 v[34:35], v[6:7], 0, s[8:9]
	s_mov_b32 m0, s38
	s_mov_b64 s[8:9], 0x40180
	global_load_lds_dwordx4 v[34:35], off
	v_lshl_add_u64 v[34:35], v[6:7], 0, s[8:9]
	s_mov_b32 m0, s39
	s_mov_b64 s[8:9], 0x60180
	global_load_lds_dwordx4 v[34:35], off
	v_lshl_add_u64 v[34:35], v[6:7], 0, s[8:9]
	s_mov_b32 m0, s56
	s_nop 0
	global_load_lds_dwordx4 v[34:35], off
	ds_read_b128 v[52:55], v10 offset:49152
	ds_read_b128 v[56:59], v10 offset:51200
	ds_read_b128 v[60:63], v10 offset:53248
	ds_read_b128 v[64:67], v10 offset:55296
	ds_read_b128 v[72:75], v13
	ds_read_b128 v[76:79], v13 offset:2048
	ds_read_b128 v[124:127], v13 offset:4096
	ds_read_b128 v[128:131], v13 offset:6144
	s_waitcnt lgkmcnt(8)
	v_mfma_f32_16x16x32_bf16 v[84:87], v[152:155], v[26:29], v[84:87]
	v_mfma_f32_16x16x32_bf16 v[88:91], v[156:159], v[26:29], v[88:91]
	v_mfma_f32_16x16x32_bf16 v[92:95], v[160:163], v[26:29], v[92:95]
	v_mfma_f32_16x16x32_bf16 v[26:29], v[164:167], v[26:29], v[44:47]
	v_mfma_f32_16x16x32_bf16 v[44:47], v[152:155], v[132:135], v[102:105]
	v_mfma_f32_16x16x32_bf16 v[102:105], v[156:159], v[132:135], v[106:109]
	v_mfma_f32_16x16x32_bf16 v[106:109], v[160:163], v[132:135], v[112:115]
	v_mfma_f32_16x16x32_bf16 v[112:115], v[164:167], v[132:135], v[14:17]
	v_mfma_f32_16x16x32_bf16 v[48:51], v[152:155], v[138:141], v[48:51]
	v_mfma_f32_16x16x32_bf16 v[116:119], v[156:159], v[138:141], v[116:119]
	v_mfma_f32_16x16x32_bf16 v[120:123], v[160:163], v[138:141], v[120:123]
	v_mfma_f32_16x16x32_bf16 v[16:19], v[164:167], v[138:141], v[18:21]
	v_mfma_f32_16x16x32_bf16 v[40:43], v[152:155], v[142:145], v[40:43]
	v_mfma_f32_16x16x32_bf16 v[34:37], v[156:159], v[142:145], v[36:39]
	v_mfma_f32_16x16x32_bf16 v[30:33], v[160:163], v[142:145], v[30:33]
	v_mfma_f32_16x16x32_bf16 v[20:23], v[164:167], v[142:145], v[22:25]
	s_add_i32 s77, 0, 0x18000
	s_waitcnt vmcnt(6) lgkmcnt(0)
	s_barrier
	v_add_u32_e32 v14, s77, v68
	v_add_u32_e32 v15, s77, v69
	ds_read_b128 v[132:135], v14
	ds_read_b128 v[138:141], v14 offset:2048
	ds_read_b128 v[142:145], v14 offset:4096
	ds_read_b128 v[152:155], v14 offset:6144
	ds_read_b128 v[156:159], v15
	ds_read_b128 v[160:163], v15 offset:2048
	ds_read_b128 v[164:167], v15 offset:4096
	ds_read_b128 v[168:171], v15 offset:6144
	v_mfma_f32_16x16x32_bf16 v[84:87], v[72:75], v[52:55], v[84:87]
	v_mfma_f32_16x16x32_bf16 v[88:91], v[76:79], v[52:55], v[88:91]
	v_mfma_f32_16x16x32_bf16 v[92:95], v[124:127], v[52:55], v[92:95]
	v_mfma_f32_16x16x32_bf16 v[24:27], v[128:131], v[52:55], v[26:29]
	v_mfma_f32_16x16x32_bf16 v[44:47], v[72:75], v[56:59], v[44:47]
	v_mfma_f32_16x16x32_bf16 v[52:55], v[76:79], v[56:59], v[102:105]
	v_mfma_f32_16x16x32_bf16 v[102:105], v[124:127], v[56:59], v[106:109]
	v_mfma_f32_16x16x32_bf16 v[56:59], v[128:131], v[56:59], v[112:115]
	v_mfma_f32_16x16x32_bf16 v[48:51], v[72:75], v[60:63], v[48:51]
	v_mfma_f32_16x16x32_bf16 v[106:109], v[76:79], v[60:63], v[116:119]
	v_mfma_f32_16x16x32_bf16 v[112:115], v[124:127], v[60:63], v[120:123]
	v_mfma_f32_16x16x32_bf16 v[60:63], v[128:131], v[60:63], v[16:19]
	v_mfma_f32_16x16x32_bf16 v[38:41], v[72:75], v[64:67], v[40:43]
	v_mfma_f32_16x16x32_bf16 v[34:37], v[76:79], v[64:67], v[34:37]
	v_mfma_f32_16x16x32_bf16 v[28:31], v[124:127], v[64:67], v[30:33]
	v_mfma_f32_16x16x32_bf16 v[18:21], v[128:131], v[64:67], v[20:23]
	s_mov_b64 s[8:9], 0x200
	s_mov_b32 m0, s60
	v_lshl_add_u64 v[16:17], v[2:3], 0, s[8:9]
	global_load_lds_dwordx4 v[16:17], off
	v_lshl_add_u64 v[16:17], v[4:5], 0, s[8:9]
	s_mov_b32 m0, s59
	s_nop 0
	global_load_lds_dwordx4 v[16:17], off
	v_lshl_add_u64 v[16:17], v[6:7], 0, s[8:9]
	s_mov_b32 m0, s61
	s_mov_b64 s[8:9], 0x20200
	global_load_lds_dwordx4 v[16:17], off
	v_lshl_add_u64 v[16:17], v[6:7], 0, s[8:9]
	s_mov_b32 m0, s62
	s_mov_b64 s[8:9], 0x40200
	global_load_lds_dwordx4 v[16:17], off
	v_lshl_add_u64 v[16:17], v[6:7], 0, s[8:9]
	s_mov_b32 m0, s63
	s_mov_b64 s[8:9], 0x60200
	global_load_lds_dwordx4 v[16:17], off
	v_lshl_add_u64 v[16:17], v[6:7], 0, s[8:9]
	s_mov_b32 m0, s72
	s_nop 0
	global_load_lds_dwordx4 v[16:17], off
	v_add_u32_e32 v16, s77, v80
	v_add_u32_e32 v17, s77, v81
	ds_read_b128 v[64:67], v16
	ds_read_b128 v[72:75], v16 offset:2048
	ds_read_b128 v[76:79], v16 offset:4096
	ds_read_b128 v[116:119], v16 offset:6144
	ds_read_b128 v[120:123], v17
	ds_read_b128 v[124:127], v17 offset:2048
	ds_read_b128 v[128:131], v17 offset:4096
	ds_read_b128 v[172:175], v17 offset:6144
	s_waitcnt lgkmcnt(8)
	v_mfma_f32_16x16x32_bf16 v[84:87], v[156:159], v[132:135], v[84:87]
	v_mfma_f32_16x16x32_bf16 v[88:91], v[160:163], v[132:135], v[88:91]
	v_mfma_f32_16x16x32_bf16 v[92:95], v[164:167], v[132:135], v[92:95]
	v_mfma_f32_16x16x32_bf16 v[22:25], v[168:171], v[132:135], v[24:27]
	v_mfma_f32_16x16x32_bf16 v[42:45], v[156:159], v[138:141], v[44:47]
	v_mfma_f32_16x16x32_bf16 v[52:55], v[160:163], v[138:141], v[52:55]
	v_mfma_f32_16x16x32_bf16 v[102:105], v[164:167], v[138:141], v[102:105]
	v_mfma_f32_16x16x32_bf16 v[56:59], v[168:171], v[138:141], v[56:59]
	v_mfma_f32_16x16x32_bf16 v[46:49], v[156:159], v[142:145], v[48:51]
	v_mfma_f32_16x16x32_bf16 v[106:109], v[160:163], v[142:145], v[106:109]
	v_mfma_f32_16x16x32_bf16 v[112:115], v[164:167], v[142:145], v[112:115]
	v_mfma_f32_16x16x32_bf16 v[60:63], v[168:171], v[142:145], v[60:63]
	v_mfma_f32_16x16x32_bf16 v[38:41], v[156:159], v[152:155], v[38:41]
	v_mfma_f32_16x16x32_bf16 v[32:35], v[160:163], v[152:155], v[34:37]
	v_mfma_f32_16x16x32_bf16 v[26:29], v[164:167], v[152:155], v[28:31]
	v_mfma_f32_16x16x32_bf16 v[18:21], v[168:171], v[152:155], v[18:21]
	s_waitcnt vmcnt(6) lgkmcnt(0)
	s_barrier
	ds_read_b128 v[132:135], v8
	ds_read_b128 v[138:141], v8 offset:2048
	ds_read_b128 v[142:145], v8 offset:4096
	ds_read_b128 v[152:155], v8 offset:6144
	ds_read_b128 v[156:159], v9 offset:16384
	ds_read_b128 v[160:163], v9 offset:18432
	ds_read_b128 v[164:167], v9 offset:20480
	ds_read_b128 v[168:171], v9 offset:22528
	v_mfma_f32_16x16x32_bf16 v[84:87], v[120:123], v[64:67], v[84:87]
	v_mfma_f32_16x16x32_bf16 v[88:91], v[124:127], v[64:67], v[88:91]
	v_mfma_f32_16x16x32_bf16 v[92:95], v[128:131], v[64:67], v[92:95]
	v_mfma_f32_16x16x32_bf16 v[22:25], v[172:175], v[64:67], v[22:25]
	v_mfma_f32_16x16x32_bf16 v[42:45], v[120:123], v[72:75], v[42:45]
	v_mfma_f32_16x16x32_bf16 v[50:53], v[124:127], v[72:75], v[52:55]
	v_mfma_f32_16x16x32_bf16 v[64:67], v[128:131], v[72:75], v[102:105]
	v_mfma_f32_16x16x32_bf16 v[54:57], v[172:175], v[72:75], v[56:59]
	v_mfma_f32_16x16x32_bf16 v[46:49], v[120:123], v[76:79], v[46:49]
	v_mfma_f32_16x16x32_bf16 v[72:75], v[124:127], v[76:79], v[106:109]
	v_mfma_f32_16x16x32_bf16 v[102:105], v[128:131], v[76:79], v[112:115]
	v_mfma_f32_16x16x32_bf16 v[58:61], v[172:175], v[76:79], v[60:63]
	v_mfma_f32_16x16x32_bf16 v[36:39], v[120:123], v[116:119], v[38:41]
	v_mfma_f32_16x16x32_bf16 v[30:33], v[124:127], v[116:119], v[32:35]
	v_mfma_f32_16x16x32_bf16 v[26:29], v[128:131], v[116:119], v[26:29]
	v_mfma_f32_16x16x32_bf16 v[18:21], v[172:175], v[116:119], v[18:21]
	s_mov_b64 s[8:9], 0x280
	s_mov_b32 m0, s64
	v_lshl_add_u64 v[34:35], v[2:3], 0, s[8:9]
	global_load_lds_dwordx4 v[34:35], off
	v_lshl_add_u64 v[34:35], v[4:5], 0, s[8:9]
	s_mov_b32 m0, s71
	s_nop 0
	global_load_lds_dwordx4 v[34:35], off
	v_lshl_add_u64 v[34:35], v[6:7], 0, s[8:9]
	s_mov_b32 m0, s73
	s_mov_b64 s[8:9], 0x20280
	global_load_lds_dwordx4 v[34:35], off
	v_lshl_add_u64 v[34:35], v[6:7], 0, s[8:9]
	s_mov_b32 m0, s74
	s_mov_b64 s[8:9], 0x40280
	global_load_lds_dwordx4 v[34:35], off
	v_lshl_add_u64 v[34:35], v[6:7], 0, s[8:9]
	s_mov_b32 m0, s75
	s_mov_b64 s[8:9], 0x60280
	global_load_lds_dwordx4 v[34:35], off
	v_lshl_add_u64 v[34:35], v[6:7], 0, s[8:9]
	s_mov_b32 m0, s76
	s_nop 0
	global_load_lds_dwordx4 v[34:35], off
	ds_read_b128 v[76:79], v10
	ds_read_b128 v[106:109], v10 offset:2048
	ds_read_b128 v[112:115], v10 offset:4096
	ds_read_b128 v[116:119], v10 offset:6144
	ds_read_b128 v[120:123], v11 offset:16384
	ds_read_b128 v[124:127], v11 offset:18432
	ds_read_b128 v[128:131], v11 offset:20480
	ds_read_b128 v[172:175], v11 offset:22528
	s_waitcnt lgkmcnt(8)
	v_mfma_f32_16x16x32_bf16 v[84:87], v[156:159], v[132:135], v[84:87]
	v_mfma_f32_16x16x32_bf16 v[88:91], v[160:163], v[132:135], v[88:91]
	v_mfma_f32_16x16x32_bf16 v[92:95], v[164:167], v[132:135], v[92:95]
	v_mfma_f32_16x16x32_bf16 v[22:25], v[168:171], v[132:135], v[22:25]
	v_mfma_f32_16x16x32_bf16 v[40:43], v[156:159], v[138:141], v[42:45]
	v_mfma_f32_16x16x32_bf16 v[50:53], v[160:163], v[138:141], v[50:53]
	v_mfma_f32_16x16x32_bf16 v[62:65], v[164:167], v[138:141], v[64:67]
	v_mfma_f32_16x16x32_bf16 v[54:57], v[168:171], v[138:141], v[54:57]
	v_mfma_f32_16x16x32_bf16 v[44:47], v[156:159], v[142:145], v[46:49]
	v_mfma_f32_16x16x32_bf16 v[66:69], v[160:163], v[142:145], v[72:75]
	v_mfma_f32_16x16x32_bf16 v[72:75], v[164:167], v[142:145], v[102:105]
	v_mfma_f32_16x16x32_bf16 v[58:61], v[168:171], v[142:145], v[58:61]
	v_mfma_f32_16x16x32_bf16 v[34:37], v[156:159], v[152:155], v[36:39]
	v_mfma_f32_16x16x32_bf16 v[30:33], v[160:163], v[152:155], v[30:33]
	v_mfma_f32_16x16x32_bf16 v[26:29], v[164:167], v[152:155], v[26:29]
	v_mfma_f32_16x16x32_bf16 v[18:21], v[168:171], v[152:155], v[18:21]
	s_waitcnt vmcnt(6) lgkmcnt(0)
	s_barrier
	ds_read_b128 v[102:105], v8 offset:49152
	ds_read_b128 v[132:135], v8 offset:51200
	ds_read_b128 v[138:141], v8 offset:53248
	ds_read_b128 v[142:145], v8 offset:55296
	ds_read_b128 v[152:155], v12
	ds_read_b128 v[156:159], v12 offset:2048
	ds_read_b128 v[160:163], v12 offset:4096
	ds_read_b128 v[164:167], v12 offset:6144
	v_mfma_f32_16x16x32_bf16 v[84:87], v[120:123], v[76:79], v[84:87]
	v_mfma_f32_16x16x32_bf16 v[88:91], v[124:127], v[76:79], v[88:91]
	v_mfma_f32_16x16x32_bf16 v[92:95], v[128:131], v[76:79], v[92:95]
	v_mfma_f32_16x16x32_bf16 v[22:25], v[172:175], v[76:79], v[22:25]
	v_mfma_f32_16x16x32_bf16 v[38:41], v[120:123], v[106:109], v[40:43]
	v_mfma_f32_16x16x32_bf16 v[48:51], v[124:127], v[106:109], v[50:53]
	v_mfma_f32_16x16x32_bf16 v[62:65], v[128:131], v[106:109], v[62:65]
	v_mfma_f32_16x16x32_bf16 v[52:55], v[172:175], v[106:109], v[54:57]
	v_mfma_f32_16x16x32_bf16 v[42:45], v[120:123], v[112:115], v[44:47]
	v_mfma_f32_16x16x32_bf16 v[66:69], v[124:127], v[112:115], v[66:69]
	v_mfma_f32_16x16x32_bf16 v[72:75], v[128:131], v[112:115], v[72:75]
	v_mfma_f32_16x16x32_bf16 v[56:59], v[172:175], v[112:115], v[58:61]
	v_mfma_f32_16x16x32_bf16 v[34:37], v[120:123], v[116:119], v[34:37]
	v_mfma_f32_16x16x32_bf16 v[30:33], v[124:127], v[116:119], v[30:33]
	v_mfma_f32_16x16x32_bf16 v[26:29], v[128:131], v[116:119], v[26:29]
	v_mfma_f32_16x16x32_bf16 v[18:21], v[172:175], v[116:119], v[18:21]
	s_mov_b64 s[8:9], 0x300
	s_mov_b32 m0, s57
	v_lshl_add_u64 v[46:47], v[2:3], 0, s[8:9]
	global_load_lds_dwordx4 v[46:47], off
	v_lshl_add_u64 v[46:47], v[4:5], 0, s[8:9]
	s_mov_b32 m0, s5
	s_nop 0
	global_load_lds_dwordx4 v[46:47], off
	v_lshl_add_u64 v[46:47], v[6:7], 0, s[8:9]
	s_mov_b32 m0, s33
	s_mov_b64 s[8:9], 0x20300
	global_load_lds_dwordx4 v[46:47], off
	v_lshl_add_u64 v[46:47], v[6:7], 0, s[8:9]
	s_mov_b32 m0, s38
	s_mov_b64 s[8:9], 0x40300
	global_load_lds_dwordx4 v[46:47], off
	v_lshl_add_u64 v[46:47], v[6:7], 0, s[8:9]
	s_mov_b32 m0, s39
	s_mov_b64 s[8:9], 0x60300
	global_load_lds_dwordx4 v[46:47], off
	v_lshl_add_u64 v[46:47], v[6:7], 0, s[8:9]
	s_mov_b32 m0, s56
	s_nop 0
	global_load_lds_dwordx4 v[46:47], off
	ds_read_b128 v[76:79], v10 offset:49152
	ds_read_b128 v[106:109], v10 offset:51200
	ds_read_b128 v[112:115], v10 offset:53248
	ds_read_b128 v[116:119], v10 offset:55296
	ds_read_b128 v[120:123], v13
	ds_read_b128 v[124:127], v13 offset:2048
	ds_read_b128 v[128:131], v13 offset:4096
	ds_read_b128 v[168:171], v13 offset:6144
	s_waitcnt lgkmcnt(8)
	v_mfma_f32_16x16x32_bf16 v[84:87], v[152:155], v[102:105], v[84:87]
	v_mfma_f32_16x16x32_bf16 v[88:91], v[156:159], v[102:105], v[88:91]
	v_mfma_f32_16x16x32_bf16 v[92:95], v[160:163], v[102:105], v[92:95]
	v_mfma_f32_16x16x32_bf16 v[22:25], v[164:167], v[102:105], v[22:25]
	v_mfma_f32_16x16x32_bf16 v[38:41], v[152:155], v[132:135], v[38:41]
	v_mfma_f32_16x16x32_bf16 v[46:49], v[156:159], v[132:135], v[48:51]
	v_mfma_f32_16x16x32_bf16 v[60:63], v[160:163], v[132:135], v[62:65]
	v_mfma_f32_16x16x32_bf16 v[50:53], v[164:167], v[132:135], v[52:55]
	v_mfma_f32_16x16x32_bf16 v[42:45], v[152:155], v[138:141], v[42:45]
	v_mfma_f32_16x16x32_bf16 v[64:67], v[156:159], v[138:141], v[66:69]
	v_mfma_f32_16x16x32_bf16 v[72:75], v[160:163], v[138:141], v[72:75]
	v_mfma_f32_16x16x32_bf16 v[54:57], v[164:167], v[138:141], v[56:59]
	v_mfma_f32_16x16x32_bf16 v[34:37], v[152:155], v[142:145], v[34:37]
	v_mfma_f32_16x16x32_bf16 v[30:33], v[156:159], v[142:145], v[30:33]
	v_mfma_f32_16x16x32_bf16 v[26:29], v[160:163], v[142:145], v[26:29]
	v_mfma_f32_16x16x32_bf16 v[18:21], v[164:167], v[142:145], v[18:21]
	s_waitcnt vmcnt(6) lgkmcnt(0)
	s_barrier
	ds_read_b128 v[102:105], v14
	ds_read_b128 v[132:135], v14 offset:2048
	ds_read_b128 v[138:141], v14 offset:4096
	ds_read_b128 v[142:145], v14 offset:6144
	ds_read_b128 v[152:155], v15
	ds_read_b128 v[156:159], v15 offset:2048
	ds_read_b128 v[160:163], v15 offset:4096
	ds_read_b128 v[164:167], v15 offset:6144
	v_mfma_f32_16x16x32_bf16 v[84:87], v[120:123], v[76:79], v[84:87]
	v_mfma_f32_16x16x32_bf16 v[88:91], v[124:127], v[76:79], v[88:91]
	v_mfma_f32_16x16x32_bf16 v[92:95], v[128:131], v[76:79], v[92:95]
	v_mfma_f32_16x16x32_bf16 v[22:25], v[168:171], v[76:79], v[22:25]
	v_mfma_f32_16x16x32_bf16 v[38:41], v[120:123], v[106:109], v[38:41]
	v_mfma_f32_16x16x32_bf16 v[46:49], v[124:127], v[106:109], v[46:49]
	v_mfma_f32_16x16x32_bf16 v[58:61], v[128:131], v[106:109], v[60:63]
	v_mfma_f32_16x16x32_bf16 v[50:53], v[168:171], v[106:109], v[50:53]
	v_mfma_f32_16x16x32_bf16 v[42:45], v[120:123], v[112:115], v[42:45]
	v_mfma_f32_16x16x32_bf16 v[62:65], v[124:127], v[112:115], v[64:67]
	v_mfma_f32_16x16x32_bf16 v[66:69], v[128:131], v[112:115], v[72:75]
	v_mfma_f32_16x16x32_bf16 v[54:57], v[168:171], v[112:115], v[54:57]
	v_mfma_f32_16x16x32_bf16 v[34:37], v[120:123], v[116:119], v[34:37]
	v_mfma_f32_16x16x32_bf16 v[30:33], v[124:127], v[116:119], v[30:33]
	v_mfma_f32_16x16x32_bf16 v[26:29], v[128:131], v[116:119], v[26:29]
	v_mfma_f32_16x16x32_bf16 v[18:21], v[168:171], v[116:119], v[18:21]
	s_mov_b64 s[8:9], 0x380
	s_mov_b32 m0, s60
	v_lshl_add_u64 v[72:73], v[2:3], 0, s[8:9]
	global_load_lds_dwordx4 v[72:73], off
	v_lshl_add_u64 v[72:73], v[4:5], 0, s[8:9]
	s_mov_b32 m0, s59
	s_nop 0
	global_load_lds_dwordx4 v[72:73], off
	v_lshl_add_u64 v[72:73], v[6:7], 0, s[8:9]
	s_mov_b32 m0, s61
	s_mov_b64 s[8:9], 0x20380
	global_load_lds_dwordx4 v[72:73], off
	v_lshl_add_u64 v[72:73], v[6:7], 0, s[8:9]
	s_mov_b32 m0, s62
	s_mov_b64 s[8:9], 0x40380
	global_load_lds_dwordx4 v[72:73], off
	v_lshl_add_u64 v[72:73], v[6:7], 0, s[8:9]
	s_mov_b32 m0, s63
	s_mov_b64 s[8:9], 0x60380
	global_load_lds_dwordx4 v[72:73], off
	v_lshl_add_u64 v[72:73], v[6:7], 0, s[8:9]
	s_mov_b32 m0, s72
	s_nop 0
	global_load_lds_dwordx4 v[72:73], off
	ds_read_b128 v[72:75], v16
	ds_read_b128 v[76:79], v16 offset:2048
	ds_read_b128 v[106:109], v16 offset:4096
	ds_read_b128 v[112:115], v16 offset:6144
	ds_read_b128 v[116:119], v17
	ds_read_b128 v[120:123], v17 offset:2048
	ds_read_b128 v[124:127], v17 offset:4096
	ds_read_b128 v[128:131], v17 offset:6144
	s_waitcnt lgkmcnt(8)
	v_mfma_f32_16x16x32_bf16 v[84:87], v[152:155], v[102:105], v[84:87]
	v_mfma_f32_16x16x32_bf16 v[88:91], v[156:159], v[102:105], v[88:91]
	v_mfma_f32_16x16x32_bf16 v[92:95], v[160:163], v[102:105], v[92:95]
	v_mfma_f32_16x16x32_bf16 v[22:25], v[164:167], v[102:105], v[22:25]
	v_mfma_f32_16x16x32_bf16 v[38:41], v[152:155], v[132:135], v[38:41]
	v_mfma_f32_16x16x32_bf16 v[46:49], v[156:159], v[132:135], v[46:49]
	v_mfma_f32_16x16x32_bf16 v[58:61], v[160:163], v[132:135], v[58:61]
	v_mfma_f32_16x16x32_bf16 v[50:53], v[164:167], v[132:135], v[50:53]
	v_mfma_f32_16x16x32_bf16 v[42:45], v[152:155], v[138:141], v[42:45]
	v_mfma_f32_16x16x32_bf16 v[62:65], v[156:159], v[138:141], v[62:65]
	v_mfma_f32_16x16x32_bf16 v[66:69], v[160:163], v[138:141], v[66:69]
	v_mfma_f32_16x16x32_bf16 v[54:57], v[164:167], v[138:141], v[54:57]
	v_mfma_f32_16x16x32_bf16 v[34:37], v[152:155], v[142:145], v[34:37]
	v_mfma_f32_16x16x32_bf16 v[30:33], v[156:159], v[142:145], v[30:33]
	v_mfma_f32_16x16x32_bf16 v[26:29], v[160:163], v[142:145], v[26:29]
	v_mfma_f32_16x16x32_bf16 v[18:21], v[164:167], v[142:145], v[18:21]
	s_waitcnt vmcnt(6) lgkmcnt(0)
	s_barrier
	ds_read_b128 v[102:105], v8
	ds_read_b128 v[132:135], v8 offset:2048
	ds_read_b128 v[138:141], v8 offset:4096
	ds_read_b128 v[142:145], v8 offset:6144
	ds_read_b128 v[152:155], v9 offset:16384
	ds_read_b128 v[156:159], v9 offset:18432
	ds_read_b128 v[160:163], v9 offset:20480
	ds_read_b128 v[164:167], v9 offset:22528
	v_mfma_f32_16x16x32_bf16 v[84:87], v[116:119], v[72:75], v[84:87]
	v_mfma_f32_16x16x32_bf16 v[88:91], v[120:123], v[72:75], v[88:91]
	v_mfma_f32_16x16x32_bf16 v[92:95], v[124:127], v[72:75], v[92:95]
	v_mfma_f32_16x16x32_bf16 v[22:25], v[128:131], v[72:75], v[22:25]
	v_mfma_f32_16x16x32_bf16 v[38:41], v[116:119], v[76:79], v[38:41]
	v_mfma_f32_16x16x32_bf16 v[46:49], v[120:123], v[76:79], v[46:49]
	v_mfma_f32_16x16x32_bf16 v[58:61], v[124:127], v[76:79], v[58:61]
	v_mfma_f32_16x16x32_bf16 v[50:53], v[128:131], v[76:79], v[50:53]
	v_mfma_f32_16x16x32_bf16 v[42:45], v[116:119], v[106:109], v[42:45]
	v_mfma_f32_16x16x32_bf16 v[62:65], v[120:123], v[106:109], v[62:65]
	v_mfma_f32_16x16x32_bf16 v[66:69], v[124:127], v[106:109], v[66:69]
	v_mfma_f32_16x16x32_bf16 v[54:57], v[128:131], v[106:109], v[54:57]
	v_mfma_f32_16x16x32_bf16 v[34:37], v[116:119], v[112:115], v[34:37]
	v_mfma_f32_16x16x32_bf16 v[30:33], v[120:123], v[112:115], v[30:33]
	v_mfma_f32_16x16x32_bf16 v[26:29], v[124:127], v[112:115], v[26:29]
	v_mfma_f32_16x16x32_bf16 v[18:21], v[128:131], v[112:115], v[18:21]
	s_mov_b64 s[8:9], 0x400
	s_mov_b32 m0, s64
	v_lshl_add_u64 v[72:73], v[2:3], 0, s[8:9]
	global_load_lds_dwordx4 v[72:73], off
	v_lshl_add_u64 v[72:73], v[4:5], 0, s[8:9]
	s_mov_b32 m0, s71
	s_nop 0
	global_load_lds_dwordx4 v[72:73], off
	v_lshl_add_u64 v[72:73], v[6:7], 0, s[8:9]
	s_mov_b32 m0, s73
	s_mov_b64 s[8:9], 0x20400
	global_load_lds_dwordx4 v[72:73], off
	v_lshl_add_u64 v[72:73], v[6:7], 0, s[8:9]
	s_mov_b32 m0, s74
	s_mov_b64 s[8:9], 0x40400
	global_load_lds_dwordx4 v[72:73], off
	v_lshl_add_u64 v[72:73], v[6:7], 0, s[8:9]
	s_mov_b32 m0, s75
	s_mov_b64 s[8:9], 0x60400
	global_load_lds_dwordx4 v[72:73], off
	v_lshl_add_u64 v[72:73], v[6:7], 0, s[8:9]
	s_mov_b32 m0, s76
	s_nop 0
	global_load_lds_dwordx4 v[72:73], off
	ds_read_b128 v[72:75], v10
	ds_read_b128 v[76:79], v10 offset:2048
	ds_read_b128 v[106:109], v10 offset:4096
	ds_read_b128 v[112:115], v10 offset:6144
	ds_read_b128 v[116:119], v11 offset:16384
	ds_read_b128 v[120:123], v11 offset:18432
	ds_read_b128 v[124:127], v11 offset:20480
	ds_read_b128 v[128:131], v11 offset:22528
	s_waitcnt lgkmcnt(8)
	v_mfma_f32_16x16x32_bf16 v[84:87], v[152:155], v[102:105], v[84:87]
	v_mfma_f32_16x16x32_bf16 v[88:91], v[156:159], v[102:105], v[88:91]
	v_mfma_f32_16x16x32_bf16 v[92:95], v[160:163], v[102:105], v[92:95]
	v_mfma_f32_16x16x32_bf16 v[22:25], v[164:167], v[102:105], v[22:25]
	v_mfma_f32_16x16x32_bf16 v[38:41], v[152:155], v[132:135], v[38:41]
	v_mfma_f32_16x16x32_bf16 v[46:49], v[156:159], v[132:135], v[46:49]
	v_mfma_f32_16x16x32_bf16 v[58:61], v[160:163], v[132:135], v[58:61]
	v_mfma_f32_16x16x32_bf16 v[50:53], v[164:167], v[132:135], v[50:53]
	v_mfma_f32_16x16x32_bf16 v[42:45], v[152:155], v[138:141], v[42:45]
	v_mfma_f32_16x16x32_bf16 v[62:65], v[156:159], v[138:141], v[62:65]
	v_mfma_f32_16x16x32_bf16 v[66:69], v[160:163], v[138:141], v[66:69]
	v_mfma_f32_16x16x32_bf16 v[54:57], v[164:167], v[138:141], v[54:57]
	v_mfma_f32_16x16x32_bf16 v[34:37], v[152:155], v[142:145], v[34:37]
	v_mfma_f32_16x16x32_bf16 v[30:33], v[156:159], v[142:145], v[30:33]
	v_mfma_f32_16x16x32_bf16 v[26:29], v[160:163], v[142:145], v[26:29]
	v_mfma_f32_16x16x32_bf16 v[18:21], v[164:167], v[142:145], v[18:21]
	s_waitcnt vmcnt(6) lgkmcnt(0)
	s_barrier
	ds_read_b128 v[102:105], v8 offset:49152
	ds_read_b128 v[132:135], v8 offset:51200
	ds_read_b128 v[138:141], v8 offset:53248
	ds_read_b128 v[142:145], v8 offset:55296
	ds_read_b128 v[152:155], v12
	ds_read_b128 v[156:159], v12 offset:2048
	ds_read_b128 v[160:163], v12 offset:4096
	ds_read_b128 v[164:167], v12 offset:6144
	v_mfma_f32_16x16x32_bf16 v[84:87], v[116:119], v[72:75], v[84:87]
	v_mfma_f32_16x16x32_bf16 v[88:91], v[120:123], v[72:75], v[88:91]
	v_mfma_f32_16x16x32_bf16 v[92:95], v[124:127], v[72:75], v[92:95]
	v_mfma_f32_16x16x32_bf16 v[22:25], v[128:131], v[72:75], v[22:25]
	v_mfma_f32_16x16x32_bf16 v[38:41], v[116:119], v[76:79], v[38:41]
	v_mfma_f32_16x16x32_bf16 v[46:49], v[120:123], v[76:79], v[46:49]
	v_mfma_f32_16x16x32_bf16 v[58:61], v[124:127], v[76:79], v[58:61]
	v_mfma_f32_16x16x32_bf16 v[50:53], v[128:131], v[76:79], v[50:53]
	v_mfma_f32_16x16x32_bf16 v[42:45], v[116:119], v[106:109], v[42:45]
	v_mfma_f32_16x16x32_bf16 v[62:65], v[120:123], v[106:109], v[62:65]
	v_mfma_f32_16x16x32_bf16 v[66:69], v[124:127], v[106:109], v[66:69]
	v_mfma_f32_16x16x32_bf16 v[54:57], v[128:131], v[106:109], v[54:57]
	v_mfma_f32_16x16x32_bf16 v[34:37], v[116:119], v[112:115], v[34:37]
	v_mfma_f32_16x16x32_bf16 v[30:33], v[120:123], v[112:115], v[30:33]
	v_mfma_f32_16x16x32_bf16 v[26:29], v[124:127], v[112:115], v[26:29]
	v_mfma_f32_16x16x32_bf16 v[18:21], v[128:131], v[112:115], v[18:21]
	s_mov_b64 s[8:9], 0x480
	s_mov_b32 m0, s57
	v_lshl_add_u64 v[72:73], v[2:3], 0, s[8:9]
	global_load_lds_dwordx4 v[72:73], off
	v_lshl_add_u64 v[72:73], v[4:5], 0, s[8:9]
	s_mov_b32 m0, s5
	s_nop 0
	global_load_lds_dwordx4 v[72:73], off
	v_lshl_add_u64 v[72:73], v[6:7], 0, s[8:9]
	s_mov_b32 m0, s33
	s_mov_b64 s[8:9], 0x20480
	global_load_lds_dwordx4 v[72:73], off
	v_lshl_add_u64 v[72:73], v[6:7], 0, s[8:9]
	s_mov_b32 m0, s38
	s_mov_b64 s[8:9], 0x40480
	global_load_lds_dwordx4 v[72:73], off
	v_lshl_add_u64 v[72:73], v[6:7], 0, s[8:9]
	s_mov_b32 m0, s39
	s_mov_b64 s[8:9], 0x60480
	global_load_lds_dwordx4 v[72:73], off
	v_lshl_add_u64 v[72:73], v[6:7], 0, s[8:9]
	s_mov_b32 m0, s56
	s_nop 0
	global_load_lds_dwordx4 v[72:73], off
	ds_read_b128 v[72:75], v10 offset:49152
	ds_read_b128 v[76:79], v10 offset:51200
	ds_read_b128 v[106:109], v10 offset:53248
	ds_read_b128 v[112:115], v10 offset:55296
	ds_read_b128 v[116:119], v13
	ds_read_b128 v[120:123], v13 offset:2048
	ds_read_b128 v[124:127], v13 offset:4096
	ds_read_b128 v[128:131], v13 offset:6144
	s_waitcnt lgkmcnt(8)
	v_mfma_f32_16x16x32_bf16 v[84:87], v[152:155], v[102:105], v[84:87]
	v_mfma_f32_16x16x32_bf16 v[88:91], v[156:159], v[102:105], v[88:91]
	v_mfma_f32_16x16x32_bf16 v[92:95], v[160:163], v[102:105], v[92:95]
	v_mfma_f32_16x16x32_bf16 v[22:25], v[164:167], v[102:105], v[22:25]
	v_mfma_f32_16x16x32_bf16 v[38:41], v[152:155], v[132:135], v[38:41]
	v_mfma_f32_16x16x32_bf16 v[46:49], v[156:159], v[132:135], v[46:49]
	v_mfma_f32_16x16x32_bf16 v[58:61], v[160:163], v[132:135], v[58:61]
	v_mfma_f32_16x16x32_bf16 v[50:53], v[164:167], v[132:135], v[50:53]
	v_mfma_f32_16x16x32_bf16 v[42:45], v[152:155], v[138:141], v[42:45]
	v_mfma_f32_16x16x32_bf16 v[62:65], v[156:159], v[138:141], v[62:65]
	v_mfma_f32_16x16x32_bf16 v[66:69], v[160:163], v[138:141], v[66:69]
	v_mfma_f32_16x16x32_bf16 v[54:57], v[164:167], v[138:141], v[54:57]
	v_mfma_f32_16x16x32_bf16 v[34:37], v[152:155], v[142:145], v[34:37]
	v_mfma_f32_16x16x32_bf16 v[30:33], v[156:159], v[142:145], v[30:33]
	v_mfma_f32_16x16x32_bf16 v[26:29], v[160:163], v[142:145], v[26:29]
	v_mfma_f32_16x16x32_bf16 v[18:21], v[164:167], v[142:145], v[18:21]
	s_waitcnt vmcnt(6) lgkmcnt(0)
	s_barrier
	ds_read_b128 v[102:105], v14
	ds_read_b128 v[132:135], v14 offset:2048
	ds_read_b128 v[138:141], v14 offset:4096
	ds_read_b128 v[142:145], v14 offset:6144
	ds_read_b128 v[152:155], v15
	ds_read_b128 v[156:159], v15 offset:2048
	ds_read_b128 v[160:163], v15 offset:4096
	ds_read_b128 v[164:167], v15 offset:6144
	v_mfma_f32_16x16x32_bf16 v[84:87], v[116:119], v[72:75], v[84:87]
	v_mfma_f32_16x16x32_bf16 v[88:91], v[120:123], v[72:75], v[88:91]
	v_mfma_f32_16x16x32_bf16 v[92:95], v[124:127], v[72:75], v[92:95]
	v_mfma_f32_16x16x32_bf16 v[22:25], v[128:131], v[72:75], v[22:25]
	v_mfma_f32_16x16x32_bf16 v[38:41], v[116:119], v[76:79], v[38:41]
	v_mfma_f32_16x16x32_bf16 v[46:49], v[120:123], v[76:79], v[46:49]
	v_mfma_f32_16x16x32_bf16 v[58:61], v[124:127], v[76:79], v[58:61]
	v_mfma_f32_16x16x32_bf16 v[50:53], v[128:131], v[76:79], v[50:53]
	v_mfma_f32_16x16x32_bf16 v[42:45], v[116:119], v[106:109], v[42:45]
	v_mfma_f32_16x16x32_bf16 v[62:65], v[120:123], v[106:109], v[62:65]
	v_mfma_f32_16x16x32_bf16 v[66:69], v[124:127], v[106:109], v[66:69]
	v_mfma_f32_16x16x32_bf16 v[54:57], v[128:131], v[106:109], v[54:57]
	v_mfma_f32_16x16x32_bf16 v[34:37], v[116:119], v[112:115], v[34:37]
	v_mfma_f32_16x16x32_bf16 v[30:33], v[120:123], v[112:115], v[30:33]
	v_mfma_f32_16x16x32_bf16 v[26:29], v[124:127], v[112:115], v[26:29]
	v_mfma_f32_16x16x32_bf16 v[18:21], v[128:131], v[112:115], v[18:21]
	s_mov_b64 s[8:9], 0x500
	s_mov_b32 m0, s60
	v_lshl_add_u64 v[72:73], v[2:3], 0, s[8:9]
	global_load_lds_dwordx4 v[72:73], off
	v_lshl_add_u64 v[72:73], v[4:5], 0, s[8:9]
	s_mov_b32 m0, s59
	s_nop 0
	global_load_lds_dwordx4 v[72:73], off
	v_lshl_add_u64 v[72:73], v[6:7], 0, s[8:9]
	s_mov_b32 m0, s61
	s_mov_b64 s[8:9], 0x20500
	global_load_lds_dwordx4 v[72:73], off
	v_lshl_add_u64 v[72:73], v[6:7], 0, s[8:9]
	s_mov_b32 m0, s62
	s_mov_b64 s[8:9], 0x40500
	global_load_lds_dwordx4 v[72:73], off
	v_lshl_add_u64 v[72:73], v[6:7], 0, s[8:9]
	s_mov_b32 m0, s63
	s_mov_b64 s[8:9], 0x60500
	global_load_lds_dwordx4 v[72:73], off
	v_lshl_add_u64 v[72:73], v[6:7], 0, s[8:9]
	s_mov_b32 m0, s72
	s_nop 0
	global_load_lds_dwordx4 v[72:73], off
	ds_read_b128 v[72:75], v16
	ds_read_b128 v[76:79], v16 offset:2048
	ds_read_b128 v[106:109], v16 offset:4096
	ds_read_b128 v[112:115], v16 offset:6144
	ds_read_b128 v[116:119], v17
	ds_read_b128 v[120:123], v17 offset:2048
	ds_read_b128 v[124:127], v17 offset:4096
	ds_read_b128 v[128:131], v17 offset:6144
	s_waitcnt lgkmcnt(8)
	v_mfma_f32_16x16x32_bf16 v[84:87], v[152:155], v[102:105], v[84:87]
	v_mfma_f32_16x16x32_bf16 v[88:91], v[156:159], v[102:105], v[88:91]
	v_mfma_f32_16x16x32_bf16 v[92:95], v[160:163], v[102:105], v[92:95]
	v_mfma_f32_16x16x32_bf16 v[22:25], v[164:167], v[102:105], v[22:25]
	v_mfma_f32_16x16x32_bf16 v[38:41], v[152:155], v[132:135], v[38:41]
	v_mfma_f32_16x16x32_bf16 v[46:49], v[156:159], v[132:135], v[46:49]
	v_mfma_f32_16x16x32_bf16 v[58:61], v[160:163], v[132:135], v[58:61]
	v_mfma_f32_16x16x32_bf16 v[50:53], v[164:167], v[132:135], v[50:53]
	v_mfma_f32_16x16x32_bf16 v[42:45], v[152:155], v[138:141], v[42:45]
	v_mfma_f32_16x16x32_bf16 v[62:65], v[156:159], v[138:141], v[62:65]
	v_mfma_f32_16x16x32_bf16 v[66:69], v[160:163], v[138:141], v[66:69]
	v_mfma_f32_16x16x32_bf16 v[54:57], v[164:167], v[138:141], v[54:57]
	v_mfma_f32_16x16x32_bf16 v[34:37], v[152:155], v[142:145], v[34:37]
	v_mfma_f32_16x16x32_bf16 v[30:33], v[156:159], v[142:145], v[30:33]
	v_mfma_f32_16x16x32_bf16 v[26:29], v[160:163], v[142:145], v[26:29]
	v_mfma_f32_16x16x32_bf16 v[18:21], v[164:167], v[142:145], v[18:21]
	s_waitcnt vmcnt(6) lgkmcnt(0)
	s_barrier
	ds_read_b128 v[102:105], v8
	ds_read_b128 v[132:135], v8 offset:2048
	ds_read_b128 v[138:141], v8 offset:4096
	ds_read_b128 v[142:145], v8 offset:6144
	ds_read_b128 v[152:155], v9 offset:16384
	ds_read_b128 v[156:159], v9 offset:18432
	ds_read_b128 v[160:163], v9 offset:20480
	ds_read_b128 v[164:167], v9 offset:22528
	v_mfma_f32_16x16x32_bf16 v[84:87], v[116:119], v[72:75], v[84:87]
	v_mfma_f32_16x16x32_bf16 v[88:91], v[120:123], v[72:75], v[88:91]
	v_mfma_f32_16x16x32_bf16 v[92:95], v[124:127], v[72:75], v[92:95]
	v_mfma_f32_16x16x32_bf16 v[22:25], v[128:131], v[72:75], v[22:25]
	v_mfma_f32_16x16x32_bf16 v[38:41], v[116:119], v[76:79], v[38:41]
	v_mfma_f32_16x16x32_bf16 v[46:49], v[120:123], v[76:79], v[46:49]
	v_mfma_f32_16x16x32_bf16 v[58:61], v[124:127], v[76:79], v[58:61]
	v_mfma_f32_16x16x32_bf16 v[50:53], v[128:131], v[76:79], v[50:53]
	v_mfma_f32_16x16x32_bf16 v[42:45], v[116:119], v[106:109], v[42:45]
	v_mfma_f32_16x16x32_bf16 v[62:65], v[120:123], v[106:109], v[62:65]
	v_mfma_f32_16x16x32_bf16 v[66:69], v[124:127], v[106:109], v[66:69]
	v_mfma_f32_16x16x32_bf16 v[54:57], v[128:131], v[106:109], v[54:57]
	v_mfma_f32_16x16x32_bf16 v[34:37], v[116:119], v[112:115], v[34:37]
	v_mfma_f32_16x16x32_bf16 v[30:33], v[120:123], v[112:115], v[30:33]
	v_mfma_f32_16x16x32_bf16 v[26:29], v[124:127], v[112:115], v[26:29]
	v_mfma_f32_16x16x32_bf16 v[18:21], v[128:131], v[112:115], v[18:21]
	s_mov_b64 s[8:9], 0x580
	s_mov_b32 m0, s64
	v_lshl_add_u64 v[72:73], v[2:3], 0, s[8:9]
	global_load_lds_dwordx4 v[72:73], off
	v_lshl_add_u64 v[72:73], v[4:5], 0, s[8:9]
	s_mov_b32 m0, s71
	s_nop 0
	global_load_lds_dwordx4 v[72:73], off
	v_lshl_add_u64 v[72:73], v[6:7], 0, s[8:9]
	s_mov_b32 m0, s73
	s_mov_b64 s[8:9], 0x20580
	global_load_lds_dwordx4 v[72:73], off
	v_lshl_add_u64 v[72:73], v[6:7], 0, s[8:9]
	s_mov_b32 m0, s74
	s_mov_b64 s[8:9], 0x40580
	global_load_lds_dwordx4 v[72:73], off
	v_lshl_add_u64 v[72:73], v[6:7], 0, s[8:9]
	s_mov_b32 m0, s75
	s_mov_b64 s[8:9], 0x60580
	global_load_lds_dwordx4 v[72:73], off
	v_lshl_add_u64 v[72:73], v[6:7], 0, s[8:9]
	s_mov_b32 m0, s76
	s_nop 0
	global_load_lds_dwordx4 v[72:73], off
	ds_read_b128 v[72:75], v10
	ds_read_b128 v[76:79], v10 offset:2048
	ds_read_b128 v[106:109], v10 offset:4096
	ds_read_b128 v[112:115], v10 offset:6144
	ds_read_b128 v[116:119], v11 offset:16384
	ds_read_b128 v[120:123], v11 offset:18432
	ds_read_b128 v[124:127], v11 offset:20480
	ds_read_b128 v[128:131], v11 offset:22528
	s_waitcnt lgkmcnt(8)
	v_mfma_f32_16x16x32_bf16 v[84:87], v[152:155], v[102:105], v[84:87]
	v_mfma_f32_16x16x32_bf16 v[88:91], v[156:159], v[102:105], v[88:91]
	v_mfma_f32_16x16x32_bf16 v[92:95], v[160:163], v[102:105], v[92:95]
	v_mfma_f32_16x16x32_bf16 v[22:25], v[164:167], v[102:105], v[22:25]
	v_mfma_f32_16x16x32_bf16 v[38:41], v[152:155], v[132:135], v[38:41]
	v_mfma_f32_16x16x32_bf16 v[46:49], v[156:159], v[132:135], v[46:49]
	v_mfma_f32_16x16x32_bf16 v[58:61], v[160:163], v[132:135], v[58:61]
	v_mfma_f32_16x16x32_bf16 v[50:53], v[164:167], v[132:135], v[50:53]
	v_mfma_f32_16x16x32_bf16 v[42:45], v[152:155], v[138:141], v[42:45]
	v_mfma_f32_16x16x32_bf16 v[62:65], v[156:159], v[138:141], v[62:65]
	v_mfma_f32_16x16x32_bf16 v[66:69], v[160:163], v[138:141], v[66:69]
	v_mfma_f32_16x16x32_bf16 v[54:57], v[164:167], v[138:141], v[54:57]
	v_mfma_f32_16x16x32_bf16 v[34:37], v[152:155], v[142:145], v[34:37]
	v_mfma_f32_16x16x32_bf16 v[30:33], v[156:159], v[142:145], v[30:33]
	v_mfma_f32_16x16x32_bf16 v[26:29], v[160:163], v[142:145], v[26:29]
	v_mfma_f32_16x16x32_bf16 v[18:21], v[164:167], v[142:145], v[18:21]
	s_waitcnt vmcnt(6) lgkmcnt(0)
	s_barrier
	ds_read_b128 v[102:105], v8 offset:49152
	ds_read_b128 v[132:135], v8 offset:51200
	ds_read_b128 v[138:141], v8 offset:53248
	ds_read_b128 v[142:145], v8 offset:55296
	ds_read_b128 v[152:155], v12
	ds_read_b128 v[156:159], v12 offset:2048
	ds_read_b128 v[160:163], v12 offset:4096
	ds_read_b128 v[164:167], v12 offset:6144
	v_mfma_f32_16x16x32_bf16 v[84:87], v[116:119], v[72:75], v[84:87]
	v_mfma_f32_16x16x32_bf16 v[88:91], v[120:123], v[72:75], v[88:91]
	v_mfma_f32_16x16x32_bf16 v[92:95], v[124:127], v[72:75], v[92:95]
	v_mfma_f32_16x16x32_bf16 v[22:25], v[128:131], v[72:75], v[22:25]
	v_mfma_f32_16x16x32_bf16 v[38:41], v[116:119], v[76:79], v[38:41]
	v_mfma_f32_16x16x32_bf16 v[46:49], v[120:123], v[76:79], v[46:49]
	v_mfma_f32_16x16x32_bf16 v[58:61], v[124:127], v[76:79], v[58:61]
	v_mfma_f32_16x16x32_bf16 v[50:53], v[128:131], v[76:79], v[50:53]
	v_mfma_f32_16x16x32_bf16 v[42:45], v[116:119], v[106:109], v[42:45]
	v_mfma_f32_16x16x32_bf16 v[62:65], v[120:123], v[106:109], v[62:65]
	v_mfma_f32_16x16x32_bf16 v[66:69], v[124:127], v[106:109], v[66:69]
	v_mfma_f32_16x16x32_bf16 v[54:57], v[128:131], v[106:109], v[54:57]
	v_mfma_f32_16x16x32_bf16 v[34:37], v[116:119], v[112:115], v[34:37]
	v_mfma_f32_16x16x32_bf16 v[30:33], v[120:123], v[112:115], v[30:33]
	v_mfma_f32_16x16x32_bf16 v[26:29], v[124:127], v[112:115], v[26:29]
	v_mfma_f32_16x16x32_bf16 v[18:21], v[128:131], v[112:115], v[18:21]
	s_mov_b64 s[8:9], 0x600
	s_mov_b32 m0, s57
	v_lshl_add_u64 v[72:73], v[2:3], 0, s[8:9]
	global_load_lds_dwordx4 v[72:73], off
	v_lshl_add_u64 v[72:73], v[4:5], 0, s[8:9]
	s_mov_b32 m0, s5
	s_nop 0
	global_load_lds_dwordx4 v[72:73], off
	v_lshl_add_u64 v[72:73], v[6:7], 0, s[8:9]
	s_mov_b32 m0, s33
	s_mov_b64 s[8:9], 0x20600
	global_load_lds_dwordx4 v[72:73], off
	v_lshl_add_u64 v[72:73], v[6:7], 0, s[8:9]
	s_mov_b32 m0, s38
	s_mov_b64 s[8:9], 0x40600
	global_load_lds_dwordx4 v[72:73], off
	v_lshl_add_u64 v[72:73], v[6:7], 0, s[8:9]
	s_mov_b32 m0, s39
	s_mov_b64 s[8:9], 0x60600
	global_load_lds_dwordx4 v[72:73], off
	v_lshl_add_u64 v[72:73], v[6:7], 0, s[8:9]
	s_mov_b32 m0, s56
	s_nop 0
	global_load_lds_dwordx4 v[72:73], off
	ds_read_b128 v[72:75], v10 offset:49152
	ds_read_b128 v[76:79], v10 offset:51200
	ds_read_b128 v[106:109], v10 offset:53248
	ds_read_b128 v[112:115], v10 offset:55296
	ds_read_b128 v[116:119], v13
	ds_read_b128 v[120:123], v13 offset:2048
	ds_read_b128 v[124:127], v13 offset:4096
	ds_read_b128 v[128:131], v13 offset:6144
	s_waitcnt lgkmcnt(8)
	v_mfma_f32_16x16x32_bf16 v[84:87], v[152:155], v[102:105], v[84:87]
	v_mfma_f32_16x16x32_bf16 v[88:91], v[156:159], v[102:105], v[88:91]
	v_mfma_f32_16x16x32_bf16 v[92:95], v[160:163], v[102:105], v[92:95]
	v_mfma_f32_16x16x32_bf16 v[22:25], v[164:167], v[102:105], v[22:25]
	v_mfma_f32_16x16x32_bf16 v[38:41], v[152:155], v[132:135], v[38:41]
	v_mfma_f32_16x16x32_bf16 v[46:49], v[156:159], v[132:135], v[46:49]
	v_mfma_f32_16x16x32_bf16 v[58:61], v[160:163], v[132:135], v[58:61]
	v_mfma_f32_16x16x32_bf16 v[50:53], v[164:167], v[132:135], v[50:53]
	v_mfma_f32_16x16x32_bf16 v[42:45], v[152:155], v[138:141], v[42:45]
	v_mfma_f32_16x16x32_bf16 v[62:65], v[156:159], v[138:141], v[62:65]
	v_mfma_f32_16x16x32_bf16 v[66:69], v[160:163], v[138:141], v[66:69]
	v_mfma_f32_16x16x32_bf16 v[54:57], v[164:167], v[138:141], v[54:57]
	v_mfma_f32_16x16x32_bf16 v[34:37], v[152:155], v[142:145], v[34:37]
	v_mfma_f32_16x16x32_bf16 v[30:33], v[156:159], v[142:145], v[30:33]
	v_mfma_f32_16x16x32_bf16 v[26:29], v[160:163], v[142:145], v[26:29]
	v_mfma_f32_16x16x32_bf16 v[18:21], v[164:167], v[142:145], v[18:21]
	s_waitcnt vmcnt(6) lgkmcnt(0)
	s_barrier
	ds_read_b128 v[102:105], v14
	ds_read_b128 v[132:135], v14 offset:2048
	ds_read_b128 v[138:141], v14 offset:4096
	ds_read_b128 v[142:145], v14 offset:6144
	ds_read_b128 v[152:155], v15
	ds_read_b128 v[156:159], v15 offset:2048
	ds_read_b128 v[160:163], v15 offset:4096
	ds_read_b128 v[164:167], v15 offset:6144
	v_mfma_f32_16x16x32_bf16 v[84:87], v[116:119], v[72:75], v[84:87]
	v_mfma_f32_16x16x32_bf16 v[88:91], v[120:123], v[72:75], v[88:91]
	v_mfma_f32_16x16x32_bf16 v[92:95], v[124:127], v[72:75], v[92:95]
	v_mfma_f32_16x16x32_bf16 v[22:25], v[128:131], v[72:75], v[22:25]
	v_mfma_f32_16x16x32_bf16 v[38:41], v[116:119], v[76:79], v[38:41]
	v_mfma_f32_16x16x32_bf16 v[46:49], v[120:123], v[76:79], v[46:49]
	v_mfma_f32_16x16x32_bf16 v[58:61], v[124:127], v[76:79], v[58:61]
	v_mfma_f32_16x16x32_bf16 v[50:53], v[128:131], v[76:79], v[50:53]
	v_mfma_f32_16x16x32_bf16 v[42:45], v[116:119], v[106:109], v[42:45]
	v_mfma_f32_16x16x32_bf16 v[62:65], v[120:123], v[106:109], v[62:65]
	v_mfma_f32_16x16x32_bf16 v[66:69], v[124:127], v[106:109], v[66:69]
	v_mfma_f32_16x16x32_bf16 v[54:57], v[128:131], v[106:109], v[54:57]
	v_mfma_f32_16x16x32_bf16 v[34:37], v[116:119], v[112:115], v[34:37]
	v_mfma_f32_16x16x32_bf16 v[30:33], v[120:123], v[112:115], v[30:33]
	v_mfma_f32_16x16x32_bf16 v[26:29], v[124:127], v[112:115], v[26:29]
	v_mfma_f32_16x16x32_bf16 v[18:21], v[128:131], v[112:115], v[18:21]
	s_mov_b64 s[8:9], 0x680
	s_mov_b32 m0, s60
	v_lshl_add_u64 v[72:73], v[2:3], 0, s[8:9]
	global_load_lds_dwordx4 v[72:73], off
	v_lshl_add_u64 v[72:73], v[4:5], 0, s[8:9]
	s_mov_b32 m0, s59
	s_nop 0
	global_load_lds_dwordx4 v[72:73], off
	v_lshl_add_u64 v[72:73], v[6:7], 0, s[8:9]
	s_mov_b32 m0, s61
	s_mov_b64 s[8:9], 0x20680
	global_load_lds_dwordx4 v[72:73], off
	v_lshl_add_u64 v[72:73], v[6:7], 0, s[8:9]
	s_mov_b32 m0, s62
	s_mov_b64 s[8:9], 0x40680
	global_load_lds_dwordx4 v[72:73], off
	v_lshl_add_u64 v[72:73], v[6:7], 0, s[8:9]
	s_mov_b32 m0, s63
	s_mov_b64 s[8:9], 0x60680
	global_load_lds_dwordx4 v[72:73], off
	v_lshl_add_u64 v[72:73], v[6:7], 0, s[8:9]
	s_mov_b32 m0, s72
	s_nop 0
	global_load_lds_dwordx4 v[72:73], off
	s_mov_b64 s[8:9], exec
	v_readlane_b32 s20, v197, 0
	v_readlane_b32 s21, v197, 1
	s_and_b64 s[20:21], s[8:9], s[20:21]
	s_mov_b64 exec, s[20:21]
	s_cbranch_execz .Ldq_skip1
	v_mov_b32_e32 v251, 0
	v_mov_b32_e32 v252, 1
	global_atomic_add v250, v251, v252, s[92:93] offset:8 sc0
.Ldq_skip1:
	s_mov_b64 exec, s[8:9]
	s_mov_b32 s99, 1
	ds_read_b128 v[72:75], v16
	ds_read_b128 v[76:79], v16 offset:2048
	ds_read_b128 v[106:109], v16 offset:4096
	ds_read_b128 v[112:115], v16 offset:6144
	ds_read_b128 v[116:119], v17
	ds_read_b128 v[120:123], v17 offset:2048
	ds_read_b128 v[124:127], v17 offset:4096
	ds_read_b128 v[128:131], v17 offset:6144
	s_waitcnt lgkmcnt(8)
	v_mfma_f32_16x16x32_bf16 v[84:87], v[152:155], v[102:105], v[84:87]
	v_mfma_f32_16x16x32_bf16 v[88:91], v[156:159], v[102:105], v[88:91]
	v_mfma_f32_16x16x32_bf16 v[92:95], v[160:163], v[102:105], v[92:95]
	v_mfma_f32_16x16x32_bf16 v[22:25], v[164:167], v[102:105], v[22:25]
	v_mfma_f32_16x16x32_bf16 v[38:41], v[152:155], v[132:135], v[38:41]
	v_mfma_f32_16x16x32_bf16 v[46:49], v[156:159], v[132:135], v[46:49]
	v_mfma_f32_16x16x32_bf16 v[58:61], v[160:163], v[132:135], v[58:61]
	v_mfma_f32_16x16x32_bf16 v[50:53], v[164:167], v[132:135], v[50:53]
	v_mfma_f32_16x16x32_bf16 v[42:45], v[152:155], v[138:141], v[42:45]
	v_mfma_f32_16x16x32_bf16 v[62:65], v[156:159], v[138:141], v[62:65]
	v_mfma_f32_16x16x32_bf16 v[66:69], v[160:163], v[138:141], v[66:69]
	v_mfma_f32_16x16x32_bf16 v[54:57], v[164:167], v[138:141], v[54:57]
	v_mfma_f32_16x16x32_bf16 v[34:37], v[152:155], v[142:145], v[34:37]
	v_mfma_f32_16x16x32_bf16 v[30:33], v[156:159], v[142:145], v[30:33]
	v_mfma_f32_16x16x32_bf16 v[26:29], v[160:163], v[142:145], v[26:29]
	v_mfma_f32_16x16x32_bf16 v[18:21], v[164:167], v[142:145], v[18:21]
	s_waitcnt vmcnt(6) lgkmcnt(0)
	s_barrier
	ds_read_b128 v[102:105], v8
	ds_read_b128 v[132:135], v8 offset:2048
	ds_read_b128 v[138:141], v8 offset:4096
	ds_read_b128 v[142:145], v8 offset:6144
	ds_read_b128 v[152:155], v9 offset:16384
	ds_read_b128 v[156:159], v9 offset:18432
	ds_read_b128 v[160:163], v9 offset:20480
	ds_read_b128 v[164:167], v9 offset:22528
	v_mfma_f32_16x16x32_bf16 v[84:87], v[116:119], v[72:75], v[84:87]
	v_mfma_f32_16x16x32_bf16 v[88:91], v[120:123], v[72:75], v[88:91]
	v_mfma_f32_16x16x32_bf16 v[92:95], v[124:127], v[72:75], v[92:95]
	v_mfma_f32_16x16x32_bf16 v[22:25], v[128:131], v[72:75], v[22:25]
	v_mfma_f32_16x16x32_bf16 v[38:41], v[116:119], v[76:79], v[38:41]
	v_mfma_f32_16x16x32_bf16 v[46:49], v[120:123], v[76:79], v[46:49]
	v_mfma_f32_16x16x32_bf16 v[58:61], v[124:127], v[76:79], v[58:61]
	v_mfma_f32_16x16x32_bf16 v[50:53], v[128:131], v[76:79], v[50:53]
	v_mfma_f32_16x16x32_bf16 v[42:45], v[116:119], v[106:109], v[42:45]
	v_mfma_f32_16x16x32_bf16 v[62:65], v[120:123], v[106:109], v[62:65]
	v_mfma_f32_16x16x32_bf16 v[66:69], v[124:127], v[106:109], v[66:69]
	v_mfma_f32_16x16x32_bf16 v[54:57], v[128:131], v[106:109], v[54:57]
	v_mfma_f32_16x16x32_bf16 v[34:37], v[116:119], v[112:115], v[34:37]
	v_mfma_f32_16x16x32_bf16 v[30:33], v[120:123], v[112:115], v[30:33]
	v_mfma_f32_16x16x32_bf16 v[26:29], v[124:127], v[112:115], v[26:29]
	v_mfma_f32_16x16x32_bf16 v[18:21], v[128:131], v[112:115], v[18:21]
	s_mov_b64 s[8:9], 0x700
	s_mov_b32 m0, s64
	v_lshl_add_u64 v[72:73], v[2:3], 0, s[8:9]
	global_load_lds_dwordx4 v[72:73], off
	v_lshl_add_u64 v[72:73], v[4:5], 0, s[8:9]
	s_mov_b32 m0, s71
	s_nop 0
	global_load_lds_dwordx4 v[72:73], off
	v_lshl_add_u64 v[72:73], v[6:7], 0, s[8:9]
	s_mov_b32 m0, s73
	s_mov_b64 s[8:9], 0x20700
	global_load_lds_dwordx4 v[72:73], off
	v_lshl_add_u64 v[72:73], v[6:7], 0, s[8:9]
	s_mov_b32 m0, s74
	s_mov_b64 s[8:9], 0x40700
	global_load_lds_dwordx4 v[72:73], off
	v_lshl_add_u64 v[72:73], v[6:7], 0, s[8:9]
	s_mov_b32 m0, s75
	s_mov_b64 s[8:9], 0x60700
	global_load_lds_dwordx4 v[72:73], off
	v_lshl_add_u64 v[72:73], v[6:7], 0, s[8:9]
	s_mov_b32 m0, s76
	s_nop 0
	global_load_lds_dwordx4 v[72:73], off
	ds_read_b128 v[72:75], v10
	ds_read_b128 v[76:79], v10 offset:2048
	ds_read_b128 v[106:109], v10 offset:4096
	ds_read_b128 v[112:115], v10 offset:6144
	ds_read_b128 v[116:119], v11 offset:16384
	ds_read_b128 v[120:123], v11 offset:18432
	ds_read_b128 v[124:127], v11 offset:20480
	ds_read_b128 v[128:131], v11 offset:22528
	s_waitcnt lgkmcnt(8)
	v_mfma_f32_16x16x32_bf16 v[84:87], v[152:155], v[102:105], v[84:87]
	v_mfma_f32_16x16x32_bf16 v[88:91], v[156:159], v[102:105], v[88:91]
	v_mfma_f32_16x16x32_bf16 v[92:95], v[160:163], v[102:105], v[92:95]
	v_mfma_f32_16x16x32_bf16 v[22:25], v[164:167], v[102:105], v[22:25]
	v_mfma_f32_16x16x32_bf16 v[38:41], v[152:155], v[132:135], v[38:41]
	v_mfma_f32_16x16x32_bf16 v[46:49], v[156:159], v[132:135], v[46:49]
	v_mfma_f32_16x16x32_bf16 v[58:61], v[160:163], v[132:135], v[58:61]
	v_mfma_f32_16x16x32_bf16 v[50:53], v[164:167], v[132:135], v[50:53]
	v_mfma_f32_16x16x32_bf16 v[42:45], v[152:155], v[138:141], v[42:45]
	v_mfma_f32_16x16x32_bf16 v[62:65], v[156:159], v[138:141], v[62:65]
	v_mfma_f32_16x16x32_bf16 v[66:69], v[160:163], v[138:141], v[66:69]
	v_mfma_f32_16x16x32_bf16 v[54:57], v[164:167], v[138:141], v[54:57]
	v_mfma_f32_16x16x32_bf16 v[34:37], v[152:155], v[142:145], v[34:37]
	v_mfma_f32_16x16x32_bf16 v[30:33], v[156:159], v[142:145], v[30:33]
	v_mfma_f32_16x16x32_bf16 v[26:29], v[160:163], v[142:145], v[26:29]
	v_mfma_f32_16x16x32_bf16 v[18:21], v[164:167], v[142:145], v[18:21]
	s_waitcnt vmcnt(6) lgkmcnt(0)
	s_barrier
	ds_read_b128 v[102:105], v8 offset:49152
	ds_read_b128 v[132:135], v8 offset:51200
	ds_read_b128 v[138:141], v8 offset:53248
	ds_read_b128 v[142:145], v8 offset:55296
	ds_read_b128 v[152:155], v12
	ds_read_b128 v[156:159], v12 offset:2048
	ds_read_b128 v[160:163], v12 offset:4096
	ds_read_b128 v[164:167], v12 offset:6144
	v_mfma_f32_16x16x32_bf16 v[84:87], v[116:119], v[72:75], v[84:87]
	v_mfma_f32_16x16x32_bf16 v[88:91], v[120:123], v[72:75], v[88:91]
	v_mfma_f32_16x16x32_bf16 v[92:95], v[124:127], v[72:75], v[92:95]
	v_mfma_f32_16x16x32_bf16 v[22:25], v[128:131], v[72:75], v[22:25]
	v_mfma_f32_16x16x32_bf16 v[38:41], v[116:119], v[76:79], v[38:41]
	v_mfma_f32_16x16x32_bf16 v[46:49], v[120:123], v[76:79], v[46:49]
	v_mfma_f32_16x16x32_bf16 v[58:61], v[124:127], v[76:79], v[58:61]
	v_mfma_f32_16x16x32_bf16 v[50:53], v[128:131], v[76:79], v[50:53]
	v_mfma_f32_16x16x32_bf16 v[42:45], v[116:119], v[106:109], v[42:45]
	v_mfma_f32_16x16x32_bf16 v[62:65], v[120:123], v[106:109], v[62:65]
	v_mfma_f32_16x16x32_bf16 v[66:69], v[124:127], v[106:109], v[66:69]
	v_mfma_f32_16x16x32_bf16 v[54:57], v[128:131], v[106:109], v[54:57]
	v_mfma_f32_16x16x32_bf16 v[34:37], v[116:119], v[112:115], v[34:37]
	v_mfma_f32_16x16x32_bf16 v[30:33], v[120:123], v[112:115], v[30:33]
	v_mfma_f32_16x16x32_bf16 v[26:29], v[124:127], v[112:115], v[26:29]
	v_mfma_f32_16x16x32_bf16 v[18:21], v[128:131], v[112:115], v[18:21]
	s_mov_b64 s[8:9], 0x780
	s_mov_b32 m0, s57
	v_lshl_add_u64 v[2:3], v[2:3], 0, s[8:9]
	global_load_lds_dwordx4 v[2:3], off
	v_lshl_add_u64 v[2:3], v[4:5], 0, s[8:9]
	s_mov_b32 m0, s5
	s_nop 0
	global_load_lds_dwordx4 v[2:3], off
	v_lshl_add_u64 v[2:3], v[6:7], 0, s[8:9]
	s_mov_b32 m0, s33
	s_mov_b64 s[8:9], 0x20780
	global_load_lds_dwordx4 v[2:3], off
	v_lshl_add_u64 v[2:3], v[6:7], 0, s[8:9]
	s_mov_b32 m0, s38
	s_mov_b64 s[8:9], 0x40780
	global_load_lds_dwordx4 v[2:3], off
	v_lshl_add_u64 v[2:3], v[6:7], 0, s[8:9]
	s_mov_b32 m0, s39
	s_mov_b64 s[8:9], 0x60780
	global_load_lds_dwordx4 v[2:3], off
	v_lshl_add_u64 v[2:3], v[6:7], 0, s[8:9]
	s_mov_b32 m0, s56
	s_nop 0
	global_load_lds_dwordx4 v[2:3], off
	ds_read_b128 v[2:5], v10 offset:49152
	ds_read_b128 v[72:75], v10 offset:51200
	ds_read_b128 v[76:79], v10 offset:53248
	ds_read_b128 v[106:109], v10 offset:55296
	ds_read_b128 v[112:115], v13
	ds_read_b128 v[116:119], v13 offset:2048
	ds_read_b128 v[120:123], v13 offset:4096
	ds_read_b128 v[124:127], v13 offset:6144
	s_waitcnt lgkmcnt(8)
	v_mfma_f32_16x16x32_bf16 v[84:87], v[152:155], v[102:105], v[84:87]
	v_mfma_f32_16x16x32_bf16 v[88:91], v[156:159], v[102:105], v[88:91]
	v_mfma_f32_16x16x32_bf16 v[92:95], v[160:163], v[102:105], v[92:95]
	v_mfma_f32_16x16x32_bf16 v[22:25], v[164:167], v[102:105], v[22:25]
	v_mfma_f32_16x16x32_bf16 v[38:41], v[152:155], v[132:135], v[38:41]
	v_mfma_f32_16x16x32_bf16 v[46:49], v[156:159], v[132:135], v[46:49]
	v_mfma_f32_16x16x32_bf16 v[58:61], v[160:163], v[132:135], v[58:61]
	v_mfma_f32_16x16x32_bf16 v[50:53], v[164:167], v[132:135], v[50:53]
	v_mfma_f32_16x16x32_bf16 v[42:45], v[152:155], v[138:141], v[42:45]
	v_mfma_f32_16x16x32_bf16 v[62:65], v[156:159], v[138:141], v[62:65]
	v_mfma_f32_16x16x32_bf16 v[66:69], v[160:163], v[138:141], v[66:69]
	v_mfma_f32_16x16x32_bf16 v[54:57], v[164:167], v[138:141], v[54:57]
	v_mfma_f32_16x16x32_bf16 v[34:37], v[152:155], v[142:145], v[34:37]
	v_mfma_f32_16x16x32_bf16 v[30:33], v[156:159], v[142:145], v[30:33]
	v_mfma_f32_16x16x32_bf16 v[26:29], v[160:163], v[142:145], v[26:29]
	v_mfma_f32_16x16x32_bf16 v[18:21], v[164:167], v[142:145], v[18:21]
	s_waitcnt vmcnt(6) lgkmcnt(0)
	s_barrier
	ds_read_b128 v[102:105], v14
	ds_read_b128 v[128:131], v14 offset:2048
	ds_read_b128 v[132:135], v14 offset:4096
	ds_read_b128 v[138:141], v14 offset:6144
	ds_read_b128 v[142:145], v15
	ds_read_b128 v[152:155], v15 offset:2048
	ds_read_b128 v[156:159], v15 offset:4096
	ds_read_b128 v[12:15], v15 offset:6144
	v_mfma_f32_16x16x32_bf16 v[84:87], v[112:115], v[2:5], v[84:87]
	v_mfma_f32_16x16x32_bf16 v[88:91], v[116:119], v[2:5], v[88:91]
	v_mfma_f32_16x16x32_bf16 v[92:95], v[120:123], v[2:5], v[92:95]
	v_mfma_f32_16x16x32_bf16 v[2:5], v[124:127], v[2:5], v[22:25]
	v_mfma_f32_16x16x32_bf16 v[22:25], v[112:115], v[72:75], v[38:41]
	v_mfma_f32_16x16x32_bf16 v[38:41], v[116:119], v[72:75], v[46:49]
	v_mfma_f32_16x16x32_bf16 v[46:49], v[120:123], v[72:75], v[58:61]
	v_mfma_f32_16x16x32_bf16 v[50:53], v[124:127], v[72:75], v[50:53]
	v_mfma_f32_16x16x32_bf16 v[42:45], v[112:115], v[76:79], v[42:45]
	v_mfma_f32_16x16x32_bf16 v[58:61], v[116:119], v[76:79], v[62:65]
	v_mfma_f32_16x16x32_bf16 v[62:65], v[120:123], v[76:79], v[66:69]
	v_mfma_f32_16x16x32_bf16 v[54:57], v[124:127], v[76:79], v[54:57]
	v_mfma_f32_16x16x32_bf16 v[34:37], v[112:115], v[106:109], v[34:37]
	v_mfma_f32_16x16x32_bf16 v[30:33], v[116:119], v[106:109], v[30:33]
	v_mfma_f32_16x16x32_bf16 v[26:29], v[120:123], v[106:109], v[26:29]
	v_mfma_f32_16x16x32_bf16 v[18:21], v[124:127], v[106:109], v[18:21]
	ds_read_b128 v[66:69], v16
	ds_read_b128 v[72:75], v16 offset:2048
	ds_read_b128 v[76:79], v16 offset:4096
	ds_read_b128 v[106:109], v16 offset:6144
	ds_read_b128 v[112:115], v17
	ds_read_b128 v[116:119], v17 offset:2048
	ds_read_b128 v[120:123], v17 offset:4096
	ds_read_b128 v[124:127], v17 offset:6144
	s_waitcnt lgkmcnt(8)
	v_mfma_f32_16x16x32_bf16 v[84:87], v[142:145], v[102:105], v[84:87]
	v_mfma_f32_16x16x32_bf16 v[88:91], v[152:155], v[102:105], v[88:91]
	v_mfma_f32_16x16x32_bf16 v[92:95], v[156:159], v[102:105], v[92:95]
	v_mfma_f32_16x16x32_bf16 v[2:5], v[12:15], v[102:105], v[2:5]
	v_mfma_f32_16x16x32_bf16 v[22:25], v[142:145], v[128:131], v[22:25]
	v_mfma_f32_16x16x32_bf16 v[38:41], v[152:155], v[128:131], v[38:41]
	v_mfma_f32_16x16x32_bf16 v[46:49], v[156:159], v[128:131], v[46:49]
	v_mfma_f32_16x16x32_bf16 v[50:53], v[12:15], v[128:131], v[50:53]
	v_mfma_f32_16x16x32_bf16 v[42:45], v[142:145], v[132:135], v[42:45]
	v_mfma_f32_16x16x32_bf16 v[58:61], v[152:155], v[132:135], v[58:61]
	v_mfma_f32_16x16x32_bf16 v[62:65], v[156:159], v[132:135], v[62:65]
	v_mfma_f32_16x16x32_bf16 v[54:57], v[12:15], v[132:135], v[54:57]
	v_mfma_f32_16x16x32_bf16 v[34:37], v[142:145], v[138:141], v[34:37]
	v_mfma_f32_16x16x32_bf16 v[30:33], v[152:155], v[138:141], v[30:33]
	v_mfma_f32_16x16x32_bf16 v[26:29], v[156:159], v[138:141], v[26:29]
	v_mfma_f32_16x16x32_bf16 v[12:15], v[12:15], v[138:141], v[18:21]
	s_waitcnt vmcnt(0) lgkmcnt(0)
	s_barrier
	s_nop 1
	ds_read_b128 v[16:19], v8
	ds_read_b128 v[102:105], v8 offset:2048
	ds_read_b128 v[128:131], v8 offset:4096
	ds_read_b128 v[132:135], v8 offset:6144
	ds_read_b128 v[138:141], v9 offset:16384
	ds_read_b128 v[142:145], v9 offset:18432
	ds_read_b128 v[152:155], v9 offset:20480
	ds_read_b128 v[6:9], v9 offset:22528
	v_mfma_f32_16x16x32_bf16 v[84:87], v[112:115], v[66:69], v[84:87]
	v_mfma_f32_16x16x32_bf16 v[88:91], v[116:119], v[66:69], v[88:91]
	v_mfma_f32_16x16x32_bf16 v[92:95], v[120:123], v[66:69], v[92:95]
	v_mfma_f32_16x16x32_bf16 v[2:5], v[124:127], v[66:69], v[2:5]
	v_mfma_f32_16x16x32_bf16 v[20:23], v[112:115], v[72:75], v[22:25]
	v_mfma_f32_16x16x32_bf16 v[38:41], v[116:119], v[72:75], v[38:41]
	v_mfma_f32_16x16x32_bf16 v[46:49], v[120:123], v[72:75], v[46:49]
	v_mfma_f32_16x16x32_bf16 v[50:53], v[124:127], v[72:75], v[50:53]
	v_mfma_f32_16x16x32_bf16 v[42:45], v[112:115], v[76:79], v[42:45]
	v_mfma_f32_16x16x32_bf16 v[58:61], v[116:119], v[76:79], v[58:61]
	v_mfma_f32_16x16x32_bf16 v[62:65], v[120:123], v[76:79], v[62:65]
	v_mfma_f32_16x16x32_bf16 v[54:57], v[124:127], v[76:79], v[54:57]
	v_mfma_f32_16x16x32_bf16 v[34:37], v[112:115], v[106:109], v[34:37]
	v_mfma_f32_16x16x32_bf16 v[30:33], v[116:119], v[106:109], v[30:33]
	v_mfma_f32_16x16x32_bf16 v[24:27], v[120:123], v[106:109], v[26:29]
	v_mfma_f32_16x16x32_bf16 v[12:15], v[124:127], v[106:109], v[12:15]
	ds_read_b128 v[66:69], v10
	ds_read_b128 v[72:75], v10 offset:2048
	ds_read_b128 v[76:79], v10 offset:4096
	ds_read_b128 v[106:109], v10 offset:6144
	ds_read_b128 v[112:115], v11 offset:16384
	ds_read_b128 v[116:119], v11 offset:18432
	ds_read_b128 v[120:123], v11 offset:20480
	ds_read_b128 v[124:127], v11 offset:22528
	s_waitcnt lgkmcnt(8)
	v_mfma_f32_16x16x32_bf16 v[84:87], v[138:141], v[16:19], v[84:87]
	v_mfma_f32_16x16x32_bf16 v[88:91], v[142:145], v[16:19], v[88:91]
	v_mfma_f32_16x16x32_bf16 v[92:95], v[152:155], v[16:19], v[92:95]
	v_mfma_f32_16x16x32_bf16 v[2:5], v[6:9], v[16:19], v[2:5]
	v_mfma_f32_16x16x32_bf16 v[16:19], v[138:141], v[102:105], v[20:23]
	v_mfma_f32_16x16x32_bf16 v[20:23], v[142:145], v[102:105], v[38:41]
	v_mfma_f32_16x16x32_bf16 v[38:41], v[152:155], v[102:105], v[46:49]
	v_mfma_f32_16x16x32_bf16 v[46:49], v[6:9], v[102:105], v[50:53]
	v_mfma_f32_16x16x32_bf16 v[42:45], v[138:141], v[128:131], v[42:45]
	v_mfma_f32_16x16x32_bf16 v[102:105], v[142:145], v[128:131], v[58:61]
	v_mfma_f32_16x16x32_bf16 v[156:159], v[152:155], v[128:131], v[62:65]
	v_mfma_f32_16x16x32_bf16 v[128:131], v[6:9], v[128:131], v[54:57]
	v_mfma_f32_16x16x32_bf16 v[34:37], v[138:141], v[132:135], v[34:37]
	v_mfma_f32_16x16x32_bf16 v[138:141], v[142:145], v[132:135], v[30:33]
	v_mfma_f32_16x16x32_bf16 v[24:27], v[152:155], v[132:135], v[24:27]
	v_mfma_f32_16x16x32_bf16 v[132:135], v[6:9], v[132:135], v[12:15]
	s_waitcnt vmcnt(0) lgkmcnt(0)
	s_barrier
	v_mfma_f32_16x16x32_bf16 v[84:87], v[112:115], v[66:69], v[84:87]
	v_mfma_f32_16x16x32_bf16 v[88:91], v[116:119], v[66:69], v[88:91]
	v_mfma_f32_16x16x32_bf16 v[92:95], v[120:123], v[66:69], v[92:95]
	v_mfma_f32_16x16x32_bf16 v[142:145], v[124:127], v[66:69], v[2:5]
	v_mfma_f32_16x16x32_bf16 v[62:65], v[112:115], v[72:75], v[16:19]
	v_mfma_f32_16x16x32_bf16 v[58:61], v[116:119], v[72:75], v[20:23]
	v_mfma_f32_16x16x32_bf16 v[54:57], v[120:123], v[72:75], v[38:41]
	v_mfma_f32_16x16x32_bf16 v[50:53], v[124:127], v[72:75], v[46:49]
	v_mfma_f32_16x16x32_bf16 v[46:49], v[112:115], v[76:79], v[42:45]
	v_mfma_f32_16x16x32_bf16 v[42:45], v[116:119], v[76:79], v[102:105]
	v_mfma_f32_16x16x32_bf16 v[38:41], v[120:123], v[76:79], v[156:159]
	v_mfma_f32_16x16x32_bf16 v[30:33], v[124:127], v[76:79], v[128:131]
	v_mfma_f32_16x16x32_bf16 v[14:17], v[112:115], v[106:109], v[34:37]
	v_mfma_f32_16x16x32_bf16 v[10:13], v[116:119], v[106:109], v[138:141]
	v_mfma_f32_16x16x32_bf16 v[6:9], v[120:123], v[106:109], v[24:27]
	v_mfma_f32_16x16x32_bf16 v[2:5], v[124:127], v[106:109], v[132:135]
	v_readlane_b32 s72, v197, 2
	s_waitcnt lgkmcnt(0)
	s_barrier
	v_lshlrev_b32_e32 v18, 4, v110
	v_readlane_b32 s76, v197, 6
	v_readlane_b32 s77, v197, 7
	s_nop 4
	global_load_dwordx4 v[34:37], v18, s[76:77]
	global_load_dwordx4 v[26:29], v18, s[76:77] offset:64
	global_load_dwordx4 v[22:25], v18, s[76:77] offset:128
	s_nop 0
	global_load_dwordx4 v[18:21], v18, s[76:77] offset:192
	v_lshl_add_u32 v66, v82, 6, s1
	v_and_b32_e32 v67, 64, v150
	v_lshrrev_b32_e32 v68, 8, v66
	v_and_b32_e32 v80, 0xc0, v66
	v_xor_b32_e32 v66, 16, v150
	v_add_u32_e32 v67, 64, v67
	v_cmp_lt_i32_e32 vcc, v66, v67
	v_mov_b32_e32 v72, v85
	v_mov_b32_e32 v73, v89
	v_cndmask_b32_e32 v66, v150, v66, vcc
	v_lshlrev_b32_e32 v96, 2, v66
	v_xor_b32_e32 v66, 32, v150
	v_cmp_lt_i32_e32 vcc, v66, v67
	v_mul_hi_i32_i24_e32 v67, 0x1100, v68
	v_mov_b32_e32 v69, v88
	v_cndmask_b32_e32 v66, v150, v66, vcc
	v_lshlrev_b32_e32 v97, 2, v66
	v_mul_i32_i24_e32 v66, 0x1100, v68
	v_mov_b32_e32 v68, v84
	v_pk_mul_f32 v[72:73], v[72:73], v[72:73]
	v_mov_b32_e32 v74, v93
	v_pk_fma_f32 v[68:69], v[68:69], v[68:69], v[72:73]
	v_mov_b32_e32 v72, v86
	v_mov_b32_e32 v73, v90
	v_pk_fma_f32 v[68:69], v[72:73], v[72:73], v[68:69]
	v_mov_b32_e32 v72, v87
	v_mov_b32_e32 v73, v91
	v_mov_b32_e32 v75, v143
	v_pk_fma_f32 v[68:69], v[72:73], v[72:73], v[68:69]
	v_mov_b32_e32 v72, v92
	v_mov_b32_e32 v73, v142
	v_pk_mul_f32 v[74:75], v[74:75], v[74:75]
	v_mov_b32_e32 v76, v63
	v_pk_fma_f32 v[72:73], v[72:73], v[72:73], v[74:75]
	v_mov_b32_e32 v74, v94
	v_mov_b32_e32 v75, v144
	v_pk_fma_f32 v[72:73], v[74:75], v[74:75], v[72:73]
	v_mov_b32_e32 v74, v95
	v_mov_b32_e32 v75, v145
	v_mov_b32_e32 v77, v59
	v_pk_fma_f32 v[72:73], v[74:75], v[74:75], v[72:73]
	v_mov_b32_e32 v74, v62
	v_mov_b32_e32 v75, v58
	v_pk_mul_f32 v[76:77], v[76:77], v[76:77]
	v_mov_b32_e32 v78, v55
	v_pk_fma_f32 v[74:75], v[74:75], v[74:75], v[76:77]
	v_mov_b32_e32 v76, v64
	v_mov_b32_e32 v77, v60
	v_pk_fma_f32 v[74:75], v[76:77], v[76:77], v[74:75]
	v_mov_b32_e32 v76, v65
	v_mov_b32_e32 v77, v61
	v_mov_b32_e32 v79, v51
	v_pk_fma_f32 v[74:75], v[76:77], v[76:77], v[74:75]
	v_mov_b32_e32 v76, v54
	v_mov_b32_e32 v77, v50
	v_pk_mul_f32 v[78:79], v[78:79], v[78:79]
	s_lshl_b32 s0, s0, 9
	v_pk_fma_f32 v[76:77], v[76:77], v[76:77], v[78:79]
	v_mov_b32_e32 v78, v56
	v_mov_b32_e32 v79, v52
	v_pk_fma_f32 v[76:77], v[78:79], v[78:79], v[76:77]
	v_mov_b32_e32 v78, v57
	v_mov_b32_e32 v79, v53
	v_pk_fma_f32 v[76:77], v[78:79], v[78:79], v[76:77]
	v_mov_b32_e32 v78, v74
	v_mov_b32_e32 v79, v68
	v_mov_b32_e32 v68, v75
	v_pk_add_f32 v[68:69], v[78:79], v[68:69]
	v_mov_b32_e32 v74, v76
	v_mov_b32_e32 v75, v72
	v_pk_add_f32 v[68:69], v[68:69], v[74:75]
	v_mov_b32_e32 v72, v77
	v_pk_add_f32 v[68:69], v[68:69], v[72:73]
	ds_bpermute_b32 v73, v96, v69
	ds_bpermute_b32 v72, v96, v68
	v_lshl_or_b32 v98, v83, 7, s0
	s_mov_b32 s0, 0x358637bd
	v_readlane_b32 s83, v197, 13
	s_mov_b32 s8, 0x3c800000
	s_waitcnt lgkmcnt(0)
	v_pk_add_f32 v[68:69], v[68:69], v[72:73]
	ds_bpermute_b32 v73, v97, v69
	ds_bpermute_b32 v72, v97, v68
	s_mov_b32 s83, 0x800000
	v_readlane_b32 s82, v197, 12
	s_mov_b64 s[38:39], 0x1000
	s_movk_i32 s82, 0x600
	s_waitcnt lgkmcnt(0)
	v_pk_add_f32 v[68:69], v[68:69], v[72:73]
	v_mov_b64_e32 v[72:73], s[0:1]
	v_pk_fma_f32 v[76:77], v[68:69], s[8:9], v[72:73] op_sel_hi:[1,0,0]
	v_lshl_add_u64 v[66:67], v[66:67], 0, s[38:39]
	v_mul_f32_e32 v68, 0x4b800000, v77
	v_cmp_gt_f32_e32 vcc, s83, v77
	v_mul_lo_u32 v100, v67, s82
	v_or3_b32 v102, v80, v101, v66
	v_cndmask_b32_e32 v68, v77, v68, vcc
	v_rsq_f32_e32 v77, v68
	v_mov_b64_e32 v[66:67], s[14:15]
	v_mad_u64_u32 v[74:75], s[38:39], v102, s82, v[66:67]
	v_mul_f32_e32 v78, 0x45800000, v77
	v_cndmask_b32_e32 v78, v77, v78, vcc
	v_add_u32_e32 v75, v100, v75
	v_pk_mul_f32 v[80:81], v[84:85], v[78:79] op_sel_hi:[1,0]
	v_pk_mul_f32 v[84:85], v[86:87], v[78:79] op_sel_hi:[1,0]
	v_lshl_add_u64 v[74:75], v[74:75], 0, v[98:99]
	v_lshlrev_b32_e32 v68, 3, v110
	v_mov_b32_e32 v69, v99
	s_waitcnt vmcnt(0)
	v_pk_mul_f32 v[84:85], v[36:37], v[84:85]
	v_pk_mul_f32 v[80:81], v[34:35], v[80:81]
	v_lshl_add_u64 v[74:75], v[74:75], 0, v[68:69]
	v_cvt_pk_bf16_f32 v80, v80, v81
	v_cvt_pk_bf16_f32 v81, v84, v85
	global_store_dwordx2 v[74:75], v[80:81], off
	v_pk_mul_f32 v[80:81], v[88:89], v[78:79] op_sel_hi:[1,0]
	v_pk_mul_f32 v[84:85], v[90:91], v[78:79] op_sel_hi:[1,0]
	v_pk_mul_f32 v[80:81], v[26:27], v[80:81]
	v_pk_mul_f32 v[84:85], v[28:29], v[84:85]
	v_cvt_pk_bf16_f32 v80, v80, v81
	v_cvt_pk_bf16_f32 v81, v84, v85
	global_store_dwordx2 v[74:75], v[80:81], off offset:32
	v_pk_mul_f32 v[80:81], v[92:93], v[78:79] op_sel_hi:[1,0]
	v_pk_mul_f32 v[84:85], v[94:95], v[78:79] op_sel_hi:[1,0]
	v_mul_f32_e32 v77, 0x4b800000, v76
	v_cmp_gt_f32_e32 vcc, s83, v76
	v_pk_mul_f32 v[84:85], v[24:25], v[84:85]
	v_pk_mul_f32 v[80:81], v[22:23], v[80:81]
	v_cndmask_b32_e32 v76, v76, v77, vcc
	v_cvt_pk_bf16_f32 v80, v80, v81
	v_cvt_pk_bf16_f32 v81, v84, v85
	v_rsq_f32_e32 v84, v76
	global_store_dwordx2 v[74:75], v[80:81], off offset:64
	v_pk_mul_f32 v[80:81], v[142:143], v[78:79] op_sel_hi:[1,0]
	v_pk_mul_f32 v[78:79], v[144:145], v[78:79] op_sel_hi:[1,0]
	v_pk_mul_f32 v[80:81], v[18:19], v[80:81]
	v_pk_mul_f32 v[78:79], v[20:21], v[78:79]
	v_cvt_pk_bf16_f32 v76, v80, v81
	v_cvt_pk_bf16_f32 v77, v78, v79
	global_store_dwordx2 v[74:75], v[76:77], off offset:96
	v_mul_f32_e32 v74, 0x45800000, v84
	v_or_b32_e32 v75, 16, v102
	v_cndmask_b32_e32 v74, v84, v74, vcc
	v_mad_u64_u32 v[76:77], s[0:1], v75, s82, v[66:67]
	v_add_u32_e32 v77, v100, v77
	v_pk_mul_f32 v[54:55], v[54:55], v[74:75] op_sel_hi:[1,0]
	v_pk_mul_f32 v[56:57], v[56:57], v[74:75] op_sel_hi:[1,0]
	v_lshl_add_u64 v[76:77], v[76:77], 0, v[98:99]
	v_pk_mul_f32 v[56:57], v[24:25], v[56:57]
	v_pk_mul_f32 v[54:55], v[22:23], v[54:55]
	v_lshl_add_u64 v[76:77], v[76:77], 0, v[68:69]
	v_pk_mul_f32 v[58:59], v[58:59], v[74:75] op_sel_hi:[1,0]
	v_pk_mul_f32 v[60:61], v[60:61], v[74:75] op_sel_hi:[1,0]
	v_cvt_pk_bf16_f32 v54, v54, v55
	v_cvt_pk_bf16_f32 v55, v56, v57
	v_mov_b32_e32 v56, v47
	v_mov_b32_e32 v57, v43
	v_pk_mul_f32 v[60:61], v[28:29], v[60:61]
	v_pk_mul_f32 v[58:59], v[26:27], v[58:59]
	global_store_dwordx2 v[76:77], v[54:55], off offset:64
	v_mov_b32_e32 v54, v46
	v_mov_b32_e32 v55, v42
	v_pk_mul_f32 v[56:57], v[56:57], v[56:57]
	v_cvt_pk_bf16_f32 v58, v58, v59
	v_cvt_pk_bf16_f32 v59, v60, v61
	v_pk_fma_f32 v[54:55], v[54:55], v[54:55], v[56:57]
	v_mov_b32_e32 v56, v48
	v_mov_b32_e32 v57, v44
	global_store_dwordx2 v[76:77], v[58:59], off offset:32
	v_pk_fma_f32 v[54:55], v[56:57], v[56:57], v[54:55]
	v_mov_b32_e32 v56, v49
	v_mov_b32_e32 v57, v45
	v_mov_b32_e32 v58, v39
	v_mov_b32_e32 v59, v31
	v_pk_fma_f32 v[54:55], v[56:57], v[56:57], v[54:55]
	v_mov_b32_e32 v56, v38
	v_mov_b32_e32 v57, v30
	v_pk_mul_f32 v[58:59], v[58:59], v[58:59]
	v_pk_mul_f32 v[62:63], v[62:63], v[74:75] op_sel_hi:[1,0]
	v_pk_fma_f32 v[56:57], v[56:57], v[56:57], v[58:59]
	v_mov_b32_e32 v58, v40
	v_mov_b32_e32 v59, v32
	v_pk_mul_f32 v[64:65], v[64:65], v[74:75] op_sel_hi:[1,0]
	v_pk_fma_f32 v[56:57], v[58:59], v[58:59], v[56:57]
	v_mov_b32_e32 v58, v41
	v_mov_b32_e32 v59, v33
	v_mov_b32_e32 v60, v15
	v_mov_b32_e32 v61, v11
	v_pk_mul_f32 v[64:65], v[36:37], v[64:65]
	v_pk_mul_f32 v[62:63], v[34:35], v[62:63]
	v_pk_fma_f32 v[56:57], v[58:59], v[58:59], v[56:57]
	v_mov_b32_e32 v58, v14
	v_mov_b32_e32 v59, v10
	v_pk_mul_f32 v[60:61], v[60:61], v[60:61]
	v_cvt_pk_bf16_f32 v62, v62, v63
	v_cvt_pk_bf16_f32 v63, v64, v65
	v_pk_fma_f32 v[58:59], v[58:59], v[58:59], v[60:61]
	v_mov_b32_e32 v60, v16
	v_mov_b32_e32 v61, v12
	global_store_dwordx2 v[76:77], v[62:63], off
	v_pk_fma_f32 v[58:59], v[60:61], v[60:61], v[58:59]
	v_mov_b32_e32 v60, v17
	v_mov_b32_e32 v61, v13
	v_mov_b32_e32 v62, v7
	v_mov_b32_e32 v63, v3
	v_pk_fma_f32 v[58:59], v[60:61], v[60:61], v[58:59]
	v_mov_b32_e32 v60, v6
	v_mov_b32_e32 v61, v2
	v_pk_mul_f32 v[62:63], v[62:63], v[62:63]
	v_pk_mul_f32 v[50:51], v[50:51], v[74:75] op_sel_hi:[1,0]
	v_pk_fma_f32 v[60:61], v[60:61], v[60:61], v[62:63]
	v_mov_b32_e32 v62, v8
	v_mov_b32_e32 v63, v4
	v_pk_fma_f32 v[60:61], v[62:63], v[62:63], v[60:61]
	v_mov_b32_e32 v62, v9
	v_mov_b32_e32 v63, v5
	v_pk_fma_f32 v[60:61], v[62:63], v[62:63], v[60:61]
	v_mov_b32_e32 v62, v58
	v_mov_b32_e32 v63, v54
	v_mov_b32_e32 v54, v59
	v_pk_add_f32 v[54:55], v[62:63], v[54:55]
	v_mov_b32_e32 v58, v60
	v_mov_b32_e32 v59, v56
	v_pk_add_f32 v[54:55], v[54:55], v[58:59]
	v_mov_b32_e32 v56, v61
	v_pk_add_f32 v[54:55], v[54:55], v[56:57]
	ds_bpermute_b32 v57, v96, v55
	ds_bpermute_b32 v56, v96, v54
	v_pk_mul_f32 v[52:53], v[52:53], v[74:75] op_sel_hi:[1,0]
	v_pk_mul_f32 v[50:51], v[18:19], v[50:51]
	v_pk_mul_f32 v[52:53], v[20:21], v[52:53]
	v_cvt_pk_bf16_f32 v50, v50, v51
	v_cvt_pk_bf16_f32 v51, v52, v53
	s_waitcnt lgkmcnt(0)
	v_pk_add_f32 v[52:53], v[54:55], v[56:57]
	ds_bpermute_b32 v55, v97, v53
	ds_bpermute_b32 v54, v97, v52
	global_store_dwordx2 v[76:77], v[50:51], off offset:96
	v_or_b32_e32 v50, 32, v102
	v_mad_u64_u32 v[50:51], s[0:1], v50, s82, v[66:67]
	s_waitcnt lgkmcnt(0)
	v_pk_add_f32 v[52:53], v[52:53], v[54:55]
	v_add_u32_e32 v51, v100, v51
	v_pk_fma_f32 v[52:53], v[52:53], s[8:9], v[72:73] op_sel_hi:[1,0,0]
	v_lshl_add_u64 v[50:51], v[50:51], 0, v[98:99]
	v_mul_f32_e32 v54, 0x4b800000, v53
	v_cmp_gt_f32_e32 vcc, s83, v53
	v_lshl_add_u64 v[50:51], v[50:51], 0, v[68:69]
	v_readlane_b32 s84, v197, 14
	v_cndmask_b32_e32 v53, v53, v54, vcc
	v_rsq_f32_e32 v53, v53
	v_readlane_b32 s85, v197, 15
	v_readlane_b32 s78, v197, 8
	v_readlane_b32 s79, v197, 9
	v_mul_f32_e32 v54, 0x45800000, v53
	v_cndmask_b32_e32 v54, v53, v54, vcc
	v_pk_mul_f32 v[38:39], v[38:39], v[54:55] op_sel_hi:[1,0]
	v_pk_mul_f32 v[40:41], v[40:41], v[54:55] op_sel_hi:[1,0]
	v_pk_mul_f32 v[38:39], v[22:23], v[38:39]
	v_pk_mul_f32 v[40:41], v[24:25], v[40:41]
	v_cvt_pk_bf16_f32 v38, v38, v39
	v_cvt_pk_bf16_f32 v39, v40, v41
	global_store_dwordx2 v[50:51], v[38:39], off offset:64
	v_mul_f32_e32 v38, 0x4b800000, v52
	v_cmp_gt_f32_e32 vcc, s83, v52
	v_pk_mul_f32 v[30:31], v[30:31], v[54:55] op_sel_hi:[1,0]
	v_pk_mul_f32 v[32:33], v[32:33], v[54:55] op_sel_hi:[1,0]
	v_cndmask_b32_e32 v38, v52, v38, vcc
	v_rsq_f32_e32 v38, v38
	v_pk_mul_f32 v[32:33], v[20:21], v[32:33]
	v_pk_mul_f32 v[30:31], v[18:19], v[30:31]
	v_pk_mul_f32 v[46:47], v[46:47], v[54:55] op_sel_hi:[1,0]
	v_cvt_pk_bf16_f32 v30, v30, v31
	v_cvt_pk_bf16_f32 v31, v32, v33
	global_store_dwordx2 v[50:51], v[30:31], off offset:96
	v_mul_f32_e32 v30, 0x45800000, v38
	v_or_b32_e32 v31, 48, v102
	v_cndmask_b32_e32 v30, v38, v30, vcc
	v_mad_u64_u32 v[32:33], s[0:1], v31, s82, v[66:67]
	v_pk_mul_f32 v[48:49], v[48:49], v[54:55] op_sel_hi:[1,0]
	v_pk_mul_f32 v[42:43], v[42:43], v[54:55] op_sel_hi:[1,0]
	v_pk_mul_f32 v[44:45], v[44:45], v[54:55] op_sel_hi:[1,0]
	v_add_u32_e32 v33, v100, v33
	v_pk_mul_f32 v[14:15], v[14:15], v[30:31] op_sel_hi:[1,0]
	v_pk_mul_f32 v[16:17], v[16:17], v[30:31] op_sel_hi:[1,0]
	v_pk_mul_f32 v[10:11], v[10:11], v[30:31] op_sel_hi:[1,0]
	v_pk_mul_f32 v[12:13], v[12:13], v[30:31] op_sel_hi:[1,0]
	v_pk_mul_f32 v[6:7], v[6:7], v[30:31] op_sel_hi:[1,0]
	v_pk_mul_f32 v[8:9], v[8:9], v[30:31] op_sel_hi:[1,0]
	v_pk_mul_f32 v[2:3], v[2:3], v[30:31] op_sel_hi:[1,0]
	v_pk_mul_f32 v[4:5], v[4:5], v[30:31] op_sel_hi:[1,0]
	v_readlane_b32 s80, v197, 10
	v_readlane_b32 s81, v197, 11
	s_movk_i32 s84, 0xfa00
	v_pk_mul_f32 v[48:49], v[36:37], v[48:49]
	v_pk_mul_f32 v[46:47], v[34:35], v[46:47]
	v_pk_mul_f32 v[44:45], v[28:29], v[44:45]
	v_pk_mul_f32 v[42:43], v[26:27], v[42:43]
	v_lshl_add_u64 v[32:33], v[32:33], 0, v[98:99]
	v_pk_mul_f32 v[16:17], v[36:37], v[16:17]
	v_pk_mul_f32 v[14:15], v[34:35], v[14:15]
	v_pk_mul_f32 v[12:13], v[28:29], v[12:13]
	v_pk_mul_f32 v[10:11], v[26:27], v[10:11]
	v_pk_mul_f32 v[8:9], v[24:25], v[8:9]
	v_pk_mul_f32 v[6:7], v[22:23], v[6:7]
	v_pk_mul_f32 v[4:5], v[20:21], v[4:5]
	v_pk_mul_f32 v[2:3], v[18:19], v[2:3]
	s_mov_b32 s85, -1
	s_mov_b32 s79, 0x1ffffc0
	s_mov_b64 s[80:81], 0x80
	s_mov_b32 s78, 0xc0000
	v_cvt_pk_bf16_f32 v46, v46, v47
	v_cvt_pk_bf16_f32 v47, v48, v49
	v_cvt_pk_bf16_f32 v42, v42, v43
	v_cvt_pk_bf16_f32 v43, v44, v45
	v_lshl_add_u64 v[32:33], v[32:33], 0, v[68:69]
	v_cvt_pk_bf16_f32 v14, v14, v15
	v_cvt_pk_bf16_f32 v15, v16, v17
	v_cvt_pk_bf16_f32 v10, v10, v11
	v_cvt_pk_bf16_f32 v11, v12, v13
	v_cvt_pk_bf16_f32 v6, v6, v7
	v_cvt_pk_bf16_f32 v7, v8, v9
	v_cvt_pk_bf16_f32 v2, v2, v3
	v_cvt_pk_bf16_f32 v3, v4, v5
	v_readlane_b32 s73, v197, 3
	v_readlane_b32 s74, v197, 4
	v_readlane_b32 s75, v197, 5
	v_readlane_b32 s86, v197, 16
	v_readlane_b32 s87, v197, 17
	global_store_dwordx2 v[50:51], v[46:47], off
	global_store_dwordx2 v[50:51], v[42:43], off offset:32
	global_store_dwordx2 v[32:33], v[14:15], off
	global_store_dwordx2 v[32:33], v[10:11], off offset:32
	global_store_dwordx2 v[32:33], v[6:7], off offset:64
	global_store_dwordx2 v[32:33], v[2:3], off offset:96

.LBB0_310:
	s_andn2_b64 vcc, exec, s[0:1]
	s_cbranch_vccnz .LBB0_312
	s_lshl_b32 s0, s4, 1
	s_and_b32 s1, s0, 0xf80
	v_add_u32_e32 v4, s1, v70
	s_lshl_b32 s0, s4, 8
	v_ashrrev_i32_e32 v5, 31, v4
	s_and_b32 s5, s0, 0x3f00
	v_mov_b32_e32 v14, v0
	v_lshlrev_b64 v[2:3], 11, v[4:5]
	v_add_u32_e32 v4, 64, v4
	v_add_u32_e32 v6, s5, v70
	v_readlane_b32 s8, v197, 34
	v_readfirstlane_b32 s5, v14
	v_ashrrev_i32_e32 v5, 31, v4
	s_lshl_b32 s5, s5, 4
	v_readlane_b32 s9, v197, 35
	v_readlane_b32 s10, v197, 36
	v_readlane_b32 s11, v197, 37
	v_readlane_b32 s12, v197, 38
	v_readlane_b32 s13, v197, 39
	v_readlane_b32 s14, v197, 40
	v_readlane_b32 s15, v197, 41
	v_readlane_b32 s16, v197, 42
	v_readlane_b32 s17, v197, 43
	v_readlane_b32 s18, v197, 44
	v_readlane_b32 s19, v197, 45
	v_readlane_b32 s20, v197, 46
	v_readlane_b32 s21, v197, 47
	v_readlane_b32 s22, v197, 48
	v_readlane_b32 s23, v197, 49
	v_lshlrev_b64 v[4:5], 11, v[4:5]
	s_and_b32 s5, s5, 0xfffffc00
	v_lshl_add_u64 v[2:3], s[10:11], 0, v[2:3]
	v_lshlrev_b32_e32 v98, 1, v71
	v_lshl_add_u64 v[4:5], s[10:11], 0, v[4:5]
	v_ashrrev_i32_e32 v7, 31, v6
	v_readlane_b32 s8, v196, 6
	s_add_i32 s57, s5, 0
	v_lshl_add_u64 v[2:3], v[2:3], 0, v[98:99]
	v_lshlrev_b64 v[6:7], 11, v[6:7]
	v_readlane_b32 s9, v196, 7
	s_mov_b32 m0, s57
	s_add_i32 s5, s57, 0x2000
	v_lshl_add_u64 v[4:5], v[4:5], 0, v[98:99]
	v_lshl_add_u64 v[6:7], s[8:9], 0, v[6:7]
	global_load_lds_dwordx4 v[2:3], off
	s_mov_b32 m0, s5
	s_add_i32 s33, s57, 0x4000
	v_lshl_add_u64 v[6:7], v[6:7], 0, v[98:99]
	s_mov_b64 s[8:9], 0x20000
	global_load_lds_dwordx4 v[4:5], off
	s_mov_b32 m0, s33
	s_add_i32 s38, s57, 0x6000
	v_lshl_add_u64 v[8:9], v[6:7], 0, s[8:9]
	global_load_lds_dwordx4 v[6:7], off
	s_mov_b32 m0, s38
	s_add_i32 s39, s57, 0x8000
	v_lshl_add_u64 v[10:11], v[6:7], 0, s[68:69]
	s_mov_b64 s[8:9], 0x60000
	global_load_lds_dwordx4 v[8:9], off
	s_mov_b32 m0, s39
	s_add_i32 s56, s57, 0xa000
	v_lshl_add_u64 v[12:13], v[6:7], 0, s[8:9]
	global_load_lds_dwordx4 v[10:11], off
	s_mov_b32 m0, s56
	s_add_i32 s60, s57, 0xc000
	global_load_lds_dwordx4 v[12:13], off
	v_lshl_add_u64 v[8:9], v[2:3], 0, s[80:81]
	s_mov_b32 m0, s60
	s_add_i32 s59, s57, 0xe000
	global_load_lds_dwordx4 v[8:9], off
	v_lshl_add_u64 v[8:9], v[4:5], 0, s[80:81]
	s_mov_b32 m0, s59
	s_add_i32 s61, s57, 0x10000
	global_load_lds_dwordx4 v[8:9], off
	v_lshl_add_u64 v[8:9], v[6:7], 0, s[80:81]
	s_mov_b32 m0, s61
	s_mov_b64 s[8:9], 0x20080
	s_add_i32 s62, s57, 0x12000
	global_load_lds_dwordx4 v[8:9], off
	v_lshl_add_u64 v[8:9], v[6:7], 0, s[8:9]
	s_mov_b32 m0, s62
	s_mov_b64 s[8:9], 0x40080
	s_add_i32 s63, s57, 0x14000
	global_load_lds_dwordx4 v[8:9], off
	v_lshl_add_u64 v[8:9], v[6:7], 0, s[8:9]
	s_mov_b32 m0, s63
	s_mov_b64 s[8:9], 0x60080
	s_add_i32 s72, s57, 0x16000
	global_load_lds_dwordx4 v[8:9], off
	v_lshl_add_u64 v[8:9], v[6:7], 0, s[8:9]
	s_mov_b32 m0, s72
	v_lshrrev_b32_e32 v15, 4, v14
	v_bfe_u32 v16, v14, 4, 2
	v_and_b32_e32 v17, 15, v14
	global_load_lds_dwordx4 v[8:9], off
	v_bfe_u32 v8, v14, 1, 3
	v_lshrrev_b32_e32 v9, 2, v14
	v_and_or_b32 v9, v9, s79, v17
	v_lshlrev_b32_e32 v10, 7, v14
	v_bitop3_b32 v11, v15, v8, 3 bitop3:0x6c
	v_bitop3_b32 v8, v16, v8, 4 bitop3:0x36
	v_lshlrev_b32_e32 v9, 7, v9
	v_and_b32_e32 v60, 0x6780, v10
	v_lshlrev_b32_e32 v11, 4, v11
	v_lshlrev_b32_e32 v61, 4, v8
	v_add_u32_e32 v10, 0x4000, v60
	v_or_b32_e32 v68, v11, v9
	v_or_b32_e32 v80, v61, v9
	v_or_b32_e32 v9, v11, v60
	s_add_i32 s64, s57, 0x18000
	s_waitcnt vmcnt(6)
	s_barrier
	v_or_b32_e32 v69, v11, v10
	v_or_b32_e32 v81, v61, v10
	v_add_u32_e32 v8, 0, v68
	v_add_u32_e32 v9, 0, v9
	v_lshl_add_u64 v[10:11], v[2:3], 0, s[96:97]
	s_mov_b32 m0, s64
	s_add_i32 s71, s57, 0x1a000
	ds_read_b128 v[12:15], v8
	ds_read_b128 v[16:19], v8 offset:2048
	ds_read_b128 v[20:23], v8 offset:4096
	ds_read_b128 v[24:27], v8 offset:6144
	ds_read_b128 v[28:31], v9 offset:22528
	ds_read_b128 v[32:35], v9 offset:20480
	ds_read_b128 v[36:39], v9 offset:18432
	ds_read_b128 v[40:43], v9 offset:16384
	global_load_lds_dwordx4 v[10:11], off
	v_lshl_add_u64 v[10:11], v[4:5], 0, s[96:97]
	s_mov_b32 m0, s71
	s_add_i32 s73, s57, 0x1c000
	global_load_lds_dwordx4 v[10:11], off
	v_lshl_add_u64 v[10:11], v[6:7], 0, s[96:97]
	s_mov_b32 m0, s73
	s_mov_b64 s[8:9], 0x20100
	s_add_i32 s74, s57, 0x1e000
	global_load_lds_dwordx4 v[10:11], off
	v_lshl_add_u64 v[10:11], v[6:7], 0, s[8:9]
	s_mov_b32 m0, s74
	s_mov_b64 s[8:9], 0x40100
	s_add_i32 s75, s57, 0x20000
	global_load_lds_dwordx4 v[10:11], off
	v_lshl_add_u64 v[10:11], v[6:7], 0, s[8:9]
	s_mov_b32 m0, s75
	s_mov_b64 s[8:9], 0x60100
	s_add_i32 s76, s57, 0x22000
	global_load_lds_dwordx4 v[10:11], off
	v_lshl_add_u64 v[10:11], v[6:7], 0, s[8:9]
	s_mov_b32 m0, s76
	v_readlane_b32 s10, v196, 8
	global_load_lds_dwordx4 v[10:11], off
	v_or_b32_e32 v11, v61, v60
	v_add_u32_e32 v10, 0, v80
	v_add_u32_e32 v11, 0, v11
	ds_read_b128 v[44:47], v10
	ds_read_b128 v[48:51], v10 offset:2048
	ds_read_b128 v[52:55], v10 offset:4096
	ds_read_b128 v[56:59], v10 offset:6144
	ds_read_b128 v[60:63], v11 offset:16384
	ds_read_b128 v[64:67], v11 offset:18432
	ds_read_b128 v[72:75], v11 offset:20480
	ds_read_b128 v[76:79], v11 offset:22528
	v_readlane_b32 s11, v196, 9
	v_readlane_b32 s12, v196, 10
	v_readlane_b32 s13, v196, 11
	v_readlane_b32 s14, v196, 12
	v_readlane_b32 s15, v196, 13
	v_readlane_b32 s16, v196, 14
	v_readlane_b32 s17, v196, 15
	v_readlane_b32 s18, v196, 16
	v_readlane_b32 s19, v196, 17
	v_readlane_b32 s20, v196, 18
	v_readlane_b32 s21, v196, 19
	v_readlane_b32 s22, v196, 20
	v_readlane_b32 s23, v196, 21
	s_waitcnt lgkmcnt(8)
	v_mfma_f32_16x16x32_bf16 v[84:87], v[40:43], v[12:15], 0
	v_mfma_f32_16x16x32_bf16 v[88:91], v[36:39], v[12:15], 0
	v_mfma_f32_16x16x32_bf16 v[92:95], v[32:35], v[12:15], 0
	v_mfma_f32_16x16x32_bf16 v[102:105], v[28:31], v[12:15], 0
	v_mfma_f32_16x16x32_bf16 v[106:109], v[40:43], v[16:19], 0
	v_mfma_f32_16x16x32_bf16 v[112:115], v[36:39], v[16:19], 0
	v_mfma_f32_16x16x32_bf16 v[116:119], v[32:35], v[16:19], 0
	v_mfma_f32_16x16x32_bf16 v[14:17], v[28:31], v[16:19], 0
	v_mfma_f32_16x16x32_bf16 v[120:123], v[40:43], v[20:23], 0
	v_mfma_f32_16x16x32_bf16 v[124:127], v[36:39], v[20:23], 0
	v_mfma_f32_16x16x32_bf16 v[128:131], v[32:35], v[20:23], 0
	v_mfma_f32_16x16x32_bf16 v[18:21], v[28:31], v[20:23], 0
	v_mfma_f32_16x16x32_bf16 v[40:43], v[40:43], v[24:27], 0
	v_mfma_f32_16x16x32_bf16 v[36:39], v[36:39], v[24:27], 0
	v_mfma_f32_16x16x32_bf16 v[32:35], v[32:35], v[24:27], 0
	v_mfma_f32_16x16x32_bf16 v[22:25], v[28:31], v[24:27], 0
	s_add_i32 s77, 0, 0xc000
	s_waitcnt vmcnt(6) lgkmcnt(0)
	s_barrier
	v_add_u32_e32 v12, s77, v69
	ds_read_b128 v[26:29], v8 offset:49152
	ds_read_b128 v[132:135], v8 offset:51200
	ds_read_b128 v[138:141], v8 offset:53248
	ds_read_b128 v[142:145], v8 offset:55296
	ds_read_b128 v[152:155], v12
	ds_read_b128 v[156:159], v12 offset:2048
	ds_read_b128 v[160:163], v12 offset:4096
	ds_read_b128 v[164:167], v12 offset:6144
	v_mfma_f32_16x16x32_bf16 v[84:87], v[60:63], v[44:47], v[84:87]
	v_mfma_f32_16x16x32_bf16 v[88:91], v[64:67], v[44:47], v[88:91]
	v_mfma_f32_16x16x32_bf16 v[92:95], v[72:75], v[44:47], v[92:95]
	v_mfma_f32_16x16x32_bf16 v[44:47], v[76:79], v[44:47], v[102:105]
	v_mfma_f32_16x16x32_bf16 v[102:105], v[60:63], v[48:51], v[106:109]
	v_mfma_f32_16x16x32_bf16 v[106:109], v[64:67], v[48:51], v[112:115]
	v_mfma_f32_16x16x32_bf16 v[112:115], v[72:75], v[48:51], v[116:119]
	v_mfma_f32_16x16x32_bf16 v[14:17], v[76:79], v[48:51], v[14:17]
	v_mfma_f32_16x16x32_bf16 v[48:51], v[60:63], v[52:55], v[120:123]
	v_mfma_f32_16x16x32_bf16 v[116:119], v[64:67], v[52:55], v[124:127]
	v_mfma_f32_16x16x32_bf16 v[120:123], v[72:75], v[52:55], v[128:131]
	v_mfma_f32_16x16x32_bf16 v[18:21], v[76:79], v[52:55], v[18:21]
	v_mfma_f32_16x16x32_bf16 v[40:43], v[60:63], v[56:59], v[40:43]
	v_mfma_f32_16x16x32_bf16 v[36:39], v[64:67], v[56:59], v[36:39]
	v_mfma_f32_16x16x32_bf16 v[30:33], v[72:75], v[56:59], v[32:35]
	v_mfma_f32_16x16x32_bf16 v[22:25], v[76:79], v[56:59], v[22:25]
	s_mov_b64 s[8:9], 0x180
	s_mov_b32 m0, s57
	v_lshl_add_u64 v[34:35], v[2:3], 0, s[8:9]
	global_load_lds_dwordx4 v[34:35], off
	v_lshl_add_u64 v[34:35], v[4:5], 0, s[8:9]
	s_mov_b32 m0, s5
	v_add_u32_e32 v13, s77, v81
	global_load_lds_dwordx4 v[34:35], off
	v_lshl_add_u64 v[34:35], v[6:7], 0, s[8:9]
	s_mov_b32 m0, s33
	s_mov_b64 s[8:9], 0x20180
	global_load_lds_dwordx4 v[34:35], off
	v_lshl_add_u64 v[34:35], v[6:7], 0, s[8:9]
	s_mov_b32 m0, s38
	s_mov_b64 s[8:9], 0x40180
	global_load_lds_dwordx4 v[34:35], off
	v_lshl_add_u64 v[34:35], v[6:7], 0, s[8:9]
	s_mov_b32 m0, s39
	s_mov_b64 s[8:9], 0x60180
	global_load_lds_dwordx4 v[34:35], off
	v_lshl_add_u64 v[34:35], v[6:7], 0, s[8:9]
	s_mov_b32 m0, s56
	s_nop 0
	global_load_lds_dwordx4 v[34:35], off
	ds_read_b128 v[52:55], v10 offset:49152
	ds_read_b128 v[56:59], v10 offset:51200
	ds_read_b128 v[60:63], v10 offset:53248
	ds_read_b128 v[64:67], v10 offset:55296
	ds_read_b128 v[72:75], v13
	ds_read_b128 v[76:79], v13 offset:2048
	ds_read_b128 v[124:127], v13 offset:4096
	ds_read_b128 v[128:131], v13 offset:6144
	s_waitcnt lgkmcnt(8)
	v_mfma_f32_16x16x32_bf16 v[84:87], v[152:155], v[26:29], v[84:87]
	v_mfma_f32_16x16x32_bf16 v[88:91], v[156:159], v[26:29], v[88:91]
	v_mfma_f32_16x16x32_bf16 v[92:95], v[160:163], v[26:29], v[92:95]
	v_mfma_f32_16x16x32_bf16 v[26:29], v[164:167], v[26:29], v[44:47]
	v_mfma_f32_16x16x32_bf16 v[44:47], v[152:155], v[132:135], v[102:105]
	v_mfma_f32_16x16x32_bf16 v[102:105], v[156:159], v[132:135], v[106:109]
	v_mfma_f32_16x16x32_bf16 v[106:109], v[160:163], v[132:135], v[112:115]
	v_mfma_f32_16x16x32_bf16 v[112:115], v[164:167], v[132:135], v[14:17]
	v_mfma_f32_16x16x32_bf16 v[48:51], v[152:155], v[138:141], v[48:51]
	v_mfma_f32_16x16x32_bf16 v[116:119], v[156:159], v[138:141], v[116:119]
	v_mfma_f32_16x16x32_bf16 v[120:123], v[160:163], v[138:141], v[120:123]
	v_mfma_f32_16x16x32_bf16 v[16:19], v[164:167], v[138:141], v[18:21]
	v_mfma_f32_16x16x32_bf16 v[40:43], v[152:155], v[142:145], v[40:43]
	v_mfma_f32_16x16x32_bf16 v[34:37], v[156:159], v[142:145], v[36:39]
	v_mfma_f32_16x16x32_bf16 v[30:33], v[160:163], v[142:145], v[30:33]
	v_mfma_f32_16x16x32_bf16 v[20:23], v[164:167], v[142:145], v[22:25]
	s_add_i32 s77, 0, 0x18000
	s_waitcnt vmcnt(6) lgkmcnt(0)
	s_barrier
	v_add_u32_e32 v14, s77, v68
	v_add_u32_e32 v15, s77, v69
	ds_read_b128 v[132:135], v14
	ds_read_b128 v[138:141], v14 offset:2048
	ds_read_b128 v[142:145], v14 offset:4096
	ds_read_b128 v[152:155], v14 offset:6144
	ds_read_b128 v[156:159], v15
	ds_read_b128 v[160:163], v15 offset:2048
	ds_read_b128 v[164:167], v15 offset:4096
	ds_read_b128 v[168:171], v15 offset:6144
	v_mfma_f32_16x16x32_bf16 v[84:87], v[72:75], v[52:55], v[84:87]
	v_mfma_f32_16x16x32_bf16 v[88:91], v[76:79], v[52:55], v[88:91]
	v_mfma_f32_16x16x32_bf16 v[92:95], v[124:127], v[52:55], v[92:95]
	v_mfma_f32_16x16x32_bf16 v[24:27], v[128:131], v[52:55], v[26:29]
	v_mfma_f32_16x16x32_bf16 v[44:47], v[72:75], v[56:59], v[44:47]
	v_mfma_f32_16x16x32_bf16 v[52:55], v[76:79], v[56:59], v[102:105]
	v_mfma_f32_16x16x32_bf16 v[102:105], v[124:127], v[56:59], v[106:109]
	v_mfma_f32_16x16x32_bf16 v[56:59], v[128:131], v[56:59], v[112:115]
	v_mfma_f32_16x16x32_bf16 v[48:51], v[72:75], v[60:63], v[48:51]
	v_mfma_f32_16x16x32_bf16 v[106:109], v[76:79], v[60:63], v[116:119]
	v_mfma_f32_16x16x32_bf16 v[112:115], v[124:127], v[60:63], v[120:123]
	v_mfma_f32_16x16x32_bf16 v[60:63], v[128:131], v[60:63], v[16:19]
	v_mfma_f32_16x16x32_bf16 v[38:41], v[72:75], v[64:67], v[40:43]
	v_mfma_f32_16x16x32_bf16 v[34:37], v[76:79], v[64:67], v[34:37]
	v_mfma_f32_16x16x32_bf16 v[28:31], v[124:127], v[64:67], v[30:33]
	v_mfma_f32_16x16x32_bf16 v[18:21], v[128:131], v[64:67], v[20:23]
	s_mov_b64 s[8:9], 0x200
	s_mov_b32 m0, s60
	v_lshl_add_u64 v[16:17], v[2:3], 0, s[8:9]
	global_load_lds_dwordx4 v[16:17], off
	v_lshl_add_u64 v[16:17], v[4:5], 0, s[8:9]
	s_mov_b32 m0, s59
	s_nop 0
	global_load_lds_dwordx4 v[16:17], off
	v_lshl_add_u64 v[16:17], v[6:7], 0, s[8:9]
	s_mov_b32 m0, s61
	s_mov_b64 s[8:9], 0x20200
	global_load_lds_dwordx4 v[16:17], off
	v_lshl_add_u64 v[16:17], v[6:7], 0, s[8:9]
	s_mov_b32 m0, s62
	s_mov_b64 s[8:9], 0x40200
	global_load_lds_dwordx4 v[16:17], off
	v_lshl_add_u64 v[16:17], v[6:7], 0, s[8:9]
	s_mov_b32 m0, s63
	s_mov_b64 s[8:9], 0x60200
	global_load_lds_dwordx4 v[16:17], off
	v_lshl_add_u64 v[16:17], v[6:7], 0, s[8:9]
	s_mov_b32 m0, s72
	s_nop 0
	global_load_lds_dwordx4 v[16:17], off
	v_add_u32_e32 v16, s77, v80
	v_add_u32_e32 v17, s77, v81
	ds_read_b128 v[64:67], v16
	ds_read_b128 v[72:75], v16 offset:2048
	ds_read_b128 v[76:79], v16 offset:4096
	ds_read_b128 v[116:119], v16 offset:6144
	ds_read_b128 v[120:123], v17
	ds_read_b128 v[124:127], v17 offset:2048
	ds_read_b128 v[128:131], v17 offset:4096
	ds_read_b128 v[172:175], v17 offset:6144
	s_waitcnt lgkmcnt(8)
	v_mfma_f32_16x16x32_bf16 v[84:87], v[156:159], v[132:135], v[84:87]
	v_mfma_f32_16x16x32_bf16 v[88:91], v[160:163], v[132:135], v[88:91]
	v_mfma_f32_16x16x32_bf16 v[92:95], v[164:167], v[132:135], v[92:95]
	v_mfma_f32_16x16x32_bf16 v[22:25], v[168:171], v[132:135], v[24:27]
	v_mfma_f32_16x16x32_bf16 v[42:45], v[156:159], v[138:141], v[44:47]
	v_mfma_f32_16x16x32_bf16 v[52:55], v[160:163], v[138:141], v[52:55]
	v_mfma_f32_16x16x32_bf16 v[102:105], v[164:167], v[138:141], v[102:105]
	v_mfma_f32_16x16x32_bf16 v[56:59], v[168:171], v[138:141], v[56:59]
	v_mfma_f32_16x16x32_bf16 v[46:49], v[156:159], v[142:145], v[48:51]
	v_mfma_f32_16x16x32_bf16 v[106:109], v[160:163], v[142:145], v[106:109]
	v_mfma_f32_16x16x32_bf16 v[112:115], v[164:167], v[142:145], v[112:115]
	v_mfma_f32_16x16x32_bf16 v[60:63], v[168:171], v[142:145], v[60:63]
	v_mfma_f32_16x16x32_bf16 v[38:41], v[156:159], v[152:155], v[38:41]
	v_mfma_f32_16x16x32_bf16 v[32:35], v[160:163], v[152:155], v[34:37]
	v_mfma_f32_16x16x32_bf16 v[26:29], v[164:167], v[152:155], v[28:31]
	v_mfma_f32_16x16x32_bf16 v[18:21], v[168:171], v[152:155], v[18:21]
	s_waitcnt vmcnt(6) lgkmcnt(0)
	s_barrier
	ds_read_b128 v[132:135], v8
	ds_read_b128 v[138:141], v8 offset:2048
	ds_read_b128 v[142:145], v8 offset:4096
	ds_read_b128 v[152:155], v8 offset:6144
	ds_read_b128 v[156:159], v9 offset:16384
	ds_read_b128 v[160:163], v9 offset:18432
	ds_read_b128 v[164:167], v9 offset:20480
	ds_read_b128 v[168:171], v9 offset:22528
	v_mfma_f32_16x16x32_bf16 v[84:87], v[120:123], v[64:67], v[84:87]
	v_mfma_f32_16x16x32_bf16 v[88:91], v[124:127], v[64:67], v[88:91]
	v_mfma_f32_16x16x32_bf16 v[92:95], v[128:131], v[64:67], v[92:95]
	v_mfma_f32_16x16x32_bf16 v[22:25], v[172:175], v[64:67], v[22:25]
	v_mfma_f32_16x16x32_bf16 v[42:45], v[120:123], v[72:75], v[42:45]
	v_mfma_f32_16x16x32_bf16 v[50:53], v[124:127], v[72:75], v[52:55]
	v_mfma_f32_16x16x32_bf16 v[64:67], v[128:131], v[72:75], v[102:105]
	v_mfma_f32_16x16x32_bf16 v[54:57], v[172:175], v[72:75], v[56:59]
	v_mfma_f32_16x16x32_bf16 v[46:49], v[120:123], v[76:79], v[46:49]
	v_mfma_f32_16x16x32_bf16 v[72:75], v[124:127], v[76:79], v[106:109]
	v_mfma_f32_16x16x32_bf16 v[102:105], v[128:131], v[76:79], v[112:115]
	v_mfma_f32_16x16x32_bf16 v[58:61], v[172:175], v[76:79], v[60:63]
	v_mfma_f32_16x16x32_bf16 v[36:39], v[120:123], v[116:119], v[38:41]
	v_mfma_f32_16x16x32_bf16 v[30:33], v[124:127], v[116:119], v[32:35]
	v_mfma_f32_16x16x32_bf16 v[26:29], v[128:131], v[116:119], v[26:29]
	v_mfma_f32_16x16x32_bf16 v[18:21], v[172:175], v[116:119], v[18:21]
	s_mov_b64 s[8:9], 0x280
	s_mov_b32 m0, s64
	v_lshl_add_u64 v[34:35], v[2:3], 0, s[8:9]
	global_load_lds_dwordx4 v[34:35], off
	v_lshl_add_u64 v[34:35], v[4:5], 0, s[8:9]
	s_mov_b32 m0, s71
	s_nop 0
	global_load_lds_dwordx4 v[34:35], off
	v_lshl_add_u64 v[34:35], v[6:7], 0, s[8:9]
	s_mov_b32 m0, s73
	s_mov_b64 s[8:9], 0x20280
	global_load_lds_dwordx4 v[34:35], off
	v_lshl_add_u64 v[34:35], v[6:7], 0, s[8:9]
	s_mov_b32 m0, s74
	s_mov_b64 s[8:9], 0x40280
	global_load_lds_dwordx4 v[34:35], off
	v_lshl_add_u64 v[34:35], v[6:7], 0, s[8:9]
	s_mov_b32 m0, s75
	s_mov_b64 s[8:9], 0x60280
	global_load_lds_dwordx4 v[34:35], off
	v_lshl_add_u64 v[34:35], v[6:7], 0, s[8:9]
	s_mov_b32 m0, s76
	s_nop 0
	global_load_lds_dwordx4 v[34:35], off
	ds_read_b128 v[76:79], v10
	ds_read_b128 v[106:109], v10 offset:2048
	ds_read_b128 v[112:115], v10 offset:4096
	ds_read_b128 v[116:119], v10 offset:6144
	ds_read_b128 v[120:123], v11 offset:16384
	ds_read_b128 v[124:127], v11 offset:18432
	ds_read_b128 v[128:131], v11 offset:20480
	ds_read_b128 v[172:175], v11 offset:22528
	s_waitcnt lgkmcnt(8)
	v_mfma_f32_16x16x32_bf16 v[84:87], v[156:159], v[132:135], v[84:87]
	v_mfma_f32_16x16x32_bf16 v[88:91], v[160:163], v[132:135], v[88:91]
	v_mfma_f32_16x16x32_bf16 v[92:95], v[164:167], v[132:135], v[92:95]
	v_mfma_f32_16x16x32_bf16 v[22:25], v[168:171], v[132:135], v[22:25]
	v_mfma_f32_16x16x32_bf16 v[40:43], v[156:159], v[138:141], v[42:45]
	v_mfma_f32_16x16x32_bf16 v[50:53], v[160:163], v[138:141], v[50:53]
	v_mfma_f32_16x16x32_bf16 v[62:65], v[164:167], v[138:141], v[64:67]
	v_mfma_f32_16x16x32_bf16 v[54:57], v[168:171], v[138:141], v[54:57]
	v_mfma_f32_16x16x32_bf16 v[44:47], v[156:159], v[142:145], v[46:49]
	v_mfma_f32_16x16x32_bf16 v[66:69], v[160:163], v[142:145], v[72:75]
	v_mfma_f32_16x16x32_bf16 v[72:75], v[164:167], v[142:145], v[102:105]
	v_mfma_f32_16x16x32_bf16 v[58:61], v[168:171], v[142:145], v[58:61]
	v_mfma_f32_16x16x32_bf16 v[34:37], v[156:159], v[152:155], v[36:39]
	v_mfma_f32_16x16x32_bf16 v[30:33], v[160:163], v[152:155], v[30:33]
	v_mfma_f32_16x16x32_bf16 v[26:29], v[164:167], v[152:155], v[26:29]
	v_mfma_f32_16x16x32_bf16 v[18:21], v[168:171], v[152:155], v[18:21]
	s_waitcnt vmcnt(6) lgkmcnt(0)
	s_barrier
	ds_read_b128 v[102:105], v8 offset:49152
	ds_read_b128 v[132:135], v8 offset:51200
	ds_read_b128 v[138:141], v8 offset:53248
	ds_read_b128 v[142:145], v8 offset:55296
	ds_read_b128 v[152:155], v12
	ds_read_b128 v[156:159], v12 offset:2048
	ds_read_b128 v[160:163], v12 offset:4096
	ds_read_b128 v[164:167], v12 offset:6144
	v_mfma_f32_16x16x32_bf16 v[84:87], v[120:123], v[76:79], v[84:87]
	v_mfma_f32_16x16x32_bf16 v[88:91], v[124:127], v[76:79], v[88:91]
	v_mfma_f32_16x16x32_bf16 v[92:95], v[128:131], v[76:79], v[92:95]
	v_mfma_f32_16x16x32_bf16 v[22:25], v[172:175], v[76:79], v[22:25]
	v_mfma_f32_16x16x32_bf16 v[38:41], v[120:123], v[106:109], v[40:43]
	v_mfma_f32_16x16x32_bf16 v[48:51], v[124:127], v[106:109], v[50:53]
	v_mfma_f32_16x16x32_bf16 v[62:65], v[128:131], v[106:109], v[62:65]
	v_mfma_f32_16x16x32_bf16 v[52:55], v[172:175], v[106:109], v[54:57]
	v_mfma_f32_16x16x32_bf16 v[42:45], v[120:123], v[112:115], v[44:47]
	v_mfma_f32_16x16x32_bf16 v[66:69], v[124:127], v[112:115], v[66:69]
	v_mfma_f32_16x16x32_bf16 v[72:75], v[128:131], v[112:115], v[72:75]
	v_mfma_f32_16x16x32_bf16 v[56:59], v[172:175], v[112:115], v[58:61]
	v_mfma_f32_16x16x32_bf16 v[34:37], v[120:123], v[116:119], v[34:37]
	v_mfma_f32_16x16x32_bf16 v[30:33], v[124:127], v[116:119], v[30:33]
	v_mfma_f32_16x16x32_bf16 v[26:29], v[128:131], v[116:119], v[26:29]
	v_mfma_f32_16x16x32_bf16 v[18:21], v[172:175], v[116:119], v[18:21]
	s_mov_b64 s[8:9], 0x300
	s_mov_b32 m0, s57
	v_lshl_add_u64 v[46:47], v[2:3], 0, s[8:9]
	global_load_lds_dwordx4 v[46:47], off
	v_lshl_add_u64 v[46:47], v[4:5], 0, s[8:9]
	s_mov_b32 m0, s5
	s_nop 0
	global_load_lds_dwordx4 v[46:47], off
	v_lshl_add_u64 v[46:47], v[6:7], 0, s[8:9]
	s_mov_b32 m0, s33
	s_mov_b64 s[8:9], 0x20300
	global_load_lds_dwordx4 v[46:47], off
	v_lshl_add_u64 v[46:47], v[6:7], 0, s[8:9]
	s_mov_b32 m0, s38
	s_mov_b64 s[8:9], 0x40300
	global_load_lds_dwordx4 v[46:47], off
	v_lshl_add_u64 v[46:47], v[6:7], 0, s[8:9]
	s_mov_b32 m0, s39
	s_mov_b64 s[8:9], 0x60300
	global_load_lds_dwordx4 v[46:47], off
	v_lshl_add_u64 v[46:47], v[6:7], 0, s[8:9]
	s_mov_b32 m0, s56
	s_nop 0
	global_load_lds_dwordx4 v[46:47], off
	ds_read_b128 v[76:79], v10 offset:49152
	ds_read_b128 v[106:109], v10 offset:51200
	ds_read_b128 v[112:115], v10 offset:53248
	ds_read_b128 v[116:119], v10 offset:55296
	ds_read_b128 v[120:123], v13
	ds_read_b128 v[124:127], v13 offset:2048
	ds_read_b128 v[128:131], v13 offset:4096
	ds_read_b128 v[168:171], v13 offset:6144
	s_waitcnt lgkmcnt(8)
	v_mfma_f32_16x16x32_bf16 v[84:87], v[152:155], v[102:105], v[84:87]
	v_mfma_f32_16x16x32_bf16 v[88:91], v[156:159], v[102:105], v[88:91]
	v_mfma_f32_16x16x32_bf16 v[92:95], v[160:163], v[102:105], v[92:95]
	v_mfma_f32_16x16x32_bf16 v[22:25], v[164:167], v[102:105], v[22:25]
	v_mfma_f32_16x16x32_bf16 v[38:41], v[152:155], v[132:135], v[38:41]
	v_mfma_f32_16x16x32_bf16 v[46:49], v[156:159], v[132:135], v[48:51]
	v_mfma_f32_16x16x32_bf16 v[60:63], v[160:163], v[132:135], v[62:65]
	v_mfma_f32_16x16x32_bf16 v[50:53], v[164:167], v[132:135], v[52:55]
	v_mfma_f32_16x16x32_bf16 v[42:45], v[152:155], v[138:141], v[42:45]
	v_mfma_f32_16x16x32_bf16 v[64:67], v[156:159], v[138:141], v[66:69]
	v_mfma_f32_16x16x32_bf16 v[72:75], v[160:163], v[138:141], v[72:75]
	v_mfma_f32_16x16x32_bf16 v[54:57], v[164:167], v[138:141], v[56:59]
	v_mfma_f32_16x16x32_bf16 v[34:37], v[152:155], v[142:145], v[34:37]
	v_mfma_f32_16x16x32_bf16 v[30:33], v[156:159], v[142:145], v[30:33]
	v_mfma_f32_16x16x32_bf16 v[26:29], v[160:163], v[142:145], v[26:29]
	v_mfma_f32_16x16x32_bf16 v[18:21], v[164:167], v[142:145], v[18:21]
	s_waitcnt vmcnt(6) lgkmcnt(0)
	s_barrier
	ds_read_b128 v[102:105], v14
	ds_read_b128 v[132:135], v14 offset:2048
	ds_read_b128 v[138:141], v14 offset:4096
	ds_read_b128 v[142:145], v14 offset:6144
	ds_read_b128 v[152:155], v15
	ds_read_b128 v[156:159], v15 offset:2048
	ds_read_b128 v[160:163], v15 offset:4096
	ds_read_b128 v[164:167], v15 offset:6144
	v_mfma_f32_16x16x32_bf16 v[84:87], v[120:123], v[76:79], v[84:87]
	v_mfma_f32_16x16x32_bf16 v[88:91], v[124:127], v[76:79], v[88:91]
	v_mfma_f32_16x16x32_bf16 v[92:95], v[128:131], v[76:79], v[92:95]
	v_mfma_f32_16x16x32_bf16 v[22:25], v[168:171], v[76:79], v[22:25]
	v_mfma_f32_16x16x32_bf16 v[38:41], v[120:123], v[106:109], v[38:41]
	v_mfma_f32_16x16x32_bf16 v[46:49], v[124:127], v[106:109], v[46:49]
	v_mfma_f32_16x16x32_bf16 v[58:61], v[128:131], v[106:109], v[60:63]
	v_mfma_f32_16x16x32_bf16 v[50:53], v[168:171], v[106:109], v[50:53]
	v_mfma_f32_16x16x32_bf16 v[42:45], v[120:123], v[112:115], v[42:45]
	v_mfma_f32_16x16x32_bf16 v[62:65], v[124:127], v[112:115], v[64:67]
	v_mfma_f32_16x16x32_bf16 v[66:69], v[128:131], v[112:115], v[72:75]
	v_mfma_f32_16x16x32_bf16 v[54:57], v[168:171], v[112:115], v[54:57]
	v_mfma_f32_16x16x32_bf16 v[34:37], v[120:123], v[116:119], v[34:37]
	v_mfma_f32_16x16x32_bf16 v[30:33], v[124:127], v[116:119], v[30:33]
	v_mfma_f32_16x16x32_bf16 v[26:29], v[128:131], v[116:119], v[26:29]
	v_mfma_f32_16x16x32_bf16 v[18:21], v[168:171], v[116:119], v[18:21]
	s_mov_b64 s[8:9], 0x380
	s_mov_b32 m0, s60
	v_lshl_add_u64 v[72:73], v[2:3], 0, s[8:9]
	global_load_lds_dwordx4 v[72:73], off
	v_lshl_add_u64 v[72:73], v[4:5], 0, s[8:9]
	s_mov_b32 m0, s59
	s_nop 0
	global_load_lds_dwordx4 v[72:73], off
	v_lshl_add_u64 v[72:73], v[6:7], 0, s[8:9]
	s_mov_b32 m0, s61
	s_mov_b64 s[8:9], 0x20380
	global_load_lds_dwordx4 v[72:73], off
	v_lshl_add_u64 v[72:73], v[6:7], 0, s[8:9]
	s_mov_b32 m0, s62
	s_mov_b64 s[8:9], 0x40380
	global_load_lds_dwordx4 v[72:73], off
	v_lshl_add_u64 v[72:73], v[6:7], 0, s[8:9]
	s_mov_b32 m0, s63
	s_mov_b64 s[8:9], 0x60380
	global_load_lds_dwordx4 v[72:73], off
	v_lshl_add_u64 v[72:73], v[6:7], 0, s[8:9]
	s_mov_b32 m0, s72
	s_nop 0
	global_load_lds_dwordx4 v[72:73], off
	ds_read_b128 v[72:75], v16
	ds_read_b128 v[76:79], v16 offset:2048
	ds_read_b128 v[106:109], v16 offset:4096
	ds_read_b128 v[112:115], v16 offset:6144
	ds_read_b128 v[116:119], v17
	ds_read_b128 v[120:123], v17 offset:2048
	ds_read_b128 v[124:127], v17 offset:4096
	ds_read_b128 v[128:131], v17 offset:6144
	s_waitcnt lgkmcnt(8)
	v_mfma_f32_16x16x32_bf16 v[84:87], v[152:155], v[102:105], v[84:87]
	v_mfma_f32_16x16x32_bf16 v[88:91], v[156:159], v[102:105], v[88:91]
	v_mfma_f32_16x16x32_bf16 v[92:95], v[160:163], v[102:105], v[92:95]
	v_mfma_f32_16x16x32_bf16 v[22:25], v[164:167], v[102:105], v[22:25]
	v_mfma_f32_16x16x32_bf16 v[38:41], v[152:155], v[132:135], v[38:41]
	v_mfma_f32_16x16x32_bf16 v[46:49], v[156:159], v[132:135], v[46:49]
	v_mfma_f32_16x16x32_bf16 v[58:61], v[160:163], v[132:135], v[58:61]
	v_mfma_f32_16x16x32_bf16 v[50:53], v[164:167], v[132:135], v[50:53]
	v_mfma_f32_16x16x32_bf16 v[42:45], v[152:155], v[138:141], v[42:45]
	v_mfma_f32_16x16x32_bf16 v[62:65], v[156:159], v[138:141], v[62:65]
	v_mfma_f32_16x16x32_bf16 v[66:69], v[160:163], v[138:141], v[66:69]
	v_mfma_f32_16x16x32_bf16 v[54:57], v[164:167], v[138:141], v[54:57]
	v_mfma_f32_16x16x32_bf16 v[34:37], v[152:155], v[142:145], v[34:37]
	v_mfma_f32_16x16x32_bf16 v[30:33], v[156:159], v[142:145], v[30:33]
	v_mfma_f32_16x16x32_bf16 v[26:29], v[160:163], v[142:145], v[26:29]
	v_mfma_f32_16x16x32_bf16 v[18:21], v[164:167], v[142:145], v[18:21]
	s_waitcnt vmcnt(6) lgkmcnt(0)
	s_barrier
	ds_read_b128 v[102:105], v8
	ds_read_b128 v[132:135], v8 offset:2048
	ds_read_b128 v[138:141], v8 offset:4096
	ds_read_b128 v[142:145], v8 offset:6144
	ds_read_b128 v[152:155], v9 offset:16384
	ds_read_b128 v[156:159], v9 offset:18432
	ds_read_b128 v[160:163], v9 offset:20480
	ds_read_b128 v[164:167], v9 offset:22528
	v_mfma_f32_16x16x32_bf16 v[84:87], v[116:119], v[72:75], v[84:87]
	v_mfma_f32_16x16x32_bf16 v[88:91], v[120:123], v[72:75], v[88:91]
	v_mfma_f32_16x16x32_bf16 v[92:95], v[124:127], v[72:75], v[92:95]
	v_mfma_f32_16x16x32_bf16 v[22:25], v[128:131], v[72:75], v[22:25]
	v_mfma_f32_16x16x32_bf16 v[38:41], v[116:119], v[76:79], v[38:41]
	v_mfma_f32_16x16x32_bf16 v[46:49], v[120:123], v[76:79], v[46:49]
	v_mfma_f32_16x16x32_bf16 v[58:61], v[124:127], v[76:79], v[58:61]
	v_mfma_f32_16x16x32_bf16 v[50:53], v[128:131], v[76:79], v[50:53]
	v_mfma_f32_16x16x32_bf16 v[42:45], v[116:119], v[106:109], v[42:45]
	v_mfma_f32_16x16x32_bf16 v[62:65], v[120:123], v[106:109], v[62:65]
	v_mfma_f32_16x16x32_bf16 v[66:69], v[124:127], v[106:109], v[66:69]
	v_mfma_f32_16x16x32_bf16 v[54:57], v[128:131], v[106:109], v[54:57]
	v_mfma_f32_16x16x32_bf16 v[34:37], v[116:119], v[112:115], v[34:37]
	v_mfma_f32_16x16x32_bf16 v[30:33], v[120:123], v[112:115], v[30:33]
	v_mfma_f32_16x16x32_bf16 v[26:29], v[124:127], v[112:115], v[26:29]
	v_mfma_f32_16x16x32_bf16 v[18:21], v[128:131], v[112:115], v[18:21]
	s_mov_b64 s[8:9], 0x400
	s_mov_b32 m0, s64
	v_lshl_add_u64 v[72:73], v[2:3], 0, s[8:9]
	global_load_lds_dwordx4 v[72:73], off
	v_lshl_add_u64 v[72:73], v[4:5], 0, s[8:9]
	s_mov_b32 m0, s71
	s_nop 0
	global_load_lds_dwordx4 v[72:73], off
	v_lshl_add_u64 v[72:73], v[6:7], 0, s[8:9]
	s_mov_b32 m0, s73
	s_mov_b64 s[8:9], 0x20400
	global_load_lds_dwordx4 v[72:73], off
	v_lshl_add_u64 v[72:73], v[6:7], 0, s[8:9]
	s_mov_b32 m0, s74
	s_mov_b64 s[8:9], 0x40400
	global_load_lds_dwordx4 v[72:73], off
	v_lshl_add_u64 v[72:73], v[6:7], 0, s[8:9]
	s_mov_b32 m0, s75
	s_mov_b64 s[8:9], 0x60400
	global_load_lds_dwordx4 v[72:73], off
	v_lshl_add_u64 v[72:73], v[6:7], 0, s[8:9]
	s_mov_b32 m0, s76
	s_nop 0
	global_load_lds_dwordx4 v[72:73], off
	ds_read_b128 v[72:75], v10
	ds_read_b128 v[76:79], v10 offset:2048
	ds_read_b128 v[106:109], v10 offset:4096
	ds_read_b128 v[112:115], v10 offset:6144
	ds_read_b128 v[116:119], v11 offset:16384
	ds_read_b128 v[120:123], v11 offset:18432
	ds_read_b128 v[124:127], v11 offset:20480
	ds_read_b128 v[128:131], v11 offset:22528
	s_waitcnt lgkmcnt(8)
	v_mfma_f32_16x16x32_bf16 v[84:87], v[152:155], v[102:105], v[84:87]
	v_mfma_f32_16x16x32_bf16 v[88:91], v[156:159], v[102:105], v[88:91]
	v_mfma_f32_16x16x32_bf16 v[92:95], v[160:163], v[102:105], v[92:95]
	v_mfma_f32_16x16x32_bf16 v[22:25], v[164:167], v[102:105], v[22:25]
	v_mfma_f32_16x16x32_bf16 v[38:41], v[152:155], v[132:135], v[38:41]
	v_mfma_f32_16x16x32_bf16 v[46:49], v[156:159], v[132:135], v[46:49]
	v_mfma_f32_16x16x32_bf16 v[58:61], v[160:163], v[132:135], v[58:61]
	v_mfma_f32_16x16x32_bf16 v[50:53], v[164:167], v[132:135], v[50:53]
	v_mfma_f32_16x16x32_bf16 v[42:45], v[152:155], v[138:141], v[42:45]
	v_mfma_f32_16x16x32_bf16 v[62:65], v[156:159], v[138:141], v[62:65]
	v_mfma_f32_16x16x32_bf16 v[66:69], v[160:163], v[138:141], v[66:69]
	v_mfma_f32_16x16x32_bf16 v[54:57], v[164:167], v[138:141], v[54:57]
	v_mfma_f32_16x16x32_bf16 v[34:37], v[152:155], v[142:145], v[34:37]
	v_mfma_f32_16x16x32_bf16 v[30:33], v[156:159], v[142:145], v[30:33]
	v_mfma_f32_16x16x32_bf16 v[26:29], v[160:163], v[142:145], v[26:29]
	v_mfma_f32_16x16x32_bf16 v[18:21], v[164:167], v[142:145], v[18:21]
	s_waitcnt vmcnt(6) lgkmcnt(0)
	s_barrier
	ds_read_b128 v[102:105], v8 offset:49152
	ds_read_b128 v[132:135], v8 offset:51200
	ds_read_b128 v[138:141], v8 offset:53248
	ds_read_b128 v[142:145], v8 offset:55296
	ds_read_b128 v[152:155], v12
	ds_read_b128 v[156:159], v12 offset:2048
	ds_read_b128 v[160:163], v12 offset:4096
	ds_read_b128 v[164:167], v12 offset:6144
	v_mfma_f32_16x16x32_bf16 v[84:87], v[116:119], v[72:75], v[84:87]
	v_mfma_f32_16x16x32_bf16 v[88:91], v[120:123], v[72:75], v[88:91]
	v_mfma_f32_16x16x32_bf16 v[92:95], v[124:127], v[72:75], v[92:95]
	v_mfma_f32_16x16x32_bf16 v[22:25], v[128:131], v[72:75], v[22:25]
	v_mfma_f32_16x16x32_bf16 v[38:41], v[116:119], v[76:79], v[38:41]
	v_mfma_f32_16x16x32_bf16 v[46:49], v[120:123], v[76:79], v[46:49]
	v_mfma_f32_16x16x32_bf16 v[58:61], v[124:127], v[76:79], v[58:61]
	v_mfma_f32_16x16x32_bf16 v[50:53], v[128:131], v[76:79], v[50:53]
	v_mfma_f32_16x16x32_bf16 v[42:45], v[116:119], v[106:109], v[42:45]
	v_mfma_f32_16x16x32_bf16 v[62:65], v[120:123], v[106:109], v[62:65]
	v_mfma_f32_16x16x32_bf16 v[66:69], v[124:127], v[106:109], v[66:69]
	v_mfma_f32_16x16x32_bf16 v[54:57], v[128:131], v[106:109], v[54:57]
	v_mfma_f32_16x16x32_bf16 v[34:37], v[116:119], v[112:115], v[34:37]
	v_mfma_f32_16x16x32_bf16 v[30:33], v[120:123], v[112:115], v[30:33]
	v_mfma_f32_16x16x32_bf16 v[26:29], v[124:127], v[112:115], v[26:29]
	v_mfma_f32_16x16x32_bf16 v[18:21], v[128:131], v[112:115], v[18:21]
	s_mov_b64 s[8:9], 0x480
	s_mov_b32 m0, s57
	v_lshl_add_u64 v[72:73], v[2:3], 0, s[8:9]
	global_load_lds_dwordx4 v[72:73], off
	v_lshl_add_u64 v[72:73], v[4:5], 0, s[8:9]
	s_mov_b32 m0, s5
	s_nop 0
	global_load_lds_dwordx4 v[72:73], off
	v_lshl_add_u64 v[72:73], v[6:7], 0, s[8:9]
	s_mov_b32 m0, s33
	s_mov_b64 s[8:9], 0x20480
	global_load_lds_dwordx4 v[72:73], off
	v_lshl_add_u64 v[72:73], v[6:7], 0, s[8:9]
	s_mov_b32 m0, s38
	s_mov_b64 s[8:9], 0x40480
	global_load_lds_dwordx4 v[72:73], off
	v_lshl_add_u64 v[72:73], v[6:7], 0, s[8:9]
	s_mov_b32 m0, s39
	s_mov_b64 s[8:9], 0x60480
	global_load_lds_dwordx4 v[72:73], off
	v_lshl_add_u64 v[72:73], v[6:7], 0, s[8:9]
	s_mov_b32 m0, s56
	s_nop 0
	global_load_lds_dwordx4 v[72:73], off
	ds_read_b128 v[72:75], v10 offset:49152
	ds_read_b128 v[76:79], v10 offset:51200
	ds_read_b128 v[106:109], v10 offset:53248
	ds_read_b128 v[112:115], v10 offset:55296
	ds_read_b128 v[116:119], v13
	ds_read_b128 v[120:123], v13 offset:2048
	ds_read_b128 v[124:127], v13 offset:4096
	ds_read_b128 v[128:131], v13 offset:6144
	s_waitcnt lgkmcnt(8)
	v_mfma_f32_16x16x32_bf16 v[84:87], v[152:155], v[102:105], v[84:87]
	v_mfma_f32_16x16x32_bf16 v[88:91], v[156:159], v[102:105], v[88:91]
	v_mfma_f32_16x16x32_bf16 v[92:95], v[160:163], v[102:105], v[92:95]
	v_mfma_f32_16x16x32_bf16 v[22:25], v[164:167], v[102:105], v[22:25]
	v_mfma_f32_16x16x32_bf16 v[38:41], v[152:155], v[132:135], v[38:41]
	v_mfma_f32_16x16x32_bf16 v[46:49], v[156:159], v[132:135], v[46:49]
	v_mfma_f32_16x16x32_bf16 v[58:61], v[160:163], v[132:135], v[58:61]
	v_mfma_f32_16x16x32_bf16 v[50:53], v[164:167], v[132:135], v[50:53]
	v_mfma_f32_16x16x32_bf16 v[42:45], v[152:155], v[138:141], v[42:45]
	v_mfma_f32_16x16x32_bf16 v[62:65], v[156:159], v[138:141], v[62:65]
	v_mfma_f32_16x16x32_bf16 v[66:69], v[160:163], v[138:141], v[66:69]
	v_mfma_f32_16x16x32_bf16 v[54:57], v[164:167], v[138:141], v[54:57]
	v_mfma_f32_16x16x32_bf16 v[34:37], v[152:155], v[142:145], v[34:37]
	v_mfma_f32_16x16x32_bf16 v[30:33], v[156:159], v[142:145], v[30:33]
	v_mfma_f32_16x16x32_bf16 v[26:29], v[160:163], v[142:145], v[26:29]
	v_mfma_f32_16x16x32_bf16 v[18:21], v[164:167], v[142:145], v[18:21]
	s_waitcnt vmcnt(6) lgkmcnt(0)
	s_barrier
	ds_read_b128 v[102:105], v14
	ds_read_b128 v[132:135], v14 offset:2048
	ds_read_b128 v[138:141], v14 offset:4096
	ds_read_b128 v[142:145], v14 offset:6144
	ds_read_b128 v[152:155], v15
	ds_read_b128 v[156:159], v15 offset:2048
	ds_read_b128 v[160:163], v15 offset:4096
	ds_read_b128 v[164:167], v15 offset:6144
	v_mfma_f32_16x16x32_bf16 v[84:87], v[116:119], v[72:75], v[84:87]
	v_mfma_f32_16x16x32_bf16 v[88:91], v[120:123], v[72:75], v[88:91]
	v_mfma_f32_16x16x32_bf16 v[92:95], v[124:127], v[72:75], v[92:95]
	v_mfma_f32_16x16x32_bf16 v[22:25], v[128:131], v[72:75], v[22:25]
	v_mfma_f32_16x16x32_bf16 v[38:41], v[116:119], v[76:79], v[38:41]
	v_mfma_f32_16x16x32_bf16 v[46:49], v[120:123], v[76:79], v[46:49]
	v_mfma_f32_16x16x32_bf16 v[58:61], v[124:127], v[76:79], v[58:61]
	v_mfma_f32_16x16x32_bf16 v[50:53], v[128:131], v[76:79], v[50:53]
	v_mfma_f32_16x16x32_bf16 v[42:45], v[116:119], v[106:109], v[42:45]
	v_mfma_f32_16x16x32_bf16 v[62:65], v[120:123], v[106:109], v[62:65]
	v_mfma_f32_16x16x32_bf16 v[66:69], v[124:127], v[106:109], v[66:69]
	v_mfma_f32_16x16x32_bf16 v[54:57], v[128:131], v[106:109], v[54:57]
	v_mfma_f32_16x16x32_bf16 v[34:37], v[116:119], v[112:115], v[34:37]
	v_mfma_f32_16x16x32_bf16 v[30:33], v[120:123], v[112:115], v[30:33]
	v_mfma_f32_16x16x32_bf16 v[26:29], v[124:127], v[112:115], v[26:29]
	v_mfma_f32_16x16x32_bf16 v[18:21], v[128:131], v[112:115], v[18:21]
	s_mov_b64 s[8:9], 0x500
	s_mov_b32 m0, s60
	v_lshl_add_u64 v[72:73], v[2:3], 0, s[8:9]
	global_load_lds_dwordx4 v[72:73], off
	v_lshl_add_u64 v[72:73], v[4:5], 0, s[8:9]
	s_mov_b32 m0, s59
	s_nop 0
	global_load_lds_dwordx4 v[72:73], off
	v_lshl_add_u64 v[72:73], v[6:7], 0, s[8:9]
	s_mov_b32 m0, s61
	s_mov_b64 s[8:9], 0x20500
	global_load_lds_dwordx4 v[72:73], off
	v_lshl_add_u64 v[72:73], v[6:7], 0, s[8:9]
	s_mov_b32 m0, s62
	s_mov_b64 s[8:9], 0x40500
	global_load_lds_dwordx4 v[72:73], off
	v_lshl_add_u64 v[72:73], v[6:7], 0, s[8:9]
	s_mov_b32 m0, s63
	s_mov_b64 s[8:9], 0x60500
	global_load_lds_dwordx4 v[72:73], off
	v_lshl_add_u64 v[72:73], v[6:7], 0, s[8:9]
	s_mov_b32 m0, s72
	s_nop 0
	global_load_lds_dwordx4 v[72:73], off
	ds_read_b128 v[72:75], v16
	ds_read_b128 v[76:79], v16 offset:2048
	ds_read_b128 v[106:109], v16 offset:4096
	ds_read_b128 v[112:115], v16 offset:6144
	ds_read_b128 v[116:119], v17
	ds_read_b128 v[120:123], v17 offset:2048
	ds_read_b128 v[124:127], v17 offset:4096
	ds_read_b128 v[128:131], v17 offset:6144
	s_waitcnt lgkmcnt(8)
	v_mfma_f32_16x16x32_bf16 v[84:87], v[152:155], v[102:105], v[84:87]
	v_mfma_f32_16x16x32_bf16 v[88:91], v[156:159], v[102:105], v[88:91]
	v_mfma_f32_16x16x32_bf16 v[92:95], v[160:163], v[102:105], v[92:95]
	v_mfma_f32_16x16x32_bf16 v[22:25], v[164:167], v[102:105], v[22:25]
	v_mfma_f32_16x16x32_bf16 v[38:41], v[152:155], v[132:135], v[38:41]
	v_mfma_f32_16x16x32_bf16 v[46:49], v[156:159], v[132:135], v[46:49]
	v_mfma_f32_16x16x32_bf16 v[58:61], v[160:163], v[132:135], v[58:61]
	v_mfma_f32_16x16x32_bf16 v[50:53], v[164:167], v[132:135], v[50:53]
	v_mfma_f32_16x16x32_bf16 v[42:45], v[152:155], v[138:141], v[42:45]
	v_mfma_f32_16x16x32_bf16 v[62:65], v[156:159], v[138:141], v[62:65]
	v_mfma_f32_16x16x32_bf16 v[66:69], v[160:163], v[138:141], v[66:69]
	v_mfma_f32_16x16x32_bf16 v[54:57], v[164:167], v[138:141], v[54:57]
	v_mfma_f32_16x16x32_bf16 v[34:37], v[152:155], v[142:145], v[34:37]
	v_mfma_f32_16x16x32_bf16 v[30:33], v[156:159], v[142:145], v[30:33]
	v_mfma_f32_16x16x32_bf16 v[26:29], v[160:163], v[142:145], v[26:29]
	v_mfma_f32_16x16x32_bf16 v[18:21], v[164:167], v[142:145], v[18:21]
	s_waitcnt vmcnt(6) lgkmcnt(0)
	s_barrier
	ds_read_b128 v[102:105], v8
	ds_read_b128 v[132:135], v8 offset:2048
	ds_read_b128 v[138:141], v8 offset:4096
	ds_read_b128 v[142:145], v8 offset:6144
	ds_read_b128 v[152:155], v9 offset:16384
	ds_read_b128 v[156:159], v9 offset:18432
	ds_read_b128 v[160:163], v9 offset:20480
	ds_read_b128 v[164:167], v9 offset:22528
	v_mfma_f32_16x16x32_bf16 v[84:87], v[116:119], v[72:75], v[84:87]
	v_mfma_f32_16x16x32_bf16 v[88:91], v[120:123], v[72:75], v[88:91]
	v_mfma_f32_16x16x32_bf16 v[92:95], v[124:127], v[72:75], v[92:95]
	v_mfma_f32_16x16x32_bf16 v[22:25], v[128:131], v[72:75], v[22:25]
	v_mfma_f32_16x16x32_bf16 v[38:41], v[116:119], v[76:79], v[38:41]
	v_mfma_f32_16x16x32_bf16 v[46:49], v[120:123], v[76:79], v[46:49]
	v_mfma_f32_16x16x32_bf16 v[58:61], v[124:127], v[76:79], v[58:61]
	v_mfma_f32_16x16x32_bf16 v[50:53], v[128:131], v[76:79], v[50:53]
	v_mfma_f32_16x16x32_bf16 v[42:45], v[116:119], v[106:109], v[42:45]
	v_mfma_f32_16x16x32_bf16 v[62:65], v[120:123], v[106:109], v[62:65]
	v_mfma_f32_16x16x32_bf16 v[66:69], v[124:127], v[106:109], v[66:69]
	v_mfma_f32_16x16x32_bf16 v[54:57], v[128:131], v[106:109], v[54:57]
	v_mfma_f32_16x16x32_bf16 v[34:37], v[116:119], v[112:115], v[34:37]
	v_mfma_f32_16x16x32_bf16 v[30:33], v[120:123], v[112:115], v[30:33]
	v_mfma_f32_16x16x32_bf16 v[26:29], v[124:127], v[112:115], v[26:29]
	v_mfma_f32_16x16x32_bf16 v[18:21], v[128:131], v[112:115], v[18:21]
	s_mov_b64 s[8:9], 0x580
	s_mov_b32 m0, s64
	v_lshl_add_u64 v[72:73], v[2:3], 0, s[8:9]
	global_load_lds_dwordx4 v[72:73], off
	v_lshl_add_u64 v[72:73], v[4:5], 0, s[8:9]
	s_mov_b32 m0, s71
	s_nop 0
	global_load_lds_dwordx4 v[72:73], off
	v_lshl_add_u64 v[72:73], v[6:7], 0, s[8:9]
	s_mov_b32 m0, s73
	s_mov_b64 s[8:9], 0x20580
	global_load_lds_dwordx4 v[72:73], off
	v_lshl_add_u64 v[72:73], v[6:7], 0, s[8:9]
	s_mov_b32 m0, s74
	s_mov_b64 s[8:9], 0x40580
	global_load_lds_dwordx4 v[72:73], off
	v_lshl_add_u64 v[72:73], v[6:7], 0, s[8:9]
	s_mov_b32 m0, s75
	s_mov_b64 s[8:9], 0x60580
	global_load_lds_dwordx4 v[72:73], off
	v_lshl_add_u64 v[72:73], v[6:7], 0, s[8:9]
	s_mov_b32 m0, s76
	s_nop 0
	global_load_lds_dwordx4 v[72:73], off
	ds_read_b128 v[72:75], v10
	ds_read_b128 v[76:79], v10 offset:2048
	ds_read_b128 v[106:109], v10 offset:4096
	ds_read_b128 v[112:115], v10 offset:6144
	ds_read_b128 v[116:119], v11 offset:16384
	ds_read_b128 v[120:123], v11 offset:18432
	ds_read_b128 v[124:127], v11 offset:20480
	ds_read_b128 v[128:131], v11 offset:22528
	s_waitcnt lgkmcnt(8)
	v_mfma_f32_16x16x32_bf16 v[84:87], v[152:155], v[102:105], v[84:87]
	v_mfma_f32_16x16x32_bf16 v[88:91], v[156:159], v[102:105], v[88:91]
	v_mfma_f32_16x16x32_bf16 v[92:95], v[160:163], v[102:105], v[92:95]
	v_mfma_f32_16x16x32_bf16 v[22:25], v[164:167], v[102:105], v[22:25]
	v_mfma_f32_16x16x32_bf16 v[38:41], v[152:155], v[132:135], v[38:41]
	v_mfma_f32_16x16x32_bf16 v[46:49], v[156:159], v[132:135], v[46:49]
	v_mfma_f32_16x16x32_bf16 v[58:61], v[160:163], v[132:135], v[58:61]
	v_mfma_f32_16x16x32_bf16 v[50:53], v[164:167], v[132:135], v[50:53]
	v_mfma_f32_16x16x32_bf16 v[42:45], v[152:155], v[138:141], v[42:45]
	v_mfma_f32_16x16x32_bf16 v[62:65], v[156:159], v[138:141], v[62:65]
	v_mfma_f32_16x16x32_bf16 v[66:69], v[160:163], v[138:141], v[66:69]
	v_mfma_f32_16x16x32_bf16 v[54:57], v[164:167], v[138:141], v[54:57]
	v_mfma_f32_16x16x32_bf16 v[34:37], v[152:155], v[142:145], v[34:37]
	v_mfma_f32_16x16x32_bf16 v[30:33], v[156:159], v[142:145], v[30:33]
	v_mfma_f32_16x16x32_bf16 v[26:29], v[160:163], v[142:145], v[26:29]
	v_mfma_f32_16x16x32_bf16 v[18:21], v[164:167], v[142:145], v[18:21]
	s_waitcnt vmcnt(6) lgkmcnt(0)
	s_barrier
	ds_read_b128 v[102:105], v8 offset:49152
	ds_read_b128 v[132:135], v8 offset:51200
	ds_read_b128 v[138:141], v8 offset:53248
	ds_read_b128 v[142:145], v8 offset:55296
	ds_read_b128 v[152:155], v12
	ds_read_b128 v[156:159], v12 offset:2048
	ds_read_b128 v[160:163], v12 offset:4096
	ds_read_b128 v[164:167], v12 offset:6144
	v_mfma_f32_16x16x32_bf16 v[84:87], v[116:119], v[72:75], v[84:87]
	v_mfma_f32_16x16x32_bf16 v[88:91], v[120:123], v[72:75], v[88:91]
	v_mfma_f32_16x16x32_bf16 v[92:95], v[124:127], v[72:75], v[92:95]
	v_mfma_f32_16x16x32_bf16 v[22:25], v[128:131], v[72:75], v[22:25]
	v_mfma_f32_16x16x32_bf16 v[38:41], v[116:119], v[76:79], v[38:41]
	v_mfma_f32_16x16x32_bf16 v[46:49], v[120:123], v[76:79], v[46:49]
	v_mfma_f32_16x16x32_bf16 v[58:61], v[124:127], v[76:79], v[58:61]
	v_mfma_f32_16x16x32_bf16 v[50:53], v[128:131], v[76:79], v[50:53]
	v_mfma_f32_16x16x32_bf16 v[42:45], v[116:119], v[106:109], v[42:45]
	v_mfma_f32_16x16x32_bf16 v[62:65], v[120:123], v[106:109], v[62:65]
	v_mfma_f32_16x16x32_bf16 v[66:69], v[124:127], v[106:109], v[66:69]
	v_mfma_f32_16x16x32_bf16 v[54:57], v[128:131], v[106:109], v[54:57]
	v_mfma_f32_16x16x32_bf16 v[34:37], v[116:119], v[112:115], v[34:37]
	v_mfma_f32_16x16x32_bf16 v[30:33], v[120:123], v[112:115], v[30:33]
	v_mfma_f32_16x16x32_bf16 v[26:29], v[124:127], v[112:115], v[26:29]
	v_mfma_f32_16x16x32_bf16 v[18:21], v[128:131], v[112:115], v[18:21]
	s_mov_b64 s[8:9], 0x600
	s_mov_b32 m0, s57
	v_lshl_add_u64 v[72:73], v[2:3], 0, s[8:9]
	global_load_lds_dwordx4 v[72:73], off
	v_lshl_add_u64 v[72:73], v[4:5], 0, s[8:9]
	s_mov_b32 m0, s5
	s_nop 0
	global_load_lds_dwordx4 v[72:73], off
	v_lshl_add_u64 v[72:73], v[6:7], 0, s[8:9]
	s_mov_b32 m0, s33
	s_mov_b64 s[8:9], 0x20600
	global_load_lds_dwordx4 v[72:73], off
	v_lshl_add_u64 v[72:73], v[6:7], 0, s[8:9]
	s_mov_b32 m0, s38
	s_mov_b64 s[8:9], 0x40600
	global_load_lds_dwordx4 v[72:73], off
	v_lshl_add_u64 v[72:73], v[6:7], 0, s[8:9]
	s_mov_b32 m0, s39
	s_mov_b64 s[8:9], 0x60600
	global_load_lds_dwordx4 v[72:73], off
	v_lshl_add_u64 v[72:73], v[6:7], 0, s[8:9]
	s_mov_b32 m0, s56
	s_nop 0
	global_load_lds_dwordx4 v[72:73], off
	ds_read_b128 v[72:75], v10 offset:49152
	ds_read_b128 v[76:79], v10 offset:51200
	ds_read_b128 v[106:109], v10 offset:53248
	ds_read_b128 v[112:115], v10 offset:55296
	ds_read_b128 v[116:119], v13
	ds_read_b128 v[120:123], v13 offset:2048
	ds_read_b128 v[124:127], v13 offset:4096
	ds_read_b128 v[128:131], v13 offset:6144
	s_waitcnt lgkmcnt(8)
	v_mfma_f32_16x16x32_bf16 v[84:87], v[152:155], v[102:105], v[84:87]
	v_mfma_f32_16x16x32_bf16 v[88:91], v[156:159], v[102:105], v[88:91]
	v_mfma_f32_16x16x32_bf16 v[92:95], v[160:163], v[102:105], v[92:95]
	v_mfma_f32_16x16x32_bf16 v[22:25], v[164:167], v[102:105], v[22:25]
	v_mfma_f32_16x16x32_bf16 v[38:41], v[152:155], v[132:135], v[38:41]
	v_mfma_f32_16x16x32_bf16 v[46:49], v[156:159], v[132:135], v[46:49]
	v_mfma_f32_16x16x32_bf16 v[58:61], v[160:163], v[132:135], v[58:61]
	v_mfma_f32_16x16x32_bf16 v[50:53], v[164:167], v[132:135], v[50:53]
	v_mfma_f32_16x16x32_bf16 v[42:45], v[152:155], v[138:141], v[42:45]
	v_mfma_f32_16x16x32_bf16 v[62:65], v[156:159], v[138:141], v[62:65]
	v_mfma_f32_16x16x32_bf16 v[66:69], v[160:163], v[138:141], v[66:69]
	v_mfma_f32_16x16x32_bf16 v[54:57], v[164:167], v[138:141], v[54:57]
	v_mfma_f32_16x16x32_bf16 v[34:37], v[152:155], v[142:145], v[34:37]
	v_mfma_f32_16x16x32_bf16 v[30:33], v[156:159], v[142:145], v[30:33]
	v_mfma_f32_16x16x32_bf16 v[26:29], v[160:163], v[142:145], v[26:29]
	v_mfma_f32_16x16x32_bf16 v[18:21], v[164:167], v[142:145], v[18:21]
	s_waitcnt vmcnt(6) lgkmcnt(0)
	s_barrier
	ds_read_b128 v[102:105], v14
	ds_read_b128 v[132:135], v14 offset:2048
	ds_read_b128 v[138:141], v14 offset:4096
	ds_read_b128 v[142:145], v14 offset:6144
	ds_read_b128 v[152:155], v15
	ds_read_b128 v[156:159], v15 offset:2048
	ds_read_b128 v[160:163], v15 offset:4096
	ds_read_b128 v[164:167], v15 offset:6144
	v_mfma_f32_16x16x32_bf16 v[84:87], v[116:119], v[72:75], v[84:87]
	v_mfma_f32_16x16x32_bf16 v[88:91], v[120:123], v[72:75], v[88:91]
	v_mfma_f32_16x16x32_bf16 v[92:95], v[124:127], v[72:75], v[92:95]
	v_mfma_f32_16x16x32_bf16 v[22:25], v[128:131], v[72:75], v[22:25]
	v_mfma_f32_16x16x32_bf16 v[38:41], v[116:119], v[76:79], v[38:41]
	v_mfma_f32_16x16x32_bf16 v[46:49], v[120:123], v[76:79], v[46:49]
	v_mfma_f32_16x16x32_bf16 v[58:61], v[124:127], v[76:79], v[58:61]
	v_mfma_f32_16x16x32_bf16 v[50:53], v[128:131], v[76:79], v[50:53]
	v_mfma_f32_16x16x32_bf16 v[42:45], v[116:119], v[106:109], v[42:45]
	v_mfma_f32_16x16x32_bf16 v[62:65], v[120:123], v[106:109], v[62:65]
	v_mfma_f32_16x16x32_bf16 v[66:69], v[124:127], v[106:109], v[66:69]
	v_mfma_f32_16x16x32_bf16 v[54:57], v[128:131], v[106:109], v[54:57]
	v_mfma_f32_16x16x32_bf16 v[34:37], v[116:119], v[112:115], v[34:37]
	v_mfma_f32_16x16x32_bf16 v[30:33], v[120:123], v[112:115], v[30:33]
	v_mfma_f32_16x16x32_bf16 v[26:29], v[124:127], v[112:115], v[26:29]
	v_mfma_f32_16x16x32_bf16 v[18:21], v[128:131], v[112:115], v[18:21]
	s_mov_b64 s[8:9], 0x680
	s_mov_b32 m0, s60
	v_lshl_add_u64 v[72:73], v[2:3], 0, s[8:9]
	global_load_lds_dwordx4 v[72:73], off
	v_lshl_add_u64 v[72:73], v[4:5], 0, s[8:9]
	s_mov_b32 m0, s59
	s_nop 0
	global_load_lds_dwordx4 v[72:73], off
	v_lshl_add_u64 v[72:73], v[6:7], 0, s[8:9]
	s_mov_b32 m0, s61
	s_mov_b64 s[8:9], 0x20680
	global_load_lds_dwordx4 v[72:73], off
	v_lshl_add_u64 v[72:73], v[6:7], 0, s[8:9]
	s_mov_b32 m0, s62
	s_mov_b64 s[8:9], 0x40680
	global_load_lds_dwordx4 v[72:73], off
	v_lshl_add_u64 v[72:73], v[6:7], 0, s[8:9]
	s_mov_b32 m0, s63
	s_mov_b64 s[8:9], 0x60680
	global_load_lds_dwordx4 v[72:73], off
	v_lshl_add_u64 v[72:73], v[6:7], 0, s[8:9]
	s_mov_b32 m0, s72
	s_nop 0
	global_load_lds_dwordx4 v[72:73], off
	s_mov_b64 s[8:9], exec
	v_readlane_b32 s20, v197, 0
	v_readlane_b32 s21, v197, 1
	s_and_b64 s[20:21], s[8:9], s[20:21]
	s_mov_b64 exec, s[20:21]
	s_cbranch_execz .Ldq_skip2
	v_mov_b32_e32 v251, 0
	v_mov_b32_e32 v252, 1
	global_atomic_add v250, v251, v252, s[92:93] offset:8 sc0
.Ldq_skip2:
	s_mov_b64 exec, s[8:9]
	s_mov_b32 s99, 1
	ds_read_b128 v[72:75], v16
	ds_read_b128 v[76:79], v16 offset:2048
	ds_read_b128 v[106:109], v16 offset:4096
	ds_read_b128 v[112:115], v16 offset:6144
	ds_read_b128 v[116:119], v17
	ds_read_b128 v[120:123], v17 offset:2048
	ds_read_b128 v[124:127], v17 offset:4096
	ds_read_b128 v[128:131], v17 offset:6144
	s_waitcnt lgkmcnt(8)
	v_mfma_f32_16x16x32_bf16 v[84:87], v[152:155], v[102:105], v[84:87]
	v_mfma_f32_16x16x32_bf16 v[88:91], v[156:159], v[102:105], v[88:91]
	v_mfma_f32_16x16x32_bf16 v[92:95], v[160:163], v[102:105], v[92:95]
	v_mfma_f32_16x16x32_bf16 v[22:25], v[164:167], v[102:105], v[22:25]
	v_mfma_f32_16x16x32_bf16 v[38:41], v[152:155], v[132:135], v[38:41]
	v_mfma_f32_16x16x32_bf16 v[46:49], v[156:159], v[132:135], v[46:49]
	v_mfma_f32_16x16x32_bf16 v[58:61], v[160:163], v[132:135], v[58:61]
	v_mfma_f32_16x16x32_bf16 v[50:53], v[164:167], v[132:135], v[50:53]
	v_mfma_f32_16x16x32_bf16 v[42:45], v[152:155], v[138:141], v[42:45]
	v_mfma_f32_16x16x32_bf16 v[62:65], v[156:159], v[138:141], v[62:65]
	v_mfma_f32_16x16x32_bf16 v[66:69], v[160:163], v[138:141], v[66:69]
	v_mfma_f32_16x16x32_bf16 v[54:57], v[164:167], v[138:141], v[54:57]
	v_mfma_f32_16x16x32_bf16 v[34:37], v[152:155], v[142:145], v[34:37]
	v_mfma_f32_16x16x32_bf16 v[30:33], v[156:159], v[142:145], v[30:33]
	v_mfma_f32_16x16x32_bf16 v[26:29], v[160:163], v[142:145], v[26:29]
	v_mfma_f32_16x16x32_bf16 v[18:21], v[164:167], v[142:145], v[18:21]
	s_waitcnt vmcnt(6) lgkmcnt(0)
	s_barrier
	ds_read_b128 v[102:105], v8
	ds_read_b128 v[132:135], v8 offset:2048
	ds_read_b128 v[138:141], v8 offset:4096
	ds_read_b128 v[142:145], v8 offset:6144
	ds_read_b128 v[152:155], v9 offset:16384
	ds_read_b128 v[156:159], v9 offset:18432
	ds_read_b128 v[160:163], v9 offset:20480
	ds_read_b128 v[164:167], v9 offset:22528
	v_mfma_f32_16x16x32_bf16 v[84:87], v[116:119], v[72:75], v[84:87]
	v_mfma_f32_16x16x32_bf16 v[88:91], v[120:123], v[72:75], v[88:91]
	v_mfma_f32_16x16x32_bf16 v[92:95], v[124:127], v[72:75], v[92:95]
	v_mfma_f32_16x16x32_bf16 v[22:25], v[128:131], v[72:75], v[22:25]
	v_mfma_f32_16x16x32_bf16 v[38:41], v[116:119], v[76:79], v[38:41]
	v_mfma_f32_16x16x32_bf16 v[46:49], v[120:123], v[76:79], v[46:49]
	v_mfma_f32_16x16x32_bf16 v[58:61], v[124:127], v[76:79], v[58:61]
	v_mfma_f32_16x16x32_bf16 v[50:53], v[128:131], v[76:79], v[50:53]
	v_mfma_f32_16x16x32_bf16 v[42:45], v[116:119], v[106:109], v[42:45]
	v_mfma_f32_16x16x32_bf16 v[62:65], v[120:123], v[106:109], v[62:65]
	v_mfma_f32_16x16x32_bf16 v[66:69], v[124:127], v[106:109], v[66:69]
	v_mfma_f32_16x16x32_bf16 v[54:57], v[128:131], v[106:109], v[54:57]
	v_mfma_f32_16x16x32_bf16 v[34:37], v[116:119], v[112:115], v[34:37]
	v_mfma_f32_16x16x32_bf16 v[30:33], v[120:123], v[112:115], v[30:33]
	v_mfma_f32_16x16x32_bf16 v[26:29], v[124:127], v[112:115], v[26:29]
	v_mfma_f32_16x16x32_bf16 v[18:21], v[128:131], v[112:115], v[18:21]
	s_mov_b64 s[8:9], 0x700
	s_mov_b32 m0, s64
	v_lshl_add_u64 v[72:73], v[2:3], 0, s[8:9]
	global_load_lds_dwordx4 v[72:73], off
	v_lshl_add_u64 v[72:73], v[4:5], 0, s[8:9]
	s_mov_b32 m0, s71
	s_nop 0
	global_load_lds_dwordx4 v[72:73], off
	v_lshl_add_u64 v[72:73], v[6:7], 0, s[8:9]
	s_mov_b32 m0, s73
	s_mov_b64 s[8:9], 0x20700
	global_load_lds_dwordx4 v[72:73], off
	v_lshl_add_u64 v[72:73], v[6:7], 0, s[8:9]
	s_mov_b32 m0, s74
	s_mov_b64 s[8:9], 0x40700
	global_load_lds_dwordx4 v[72:73], off
	v_lshl_add_u64 v[72:73], v[6:7], 0, s[8:9]
	s_mov_b32 m0, s75
	s_mov_b64 s[8:9], 0x60700
	global_load_lds_dwordx4 v[72:73], off
	v_lshl_add_u64 v[72:73], v[6:7], 0, s[8:9]
	s_mov_b32 m0, s76
	s_nop 0
	global_load_lds_dwordx4 v[72:73], off
	ds_read_b128 v[72:75], v10
	ds_read_b128 v[76:79], v10 offset:2048
	ds_read_b128 v[106:109], v10 offset:4096
	ds_read_b128 v[112:115], v10 offset:6144
	ds_read_b128 v[116:119], v11 offset:16384
	ds_read_b128 v[120:123], v11 offset:18432
	ds_read_b128 v[124:127], v11 offset:20480
	ds_read_b128 v[128:131], v11 offset:22528
	s_waitcnt lgkmcnt(8)
	v_mfma_f32_16x16x32_bf16 v[84:87], v[152:155], v[102:105], v[84:87]
	v_mfma_f32_16x16x32_bf16 v[88:91], v[156:159], v[102:105], v[88:91]
	v_mfma_f32_16x16x32_bf16 v[92:95], v[160:163], v[102:105], v[92:95]
	v_mfma_f32_16x16x32_bf16 v[22:25], v[164:167], v[102:105], v[22:25]
	v_mfma_f32_16x16x32_bf16 v[38:41], v[152:155], v[132:135], v[38:41]
	v_mfma_f32_16x16x32_bf16 v[46:49], v[156:159], v[132:135], v[46:49]
	v_mfma_f32_16x16x32_bf16 v[58:61], v[160:163], v[132:135], v[58:61]
	v_mfma_f32_16x16x32_bf16 v[50:53], v[164:167], v[132:135], v[50:53]
	v_mfma_f32_16x16x32_bf16 v[42:45], v[152:155], v[138:141], v[42:45]
	v_mfma_f32_16x16x32_bf16 v[62:65], v[156:159], v[138:141], v[62:65]
	v_mfma_f32_16x16x32_bf16 v[66:69], v[160:163], v[138:141], v[66:69]
	v_mfma_f32_16x16x32_bf16 v[54:57], v[164:167], v[138:141], v[54:57]
	v_mfma_f32_16x16x32_bf16 v[34:37], v[152:155], v[142:145], v[34:37]
	v_mfma_f32_16x16x32_bf16 v[30:33], v[156:159], v[142:145], v[30:33]
	v_mfma_f32_16x16x32_bf16 v[26:29], v[160:163], v[142:145], v[26:29]
	v_mfma_f32_16x16x32_bf16 v[18:21], v[164:167], v[142:145], v[18:21]
	s_waitcnt vmcnt(6) lgkmcnt(0)
	s_barrier
	ds_read_b128 v[102:105], v8 offset:49152
	ds_read_b128 v[132:135], v8 offset:51200
	ds_read_b128 v[138:141], v8 offset:53248
	ds_read_b128 v[142:145], v8 offset:55296
	ds_read_b128 v[152:155], v12
	ds_read_b128 v[156:159], v12 offset:2048
	ds_read_b128 v[160:163], v12 offset:4096
	ds_read_b128 v[164:167], v12 offset:6144
	v_mfma_f32_16x16x32_bf16 v[84:87], v[116:119], v[72:75], v[84:87]
	v_mfma_f32_16x16x32_bf16 v[88:91], v[120:123], v[72:75], v[88:91]
	v_mfma_f32_16x16x32_bf16 v[92:95], v[124:127], v[72:75], v[92:95]
	v_mfma_f32_16x16x32_bf16 v[22:25], v[128:131], v[72:75], v[22:25]
	v_mfma_f32_16x16x32_bf16 v[38:41], v[116:119], v[76:79], v[38:41]
	v_mfma_f32_16x16x32_bf16 v[46:49], v[120:123], v[76:79], v[46:49]
	v_mfma_f32_16x16x32_bf16 v[58:61], v[124:127], v[76:79], v[58:61]
	v_mfma_f32_16x16x32_bf16 v[50:53], v[128:131], v[76:79], v[50:53]
	v_mfma_f32_16x16x32_bf16 v[42:45], v[116:119], v[106:109], v[42:45]
	v_mfma_f32_16x16x32_bf16 v[62:65], v[120:123], v[106:109], v[62:65]
	v_mfma_f32_16x16x32_bf16 v[66:69], v[124:127], v[106:109], v[66:69]
	v_mfma_f32_16x16x32_bf16 v[54:57], v[128:131], v[106:109], v[54:57]
	v_mfma_f32_16x16x32_bf16 v[34:37], v[116:119], v[112:115], v[34:37]
	v_mfma_f32_16x16x32_bf16 v[30:33], v[120:123], v[112:115], v[30:33]
	v_mfma_f32_16x16x32_bf16 v[26:29], v[124:127], v[112:115], v[26:29]
	v_mfma_f32_16x16x32_bf16 v[18:21], v[128:131], v[112:115], v[18:21]
	s_mov_b64 s[8:9], 0x780
	s_mov_b32 m0, s57
	v_lshl_add_u64 v[2:3], v[2:3], 0, s[8:9]
	global_load_lds_dwordx4 v[2:3], off
	v_lshl_add_u64 v[2:3], v[4:5], 0, s[8:9]
	s_mov_b32 m0, s5
	s_nop 0
	global_load_lds_dwordx4 v[2:3], off
	v_lshl_add_u64 v[2:3], v[6:7], 0, s[8:9]
	s_mov_b32 m0, s33
	s_mov_b64 s[8:9], 0x20780
	global_load_lds_dwordx4 v[2:3], off
	v_lshl_add_u64 v[2:3], v[6:7], 0, s[8:9]
	s_mov_b32 m0, s38
	s_mov_b64 s[8:9], 0x40780
	global_load_lds_dwordx4 v[2:3], off
	v_lshl_add_u64 v[2:3], v[6:7], 0, s[8:9]
	s_mov_b32 m0, s39
	s_mov_b64 s[8:9], 0x60780
	global_load_lds_dwordx4 v[2:3], off
	v_lshl_add_u64 v[2:3], v[6:7], 0, s[8:9]
	s_mov_b32 m0, s56
	s_nop 0
	global_load_lds_dwordx4 v[2:3], off
	ds_read_b128 v[2:5], v10 offset:49152
	ds_read_b128 v[72:75], v10 offset:51200
	ds_read_b128 v[76:79], v10 offset:53248
	ds_read_b128 v[106:109], v10 offset:55296
	ds_read_b128 v[112:115], v13
	ds_read_b128 v[116:119], v13 offset:2048
	ds_read_b128 v[120:123], v13 offset:4096
	ds_read_b128 v[124:127], v13 offset:6144
	s_waitcnt lgkmcnt(8)
	v_mfma_f32_16x16x32_bf16 v[84:87], v[152:155], v[102:105], v[84:87]
	v_mfma_f32_16x16x32_bf16 v[88:91], v[156:159], v[102:105], v[88:91]
	v_mfma_f32_16x16x32_bf16 v[92:95], v[160:163], v[102:105], v[92:95]
	v_mfma_f32_16x16x32_bf16 v[22:25], v[164:167], v[102:105], v[22:25]
	v_mfma_f32_16x16x32_bf16 v[38:41], v[152:155], v[132:135], v[38:41]
	v_mfma_f32_16x16x32_bf16 v[46:49], v[156:159], v[132:135], v[46:49]
	v_mfma_f32_16x16x32_bf16 v[58:61], v[160:163], v[132:135], v[58:61]
	v_mfma_f32_16x16x32_bf16 v[50:53], v[164:167], v[132:135], v[50:53]
	v_mfma_f32_16x16x32_bf16 v[42:45], v[152:155], v[138:141], v[42:45]
	v_mfma_f32_16x16x32_bf16 v[62:65], v[156:159], v[138:141], v[62:65]
	v_mfma_f32_16x16x32_bf16 v[66:69], v[160:163], v[138:141], v[66:69]
	v_mfma_f32_16x16x32_bf16 v[54:57], v[164:167], v[138:141], v[54:57]
	v_mfma_f32_16x16x32_bf16 v[34:37], v[152:155], v[142:145], v[34:37]
	v_mfma_f32_16x16x32_bf16 v[30:33], v[156:159], v[142:145], v[30:33]
	v_mfma_f32_16x16x32_bf16 v[26:29], v[160:163], v[142:145], v[26:29]
	v_mfma_f32_16x16x32_bf16 v[18:21], v[164:167], v[142:145], v[18:21]
	s_waitcnt vmcnt(6) lgkmcnt(0)
	s_barrier
	ds_read_b128 v[102:105], v14
	ds_read_b128 v[128:131], v14 offset:2048
	ds_read_b128 v[132:135], v14 offset:4096
	ds_read_b128 v[138:141], v14 offset:6144
	ds_read_b128 v[142:145], v15
	ds_read_b128 v[152:155], v15 offset:2048
	ds_read_b128 v[156:159], v15 offset:4096
	ds_read_b128 v[12:15], v15 offset:6144
	v_mfma_f32_16x16x32_bf16 v[84:87], v[112:115], v[2:5], v[84:87]
	v_mfma_f32_16x16x32_bf16 v[88:91], v[116:119], v[2:5], v[88:91]
	v_mfma_f32_16x16x32_bf16 v[92:95], v[120:123], v[2:5], v[92:95]
	v_mfma_f32_16x16x32_bf16 v[2:5], v[124:127], v[2:5], v[22:25]
	v_mfma_f32_16x16x32_bf16 v[22:25], v[112:115], v[72:75], v[38:41]
	v_mfma_f32_16x16x32_bf16 v[38:41], v[116:119], v[72:75], v[46:49]
	v_mfma_f32_16x16x32_bf16 v[46:49], v[120:123], v[72:75], v[58:61]
	v_mfma_f32_16x16x32_bf16 v[50:53], v[124:127], v[72:75], v[50:53]
	v_mfma_f32_16x16x32_bf16 v[42:45], v[112:115], v[76:79], v[42:45]
	v_mfma_f32_16x16x32_bf16 v[58:61], v[116:119], v[76:79], v[62:65]
	v_mfma_f32_16x16x32_bf16 v[62:65], v[120:123], v[76:79], v[66:69]
	v_mfma_f32_16x16x32_bf16 v[54:57], v[124:127], v[76:79], v[54:57]
	v_mfma_f32_16x16x32_bf16 v[34:37], v[112:115], v[106:109], v[34:37]
	v_mfma_f32_16x16x32_bf16 v[30:33], v[116:119], v[106:109], v[30:33]
	v_mfma_f32_16x16x32_bf16 v[26:29], v[120:123], v[106:109], v[26:29]
	v_mfma_f32_16x16x32_bf16 v[18:21], v[124:127], v[106:109], v[18:21]
	ds_read_b128 v[66:69], v16
	ds_read_b128 v[72:75], v16 offset:2048
	ds_read_b128 v[76:79], v16 offset:4096
	ds_read_b128 v[106:109], v16 offset:6144
	ds_read_b128 v[112:115], v17
	ds_read_b128 v[116:119], v17 offset:2048
	ds_read_b128 v[120:123], v17 offset:4096
	ds_read_b128 v[124:127], v17 offset:6144
	s_waitcnt lgkmcnt(8)
	v_mfma_f32_16x16x32_bf16 v[84:87], v[142:145], v[102:105], v[84:87]
	v_mfma_f32_16x16x32_bf16 v[88:91], v[152:155], v[102:105], v[88:91]
	v_mfma_f32_16x16x32_bf16 v[92:95], v[156:159], v[102:105], v[92:95]
	v_mfma_f32_16x16x32_bf16 v[2:5], v[12:15], v[102:105], v[2:5]
	v_mfma_f32_16x16x32_bf16 v[22:25], v[142:145], v[128:131], v[22:25]
	v_mfma_f32_16x16x32_bf16 v[38:41], v[152:155], v[128:131], v[38:41]
	v_mfma_f32_16x16x32_bf16 v[46:49], v[156:159], v[128:131], v[46:49]
	v_mfma_f32_16x16x32_bf16 v[50:53], v[12:15], v[128:131], v[50:53]
	v_mfma_f32_16x16x32_bf16 v[42:45], v[142:145], v[132:135], v[42:45]
	v_mfma_f32_16x16x32_bf16 v[58:61], v[152:155], v[132:135], v[58:61]
	v_mfma_f32_16x16x32_bf16 v[62:65], v[156:159], v[132:135], v[62:65]
	v_mfma_f32_16x16x32_bf16 v[54:57], v[12:15], v[132:135], v[54:57]
	v_mfma_f32_16x16x32_bf16 v[34:37], v[142:145], v[138:141], v[34:37]
	v_mfma_f32_16x16x32_bf16 v[30:33], v[152:155], v[138:141], v[30:33]
	v_mfma_f32_16x16x32_bf16 v[26:29], v[156:159], v[138:141], v[26:29]
	v_mfma_f32_16x16x32_bf16 v[12:15], v[12:15], v[138:141], v[18:21]
	s_waitcnt vmcnt(0) lgkmcnt(0)
	s_barrier
	s_nop 1
	ds_read_b128 v[16:19], v8
	ds_read_b128 v[102:105], v8 offset:2048
	ds_read_b128 v[128:131], v8 offset:4096
	ds_read_b128 v[132:135], v8 offset:6144
	ds_read_b128 v[138:141], v9 offset:16384
	ds_read_b128 v[142:145], v9 offset:18432
	ds_read_b128 v[152:155], v9 offset:20480
	ds_read_b128 v[6:9], v9 offset:22528
	v_mfma_f32_16x16x32_bf16 v[84:87], v[112:115], v[66:69], v[84:87]
	v_mfma_f32_16x16x32_bf16 v[88:91], v[116:119], v[66:69], v[88:91]
	v_mfma_f32_16x16x32_bf16 v[92:95], v[120:123], v[66:69], v[92:95]
	v_mfma_f32_16x16x32_bf16 v[2:5], v[124:127], v[66:69], v[2:5]
	v_mfma_f32_16x16x32_bf16 v[20:23], v[112:115], v[72:75], v[22:25]
	v_mfma_f32_16x16x32_bf16 v[38:41], v[116:119], v[72:75], v[38:41]
	v_mfma_f32_16x16x32_bf16 v[46:49], v[120:123], v[72:75], v[46:49]
	v_mfma_f32_16x16x32_bf16 v[50:53], v[124:127], v[72:75], v[50:53]
	v_mfma_f32_16x16x32_bf16 v[42:45], v[112:115], v[76:79], v[42:45]
	v_mfma_f32_16x16x32_bf16 v[58:61], v[116:119], v[76:79], v[58:61]
	v_mfma_f32_16x16x32_bf16 v[62:65], v[120:123], v[76:79], v[62:65]
	v_mfma_f32_16x16x32_bf16 v[54:57], v[124:127], v[76:79], v[54:57]
	v_mfma_f32_16x16x32_bf16 v[34:37], v[112:115], v[106:109], v[34:37]
	v_mfma_f32_16x16x32_bf16 v[30:33], v[116:119], v[106:109], v[30:33]
	v_mfma_f32_16x16x32_bf16 v[24:27], v[120:123], v[106:109], v[26:29]
	v_mfma_f32_16x16x32_bf16 v[12:15], v[124:127], v[106:109], v[12:15]
	ds_read_b128 v[66:69], v10
	ds_read_b128 v[72:75], v10 offset:2048
	ds_read_b128 v[76:79], v10 offset:4096
	ds_read_b128 v[106:109], v10 offset:6144
	ds_read_b128 v[112:115], v11 offset:16384
	ds_read_b128 v[116:119], v11 offset:18432
	ds_read_b128 v[120:123], v11 offset:20480
	ds_read_b128 v[124:127], v11 offset:22528
	s_addk_i32 s1, 0xf700
	s_waitcnt lgkmcnt(8)
	v_mfma_f32_16x16x32_bf16 v[84:87], v[138:141], v[16:19], v[84:87]
	v_mfma_f32_16x16x32_bf16 v[88:91], v[142:145], v[16:19], v[88:91]
	v_mfma_f32_16x16x32_bf16 v[92:95], v[152:155], v[16:19], v[92:95]
	v_mfma_f32_16x16x32_bf16 v[2:5], v[6:9], v[16:19], v[2:5]
	v_mfma_f32_16x16x32_bf16 v[16:19], v[138:141], v[102:105], v[20:23]
	v_mfma_f32_16x16x32_bf16 v[20:23], v[142:145], v[102:105], v[38:41]
	v_mfma_f32_16x16x32_bf16 v[38:41], v[152:155], v[102:105], v[46:49]
	v_mfma_f32_16x16x32_bf16 v[46:49], v[6:9], v[102:105], v[50:53]
	v_mfma_f32_16x16x32_bf16 v[42:45], v[138:141], v[128:131], v[42:45]
	v_mfma_f32_16x16x32_bf16 v[50:53], v[142:145], v[128:131], v[58:61]
	v_mfma_f32_16x16x32_bf16 v[58:61], v[152:155], v[128:131], v[62:65]
	v_mfma_f32_16x16x32_bf16 v[54:57], v[6:9], v[128:131], v[54:57]
	v_mfma_f32_16x16x32_bf16 v[34:37], v[138:141], v[132:135], v[34:37]
	v_mfma_f32_16x16x32_bf16 v[28:31], v[142:145], v[132:135], v[30:33]
	v_mfma_f32_16x16x32_bf16 v[24:27], v[152:155], v[132:135], v[24:27]
	v_mfma_f32_16x16x32_bf16 v[6:9], v[6:9], v[132:135], v[12:15]
	s_waitcnt vmcnt(0) lgkmcnt(0)
	s_barrier
	v_mfma_f32_16x16x32_bf16 v[10:13], v[112:115], v[66:69], v[84:87]
	v_mfma_f32_16x16x32_bf16 v[62:65], v[116:119], v[66:69], v[88:91]
	v_mfma_f32_16x16x32_bf16 v[84:87], v[120:123], v[66:69], v[92:95]
	v_mfma_f32_16x16x32_bf16 v[2:5], v[124:127], v[66:69], v[2:5]
	v_mfma_f32_16x16x32_bf16 v[14:17], v[112:115], v[72:75], v[16:19]
	v_mfma_f32_16x16x32_bf16 v[18:21], v[116:119], v[72:75], v[20:23]
	v_mfma_f32_16x16x32_bf16 v[38:41], v[120:123], v[72:75], v[38:41]
	v_mfma_f32_16x16x32_bf16 v[46:49], v[124:127], v[72:75], v[46:49]
	v_mfma_f32_16x16x32_bf16 v[42:45], v[112:115], v[76:79], v[42:45]
	v_mfma_f32_16x16x32_bf16 v[50:53], v[116:119], v[76:79], v[50:53]
	v_mfma_f32_16x16x32_bf16 v[58:61], v[120:123], v[76:79], v[58:61]
	v_mfma_f32_16x16x32_bf16 v[54:57], v[124:127], v[76:79], v[54:57]
	v_mfma_f32_16x16x32_bf16 v[32:35], v[112:115], v[106:109], v[34:37]
	v_mfma_f32_16x16x32_bf16 v[28:31], v[116:119], v[106:109], v[28:31]
	v_mfma_f32_16x16x32_bf16 v[22:25], v[120:123], v[106:109], v[24:27]
	v_mfma_f32_16x16x32_bf16 v[6:9], v[124:127], v[106:109], v[6:9]
	v_lshlrev_b32_e32 v36, 6, v83
	v_lshlrev_b32_e32 v37, 2, v110
	s_and_b32 s0, s0, 0xf00
	v_lshl_add_u32 v26, v82, 6, s1
	v_or3_b32 v66, v36, v37, s0
	s_lshl_b32 s0, s4, 4
	v_and_b32_e32 v27, 0xc0, v26
	s_and_b32 s0, s0, 0x300
	v_or3_b32 v36, s0, v27, v101
	v_lshlrev_b32_e32 v26, 4, v26
	v_and_b32_e32 v26, 0xfffff000, v26
	v_lshlrev_b32_e32 v98, 14, v36
	v_ashrrev_i32_e32 v27, 31, v26
	v_lshl_add_u64 v[36:37], s[18:19], 0, v[98:99]
	v_lshl_add_u64 v[26:27], v[26:27], 1, v[36:37]
	v_lshlrev_b32_e32 v98, 1, v66
	v_lshl_add_u64 v[26:27], v[26:27], 0, v[98:99]
	v_cvt_pk_bf16_f32 v10, v10, v11
	v_cvt_pk_bf16_f32 v11, v12, v13
	s_waitcnt lgkmcnt(0)
	s_barrier
	global_store_dwordx2 v[26:27], v[10:11], off
	v_cvt_pk_bf16_f32 v10, v62, v63
	v_cvt_pk_bf16_f32 v11, v64, v65
	global_store_dwordx2 v[26:27], v[10:11], off offset:32
	v_cvt_pk_bf16_f32 v10, v84, v85
	v_cvt_pk_bf16_f32 v11, v86, v87
	global_store_dwordx2 v[26:27], v[10:11], off offset:64
	v_add_co_u32_e32 v10, vcc, s37, v26
	v_cvt_pk_bf16_f32 v2, v2, v3
	v_cvt_pk_bf16_f32 v3, v4, v5
	v_cvt_pk_bf16_f32 v4, v14, v15
	v_cvt_pk_bf16_f32 v5, v16, v17
	v_addc_co_u32_e32 v11, vcc, 0, v27, vcc
	global_store_dwordx2 v[26:27], v[2:3], off offset:96
	v_lshl_add_u64 v[2:3], v[26:27], 0, s[68:69]
	global_store_dwordx2 v[10:11], v[4:5], off
	v_cvt_pk_bf16_f32 v4, v18, v19
	v_cvt_pk_bf16_f32 v5, v20, v21
	global_store_dwordx2 v[2:3], v[4:5], off offset:32
	v_cvt_pk_bf16_f32 v4, v38, v39
	v_cvt_pk_bf16_f32 v5, v40, v41
	global_store_dwordx2 v[2:3], v[4:5], off offset:64
	v_cvt_pk_bf16_f32 v4, v46, v47
	v_cvt_pk_bf16_f32 v5, v48, v49
	v_add_co_u32_e32 v10, vcc, s65, v26
	global_store_dwordx2 v[2:3], v[4:5], off offset:96
	v_cvt_pk_bf16_f32 v4, v42, v43
	v_cvt_pk_bf16_f32 v5, v44, v45
	v_addc_co_u32_e32 v11, vcc, 0, v27, vcc
	v_lshl_add_u64 v[2:3], v[26:27], 0, s[30:31]
	global_store_dwordx2 v[10:11], v[4:5], off
	v_cvt_pk_bf16_f32 v4, v50, v51
	v_cvt_pk_bf16_f32 v5, v52, v53
	global_store_dwordx2 v[2:3], v[4:5], off offset:32
	v_cvt_pk_bf16_f32 v4, v58, v59
	v_cvt_pk_bf16_f32 v5, v60, v61
	global_store_dwordx2 v[2:3], v[4:5], off offset:64
	v_cvt_pk_bf16_f32 v4, v54, v55
	v_cvt_pk_bf16_f32 v5, v56, v57
	v_add_co_u32_e32 v10, vcc, s78, v26
	global_store_dwordx2 v[2:3], v[4:5], off offset:96
	v_cvt_pk_bf16_f32 v4, v32, v33
	v_cvt_pk_bf16_f32 v5, v34, v35
	v_addc_co_u32_e32 v11, vcc, 0, v27, vcc
	v_lshl_add_u64 v[2:3], v[26:27], 0, s[24:25]
	global_store_dwordx2 v[10:11], v[4:5], off
	v_cvt_pk_bf16_f32 v4, v28, v29
	v_cvt_pk_bf16_f32 v5, v30, v31
	global_store_dwordx2 v[2:3], v[4:5], off offset:32
	v_cvt_pk_bf16_f32 v4, v22, v23
	v_cvt_pk_bf16_f32 v5, v24, v25
	global_store_dwordx2 v[2:3], v[4:5], off offset:64
	v_cvt_pk_bf16_f32 v4, v6, v7
	v_cvt_pk_bf16_f32 v5, v8, v9
	global_store_dwordx2 v[2:3], v[4:5], off offset:96

.Ldq_skip3:
	s_mov_b64 exec, s[8:9]
	s_mov_b32 s99, 1
	ds_read_b128 v[72:75], v16
	ds_read_b128 v[76:79], v16 offset:2048
	ds_read_b128 v[106:109], v16 offset:4096
	ds_read_b128 v[112:115], v16 offset:6144
	ds_read_b128 v[116:119], v17
	ds_read_b128 v[120:123], v17 offset:2048
	ds_read_b128 v[124:127], v17 offset:4096
	ds_read_b128 v[128:131], v17 offset:6144
	s_waitcnt lgkmcnt(8)
	v_mfma_f32_16x16x32_bf16 v[84:87], v[152:155], v[102:105], v[84:87]
	v_mfma_f32_16x16x32_bf16 v[88:91], v[156:159], v[102:105], v[88:91]
	v_mfma_f32_16x16x32_bf16 v[92:95], v[160:163], v[102:105], v[92:95]
	v_mfma_f32_16x16x32_bf16 v[22:25], v[164:167], v[102:105], v[22:25]
	v_mfma_f32_16x16x32_bf16 v[38:41], v[152:155], v[132:135], v[38:41]
	v_mfma_f32_16x16x32_bf16 v[46:49], v[156:159], v[132:135], v[46:49]
	v_mfma_f32_16x16x32_bf16 v[58:61], v[160:163], v[132:135], v[58:61]
	v_mfma_f32_16x16x32_bf16 v[50:53], v[164:167], v[132:135], v[50:53]
	v_mfma_f32_16x16x32_bf16 v[42:45], v[152:155], v[138:141], v[42:45]
	v_mfma_f32_16x16x32_bf16 v[62:65], v[156:159], v[138:141], v[62:65]
	v_mfma_f32_16x16x32_bf16 v[66:69], v[160:163], v[138:141], v[66:69]
	v_mfma_f32_16x16x32_bf16 v[54:57], v[164:167], v[138:141], v[54:57]
	v_mfma_f32_16x16x32_bf16 v[34:37], v[152:155], v[142:145], v[34:37]
	v_mfma_f32_16x16x32_bf16 v[30:33], v[156:159], v[142:145], v[30:33]
	v_mfma_f32_16x16x32_bf16 v[26:29], v[160:163], v[142:145], v[26:29]
	v_mfma_f32_16x16x32_bf16 v[18:21], v[164:167], v[142:145], v[18:21]
	s_waitcnt vmcnt(6) lgkmcnt(0)
	s_barrier
	ds_read_b128 v[102:105], v8
	ds_read_b128 v[132:135], v8 offset:2048
	ds_read_b128 v[138:141], v8 offset:4096
	ds_read_b128 v[142:145], v8 offset:6144
	ds_read_b128 v[152:155], v9 offset:16384
	ds_read_b128 v[156:159], v9 offset:18432
	ds_read_b128 v[160:163], v9 offset:20480
	ds_read_b128 v[164:167], v9 offset:22528
	v_mfma_f32_16x16x32_bf16 v[84:87], v[116:119], v[72:75], v[84:87]
	v_mfma_f32_16x16x32_bf16 v[88:91], v[120:123], v[72:75], v[88:91]
	v_mfma_f32_16x16x32_bf16 v[92:95], v[124:127], v[72:75], v[92:95]
	v_mfma_f32_16x16x32_bf16 v[22:25], v[128:131], v[72:75], v[22:25]
	v_mfma_f32_16x16x32_bf16 v[38:41], v[116:119], v[76:79], v[38:41]
	v_mfma_f32_16x16x32_bf16 v[46:49], v[120:123], v[76:79], v[46:49]
	v_mfma_f32_16x16x32_bf16 v[58:61], v[124:127], v[76:79], v[58:61]
	v_mfma_f32_16x16x32_bf16 v[50:53], v[128:131], v[76:79], v[50:53]
	v_mfma_f32_16x16x32_bf16 v[42:45], v[116:119], v[106:109], v[42:45]
	v_mfma_f32_16x16x32_bf16 v[62:65], v[120:123], v[106:109], v[62:65]
	v_mfma_f32_16x16x32_bf16 v[66:69], v[124:127], v[106:109], v[66:69]
	v_mfma_f32_16x16x32_bf16 v[54:57], v[128:131], v[106:109], v[54:57]
	v_mfma_f32_16x16x32_bf16 v[34:37], v[116:119], v[112:115], v[34:37]
	v_mfma_f32_16x16x32_bf16 v[30:33], v[120:123], v[112:115], v[30:33]
	v_mfma_f32_16x16x32_bf16 v[26:29], v[124:127], v[112:115], v[26:29]
	v_mfma_f32_16x16x32_bf16 v[18:21], v[128:131], v[112:115], v[18:21]
	s_mov_b64 s[8:9], 0x700
	s_mov_b32 m0, s64
	v_lshl_add_u64 v[72:73], v[2:3], 0, s[8:9]
	global_load_lds_dwordx4 v[72:73], off
	v_lshl_add_u64 v[72:73], v[4:5], 0, s[8:9]
	s_mov_b32 m0, s71
	s_nop 0
	global_load_lds_dwordx4 v[72:73], off
	v_lshl_add_u64 v[72:73], v[6:7], 0, s[8:9]
	s_mov_b32 m0, s73
	s_mov_b64 s[8:9], 0x20700
	global_load_lds_dwordx4 v[72:73], off
	v_lshl_add_u64 v[72:73], v[6:7], 0, s[8:9]
	s_mov_b32 m0, s74
	s_mov_b64 s[8:9], 0x40700
	global_load_lds_dwordx4 v[72:73], off
	v_lshl_add_u64 v[72:73], v[6:7], 0, s[8:9]
	s_mov_b32 m0, s75
	s_mov_b64 s[8:9], 0x60700
	global_load_lds_dwordx4 v[72:73], off
	v_lshl_add_u64 v[72:73], v[6:7], 0, s[8:9]
	s_mov_b32 m0, s76
	s_nop 0
	global_load_lds_dwordx4 v[72:73], off
	ds_read_b128 v[72:75], v10
	ds_read_b128 v[76:79], v10 offset:2048
	ds_read_b128 v[106:109], v10 offset:4096
	ds_read_b128 v[112:115], v10 offset:6144
	ds_read_b128 v[116:119], v11 offset:16384
	ds_read_b128 v[120:123], v11 offset:18432
	ds_read_b128 v[124:127], v11 offset:20480
	ds_read_b128 v[128:131], v11 offset:22528
	s_waitcnt lgkmcnt(8)
	v_mfma_f32_16x16x32_bf16 v[84:87], v[152:155], v[102:105], v[84:87]
	v_mfma_f32_16x16x32_bf16 v[88:91], v[156:159], v[102:105], v[88:91]
	v_mfma_f32_16x16x32_bf16 v[92:95], v[160:163], v[102:105], v[92:95]
	v_mfma_f32_16x16x32_bf16 v[22:25], v[164:167], v[102:105], v[22:25]
	v_mfma_f32_16x16x32_bf16 v[38:41], v[152:155], v[132:135], v[38:41]
	v_mfma_f32_16x16x32_bf16 v[46:49], v[156:159], v[132:135], v[46:49]
	v_mfma_f32_16x16x32_bf16 v[58:61], v[160:163], v[132:135], v[58:61]
	v_mfma_f32_16x16x32_bf16 v[50:53], v[164:167], v[132:135], v[50:53]
	v_mfma_f32_16x16x32_bf16 v[42:45], v[152:155], v[138:141], v[42:45]
	v_mfma_f32_16x16x32_bf16 v[62:65], v[156:159], v[138:141], v[62:65]
	v_mfma_f32_16x16x32_bf16 v[66:69], v[160:163], v[138:141], v[66:69]
	v_mfma_f32_16x16x32_bf16 v[54:57], v[164:167], v[138:141], v[54:57]
	v_mfma_f32_16x16x32_bf16 v[34:37], v[152:155], v[142:145], v[34:37]
	v_mfma_f32_16x16x32_bf16 v[30:33], v[156:159], v[142:145], v[30:33]
	v_mfma_f32_16x16x32_bf16 v[26:29], v[160:163], v[142:145], v[26:29]
	v_mfma_f32_16x16x32_bf16 v[18:21], v[164:167], v[142:145], v[18:21]
	s_waitcnt vmcnt(6) lgkmcnt(0)
	s_barrier
	ds_read_b128 v[102:105], v8 offset:49152
	ds_read_b128 v[132:135], v8 offset:51200
	ds_read_b128 v[138:141], v8 offset:53248
	ds_read_b128 v[142:145], v8 offset:55296
	ds_read_b128 v[152:155], v12
	ds_read_b128 v[156:159], v12 offset:2048
	ds_read_b128 v[160:163], v12 offset:4096
	ds_read_b128 v[164:167], v12 offset:6144
	v_mfma_f32_16x16x32_bf16 v[84:87], v[116:119], v[72:75], v[84:87]
	v_mfma_f32_16x16x32_bf16 v[88:91], v[120:123], v[72:75], v[88:91]
	v_mfma_f32_16x16x32_bf16 v[92:95], v[124:127], v[72:75], v[92:95]
	v_mfma_f32_16x16x32_bf16 v[22:25], v[128:131], v[72:75], v[22:25]
	v_mfma_f32_16x16x32_bf16 v[38:41], v[116:119], v[76:79], v[38:41]
	v_mfma_f32_16x16x32_bf16 v[46:49], v[120:123], v[76:79], v[46:49]
	v_mfma_f32_16x16x32_bf16 v[58:61], v[124:127], v[76:79], v[58:61]
	v_mfma_f32_16x16x32_bf16 v[50:53], v[128:131], v[76:79], v[50:53]
	v_mfma_f32_16x16x32_bf16 v[42:45], v[116:119], v[106:109], v[42:45]
	v_mfma_f32_16x16x32_bf16 v[62:65], v[120:123], v[106:109], v[62:65]
	v_mfma_f32_16x16x32_bf16 v[66:69], v[124:127], v[106:109], v[66:69]
	v_mfma_f32_16x16x32_bf16 v[54:57], v[128:131], v[106:109], v[54:57]
	v_mfma_f32_16x16x32_bf16 v[34:37], v[116:119], v[112:115], v[34:37]
	v_mfma_f32_16x16x32_bf16 v[30:33], v[120:123], v[112:115], v[30:33]
	v_mfma_f32_16x16x32_bf16 v[26:29], v[124:127], v[112:115], v[26:29]
	v_mfma_f32_16x16x32_bf16 v[18:21], v[128:131], v[112:115], v[18:21]
	s_mov_b64 s[8:9], 0x780
	s_mov_b32 m0, s57
	v_lshl_add_u64 v[2:3], v[2:3], 0, s[8:9]
	global_load_lds_dwordx4 v[2:3], off
	v_lshl_add_u64 v[2:3], v[4:5], 0, s[8:9]
	s_mov_b32 m0, s5
	s_nop 0
	global_load_lds_dwordx4 v[2:3], off
	v_lshl_add_u64 v[2:3], v[6:7], 0, s[8:9]
	s_mov_b32 m0, s33
	s_mov_b64 s[8:9], 0x20780
	global_load_lds_dwordx4 v[2:3], off
	v_lshl_add_u64 v[2:3], v[6:7], 0, s[8:9]
	s_mov_b32 m0, s38
	s_mov_b64 s[8:9], 0x40780
	global_load_lds_dwordx4 v[2:3], off
	v_lshl_add_u64 v[2:3], v[6:7], 0, s[8:9]
	s_mov_b32 m0, s39
	s_mov_b64 s[8:9], 0x60780
	global_load_lds_dwordx4 v[2:3], off
	v_lshl_add_u64 v[2:3], v[6:7], 0, s[8:9]
	s_mov_b32 m0, s56
	s_nop 0
	global_load_lds_dwordx4 v[2:3], off
	ds_read_b128 v[2:5], v10 offset:49152
	ds_read_b128 v[72:75], v10 offset:51200
	ds_read_b128 v[76:79], v10 offset:53248
	ds_read_b128 v[106:109], v10 offset:55296
	ds_read_b128 v[112:115], v13
	ds_read_b128 v[116:119], v13 offset:2048
	ds_read_b128 v[120:123], v13 offset:4096
	ds_read_b128 v[124:127], v13 offset:6144
	s_waitcnt lgkmcnt(8)
	v_mfma_f32_16x16x32_bf16 v[84:87], v[152:155], v[102:105], v[84:87]
	v_mfma_f32_16x16x32_bf16 v[88:91], v[156:159], v[102:105], v[88:91]
	v_mfma_f32_16x16x32_bf16 v[92:95], v[160:163], v[102:105], v[92:95]
	v_mfma_f32_16x16x32_bf16 v[22:25], v[164:167], v[102:105], v[22:25]
	v_mfma_f32_16x16x32_bf16 v[38:41], v[152:155], v[132:135], v[38:41]
	v_mfma_f32_16x16x32_bf16 v[46:49], v[156:159], v[132:135], v[46:49]
	v_mfma_f32_16x16x32_bf16 v[58:61], v[160:163], v[132:135], v[58:61]
	v_mfma_f32_16x16x32_bf16 v[50:53], v[164:167], v[132:135], v[50:53]
	v_mfma_f32_16x16x32_bf16 v[42:45], v[152:155], v[138:141], v[42:45]
	v_mfma_f32_16x16x32_bf16 v[62:65], v[156:159], v[138:141], v[62:65]
	v_mfma_f32_16x16x32_bf16 v[66:69], v[160:163], v[138:141], v[66:69]
	v_mfma_f32_16x16x32_bf16 v[54:57], v[164:167], v[138:141], v[54:57]
	v_mfma_f32_16x16x32_bf16 v[34:37], v[152:155], v[142:145], v[34:37]
	v_mfma_f32_16x16x32_bf16 v[30:33], v[156:159], v[142:145], v[30:33]
	v_mfma_f32_16x16x32_bf16 v[26:29], v[160:163], v[142:145], v[26:29]
	v_mfma_f32_16x16x32_bf16 v[18:21], v[164:167], v[142:145], v[18:21]
	s_waitcnt vmcnt(6) lgkmcnt(0)
	s_barrier
	ds_read_b128 v[102:105], v14
	ds_read_b128 v[128:131], v14 offset:2048
	ds_read_b128 v[132:135], v14 offset:4096
	ds_read_b128 v[138:141], v14 offset:6144
	ds_read_b128 v[142:145], v15
	ds_read_b128 v[152:155], v15 offset:2048
	ds_read_b128 v[156:159], v15 offset:4096
	ds_read_b128 v[12:15], v15 offset:6144
	v_mfma_f32_16x16x32_bf16 v[84:87], v[112:115], v[2:5], v[84:87]
	v_mfma_f32_16x16x32_bf16 v[88:91], v[116:119], v[2:5], v[88:91]
	v_mfma_f32_16x16x32_bf16 v[92:95], v[120:123], v[2:5], v[92:95]
	v_mfma_f32_16x16x32_bf16 v[2:5], v[124:127], v[2:5], v[22:25]
	v_mfma_f32_16x16x32_bf16 v[22:25], v[112:115], v[72:75], v[38:41]
	v_mfma_f32_16x16x32_bf16 v[38:41], v[116:119], v[72:75], v[46:49]
	v_mfma_f32_16x16x32_bf16 v[46:49], v[120:123], v[72:75], v[58:61]
	v_mfma_f32_16x16x32_bf16 v[50:53], v[124:127], v[72:75], v[50:53]
	v_mfma_f32_16x16x32_bf16 v[42:45], v[112:115], v[76:79], v[42:45]
	v_mfma_f32_16x16x32_bf16 v[58:61], v[116:119], v[76:79], v[62:65]
	v_mfma_f32_16x16x32_bf16 v[62:65], v[120:123], v[76:79], v[66:69]
	v_mfma_f32_16x16x32_bf16 v[54:57], v[124:127], v[76:79], v[54:57]
	v_mfma_f32_16x16x32_bf16 v[34:37], v[112:115], v[106:109], v[34:37]
	v_mfma_f32_16x16x32_bf16 v[30:33], v[116:119], v[106:109], v[30:33]
	v_mfma_f32_16x16x32_bf16 v[26:29], v[120:123], v[106:109], v[26:29]
	v_mfma_f32_16x16x32_bf16 v[18:21], v[124:127], v[106:109], v[18:21]
	ds_read_b128 v[66:69], v16
	ds_read_b128 v[72:75], v16 offset:2048
	ds_read_b128 v[76:79], v16 offset:4096
	ds_read_b128 v[106:109], v16 offset:6144
	ds_read_b128 v[112:115], v17
	ds_read_b128 v[116:119], v17 offset:2048
	ds_read_b128 v[120:123], v17 offset:4096
	ds_read_b128 v[124:127], v17 offset:6144
	s_waitcnt lgkmcnt(8)
	v_mfma_f32_16x16x32_bf16 v[84:87], v[142:145], v[102:105], v[84:87]
	v_mfma_f32_16x16x32_bf16 v[88:91], v[152:155], v[102:105], v[88:91]
	v_mfma_f32_16x16x32_bf16 v[92:95], v[156:159], v[102:105], v[92:95]
	v_mfma_f32_16x16x32_bf16 v[2:5], v[12:15], v[102:105], v[2:5]
	v_mfma_f32_16x16x32_bf16 v[22:25], v[142:145], v[128:131], v[22:25]
	v_mfma_f32_16x16x32_bf16 v[38:41], v[152:155], v[128:131], v[38:41]
	v_mfma_f32_16x16x32_bf16 v[46:49], v[156:159], v[128:131], v[46:49]
	v_mfma_f32_16x16x32_bf16 v[50:53], v[12:15], v[128:131], v[50:53]
	v_mfma_f32_16x16x32_bf16 v[42:45], v[142:145], v[132:135], v[42:45]
	v_mfma_f32_16x16x32_bf16 v[58:61], v[152:155], v[132:135], v[58:61]
	v_mfma_f32_16x16x32_bf16 v[62:65], v[156:159], v[132:135], v[62:65]
	v_mfma_f32_16x16x32_bf16 v[54:57], v[12:15], v[132:135], v[54:57]
	v_mfma_f32_16x16x32_bf16 v[34:37], v[142:145], v[138:141], v[34:37]
	v_mfma_f32_16x16x32_bf16 v[30:33], v[152:155], v[138:141], v[30:33]
	v_mfma_f32_16x16x32_bf16 v[26:29], v[156:159], v[138:141], v[26:29]
	v_mfma_f32_16x16x32_bf16 v[12:15], v[12:15], v[138:141], v[18:21]
	s_waitcnt vmcnt(0) lgkmcnt(0)
	s_barrier
	s_nop 1
	ds_read_b128 v[16:19], v8
	ds_read_b128 v[102:105], v8 offset:2048
	ds_read_b128 v[128:131], v8 offset:4096
	ds_read_b128 v[132:135], v8 offset:6144
	ds_read_b128 v[138:141], v9 offset:16384
	ds_read_b128 v[142:145], v9 offset:18432
	ds_read_b128 v[152:155], v9 offset:20480
	ds_read_b128 v[6:9], v9 offset:22528
	v_mfma_f32_16x16x32_bf16 v[84:87], v[112:115], v[66:69], v[84:87]
	v_mfma_f32_16x16x32_bf16 v[88:91], v[116:119], v[66:69], v[88:91]
	v_mfma_f32_16x16x32_bf16 v[92:95], v[120:123], v[66:69], v[92:95]
	v_mfma_f32_16x16x32_bf16 v[2:5], v[124:127], v[66:69], v[2:5]
	v_mfma_f32_16x16x32_bf16 v[20:23], v[112:115], v[72:75], v[22:25]
	v_mfma_f32_16x16x32_bf16 v[38:41], v[116:119], v[72:75], v[38:41]
	v_mfma_f32_16x16x32_bf16 v[46:49], v[120:123], v[72:75], v[46:49]
	v_mfma_f32_16x16x32_bf16 v[50:53], v[124:127], v[72:75], v[50:53]
	v_mfma_f32_16x16x32_bf16 v[42:45], v[112:115], v[76:79], v[42:45]
	v_mfma_f32_16x16x32_bf16 v[58:61], v[116:119], v[76:79], v[58:61]
	v_mfma_f32_16x16x32_bf16 v[62:65], v[120:123], v[76:79], v[62:65]
	v_mfma_f32_16x16x32_bf16 v[54:57], v[124:127], v[76:79], v[54:57]
	v_mfma_f32_16x16x32_bf16 v[34:37], v[112:115], v[106:109], v[34:37]
	v_mfma_f32_16x16x32_bf16 v[30:33], v[116:119], v[106:109], v[30:33]
	v_mfma_f32_16x16x32_bf16 v[24:27], v[120:123], v[106:109], v[26:29]
	v_mfma_f32_16x16x32_bf16 v[12:15], v[124:127], v[106:109], v[12:15]
	ds_read_b128 v[66:69], v10
	ds_read_b128 v[72:75], v10 offset:2048
	ds_read_b128 v[76:79], v10 offset:4096
	ds_read_b128 v[106:109], v10 offset:6144
	ds_read_b128 v[112:115], v11 offset:16384
	ds_read_b128 v[116:119], v11 offset:18432
	ds_read_b128 v[120:123], v11 offset:20480
	ds_read_b128 v[124:127], v11 offset:22528
	s_addk_i32 s1, 0xfa00
	s_waitcnt lgkmcnt(8)
	v_mfma_f32_16x16x32_bf16 v[84:87], v[138:141], v[16:19], v[84:87]
	v_mfma_f32_16x16x32_bf16 v[88:91], v[142:145], v[16:19], v[88:91]
	v_mfma_f32_16x16x32_bf16 v[92:95], v[152:155], v[16:19], v[92:95]
	v_mfma_f32_16x16x32_bf16 v[2:5], v[6:9], v[16:19], v[2:5]
	v_mfma_f32_16x16x32_bf16 v[16:19], v[138:141], v[102:105], v[20:23]
	v_mfma_f32_16x16x32_bf16 v[20:23], v[142:145], v[102:105], v[38:41]
	v_mfma_f32_16x16x32_bf16 v[38:41], v[152:155], v[102:105], v[46:49]
	v_mfma_f32_16x16x32_bf16 v[46:49], v[6:9], v[102:105], v[50:53]
	v_mfma_f32_16x16x32_bf16 v[42:45], v[138:141], v[128:131], v[42:45]
	v_mfma_f32_16x16x32_bf16 v[50:53], v[142:145], v[128:131], v[58:61]
	v_mfma_f32_16x16x32_bf16 v[58:61], v[152:155], v[128:131], v[62:65]
	v_mfma_f32_16x16x32_bf16 v[54:57], v[6:9], v[128:131], v[54:57]
	v_mfma_f32_16x16x32_bf16 v[34:37], v[138:141], v[132:135], v[34:37]
	v_mfma_f32_16x16x32_bf16 v[28:31], v[142:145], v[132:135], v[30:33]
	v_mfma_f32_16x16x32_bf16 v[24:27], v[152:155], v[132:135], v[24:27]
	v_mfma_f32_16x16x32_bf16 v[6:9], v[6:9], v[132:135], v[12:15]
	s_waitcnt vmcnt(0) lgkmcnt(0)
	s_barrier
	v_mfma_f32_16x16x32_bf16 v[10:13], v[112:115], v[66:69], v[84:87]
	v_mfma_f32_16x16x32_bf16 v[62:65], v[116:119], v[66:69], v[88:91]
	v_mfma_f32_16x16x32_bf16 v[84:87], v[120:123], v[66:69], v[92:95]
	v_mfma_f32_16x16x32_bf16 v[2:5], v[124:127], v[66:69], v[2:5]
	v_mfma_f32_16x16x32_bf16 v[14:17], v[112:115], v[72:75], v[16:19]
	v_mfma_f32_16x16x32_bf16 v[18:21], v[116:119], v[72:75], v[20:23]
	v_mfma_f32_16x16x32_bf16 v[38:41], v[120:123], v[72:75], v[38:41]
	v_mfma_f32_16x16x32_bf16 v[46:49], v[124:127], v[72:75], v[46:49]
	v_mfma_f32_16x16x32_bf16 v[42:45], v[112:115], v[76:79], v[42:45]
	v_mfma_f32_16x16x32_bf16 v[50:53], v[116:119], v[76:79], v[50:53]
	v_mfma_f32_16x16x32_bf16 v[58:61], v[120:123], v[76:79], v[58:61]
	v_mfma_f32_16x16x32_bf16 v[54:57], v[124:127], v[76:79], v[54:57]
	v_mfma_f32_16x16x32_bf16 v[32:35], v[112:115], v[106:109], v[34:37]
	v_mfma_f32_16x16x32_bf16 v[28:31], v[116:119], v[106:109], v[28:31]
	v_mfma_f32_16x16x32_bf16 v[22:25], v[120:123], v[106:109], v[24:27]
	v_mfma_f32_16x16x32_bf16 v[6:9], v[124:127], v[106:109], v[6:9]
	s_nop 1
	v_or_b32_e32 v26, s1, v101
	v_lshl_add_u32 v26, v82, 6, v26
	s_bfe_u32 s0, s0, 0x2000c
	v_mul_u32_u24_e32 v98, s0, v149
	v_ashrrev_i32_e32 v27, 31, v26
	v_lshl_add_u64 v[36:37], v[26:27], 0, v[98:99]
	v_mov_b64_e32 v[66:67], s[16:17]
	v_mad_u64_u32 v[68:69], s[0:1], v36, s70, v[66:67]
	s_lshl_b32 s0, s4, 9
	s_and_b32 s0, s0, 0x1e00
	v_mad_i32_i24 v69, v37, s70, v69
	v_lshl_or_b32 v36, v83, 7, s0
	v_mov_b32_e32 v37, v99
	v_lshl_add_u64 v[68:69], v[68:69], 0, v[36:37]
	v_lshlrev_b32_e32 v72, 4, v110
	v_mov_b32_e32 v73, v99
	v_lshl_add_u64 v[68:69], v[68:69], 0, v[72:73]
	v_cvt_pk_bf16_f32 v10, v10, v11
	v_cvt_pk_bf16_f32 v11, v12, v13
	v_cvt_pk_bf16_f32 v12, v62, v63
	v_cvt_pk_bf16_f32 v13, v64, v65
	s_waitcnt lgkmcnt(0)
	s_barrier
	global_store_dwordx4 v[68:69], v[10:13], off
	s_nop 1
	v_cvt_pk_bf16_f32 v12, v2, v3
	v_or_b32_e32 v2, 16, v26
	v_ashrrev_i32_e32 v3, 31, v2
	v_lshl_add_u64 v[2:3], v[2:3], 0, v[98:99]
	v_cvt_pk_bf16_f32 v13, v4, v5
	v_mad_u64_u32 v[4:5], s[0:1], v2, s70, v[66:67]
	v_mad_i32_i24 v5, v3, s70, v5
	v_cvt_pk_bf16_f32 v10, v84, v85
	v_cvt_pk_bf16_f32 v11, v86, v87
	v_lshl_add_u64 v[2:3], v[4:5], 0, v[36:37]
	global_store_dwordx4 v[68:69], v[10:13], off offset:64
	v_cvt_pk_bf16_f32 v4, v18, v19
	v_cvt_pk_bf16_f32 v5, v20, v21
	v_lshl_add_u64 v[10:11], v[2:3], 0, v[72:73]
	v_cvt_pk_bf16_f32 v2, v14, v15
	v_cvt_pk_bf16_f32 v3, v16, v17
	global_store_dwordx4 v[10:11], v[2:5], off
	s_nop 1
	v_cvt_pk_bf16_f32 v2, v38, v39
	v_cvt_pk_bf16_f32 v3, v40, v41
	v_cvt_pk_bf16_f32 v4, v46, v47
	v_cvt_pk_bf16_f32 v5, v48, v49
	global_store_dwordx4 v[10:11], v[2:5], off offset:64
	s_nop 1
	v_or_b32_e32 v2, 32, v26
	v_ashrrev_i32_e32 v3, 31, v2
	v_lshl_add_u64 v[2:3], v[2:3], 0, v[98:99]
	v_mad_u64_u32 v[4:5], s[0:1], v2, s70, v[66:67]
	v_mad_i32_i24 v5, v3, s70, v5
	v_lshl_add_u64 v[2:3], v[4:5], 0, v[36:37]
	v_lshl_add_u64 v[10:11], v[2:3], 0, v[72:73]
	v_cvt_pk_bf16_f32 v2, v42, v43
	v_cvt_pk_bf16_f32 v3, v44, v45
	v_cvt_pk_bf16_f32 v4, v50, v51
	v_cvt_pk_bf16_f32 v5, v52, v53
	global_store_dwordx4 v[10:11], v[2:5], off
	s_nop 1
	v_cvt_pk_bf16_f32 v2, v58, v59
	v_cvt_pk_bf16_f32 v3, v60, v61
	v_cvt_pk_bf16_f32 v4, v54, v55
	v_cvt_pk_bf16_f32 v5, v56, v57
	global_store_dwordx4 v[10:11], v[2:5], off offset:64
	s_nop 1
	v_or_b32_e32 v2, 48, v26
	v_ashrrev_i32_e32 v3, 31, v2
	v_lshl_add_u64 v[2:3], v[2:3], 0, v[98:99]
	v_mad_u64_u32 v[4:5], s[0:1], v2, s70, v[66:67]
	v_mad_i32_i24 v5, v3, s70, v5
	v_lshl_add_u64 v[2:3], v[4:5], 0, v[36:37]
	v_lshl_add_u64 v[10:11], v[2:3], 0, v[72:73]
	v_cvt_pk_bf16_f32 v2, v32, v33
	v_cvt_pk_bf16_f32 v3, v34, v35
	v_cvt_pk_bf16_f32 v4, v28, v29
	v_cvt_pk_bf16_f32 v5, v30, v31
	global_store_dwordx4 v[10:11], v[2:5], off
	s_nop 1
	v_cvt_pk_bf16_f32 v2, v22, v23
	v_cvt_pk_bf16_f32 v3, v24, v25
	v_cvt_pk_bf16_f32 v4, v6, v7
	v_cvt_pk_bf16_f32 v5, v8, v9
	global_store_dwordx4 v[10:11], v[2:5], off offset:64

.LBB0_316:
	s_mul_hi_i32 s0, s4, 0x2aaaaaab
	s_lshr_b32 s1, s0, 31
	s_add_i32 s0, s0, s1
	s_mul_i32 s1, s0, 6
	s_lshl_b32 s0, s0, 7
	v_add_u32_e32 v4, s0, v70
	v_ashrrev_i32_e32 v5, 31, v4
	v_mov_b32_e32 v14, v0
	s_sub_i32 s1, s4, s1
	v_lshlrev_b64 v[2:3], 11, v[4:5]
	v_add_u32_e32 v4, 64, v4
	v_readlane_b32 s8, v196, 6
	v_readfirstlane_b32 s4, v14
	v_ashrrev_i32_e32 v5, 31, v4
	s_lshl_b32 s1, s1, 8
	s_lshl_b32 s4, s4, 4
	v_readlane_b32 s9, v196, 7
	v_readlane_b32 s10, v196, 8
	v_readlane_b32 s11, v196, 9
	v_readlane_b32 s12, v196, 10
	v_readlane_b32 s13, v196, 11
	v_readlane_b32 s14, v196, 12
	v_readlane_b32 s15, v196, 13
	v_readlane_b32 s16, v196, 14
	v_readlane_b32 s17, v196, 15
	v_readlane_b32 s18, v196, 16
	v_readlane_b32 s19, v196, 17
	v_readlane_b32 s20, v196, 18
	v_readlane_b32 s21, v196, 19
	v_readlane_b32 s22, v196, 20
	v_readlane_b32 s23, v196, 21
	v_lshlrev_b64 v[4:5], 11, v[4:5]
	v_add_u32_e32 v6, s1, v70
	s_and_b32 s4, s4, 0xfffffc00
	v_lshl_add_u64 v[2:3], s[8:9], 0, v[2:3]
	v_lshlrev_b32_e32 v98, 1, v71
	v_lshl_add_u64 v[4:5], s[8:9], 0, v[4:5]
	v_ashrrev_i32_e32 v7, 31, v6
	v_readlane_b32 s8, v197, 34
	s_add_i32 s56, s4, 0
	v_lshl_add_u64 v[2:3], v[2:3], 0, v[98:99]
	v_lshlrev_b64 v[6:7], 11, v[6:7]
	v_readlane_b32 s10, v197, 36
	v_readlane_b32 s11, v197, 37
	s_mov_b32 m0, s56
	s_add_i32 s4, s56, 0x2000
	v_lshl_add_u64 v[4:5], v[4:5], 0, v[98:99]
	v_readlane_b32 s9, v197, 35
	v_lshl_add_u64 v[6:7], s[10:11], 0, v[6:7]
	global_load_lds_dwordx4 v[2:3], off
	s_mov_b32 m0, s4
	s_add_i32 s5, s56, 0x4000
	v_lshl_add_u64 v[6:7], v[6:7], 0, v[98:99]
	s_mov_b64 s[8:9], 0x20000
	global_load_lds_dwordx4 v[4:5], off
	s_mov_b32 m0, s5
	s_add_i32 s33, s56, 0x6000
	v_lshl_add_u64 v[8:9], v[6:7], 0, s[8:9]
	global_load_lds_dwordx4 v[6:7], off
	s_mov_b32 m0, s33
	s_add_i32 s38, s56, 0x8000
	v_lshl_add_u64 v[10:11], v[6:7], 0, s[68:69]
	s_mov_b64 s[8:9], 0x60000
	global_load_lds_dwordx4 v[8:9], off
	s_mov_b32 m0, s38
	s_add_i32 s39, s56, 0xa000
	v_lshl_add_u64 v[12:13], v[6:7], 0, s[8:9]
	global_load_lds_dwordx4 v[10:11], off
	s_mov_b32 m0, s39
	s_add_i32 s59, s56, 0xc000
	global_load_lds_dwordx4 v[12:13], off
	v_lshl_add_u64 v[8:9], v[2:3], 0, s[80:81]
	s_mov_b32 m0, s59
	s_add_i32 s57, s56, 0xe000
	global_load_lds_dwordx4 v[8:9], off
	v_lshl_add_u64 v[8:9], v[4:5], 0, s[80:81]
	s_mov_b32 m0, s57
	s_add_i32 s60, s56, 0x10000
	global_load_lds_dwordx4 v[8:9], off
	v_lshl_add_u64 v[8:9], v[6:7], 0, s[80:81]
	s_mov_b32 m0, s60
	s_mov_b64 s[8:9], 0x20080
	s_add_i32 s61, s56, 0x12000
	global_load_lds_dwordx4 v[8:9], off
	v_lshl_add_u64 v[8:9], v[6:7], 0, s[8:9]
	s_mov_b32 m0, s61
	s_mov_b64 s[8:9], 0x40080
	s_add_i32 s62, s56, 0x14000
	global_load_lds_dwordx4 v[8:9], off
	v_lshl_add_u64 v[8:9], v[6:7], 0, s[8:9]
	s_mov_b32 m0, s62
	s_mov_b64 s[8:9], 0x60080
	s_add_i32 s71, s56, 0x16000
	global_load_lds_dwordx4 v[8:9], off
	v_lshl_add_u64 v[8:9], v[6:7], 0, s[8:9]
	s_mov_b32 m0, s71
	v_lshrrev_b32_e32 v15, 4, v14
	v_bfe_u32 v16, v14, 4, 2
	v_and_b32_e32 v17, 15, v14
	global_load_lds_dwordx4 v[8:9], off
	v_bfe_u32 v8, v14, 1, 3
	v_lshrrev_b32_e32 v9, 2, v14
	v_and_or_b32 v9, v9, s79, v17
	v_lshlrev_b32_e32 v10, 7, v14
	v_bitop3_b32 v11, v15, v8, 3 bitop3:0x6c
	v_bitop3_b32 v8, v16, v8, 4 bitop3:0x36
	v_lshlrev_b32_e32 v9, 7, v9
	v_and_b32_e32 v60, 0x6780, v10
	v_lshlrev_b32_e32 v11, 4, v11
	v_lshlrev_b32_e32 v61, 4, v8
	v_add_u32_e32 v10, 0x4000, v60
	v_or_b32_e32 v80, v11, v9
	v_or_b32_e32 v96, v61, v9
	v_or_b32_e32 v9, v11, v60
	s_add_i32 s63, s56, 0x18000
	s_waitcnt vmcnt(6)
	s_barrier
	v_or_b32_e32 v81, v11, v10
	v_or_b32_e32 v97, v61, v10
	v_add_u32_e32 v8, 0, v80
	v_add_u32_e32 v9, 0, v9
	v_lshl_add_u64 v[10:11], v[2:3], 0, s[96:97]
	s_mov_b32 m0, s63
	s_add_i32 s64, s56, 0x1a000
	ds_read_b128 v[12:15], v8
	ds_read_b128 v[16:19], v8 offset:2048
	ds_read_b128 v[20:23], v8 offset:4096
	ds_read_b128 v[24:27], v8 offset:6144
	ds_read_b128 v[28:31], v9 offset:22528
	ds_read_b128 v[32:35], v9 offset:20480
	ds_read_b128 v[36:39], v9 offset:18432
	ds_read_b128 v[40:43], v9 offset:16384
	global_load_lds_dwordx4 v[10:11], off
	v_lshl_add_u64 v[10:11], v[4:5], 0, s[96:97]
	s_mov_b32 m0, s64
	s_add_i32 s72, s56, 0x1c000
	global_load_lds_dwordx4 v[10:11], off
	v_lshl_add_u64 v[10:11], v[6:7], 0, s[96:97]
	s_mov_b32 m0, s72
	s_mov_b64 s[8:9], 0x20100
	s_add_i32 s73, s56, 0x1e000
	global_load_lds_dwordx4 v[10:11], off
	v_lshl_add_u64 v[10:11], v[6:7], 0, s[8:9]
	s_mov_b32 m0, s73
	s_mov_b64 s[8:9], 0x40100
	s_add_i32 s74, s56, 0x20000
	global_load_lds_dwordx4 v[10:11], off
	v_lshl_add_u64 v[10:11], v[6:7], 0, s[8:9]
	s_mov_b32 m0, s74
	s_mov_b64 s[8:9], 0x60100
	s_add_i32 s75, s56, 0x22000
	global_load_lds_dwordx4 v[10:11], off
	v_lshl_add_u64 v[10:11], v[6:7], 0, s[8:9]
	s_mov_b32 m0, s75
	v_readlane_b32 s12, v197, 38
	global_load_lds_dwordx4 v[10:11], off
	v_or_b32_e32 v11, v61, v60
	v_add_u32_e32 v10, 0, v96
	v_add_u32_e32 v11, 0, v11
	ds_read_b128 v[44:47], v10
	ds_read_b128 v[48:51], v10 offset:2048
	ds_read_b128 v[52:55], v10 offset:4096
	ds_read_b128 v[56:59], v10 offset:6144
	ds_read_b128 v[60:63], v11 offset:16384
	ds_read_b128 v[64:67], v11 offset:18432
	ds_read_b128 v[68:71], v11 offset:20480
	ds_read_b128 v[72:75], v11 offset:22528
	v_readlane_b32 s13, v197, 39
	v_readlane_b32 s14, v197, 40
	v_readlane_b32 s15, v197, 41
	v_readlane_b32 s16, v197, 42
	v_readlane_b32 s17, v197, 43
	v_readlane_b32 s18, v197, 44
	v_readlane_b32 s19, v197, 45
	v_readlane_b32 s20, v197, 46
	v_readlane_b32 s21, v197, 47
	v_readlane_b32 s22, v197, 48
	v_readlane_b32 s23, v197, 49
	s_waitcnt lgkmcnt(8)
	v_mfma_f32_16x16x32_bf16 v[76:79], v[40:43], v[12:15], 0
	v_mfma_f32_16x16x32_bf16 v[84:87], v[36:39], v[12:15], 0
	v_mfma_f32_16x16x32_bf16 v[88:91], v[32:35], v[12:15], 0
	v_mfma_f32_16x16x32_bf16 v[92:95], v[28:31], v[12:15], 0
	v_mfma_f32_16x16x32_bf16 v[102:105], v[40:43], v[16:19], 0
	v_mfma_f32_16x16x32_bf16 v[106:109], v[36:39], v[16:19], 0
	v_mfma_f32_16x16x32_bf16 v[112:115], v[32:35], v[16:19], 0
	v_mfma_f32_16x16x32_bf16 v[14:17], v[28:31], v[16:19], 0
	v_mfma_f32_16x16x32_bf16 v[116:119], v[40:43], v[20:23], 0
	v_mfma_f32_16x16x32_bf16 v[120:123], v[36:39], v[20:23], 0
	v_mfma_f32_16x16x32_bf16 v[124:127], v[32:35], v[20:23], 0
	v_mfma_f32_16x16x32_bf16 v[18:21], v[28:31], v[20:23], 0
	v_mfma_f32_16x16x32_bf16 v[40:43], v[40:43], v[24:27], 0
	v_mfma_f32_16x16x32_bf16 v[36:39], v[36:39], v[24:27], 0
	v_mfma_f32_16x16x32_bf16 v[32:35], v[32:35], v[24:27], 0
	v_mfma_f32_16x16x32_bf16 v[22:25], v[28:31], v[24:27], 0
	s_add_i32 s76, 0, 0xc000
	s_waitcnt vmcnt(6) lgkmcnt(0)
	s_barrier
	v_add_u32_e32 v12, s76, v81
	ds_read_b128 v[26:29], v8 offset:49152
	ds_read_b128 v[128:131], v8 offset:51200
	ds_read_b128 v[132:135], v8 offset:53248
	ds_read_b128 v[138:141], v8 offset:55296
	ds_read_b128 v[142:145], v12
	ds_read_b128 v[152:155], v12 offset:2048
	ds_read_b128 v[156:159], v12 offset:4096
	ds_read_b128 v[160:163], v12 offset:6144
	v_mfma_f32_16x16x32_bf16 v[76:79], v[60:63], v[44:47], v[76:79]
	v_mfma_f32_16x16x32_bf16 v[84:87], v[64:67], v[44:47], v[84:87]
	v_mfma_f32_16x16x32_bf16 v[88:91], v[68:71], v[44:47], v[88:91]
	v_mfma_f32_16x16x32_bf16 v[44:47], v[72:75], v[44:47], v[92:95]
	v_mfma_f32_16x16x32_bf16 v[92:95], v[60:63], v[48:51], v[102:105]
	v_mfma_f32_16x16x32_bf16 v[102:105], v[64:67], v[48:51], v[106:109]
	v_mfma_f32_16x16x32_bf16 v[106:109], v[68:71], v[48:51], v[112:115]
	v_mfma_f32_16x16x32_bf16 v[14:17], v[72:75], v[48:51], v[14:17]
	v_mfma_f32_16x16x32_bf16 v[48:51], v[60:63], v[52:55], v[116:119]
	v_mfma_f32_16x16x32_bf16 v[112:115], v[64:67], v[52:55], v[120:123]
	v_mfma_f32_16x16x32_bf16 v[18:21], v[72:75], v[52:55], v[18:21]
	v_mfma_f32_16x16x32_bf16 v[40:43], v[60:63], v[56:59], v[40:43]
	v_mfma_f32_16x16x32_bf16 v[36:39], v[64:67], v[56:59], v[36:39]
	v_mfma_f32_16x16x32_bf16 v[30:33], v[68:71], v[56:59], v[32:35]
	v_mfma_f32_16x16x32_bf16 v[22:25], v[72:75], v[56:59], v[22:25]
	v_mfma_f32_16x16x32_bf16 v[116:119], v[68:71], v[52:55], v[124:127]
	s_mov_b64 s[8:9], 0x180
	s_mov_b32 m0, s56
	v_lshl_add_u64 v[34:35], v[2:3], 0, s[8:9]
	global_load_lds_dwordx4 v[34:35], off
	v_lshl_add_u64 v[34:35], v[4:5], 0, s[8:9]
	s_mov_b32 m0, s4
	v_add_u32_e32 v13, s76, v97
	global_load_lds_dwordx4 v[34:35], off
	v_lshl_add_u64 v[34:35], v[6:7], 0, s[8:9]
	s_mov_b32 m0, s5
	s_mov_b64 s[8:9], 0x20180
	global_load_lds_dwordx4 v[34:35], off
	v_lshl_add_u64 v[34:35], v[6:7], 0, s[8:9]
	s_mov_b32 m0, s33
	s_mov_b64 s[8:9], 0x40180
	global_load_lds_dwordx4 v[34:35], off
	v_lshl_add_u64 v[34:35], v[6:7], 0, s[8:9]
	s_mov_b32 m0, s38
	s_mov_b64 s[8:9], 0x60180
	global_load_lds_dwordx4 v[34:35], off
	v_lshl_add_u64 v[34:35], v[6:7], 0, s[8:9]
	s_mov_b32 m0, s39
	s_nop 0
	global_load_lds_dwordx4 v[34:35], off
	ds_read_b128 v[52:55], v10 offset:49152
	ds_read_b128 v[56:59], v10 offset:51200
	ds_read_b128 v[60:63], v10 offset:53248
	ds_read_b128 v[64:67], v10 offset:55296
	ds_read_b128 v[68:71], v13
	ds_read_b128 v[72:75], v13 offset:2048
	ds_read_b128 v[120:123], v13 offset:4096
	ds_read_b128 v[124:127], v13 offset:6144
	s_waitcnt lgkmcnt(8)
	v_mfma_f32_16x16x32_bf16 v[76:79], v[142:145], v[26:29], v[76:79]
	v_mfma_f32_16x16x32_bf16 v[84:87], v[152:155], v[26:29], v[84:87]
	v_mfma_f32_16x16x32_bf16 v[88:91], v[156:159], v[26:29], v[88:91]
	v_mfma_f32_16x16x32_bf16 v[26:29], v[160:163], v[26:29], v[44:47]
	v_mfma_f32_16x16x32_bf16 v[44:47], v[142:145], v[128:131], v[92:95]
	v_mfma_f32_16x16x32_bf16 v[92:95], v[152:155], v[128:131], v[102:105]
	v_mfma_f32_16x16x32_bf16 v[102:105], v[156:159], v[128:131], v[106:109]
	v_mfma_f32_16x16x32_bf16 v[106:109], v[160:163], v[128:131], v[14:17]
	v_mfma_f32_16x16x32_bf16 v[48:51], v[142:145], v[132:135], v[48:51]
	v_mfma_f32_16x16x32_bf16 v[112:115], v[152:155], v[132:135], v[112:115]
	v_mfma_f32_16x16x32_bf16 v[16:19], v[160:163], v[132:135], v[18:21]
	v_mfma_f32_16x16x32_bf16 v[40:43], v[142:145], v[138:141], v[40:43]
	v_mfma_f32_16x16x32_bf16 v[34:37], v[152:155], v[138:141], v[36:39]
	v_mfma_f32_16x16x32_bf16 v[30:33], v[156:159], v[138:141], v[30:33]
	v_mfma_f32_16x16x32_bf16 v[20:23], v[160:163], v[138:141], v[22:25]
	v_mfma_f32_16x16x32_bf16 v[116:119], v[156:159], v[132:135], v[116:119]
	s_add_i32 s76, 0, 0x18000
	s_waitcnt vmcnt(6) lgkmcnt(0)
	s_barrier
	v_add_u32_e32 v14, s76, v80
	v_add_u32_e32 v15, s76, v81
	ds_read_b128 v[128:131], v14
	ds_read_b128 v[132:135], v14 offset:2048
	ds_read_b128 v[138:141], v14 offset:4096
	ds_read_b128 v[142:145], v14 offset:6144
	ds_read_b128 v[152:155], v15
	ds_read_b128 v[156:159], v15 offset:2048
	ds_read_b128 v[160:163], v15 offset:4096
	ds_read_b128 v[164:167], v15 offset:6144
	v_mfma_f32_16x16x32_bf16 v[76:79], v[68:71], v[52:55], v[76:79]
	v_mfma_f32_16x16x32_bf16 v[84:87], v[72:75], v[52:55], v[84:87]
	v_mfma_f32_16x16x32_bf16 v[88:91], v[120:123], v[52:55], v[88:91]
	v_mfma_f32_16x16x32_bf16 v[24:27], v[124:127], v[52:55], v[26:29]
	v_mfma_f32_16x16x32_bf16 v[44:47], v[68:71], v[56:59], v[44:47]
	v_mfma_f32_16x16x32_bf16 v[52:55], v[72:75], v[56:59], v[92:95]
	v_mfma_f32_16x16x32_bf16 v[92:95], v[120:123], v[56:59], v[102:105]
	v_mfma_f32_16x16x32_bf16 v[56:59], v[124:127], v[56:59], v[106:109]
	v_mfma_f32_16x16x32_bf16 v[48:51], v[68:71], v[60:63], v[48:51]
	v_mfma_f32_16x16x32_bf16 v[102:105], v[72:75], v[60:63], v[112:115]
	v_mfma_f32_16x16x32_bf16 v[106:109], v[120:123], v[60:63], v[116:119]
	v_mfma_f32_16x16x32_bf16 v[60:63], v[124:127], v[60:63], v[16:19]
	v_mfma_f32_16x16x32_bf16 v[38:41], v[68:71], v[64:67], v[40:43]
	v_mfma_f32_16x16x32_bf16 v[34:37], v[72:75], v[64:67], v[34:37]
	v_mfma_f32_16x16x32_bf16 v[28:31], v[120:123], v[64:67], v[30:33]
	v_mfma_f32_16x16x32_bf16 v[18:21], v[124:127], v[64:67], v[20:23]
	s_mov_b64 s[8:9], 0x200
	s_mov_b32 m0, s59
	v_lshl_add_u64 v[16:17], v[2:3], 0, s[8:9]
	global_load_lds_dwordx4 v[16:17], off
	v_lshl_add_u64 v[16:17], v[4:5], 0, s[8:9]
	s_mov_b32 m0, s57
	s_nop 0
	global_load_lds_dwordx4 v[16:17], off
	v_lshl_add_u64 v[16:17], v[6:7], 0, s[8:9]
	s_mov_b32 m0, s60
	s_mov_b64 s[8:9], 0x20200
	global_load_lds_dwordx4 v[16:17], off
	v_lshl_add_u64 v[16:17], v[6:7], 0, s[8:9]
	s_mov_b32 m0, s61
	s_mov_b64 s[8:9], 0x40200
	global_load_lds_dwordx4 v[16:17], off
	v_lshl_add_u64 v[16:17], v[6:7], 0, s[8:9]
	s_mov_b32 m0, s62
	s_mov_b64 s[8:9], 0x60200
	global_load_lds_dwordx4 v[16:17], off
	v_lshl_add_u64 v[16:17], v[6:7], 0, s[8:9]
	s_mov_b32 m0, s71
	s_nop 0
	global_load_lds_dwordx4 v[16:17], off
	v_add_u32_e32 v16, s76, v96
	v_add_u32_e32 v17, s76, v97
	ds_read_b128 v[64:67], v16
	ds_read_b128 v[68:71], v16 offset:2048
	ds_read_b128 v[72:75], v16 offset:4096
	ds_read_b128 v[112:115], v16 offset:6144
	ds_read_b128 v[116:119], v17
	ds_read_b128 v[120:123], v17 offset:2048
	ds_read_b128 v[124:127], v17 offset:4096
	ds_read_b128 v[168:171], v17 offset:6144
	s_waitcnt lgkmcnt(8)
	v_mfma_f32_16x16x32_bf16 v[76:79], v[152:155], v[128:131], v[76:79]
	v_mfma_f32_16x16x32_bf16 v[84:87], v[156:159], v[128:131], v[84:87]
	v_mfma_f32_16x16x32_bf16 v[88:91], v[160:163], v[128:131], v[88:91]
	v_mfma_f32_16x16x32_bf16 v[22:25], v[164:167], v[128:131], v[24:27]
	v_mfma_f32_16x16x32_bf16 v[42:45], v[152:155], v[132:135], v[44:47]
	v_mfma_f32_16x16x32_bf16 v[52:55], v[156:159], v[132:135], v[52:55]
	v_mfma_f32_16x16x32_bf16 v[92:95], v[160:163], v[132:135], v[92:95]
	v_mfma_f32_16x16x32_bf16 v[56:59], v[164:167], v[132:135], v[56:59]
	v_mfma_f32_16x16x32_bf16 v[46:49], v[152:155], v[138:141], v[48:51]
	v_mfma_f32_16x16x32_bf16 v[102:105], v[156:159], v[138:141], v[102:105]
	v_mfma_f32_16x16x32_bf16 v[106:109], v[160:163], v[138:141], v[106:109]
	v_mfma_f32_16x16x32_bf16 v[60:63], v[164:167], v[138:141], v[60:63]
	v_mfma_f32_16x16x32_bf16 v[38:41], v[152:155], v[142:145], v[38:41]
	v_mfma_f32_16x16x32_bf16 v[32:35], v[156:159], v[142:145], v[34:37]
	v_mfma_f32_16x16x32_bf16 v[26:29], v[160:163], v[142:145], v[28:31]
	v_mfma_f32_16x16x32_bf16 v[18:21], v[164:167], v[142:145], v[18:21]
	s_waitcnt vmcnt(6) lgkmcnt(0)
	s_barrier
	ds_read_b128 v[128:131], v8
	ds_read_b128 v[132:135], v8 offset:2048
	ds_read_b128 v[138:141], v8 offset:4096
	ds_read_b128 v[142:145], v8 offset:6144
	ds_read_b128 v[152:155], v9 offset:16384
	ds_read_b128 v[156:159], v9 offset:18432
	ds_read_b128 v[160:163], v9 offset:20480
	ds_read_b128 v[164:167], v9 offset:22528
	v_mfma_f32_16x16x32_bf16 v[76:79], v[116:119], v[64:67], v[76:79]
	v_mfma_f32_16x16x32_bf16 v[84:87], v[120:123], v[64:67], v[84:87]
	v_mfma_f32_16x16x32_bf16 v[88:91], v[124:127], v[64:67], v[88:91]
	v_mfma_f32_16x16x32_bf16 v[22:25], v[168:171], v[64:67], v[22:25]
	v_mfma_f32_16x16x32_bf16 v[42:45], v[116:119], v[68:71], v[42:45]
	v_mfma_f32_16x16x32_bf16 v[50:53], v[120:123], v[68:71], v[52:55]
	v_mfma_f32_16x16x32_bf16 v[64:67], v[124:127], v[68:71], v[92:95]
	v_mfma_f32_16x16x32_bf16 v[54:57], v[168:171], v[68:71], v[56:59]
	v_mfma_f32_16x16x32_bf16 v[46:49], v[116:119], v[72:75], v[46:49]
	v_mfma_f32_16x16x32_bf16 v[68:71], v[120:123], v[72:75], v[102:105]
	v_mfma_f32_16x16x32_bf16 v[92:95], v[124:127], v[72:75], v[106:109]
	v_mfma_f32_16x16x32_bf16 v[58:61], v[168:171], v[72:75], v[60:63]
	v_mfma_f32_16x16x32_bf16 v[36:39], v[116:119], v[112:115], v[38:41]
	v_mfma_f32_16x16x32_bf16 v[30:33], v[120:123], v[112:115], v[32:35]
	v_mfma_f32_16x16x32_bf16 v[26:29], v[124:127], v[112:115], v[26:29]
	v_mfma_f32_16x16x32_bf16 v[18:21], v[168:171], v[112:115], v[18:21]
	s_mov_b64 s[8:9], 0x280
	s_mov_b32 m0, s63
	v_lshl_add_u64 v[34:35], v[2:3], 0, s[8:9]
	global_load_lds_dwordx4 v[34:35], off
	v_lshl_add_u64 v[34:35], v[4:5], 0, s[8:9]
	s_mov_b32 m0, s64
	s_nop 0
	global_load_lds_dwordx4 v[34:35], off
	v_lshl_add_u64 v[34:35], v[6:7], 0, s[8:9]
	s_mov_b32 m0, s72
	s_mov_b64 s[8:9], 0x20280
	global_load_lds_dwordx4 v[34:35], off
	v_lshl_add_u64 v[34:35], v[6:7], 0, s[8:9]
	s_mov_b32 m0, s73
	s_mov_b64 s[8:9], 0x40280
	global_load_lds_dwordx4 v[34:35], off
	v_lshl_add_u64 v[34:35], v[6:7], 0, s[8:9]
	s_mov_b32 m0, s74
	s_mov_b64 s[8:9], 0x60280
	global_load_lds_dwordx4 v[34:35], off
	v_lshl_add_u64 v[34:35], v[6:7], 0, s[8:9]
	s_mov_b32 m0, s75
	s_nop 0
	global_load_lds_dwordx4 v[34:35], off
	ds_read_b128 v[72:75], v10
	ds_read_b128 v[102:105], v10 offset:2048
	ds_read_b128 v[106:109], v10 offset:4096
	ds_read_b128 v[112:115], v10 offset:6144
	ds_read_b128 v[116:119], v11 offset:16384
	ds_read_b128 v[120:123], v11 offset:18432
	ds_read_b128 v[124:127], v11 offset:20480
	ds_read_b128 v[168:171], v11 offset:22528
	s_waitcnt lgkmcnt(8)
	v_mfma_f32_16x16x32_bf16 v[76:79], v[152:155], v[128:131], v[76:79]
	v_mfma_f32_16x16x32_bf16 v[84:87], v[156:159], v[128:131], v[84:87]
	v_mfma_f32_16x16x32_bf16 v[88:91], v[160:163], v[128:131], v[88:91]
	v_mfma_f32_16x16x32_bf16 v[22:25], v[164:167], v[128:131], v[22:25]
	v_mfma_f32_16x16x32_bf16 v[40:43], v[152:155], v[132:135], v[42:45]
	v_mfma_f32_16x16x32_bf16 v[50:53], v[156:159], v[132:135], v[50:53]
	v_mfma_f32_16x16x32_bf16 v[62:65], v[160:163], v[132:135], v[64:67]
	v_mfma_f32_16x16x32_bf16 v[54:57], v[164:167], v[132:135], v[54:57]
	v_mfma_f32_16x16x32_bf16 v[44:47], v[152:155], v[138:141], v[46:49]
	v_mfma_f32_16x16x32_bf16 v[66:69], v[156:159], v[138:141], v[68:71]
	v_mfma_f32_16x16x32_bf16 v[92:95], v[160:163], v[138:141], v[92:95]
	v_mfma_f32_16x16x32_bf16 v[58:61], v[164:167], v[138:141], v[58:61]
	v_mfma_f32_16x16x32_bf16 v[34:37], v[152:155], v[142:145], v[36:39]
	v_mfma_f32_16x16x32_bf16 v[30:33], v[156:159], v[142:145], v[30:33]
	v_mfma_f32_16x16x32_bf16 v[26:29], v[160:163], v[142:145], v[26:29]
	v_mfma_f32_16x16x32_bf16 v[18:21], v[164:167], v[142:145], v[18:21]
	s_waitcnt vmcnt(6) lgkmcnt(0)
	s_barrier
	ds_read_b128 v[128:131], v8 offset:49152
	ds_read_b128 v[132:135], v8 offset:51200
	ds_read_b128 v[138:141], v8 offset:53248
	ds_read_b128 v[142:145], v8 offset:55296
	ds_read_b128 v[152:155], v12
	ds_read_b128 v[156:159], v12 offset:2048
	ds_read_b128 v[160:163], v12 offset:4096
	ds_read_b128 v[164:167], v12 offset:6144
	v_mfma_f32_16x16x32_bf16 v[76:79], v[116:119], v[72:75], v[76:79]
	v_mfma_f32_16x16x32_bf16 v[84:87], v[120:123], v[72:75], v[84:87]
	v_mfma_f32_16x16x32_bf16 v[88:91], v[124:127], v[72:75], v[88:91]
	v_mfma_f32_16x16x32_bf16 v[22:25], v[168:171], v[72:75], v[22:25]
	v_mfma_f32_16x16x32_bf16 v[38:41], v[116:119], v[102:105], v[40:43]
	v_mfma_f32_16x16x32_bf16 v[48:51], v[120:123], v[102:105], v[50:53]
	v_mfma_f32_16x16x32_bf16 v[62:65], v[124:127], v[102:105], v[62:65]
	v_mfma_f32_16x16x32_bf16 v[52:55], v[168:171], v[102:105], v[54:57]
	v_mfma_f32_16x16x32_bf16 v[42:45], v[116:119], v[106:109], v[44:47]
	v_mfma_f32_16x16x32_bf16 v[66:69], v[120:123], v[106:109], v[66:69]
	v_mfma_f32_16x16x32_bf16 v[70:73], v[124:127], v[106:109], v[92:95]
	v_mfma_f32_16x16x32_bf16 v[56:59], v[168:171], v[106:109], v[58:61]
	v_mfma_f32_16x16x32_bf16 v[34:37], v[116:119], v[112:115], v[34:37]
	v_mfma_f32_16x16x32_bf16 v[30:33], v[120:123], v[112:115], v[30:33]
	v_mfma_f32_16x16x32_bf16 v[26:29], v[124:127], v[112:115], v[26:29]
	v_mfma_f32_16x16x32_bf16 v[18:21], v[168:171], v[112:115], v[18:21]
	s_mov_b64 s[8:9], 0x300
	s_mov_b32 m0, s56
	v_lshl_add_u64 v[46:47], v[2:3], 0, s[8:9]
	global_load_lds_dwordx4 v[46:47], off
	v_lshl_add_u64 v[46:47], v[4:5], 0, s[8:9]
	s_mov_b32 m0, s4
	s_nop 0
	global_load_lds_dwordx4 v[46:47], off
	v_lshl_add_u64 v[46:47], v[6:7], 0, s[8:9]
	s_mov_b32 m0, s5
	s_mov_b64 s[8:9], 0x20300
	global_load_lds_dwordx4 v[46:47], off
	v_lshl_add_u64 v[46:47], v[6:7], 0, s[8:9]
	s_mov_b32 m0, s33
	s_mov_b64 s[8:9], 0x40300
	global_load_lds_dwordx4 v[46:47], off
	v_lshl_add_u64 v[46:47], v[6:7], 0, s[8:9]
	s_mov_b32 m0, s38
	s_mov_b64 s[8:9], 0x60300
	global_load_lds_dwordx4 v[46:47], off
	v_lshl_add_u64 v[46:47], v[6:7], 0, s[8:9]
	s_mov_b32 m0, s39
	s_nop 0
	global_load_lds_dwordx4 v[46:47], off
	ds_read_b128 v[92:95], v10 offset:49152
	ds_read_b128 v[102:105], v10 offset:51200
	ds_read_b128 v[106:109], v10 offset:53248
	ds_read_b128 v[112:115], v10 offset:55296
	ds_read_b128 v[116:119], v13
	ds_read_b128 v[120:123], v13 offset:2048
	ds_read_b128 v[124:127], v13 offset:4096
	ds_read_b128 v[168:171], v13 offset:6144
	s_waitcnt lgkmcnt(8)
	v_mfma_f32_16x16x32_bf16 v[74:77], v[152:155], v[128:131], v[76:79]
	v_mfma_f32_16x16x32_bf16 v[78:81], v[156:159], v[128:131], v[84:87]
	v_mfma_f32_16x16x32_bf16 v[84:87], v[160:163], v[128:131], v[88:91]
	v_mfma_f32_16x16x32_bf16 v[22:25], v[164:167], v[128:131], v[22:25]
	v_mfma_f32_16x16x32_bf16 v[38:41], v[152:155], v[132:135], v[38:41]
	v_mfma_f32_16x16x32_bf16 v[46:49], v[156:159], v[132:135], v[48:51]
	v_mfma_f32_16x16x32_bf16 v[60:63], v[160:163], v[132:135], v[62:65]
	v_mfma_f32_16x16x32_bf16 v[50:53], v[164:167], v[132:135], v[52:55]
	v_mfma_f32_16x16x32_bf16 v[42:45], v[152:155], v[138:141], v[42:45]
	v_mfma_f32_16x16x32_bf16 v[64:67], v[156:159], v[138:141], v[66:69]
	v_mfma_f32_16x16x32_bf16 v[68:71], v[160:163], v[138:141], v[70:73]
	v_mfma_f32_16x16x32_bf16 v[54:57], v[164:167], v[138:141], v[56:59]
	v_mfma_f32_16x16x32_bf16 v[34:37], v[152:155], v[142:145], v[34:37]
	v_mfma_f32_16x16x32_bf16 v[30:33], v[156:159], v[142:145], v[30:33]
	v_mfma_f32_16x16x32_bf16 v[26:29], v[160:163], v[142:145], v[26:29]
	v_mfma_f32_16x16x32_bf16 v[18:21], v[164:167], v[142:145], v[18:21]
	s_waitcnt vmcnt(6) lgkmcnt(0)
	s_barrier
	ds_read_b128 v[88:91], v14
	ds_read_b128 v[128:131], v14 offset:2048
	ds_read_b128 v[132:135], v14 offset:4096
	ds_read_b128 v[138:141], v14 offset:6144
	ds_read_b128 v[142:145], v15
	ds_read_b128 v[152:155], v15 offset:2048
	ds_read_b128 v[156:159], v15 offset:4096
	ds_read_b128 v[160:163], v15 offset:6144
	v_mfma_f32_16x16x32_bf16 v[72:75], v[116:119], v[92:95], v[74:77]
	v_mfma_f32_16x16x32_bf16 v[76:79], v[120:123], v[92:95], v[78:81]
	v_mfma_f32_16x16x32_bf16 v[84:87], v[124:127], v[92:95], v[84:87]
	v_mfma_f32_16x16x32_bf16 v[22:25], v[168:171], v[92:95], v[22:25]
	v_mfma_f32_16x16x32_bf16 v[38:41], v[116:119], v[102:105], v[38:41]
	v_mfma_f32_16x16x32_bf16 v[46:49], v[120:123], v[102:105], v[46:49]
	v_mfma_f32_16x16x32_bf16 v[58:61], v[124:127], v[102:105], v[60:63]
	v_mfma_f32_16x16x32_bf16 v[50:53], v[168:171], v[102:105], v[50:53]
	v_mfma_f32_16x16x32_bf16 v[42:45], v[116:119], v[106:109], v[42:45]
	v_mfma_f32_16x16x32_bf16 v[62:65], v[120:123], v[106:109], v[64:67]
	v_mfma_f32_16x16x32_bf16 v[66:69], v[124:127], v[106:109], v[68:71]
	v_mfma_f32_16x16x32_bf16 v[54:57], v[168:171], v[106:109], v[54:57]
	v_mfma_f32_16x16x32_bf16 v[34:37], v[116:119], v[112:115], v[34:37]
	v_mfma_f32_16x16x32_bf16 v[30:33], v[120:123], v[112:115], v[30:33]
	v_mfma_f32_16x16x32_bf16 v[26:29], v[124:127], v[112:115], v[26:29]
	v_mfma_f32_16x16x32_bf16 v[18:21], v[168:171], v[112:115], v[18:21]
	s_mov_b64 s[8:9], 0x380
	s_mov_b32 m0, s59
	v_lshl_add_u64 v[70:71], v[2:3], 0, s[8:9]
	global_load_lds_dwordx4 v[70:71], off
	v_lshl_add_u64 v[70:71], v[4:5], 0, s[8:9]
	s_mov_b32 m0, s57
	s_nop 0
	global_load_lds_dwordx4 v[70:71], off
	v_lshl_add_u64 v[70:71], v[6:7], 0, s[8:9]
	s_mov_b32 m0, s60
	s_mov_b64 s[8:9], 0x20380
	global_load_lds_dwordx4 v[70:71], off
	v_lshl_add_u64 v[70:71], v[6:7], 0, s[8:9]
	s_mov_b32 m0, s61
	s_mov_b64 s[8:9], 0x40380
	global_load_lds_dwordx4 v[70:71], off
	v_lshl_add_u64 v[70:71], v[6:7], 0, s[8:9]
	s_mov_b32 m0, s62
	s_mov_b64 s[8:9], 0x60380
	global_load_lds_dwordx4 v[70:71], off
	v_lshl_add_u64 v[70:71], v[6:7], 0, s[8:9]
	s_mov_b32 m0, s71
	s_nop 0
	global_load_lds_dwordx4 v[70:71], off
	ds_read_b128 v[92:95], v16
	ds_read_b128 v[102:105], v16 offset:2048
	ds_read_b128 v[106:109], v16 offset:4096
	ds_read_b128 v[112:115], v16 offset:6144
	ds_read_b128 v[116:119], v17
	ds_read_b128 v[120:123], v17 offset:2048
	ds_read_b128 v[124:127], v17 offset:4096
	ds_read_b128 v[164:167], v17 offset:6144
	s_waitcnt lgkmcnt(8)
	v_mfma_f32_16x16x32_bf16 v[70:73], v[142:145], v[88:91], v[72:75]
	v_mfma_f32_16x16x32_bf16 v[74:77], v[152:155], v[88:91], v[76:79]
	v_mfma_f32_16x16x32_bf16 v[78:81], v[156:159], v[88:91], v[84:87]
	v_mfma_f32_16x16x32_bf16 v[22:25], v[160:163], v[88:91], v[22:25]
	v_mfma_f32_16x16x32_bf16 v[38:41], v[142:145], v[128:131], v[38:41]
	v_mfma_f32_16x16x32_bf16 v[46:49], v[152:155], v[128:131], v[46:49]
	v_mfma_f32_16x16x32_bf16 v[58:61], v[156:159], v[128:131], v[58:61]
	v_mfma_f32_16x16x32_bf16 v[50:53], v[160:163], v[128:131], v[50:53]
	v_mfma_f32_16x16x32_bf16 v[42:45], v[142:145], v[132:135], v[42:45]
	v_mfma_f32_16x16x32_bf16 v[62:65], v[152:155], v[132:135], v[62:65]
	v_mfma_f32_16x16x32_bf16 v[66:69], v[156:159], v[132:135], v[66:69]
	v_mfma_f32_16x16x32_bf16 v[54:57], v[160:163], v[132:135], v[54:57]
	v_mfma_f32_16x16x32_bf16 v[34:37], v[142:145], v[138:141], v[34:37]
	v_mfma_f32_16x16x32_bf16 v[30:33], v[152:155], v[138:141], v[30:33]
	v_mfma_f32_16x16x32_bf16 v[26:29], v[156:159], v[138:141], v[26:29]
	v_mfma_f32_16x16x32_bf16 v[18:21], v[160:163], v[138:141], v[18:21]
	s_waitcnt vmcnt(6) lgkmcnt(0)
	s_barrier
	ds_read_b128 v[84:87], v8
	ds_read_b128 v[88:91], v8 offset:2048
	ds_read_b128 v[128:131], v8 offset:4096
	ds_read_b128 v[132:135], v8 offset:6144
	ds_read_b128 v[138:141], v9 offset:16384
	ds_read_b128 v[142:145], v9 offset:18432
	ds_read_b128 v[152:155], v9 offset:20480
	ds_read_b128 v[156:159], v9 offset:22528
	v_mfma_f32_16x16x32_bf16 v[70:73], v[116:119], v[92:95], v[70:73]
	v_mfma_f32_16x16x32_bf16 v[74:77], v[120:123], v[92:95], v[74:77]
	v_mfma_f32_16x16x32_bf16 v[78:81], v[124:127], v[92:95], v[78:81]
	v_mfma_f32_16x16x32_bf16 v[22:25], v[164:167], v[92:95], v[22:25]
	v_mfma_f32_16x16x32_bf16 v[38:41], v[116:119], v[102:105], v[38:41]
	v_mfma_f32_16x16x32_bf16 v[46:49], v[120:123], v[102:105], v[46:49]
	v_mfma_f32_16x16x32_bf16 v[58:61], v[124:127], v[102:105], v[58:61]
	v_mfma_f32_16x16x32_bf16 v[50:53], v[164:167], v[102:105], v[50:53]
	v_mfma_f32_16x16x32_bf16 v[42:45], v[116:119], v[106:109], v[42:45]
	v_mfma_f32_16x16x32_bf16 v[62:65], v[120:123], v[106:109], v[62:65]
	v_mfma_f32_16x16x32_bf16 v[66:69], v[124:127], v[106:109], v[66:69]
	v_mfma_f32_16x16x32_bf16 v[54:57], v[164:167], v[106:109], v[54:57]
	v_mfma_f32_16x16x32_bf16 v[34:37], v[116:119], v[112:115], v[34:37]
	v_mfma_f32_16x16x32_bf16 v[30:33], v[120:123], v[112:115], v[30:33]
	v_mfma_f32_16x16x32_bf16 v[26:29], v[124:127], v[112:115], v[26:29]
	v_mfma_f32_16x16x32_bf16 v[18:21], v[164:167], v[112:115], v[18:21]
	s_mov_b64 s[8:9], 0x400
	s_mov_b32 m0, s63
	v_lshl_add_u64 v[92:93], v[2:3], 0, s[8:9]
	global_load_lds_dwordx4 v[92:93], off
	v_lshl_add_u64 v[92:93], v[4:5], 0, s[8:9]
	s_mov_b32 m0, s64
	s_nop 0
	global_load_lds_dwordx4 v[92:93], off
	v_lshl_add_u64 v[92:93], v[6:7], 0, s[8:9]
	s_mov_b32 m0, s72
	s_mov_b64 s[8:9], 0x20400
	global_load_lds_dwordx4 v[92:93], off
	v_lshl_add_u64 v[92:93], v[6:7], 0, s[8:9]
	s_mov_b32 m0, s73
	s_mov_b64 s[8:9], 0x40400
	global_load_lds_dwordx4 v[92:93], off
	v_lshl_add_u64 v[92:93], v[6:7], 0, s[8:9]
	s_mov_b32 m0, s74
	s_mov_b64 s[8:9], 0x60400
	global_load_lds_dwordx4 v[92:93], off
	v_lshl_add_u64 v[92:93], v[6:7], 0, s[8:9]
	s_mov_b32 m0, s75
	s_nop 0
	global_load_lds_dwordx4 v[92:93], off
	ds_read_b128 v[92:95], v10
	ds_read_b128 v[102:105], v10 offset:2048
	ds_read_b128 v[106:109], v10 offset:4096
	ds_read_b128 v[112:115], v10 offset:6144
	ds_read_b128 v[116:119], v11 offset:16384
	ds_read_b128 v[120:123], v11 offset:18432
	ds_read_b128 v[124:127], v11 offset:20480
	ds_read_b128 v[160:163], v11 offset:22528
	s_waitcnt lgkmcnt(8)
	v_mfma_f32_16x16x32_bf16 v[70:73], v[138:141], v[84:87], v[70:73]
	v_mfma_f32_16x16x32_bf16 v[74:77], v[142:145], v[84:87], v[74:77]
	v_mfma_f32_16x16x32_bf16 v[78:81], v[152:155], v[84:87], v[78:81]
	v_mfma_f32_16x16x32_bf16 v[22:25], v[156:159], v[84:87], v[22:25]
	v_mfma_f32_16x16x32_bf16 v[38:41], v[138:141], v[88:91], v[38:41]
	v_mfma_f32_16x16x32_bf16 v[46:49], v[142:145], v[88:91], v[46:49]
	v_mfma_f32_16x16x32_bf16 v[58:61], v[152:155], v[88:91], v[58:61]
	v_mfma_f32_16x16x32_bf16 v[50:53], v[156:159], v[88:91], v[50:53]
	v_mfma_f32_16x16x32_bf16 v[42:45], v[138:141], v[128:131], v[42:45]
	v_mfma_f32_16x16x32_bf16 v[62:65], v[142:145], v[128:131], v[62:65]
	v_mfma_f32_16x16x32_bf16 v[66:69], v[152:155], v[128:131], v[66:69]
	v_mfma_f32_16x16x32_bf16 v[54:57], v[156:159], v[128:131], v[54:57]
	v_mfma_f32_16x16x32_bf16 v[34:37], v[138:141], v[132:135], v[34:37]
	v_mfma_f32_16x16x32_bf16 v[30:33], v[142:145], v[132:135], v[30:33]
	v_mfma_f32_16x16x32_bf16 v[26:29], v[152:155], v[132:135], v[26:29]
	v_mfma_f32_16x16x32_bf16 v[18:21], v[156:159], v[132:135], v[18:21]
	s_waitcnt vmcnt(6) lgkmcnt(0)
	s_barrier
	ds_read_b128 v[84:87], v8 offset:49152
	ds_read_b128 v[88:91], v8 offset:51200
	ds_read_b128 v[128:131], v8 offset:53248
	ds_read_b128 v[132:135], v8 offset:55296
	ds_read_b128 v[138:141], v12
	ds_read_b128 v[142:145], v12 offset:2048
	ds_read_b128 v[152:155], v12 offset:4096
	ds_read_b128 v[156:159], v12 offset:6144
	v_mfma_f32_16x16x32_bf16 v[70:73], v[116:119], v[92:95], v[70:73]
	v_mfma_f32_16x16x32_bf16 v[74:77], v[120:123], v[92:95], v[74:77]
	v_mfma_f32_16x16x32_bf16 v[78:81], v[124:127], v[92:95], v[78:81]
	v_mfma_f32_16x16x32_bf16 v[22:25], v[160:163], v[92:95], v[22:25]
	v_mfma_f32_16x16x32_bf16 v[38:41], v[116:119], v[102:105], v[38:41]
	v_mfma_f32_16x16x32_bf16 v[46:49], v[120:123], v[102:105], v[46:49]
	v_mfma_f32_16x16x32_bf16 v[58:61], v[124:127], v[102:105], v[58:61]
	v_mfma_f32_16x16x32_bf16 v[50:53], v[160:163], v[102:105], v[50:53]
	v_mfma_f32_16x16x32_bf16 v[42:45], v[116:119], v[106:109], v[42:45]
	v_mfma_f32_16x16x32_bf16 v[62:65], v[120:123], v[106:109], v[62:65]
	v_mfma_f32_16x16x32_bf16 v[66:69], v[124:127], v[106:109], v[66:69]
	v_mfma_f32_16x16x32_bf16 v[54:57], v[160:163], v[106:109], v[54:57]
	v_mfma_f32_16x16x32_bf16 v[34:37], v[116:119], v[112:115], v[34:37]
	v_mfma_f32_16x16x32_bf16 v[30:33], v[120:123], v[112:115], v[30:33]
	v_mfma_f32_16x16x32_bf16 v[26:29], v[124:127], v[112:115], v[26:29]
	v_mfma_f32_16x16x32_bf16 v[18:21], v[160:163], v[112:115], v[18:21]
	s_mov_b64 s[8:9], 0x480
	s_mov_b32 m0, s56
	v_lshl_add_u64 v[92:93], v[2:3], 0, s[8:9]
	global_load_lds_dwordx4 v[92:93], off
	v_lshl_add_u64 v[92:93], v[4:5], 0, s[8:9]
	s_mov_b32 m0, s4
	s_nop 0
	global_load_lds_dwordx4 v[92:93], off
	v_lshl_add_u64 v[92:93], v[6:7], 0, s[8:9]
	s_mov_b32 m0, s5
	s_mov_b64 s[8:9], 0x20480
	global_load_lds_dwordx4 v[92:93], off
	v_lshl_add_u64 v[92:93], v[6:7], 0, s[8:9]
	s_mov_b32 m0, s33
	s_mov_b64 s[8:9], 0x40480
	global_load_lds_dwordx4 v[92:93], off
	v_lshl_add_u64 v[92:93], v[6:7], 0, s[8:9]
	s_mov_b32 m0, s38
	s_mov_b64 s[8:9], 0x60480
	global_load_lds_dwordx4 v[92:93], off
	v_lshl_add_u64 v[92:93], v[6:7], 0, s[8:9]
	s_mov_b32 m0, s39
	s_nop 0
	global_load_lds_dwordx4 v[92:93], off
	ds_read_b128 v[92:95], v10 offset:49152
	ds_read_b128 v[102:105], v10 offset:51200
	ds_read_b128 v[106:109], v10 offset:53248
	ds_read_b128 v[112:115], v10 offset:55296
	ds_read_b128 v[116:119], v13
	ds_read_b128 v[120:123], v13 offset:2048
	ds_read_b128 v[124:127], v13 offset:4096
	ds_read_b128 v[160:163], v13 offset:6144
	s_waitcnt lgkmcnt(8)
	v_mfma_f32_16x16x32_bf16 v[70:73], v[138:141], v[84:87], v[70:73]
	v_mfma_f32_16x16x32_bf16 v[74:77], v[142:145], v[84:87], v[74:77]
	v_mfma_f32_16x16x32_bf16 v[78:81], v[152:155], v[84:87], v[78:81]
	v_mfma_f32_16x16x32_bf16 v[22:25], v[156:159], v[84:87], v[22:25]
	v_mfma_f32_16x16x32_bf16 v[38:41], v[138:141], v[88:91], v[38:41]
	v_mfma_f32_16x16x32_bf16 v[46:49], v[142:145], v[88:91], v[46:49]
	v_mfma_f32_16x16x32_bf16 v[58:61], v[152:155], v[88:91], v[58:61]
	v_mfma_f32_16x16x32_bf16 v[50:53], v[156:159], v[88:91], v[50:53]
	v_mfma_f32_16x16x32_bf16 v[42:45], v[138:141], v[128:131], v[42:45]
	v_mfma_f32_16x16x32_bf16 v[62:65], v[142:145], v[128:131], v[62:65]
	v_mfma_f32_16x16x32_bf16 v[66:69], v[152:155], v[128:131], v[66:69]
	v_mfma_f32_16x16x32_bf16 v[54:57], v[156:159], v[128:131], v[54:57]
	v_mfma_f32_16x16x32_bf16 v[34:37], v[138:141], v[132:135], v[34:37]
	v_mfma_f32_16x16x32_bf16 v[30:33], v[142:145], v[132:135], v[30:33]
	v_mfma_f32_16x16x32_bf16 v[26:29], v[152:155], v[132:135], v[26:29]
	v_mfma_f32_16x16x32_bf16 v[18:21], v[156:159], v[132:135], v[18:21]
	s_waitcnt vmcnt(6) lgkmcnt(0)
	s_barrier
	ds_read_b128 v[84:87], v14
	ds_read_b128 v[88:91], v14 offset:2048
	ds_read_b128 v[128:131], v14 offset:4096
	ds_read_b128 v[132:135], v14 offset:6144
	ds_read_b128 v[138:141], v15
	ds_read_b128 v[142:145], v15 offset:2048
	ds_read_b128 v[152:155], v15 offset:4096
	ds_read_b128 v[156:159], v15 offset:6144
	v_mfma_f32_16x16x32_bf16 v[70:73], v[116:119], v[92:95], v[70:73]
	v_mfma_f32_16x16x32_bf16 v[74:77], v[120:123], v[92:95], v[74:77]
	v_mfma_f32_16x16x32_bf16 v[78:81], v[124:127], v[92:95], v[78:81]
	v_mfma_f32_16x16x32_bf16 v[22:25], v[160:163], v[92:95], v[22:25]
	v_mfma_f32_16x16x32_bf16 v[38:41], v[116:119], v[102:105], v[38:41]
	v_mfma_f32_16x16x32_bf16 v[46:49], v[120:123], v[102:105], v[46:49]
	v_mfma_f32_16x16x32_bf16 v[58:61], v[124:127], v[102:105], v[58:61]
	v_mfma_f32_16x16x32_bf16 v[50:53], v[160:163], v[102:105], v[50:53]
	v_mfma_f32_16x16x32_bf16 v[42:45], v[116:119], v[106:109], v[42:45]
	v_mfma_f32_16x16x32_bf16 v[62:65], v[120:123], v[106:109], v[62:65]
	v_mfma_f32_16x16x32_bf16 v[66:69], v[124:127], v[106:109], v[66:69]
	v_mfma_f32_16x16x32_bf16 v[54:57], v[160:163], v[106:109], v[54:57]
	v_mfma_f32_16x16x32_bf16 v[34:37], v[116:119], v[112:115], v[34:37]
	v_mfma_f32_16x16x32_bf16 v[30:33], v[120:123], v[112:115], v[30:33]
	v_mfma_f32_16x16x32_bf16 v[26:29], v[124:127], v[112:115], v[26:29]
	v_mfma_f32_16x16x32_bf16 v[18:21], v[160:163], v[112:115], v[18:21]
	s_mov_b64 s[8:9], 0x500
	s_mov_b32 m0, s59
	v_lshl_add_u64 v[92:93], v[2:3], 0, s[8:9]
	global_load_lds_dwordx4 v[92:93], off
	v_lshl_add_u64 v[92:93], v[4:5], 0, s[8:9]
	s_mov_b32 m0, s57
	s_nop 0
	global_load_lds_dwordx4 v[92:93], off
	v_lshl_add_u64 v[92:93], v[6:7], 0, s[8:9]
	s_mov_b32 m0, s60
	s_mov_b64 s[8:9], 0x20500
	global_load_lds_dwordx4 v[92:93], off
	v_lshl_add_u64 v[92:93], v[6:7], 0, s[8:9]
	s_mov_b32 m0, s61
	s_mov_b64 s[8:9], 0x40500
	global_load_lds_dwordx4 v[92:93], off
	v_lshl_add_u64 v[92:93], v[6:7], 0, s[8:9]
	s_mov_b32 m0, s62
	s_mov_b64 s[8:9], 0x60500
	global_load_lds_dwordx4 v[92:93], off
	v_lshl_add_u64 v[92:93], v[6:7], 0, s[8:9]
	s_mov_b32 m0, s71
	s_nop 0
	global_load_lds_dwordx4 v[92:93], off
	ds_read_b128 v[92:95], v16
	ds_read_b128 v[102:105], v16 offset:2048
	ds_read_b128 v[106:109], v16 offset:4096
	ds_read_b128 v[112:115], v16 offset:6144
	ds_read_b128 v[116:119], v17
	ds_read_b128 v[120:123], v17 offset:2048
	ds_read_b128 v[124:127], v17 offset:4096
	ds_read_b128 v[160:163], v17 offset:6144
	s_waitcnt lgkmcnt(8)
	v_mfma_f32_16x16x32_bf16 v[70:73], v[138:141], v[84:87], v[70:73]
	v_mfma_f32_16x16x32_bf16 v[74:77], v[142:145], v[84:87], v[74:77]
	v_mfma_f32_16x16x32_bf16 v[78:81], v[152:155], v[84:87], v[78:81]
	v_mfma_f32_16x16x32_bf16 v[22:25], v[156:159], v[84:87], v[22:25]
	v_mfma_f32_16x16x32_bf16 v[38:41], v[138:141], v[88:91], v[38:41]
	v_mfma_f32_16x16x32_bf16 v[46:49], v[142:145], v[88:91], v[46:49]
	v_mfma_f32_16x16x32_bf16 v[58:61], v[152:155], v[88:91], v[58:61]
	v_mfma_f32_16x16x32_bf16 v[50:53], v[156:159], v[88:91], v[50:53]
	v_mfma_f32_16x16x32_bf16 v[42:45], v[138:141], v[128:131], v[42:45]
	v_mfma_f32_16x16x32_bf16 v[62:65], v[142:145], v[128:131], v[62:65]
	v_mfma_f32_16x16x32_bf16 v[66:69], v[152:155], v[128:131], v[66:69]
	v_mfma_f32_16x16x32_bf16 v[54:57], v[156:159], v[128:131], v[54:57]
	v_mfma_f32_16x16x32_bf16 v[34:37], v[138:141], v[132:135], v[34:37]
	v_mfma_f32_16x16x32_bf16 v[30:33], v[142:145], v[132:135], v[30:33]
	v_mfma_f32_16x16x32_bf16 v[26:29], v[152:155], v[132:135], v[26:29]
	v_mfma_f32_16x16x32_bf16 v[18:21], v[156:159], v[132:135], v[18:21]
	s_waitcnt vmcnt(6) lgkmcnt(0)
	s_barrier
	ds_read_b128 v[84:87], v8
	ds_read_b128 v[88:91], v8 offset:2048
	ds_read_b128 v[128:131], v8 offset:4096
	ds_read_b128 v[132:135], v8 offset:6144
	ds_read_b128 v[138:141], v9 offset:16384
	ds_read_b128 v[142:145], v9 offset:18432
	ds_read_b128 v[152:155], v9 offset:20480
	ds_read_b128 v[156:159], v9 offset:22528
	v_mfma_f32_16x16x32_bf16 v[70:73], v[116:119], v[92:95], v[70:73]
	v_mfma_f32_16x16x32_bf16 v[74:77], v[120:123], v[92:95], v[74:77]
	v_mfma_f32_16x16x32_bf16 v[78:81], v[124:127], v[92:95], v[78:81]
	v_mfma_f32_16x16x32_bf16 v[22:25], v[160:163], v[92:95], v[22:25]
	v_mfma_f32_16x16x32_bf16 v[38:41], v[116:119], v[102:105], v[38:41]
	v_mfma_f32_16x16x32_bf16 v[46:49], v[120:123], v[102:105], v[46:49]
	v_mfma_f32_16x16x32_bf16 v[58:61], v[124:127], v[102:105], v[58:61]
	v_mfma_f32_16x16x32_bf16 v[50:53], v[160:163], v[102:105], v[50:53]
	v_mfma_f32_16x16x32_bf16 v[42:45], v[116:119], v[106:109], v[42:45]
	v_mfma_f32_16x16x32_bf16 v[62:65], v[120:123], v[106:109], v[62:65]
	v_mfma_f32_16x16x32_bf16 v[66:69], v[124:127], v[106:109], v[66:69]
	v_mfma_f32_16x16x32_bf16 v[54:57], v[160:163], v[106:109], v[54:57]
	v_mfma_f32_16x16x32_bf16 v[34:37], v[116:119], v[112:115], v[34:37]
	v_mfma_f32_16x16x32_bf16 v[30:33], v[120:123], v[112:115], v[30:33]
	v_mfma_f32_16x16x32_bf16 v[26:29], v[124:127], v[112:115], v[26:29]
	v_mfma_f32_16x16x32_bf16 v[18:21], v[160:163], v[112:115], v[18:21]
	s_mov_b64 s[8:9], 0x580
	s_mov_b32 m0, s63
	v_lshl_add_u64 v[92:93], v[2:3], 0, s[8:9]
	global_load_lds_dwordx4 v[92:93], off
	v_lshl_add_u64 v[92:93], v[4:5], 0, s[8:9]
	s_mov_b32 m0, s64
	s_nop 0
	global_load_lds_dwordx4 v[92:93], off
	v_lshl_add_u64 v[92:93], v[6:7], 0, s[8:9]
	s_mov_b32 m0, s72
	s_mov_b64 s[8:9], 0x20580
	global_load_lds_dwordx4 v[92:93], off
	v_lshl_add_u64 v[92:93], v[6:7], 0, s[8:9]
	s_mov_b32 m0, s73
	s_mov_b64 s[8:9], 0x40580
	global_load_lds_dwordx4 v[92:93], off
	v_lshl_add_u64 v[92:93], v[6:7], 0, s[8:9]
	s_mov_b32 m0, s74
	s_mov_b64 s[8:9], 0x60580
	global_load_lds_dwordx4 v[92:93], off
	v_lshl_add_u64 v[92:93], v[6:7], 0, s[8:9]
	s_mov_b32 m0, s75
	s_nop 0
	global_load_lds_dwordx4 v[92:93], off
	ds_read_b128 v[92:95], v10
	ds_read_b128 v[102:105], v10 offset:2048
	ds_read_b128 v[106:109], v10 offset:4096
	ds_read_b128 v[112:115], v10 offset:6144
	ds_read_b128 v[116:119], v11 offset:16384
	ds_read_b128 v[120:123], v11 offset:18432
	ds_read_b128 v[124:127], v11 offset:20480
	ds_read_b128 v[160:163], v11 offset:22528
	s_waitcnt lgkmcnt(8)
	v_mfma_f32_16x16x32_bf16 v[70:73], v[138:141], v[84:87], v[70:73]
	v_mfma_f32_16x16x32_bf16 v[74:77], v[142:145], v[84:87], v[74:77]
	v_mfma_f32_16x16x32_bf16 v[78:81], v[152:155], v[84:87], v[78:81]
	v_mfma_f32_16x16x32_bf16 v[22:25], v[156:159], v[84:87], v[22:25]
	v_mfma_f32_16x16x32_bf16 v[38:41], v[138:141], v[88:91], v[38:41]
	v_mfma_f32_16x16x32_bf16 v[46:49], v[142:145], v[88:91], v[46:49]
	v_mfma_f32_16x16x32_bf16 v[58:61], v[152:155], v[88:91], v[58:61]
	v_mfma_f32_16x16x32_bf16 v[50:53], v[156:159], v[88:91], v[50:53]
	v_mfma_f32_16x16x32_bf16 v[42:45], v[138:141], v[128:131], v[42:45]
	v_mfma_f32_16x16x32_bf16 v[62:65], v[142:145], v[128:131], v[62:65]
	v_mfma_f32_16x16x32_bf16 v[66:69], v[152:155], v[128:131], v[66:69]
	v_mfma_f32_16x16x32_bf16 v[54:57], v[156:159], v[128:131], v[54:57]
	v_mfma_f32_16x16x32_bf16 v[34:37], v[138:141], v[132:135], v[34:37]
	v_mfma_f32_16x16x32_bf16 v[30:33], v[142:145], v[132:135], v[30:33]
	v_mfma_f32_16x16x32_bf16 v[26:29], v[152:155], v[132:135], v[26:29]
	v_mfma_f32_16x16x32_bf16 v[18:21], v[156:159], v[132:135], v[18:21]
	s_waitcnt vmcnt(6) lgkmcnt(0)
	s_barrier
	ds_read_b128 v[84:87], v8 offset:49152
	ds_read_b128 v[88:91], v8 offset:51200
	ds_read_b128 v[128:131], v8 offset:53248
	ds_read_b128 v[132:135], v8 offset:55296
	ds_read_b128 v[138:141], v12
	ds_read_b128 v[142:145], v12 offset:2048
	ds_read_b128 v[152:155], v12 offset:4096
	ds_read_b128 v[156:159], v12 offset:6144
	v_mfma_f32_16x16x32_bf16 v[70:73], v[116:119], v[92:95], v[70:73]
	v_mfma_f32_16x16x32_bf16 v[74:77], v[120:123], v[92:95], v[74:77]
	v_mfma_f32_16x16x32_bf16 v[78:81], v[124:127], v[92:95], v[78:81]
	v_mfma_f32_16x16x32_bf16 v[22:25], v[160:163], v[92:95], v[22:25]
	v_mfma_f32_16x16x32_bf16 v[38:41], v[116:119], v[102:105], v[38:41]
	v_mfma_f32_16x16x32_bf16 v[46:49], v[120:123], v[102:105], v[46:49]
	v_mfma_f32_16x16x32_bf16 v[58:61], v[124:127], v[102:105], v[58:61]
	v_mfma_f32_16x16x32_bf16 v[50:53], v[160:163], v[102:105], v[50:53]
	v_mfma_f32_16x16x32_bf16 v[42:45], v[116:119], v[106:109], v[42:45]
	v_mfma_f32_16x16x32_bf16 v[62:65], v[120:123], v[106:109], v[62:65]
	v_mfma_f32_16x16x32_bf16 v[66:69], v[124:127], v[106:109], v[66:69]
	v_mfma_f32_16x16x32_bf16 v[54:57], v[160:163], v[106:109], v[54:57]
	v_mfma_f32_16x16x32_bf16 v[34:37], v[116:119], v[112:115], v[34:37]
	v_mfma_f32_16x16x32_bf16 v[30:33], v[120:123], v[112:115], v[30:33]
	v_mfma_f32_16x16x32_bf16 v[26:29], v[124:127], v[112:115], v[26:29]
	v_mfma_f32_16x16x32_bf16 v[18:21], v[160:163], v[112:115], v[18:21]
	s_mov_b64 s[8:9], 0x600
	s_mov_b32 m0, s56
	v_lshl_add_u64 v[92:93], v[2:3], 0, s[8:9]
	global_load_lds_dwordx4 v[92:93], off
	v_lshl_add_u64 v[92:93], v[4:5], 0, s[8:9]
	s_mov_b32 m0, s4
	s_nop 0
	global_load_lds_dwordx4 v[92:93], off
	v_lshl_add_u64 v[92:93], v[6:7], 0, s[8:9]
	s_mov_b32 m0, s5
	s_mov_b64 s[8:9], 0x20600
	global_load_lds_dwordx4 v[92:93], off
	v_lshl_add_u64 v[92:93], v[6:7], 0, s[8:9]
	s_mov_b32 m0, s33
	s_mov_b64 s[8:9], 0x40600
	global_load_lds_dwordx4 v[92:93], off
	v_lshl_add_u64 v[92:93], v[6:7], 0, s[8:9]
	s_mov_b32 m0, s38
	s_mov_b64 s[8:9], 0x60600
	global_load_lds_dwordx4 v[92:93], off
	v_lshl_add_u64 v[92:93], v[6:7], 0, s[8:9]
	s_mov_b32 m0, s39
	s_nop 0
	global_load_lds_dwordx4 v[92:93], off
	ds_read_b128 v[92:95], v10 offset:49152
	ds_read_b128 v[102:105], v10 offset:51200
	ds_read_b128 v[106:109], v10 offset:53248
	ds_read_b128 v[112:115], v10 offset:55296
	ds_read_b128 v[116:119], v13
	ds_read_b128 v[120:123], v13 offset:2048
	ds_read_b128 v[124:127], v13 offset:4096
	ds_read_b128 v[160:163], v13 offset:6144
	s_waitcnt lgkmcnt(8)
	v_mfma_f32_16x16x32_bf16 v[70:73], v[138:141], v[84:87], v[70:73]
	v_mfma_f32_16x16x32_bf16 v[74:77], v[142:145], v[84:87], v[74:77]
	v_mfma_f32_16x16x32_bf16 v[78:81], v[152:155], v[84:87], v[78:81]
	v_mfma_f32_16x16x32_bf16 v[22:25], v[156:159], v[84:87], v[22:25]
	v_mfma_f32_16x16x32_bf16 v[38:41], v[138:141], v[88:91], v[38:41]
	v_mfma_f32_16x16x32_bf16 v[46:49], v[142:145], v[88:91], v[46:49]
	v_mfma_f32_16x16x32_bf16 v[58:61], v[152:155], v[88:91], v[58:61]
	v_mfma_f32_16x16x32_bf16 v[50:53], v[156:159], v[88:91], v[50:53]
	v_mfma_f32_16x16x32_bf16 v[42:45], v[138:141], v[128:131], v[42:45]
	v_mfma_f32_16x16x32_bf16 v[62:65], v[142:145], v[128:131], v[62:65]
	v_mfma_f32_16x16x32_bf16 v[66:69], v[152:155], v[128:131], v[66:69]
	v_mfma_f32_16x16x32_bf16 v[54:57], v[156:159], v[128:131], v[54:57]
	v_mfma_f32_16x16x32_bf16 v[34:37], v[138:141], v[132:135], v[34:37]
	v_mfma_f32_16x16x32_bf16 v[30:33], v[142:145], v[132:135], v[30:33]
	v_mfma_f32_16x16x32_bf16 v[26:29], v[152:155], v[132:135], v[26:29]
	v_mfma_f32_16x16x32_bf16 v[18:21], v[156:159], v[132:135], v[18:21]
	s_waitcnt vmcnt(6) lgkmcnt(0)
	s_barrier
	ds_read_b128 v[84:87], v14
	ds_read_b128 v[88:91], v14 offset:2048
	ds_read_b128 v[128:131], v14 offset:4096
	ds_read_b128 v[132:135], v14 offset:6144
	ds_read_b128 v[138:141], v15
	ds_read_b128 v[142:145], v15 offset:2048
	ds_read_b128 v[152:155], v15 offset:4096
	ds_read_b128 v[156:159], v15 offset:6144
	v_mfma_f32_16x16x32_bf16 v[70:73], v[116:119], v[92:95], v[70:73]
	v_mfma_f32_16x16x32_bf16 v[74:77], v[120:123], v[92:95], v[74:77]
	v_mfma_f32_16x16x32_bf16 v[78:81], v[124:127], v[92:95], v[78:81]
	v_mfma_f32_16x16x32_bf16 v[22:25], v[160:163], v[92:95], v[22:25]
	v_mfma_f32_16x16x32_bf16 v[38:41], v[116:119], v[102:105], v[38:41]
	v_mfma_f32_16x16x32_bf16 v[46:49], v[120:123], v[102:105], v[46:49]
	v_mfma_f32_16x16x32_bf16 v[58:61], v[124:127], v[102:105], v[58:61]
	v_mfma_f32_16x16x32_bf16 v[50:53], v[160:163], v[102:105], v[50:53]
	v_mfma_f32_16x16x32_bf16 v[42:45], v[116:119], v[106:109], v[42:45]
	v_mfma_f32_16x16x32_bf16 v[62:65], v[120:123], v[106:109], v[62:65]
	v_mfma_f32_16x16x32_bf16 v[66:69], v[124:127], v[106:109], v[66:69]
	v_mfma_f32_16x16x32_bf16 v[54:57], v[160:163], v[106:109], v[54:57]
	v_mfma_f32_16x16x32_bf16 v[34:37], v[116:119], v[112:115], v[34:37]
	v_mfma_f32_16x16x32_bf16 v[30:33], v[120:123], v[112:115], v[30:33]
	v_mfma_f32_16x16x32_bf16 v[26:29], v[124:127], v[112:115], v[26:29]
	v_mfma_f32_16x16x32_bf16 v[18:21], v[160:163], v[112:115], v[18:21]
	s_mov_b64 s[8:9], 0x680
	s_mov_b32 m0, s59
	v_lshl_add_u64 v[92:93], v[2:3], 0, s[8:9]
	global_load_lds_dwordx4 v[92:93], off
	v_lshl_add_u64 v[92:93], v[4:5], 0, s[8:9]
	s_mov_b32 m0, s57
	s_nop 0
	global_load_lds_dwordx4 v[92:93], off
	v_lshl_add_u64 v[92:93], v[6:7], 0, s[8:9]
	s_mov_b32 m0, s60
	s_mov_b64 s[8:9], 0x20680
	global_load_lds_dwordx4 v[92:93], off
	v_lshl_add_u64 v[92:93], v[6:7], 0, s[8:9]
	s_mov_b32 m0, s61
	s_mov_b64 s[8:9], 0x40680
	global_load_lds_dwordx4 v[92:93], off
	v_lshl_add_u64 v[92:93], v[6:7], 0, s[8:9]
	s_mov_b32 m0, s62
	s_mov_b64 s[8:9], 0x60680
	global_load_lds_dwordx4 v[92:93], off
	v_lshl_add_u64 v[92:93], v[6:7], 0, s[8:9]
	s_mov_b32 m0, s71
	s_nop 0
	global_load_lds_dwordx4 v[92:93], off
	s_mov_b64 s[8:9], exec
	v_readlane_b32 s10, v197, 0
	v_readlane_b32 s11, v197, 1
	s_and_b64 s[10:11], s[8:9], s[10:11]
	s_mov_b64 exec, s[10:11]
	s_cbranch_execz .Ldq_skip4
	v_mov_b32_e32 v251, 0
	v_mov_b32_e32 v252, 1
	global_atomic_add v250, v251, v252, s[92:93] offset:8 sc0
.Ldq_skip4:
	s_mov_b64 exec, s[8:9]
	s_mov_b32 s99, 1
	ds_read_b128 v[92:95], v16
	ds_read_b128 v[102:105], v16 offset:2048
	ds_read_b128 v[106:109], v16 offset:4096
	ds_read_b128 v[112:115], v16 offset:6144
	ds_read_b128 v[116:119], v17
	ds_read_b128 v[120:123], v17 offset:2048
	ds_read_b128 v[124:127], v17 offset:4096
	ds_read_b128 v[160:163], v17 offset:6144
	s_waitcnt lgkmcnt(8)
	v_mfma_f32_16x16x32_bf16 v[70:73], v[138:141], v[84:87], v[70:73]
	v_mfma_f32_16x16x32_bf16 v[74:77], v[142:145], v[84:87], v[74:77]
	v_mfma_f32_16x16x32_bf16 v[78:81], v[152:155], v[84:87], v[78:81]
	v_mfma_f32_16x16x32_bf16 v[22:25], v[156:159], v[84:87], v[22:25]
	v_mfma_f32_16x16x32_bf16 v[38:41], v[138:141], v[88:91], v[38:41]
	v_mfma_f32_16x16x32_bf16 v[46:49], v[142:145], v[88:91], v[46:49]
	v_mfma_f32_16x16x32_bf16 v[58:61], v[152:155], v[88:91], v[58:61]
	v_mfma_f32_16x16x32_bf16 v[50:53], v[156:159], v[88:91], v[50:53]
	v_mfma_f32_16x16x32_bf16 v[42:45], v[138:141], v[128:131], v[42:45]
	v_mfma_f32_16x16x32_bf16 v[62:65], v[142:145], v[128:131], v[62:65]
	v_mfma_f32_16x16x32_bf16 v[66:69], v[152:155], v[128:131], v[66:69]
	v_mfma_f32_16x16x32_bf16 v[54:57], v[156:159], v[128:131], v[54:57]
	v_mfma_f32_16x16x32_bf16 v[34:37], v[138:141], v[132:135], v[34:37]
	v_mfma_f32_16x16x32_bf16 v[30:33], v[142:145], v[132:135], v[30:33]
	v_mfma_f32_16x16x32_bf16 v[26:29], v[152:155], v[132:135], v[26:29]
	v_mfma_f32_16x16x32_bf16 v[18:21], v[156:159], v[132:135], v[18:21]
	s_waitcnt vmcnt(6) lgkmcnt(0)
	s_barrier
	ds_read_b128 v[84:87], v8
	ds_read_b128 v[88:91], v8 offset:2048
	ds_read_b128 v[128:131], v8 offset:4096
	ds_read_b128 v[132:135], v8 offset:6144
	ds_read_b128 v[138:141], v9 offset:16384
	ds_read_b128 v[142:145], v9 offset:18432
	ds_read_b128 v[152:155], v9 offset:20480
	ds_read_b128 v[156:159], v9 offset:22528
	v_mfma_f32_16x16x32_bf16 v[70:73], v[116:119], v[92:95], v[70:73]
	v_mfma_f32_16x16x32_bf16 v[74:77], v[120:123], v[92:95], v[74:77]
	v_mfma_f32_16x16x32_bf16 v[78:81], v[124:127], v[92:95], v[78:81]
	v_mfma_f32_16x16x32_bf16 v[22:25], v[160:163], v[92:95], v[22:25]
	v_mfma_f32_16x16x32_bf16 v[38:41], v[116:119], v[102:105], v[38:41]
	v_mfma_f32_16x16x32_bf16 v[46:49], v[120:123], v[102:105], v[46:49]
	v_mfma_f32_16x16x32_bf16 v[58:61], v[124:127], v[102:105], v[58:61]
	v_mfma_f32_16x16x32_bf16 v[50:53], v[160:163], v[102:105], v[50:53]
	v_mfma_f32_16x16x32_bf16 v[42:45], v[116:119], v[106:109], v[42:45]
	v_mfma_f32_16x16x32_bf16 v[62:65], v[120:123], v[106:109], v[62:65]
	v_mfma_f32_16x16x32_bf16 v[66:69], v[124:127], v[106:109], v[66:69]
	v_mfma_f32_16x16x32_bf16 v[54:57], v[160:163], v[106:109], v[54:57]
	v_mfma_f32_16x16x32_bf16 v[34:37], v[116:119], v[112:115], v[34:37]
	v_mfma_f32_16x16x32_bf16 v[30:33], v[120:123], v[112:115], v[30:33]
	v_mfma_f32_16x16x32_bf16 v[26:29], v[124:127], v[112:115], v[26:29]
	v_mfma_f32_16x16x32_bf16 v[18:21], v[160:163], v[112:115], v[18:21]
	s_mov_b64 s[8:9], 0x700
	s_mov_b32 m0, s63
	v_lshl_add_u64 v[92:93], v[2:3], 0, s[8:9]
	global_load_lds_dwordx4 v[92:93], off
	v_lshl_add_u64 v[92:93], v[4:5], 0, s[8:9]
	s_mov_b32 m0, s64
	s_nop 0
	global_load_lds_dwordx4 v[92:93], off
	v_lshl_add_u64 v[92:93], v[6:7], 0, s[8:9]
	s_mov_b32 m0, s72
	s_mov_b64 s[8:9], 0x20700
	global_load_lds_dwordx4 v[92:93], off
	v_lshl_add_u64 v[92:93], v[6:7], 0, s[8:9]
	s_mov_b32 m0, s73
	s_mov_b64 s[8:9], 0x40700
	global_load_lds_dwordx4 v[92:93], off
	v_lshl_add_u64 v[92:93], v[6:7], 0, s[8:9]
	s_mov_b32 m0, s74
	s_mov_b64 s[8:9], 0x60700
	global_load_lds_dwordx4 v[92:93], off
	v_lshl_add_u64 v[92:93], v[6:7], 0, s[8:9]
	s_mov_b32 m0, s75
	s_nop 0
	global_load_lds_dwordx4 v[92:93], off
	ds_read_b128 v[92:95], v10
	ds_read_b128 v[102:105], v10 offset:2048
	ds_read_b128 v[106:109], v10 offset:4096
	ds_read_b128 v[112:115], v10 offset:6144
	ds_read_b128 v[116:119], v11 offset:16384
	ds_read_b128 v[120:123], v11 offset:18432
	ds_read_b128 v[124:127], v11 offset:20480
	ds_read_b128 v[160:163], v11 offset:22528
	s_waitcnt lgkmcnt(8)
	v_mfma_f32_16x16x32_bf16 v[70:73], v[138:141], v[84:87], v[70:73]
	v_mfma_f32_16x16x32_bf16 v[74:77], v[142:145], v[84:87], v[74:77]
	v_mfma_f32_16x16x32_bf16 v[78:81], v[152:155], v[84:87], v[78:81]
	v_mfma_f32_16x16x32_bf16 v[22:25], v[156:159], v[84:87], v[22:25]
	v_mfma_f32_16x16x32_bf16 v[38:41], v[138:141], v[88:91], v[38:41]
	v_mfma_f32_16x16x32_bf16 v[46:49], v[142:145], v[88:91], v[46:49]
	v_mfma_f32_16x16x32_bf16 v[58:61], v[152:155], v[88:91], v[58:61]
	v_mfma_f32_16x16x32_bf16 v[50:53], v[156:159], v[88:91], v[50:53]
	v_mfma_f32_16x16x32_bf16 v[42:45], v[138:141], v[128:131], v[42:45]
	v_mfma_f32_16x16x32_bf16 v[62:65], v[142:145], v[128:131], v[62:65]
	v_mfma_f32_16x16x32_bf16 v[66:69], v[152:155], v[128:131], v[66:69]
	v_mfma_f32_16x16x32_bf16 v[54:57], v[156:159], v[128:131], v[54:57]
	v_mfma_f32_16x16x32_bf16 v[34:37], v[138:141], v[132:135], v[34:37]
	v_mfma_f32_16x16x32_bf16 v[30:33], v[142:145], v[132:135], v[30:33]
	v_mfma_f32_16x16x32_bf16 v[26:29], v[152:155], v[132:135], v[26:29]
	v_mfma_f32_16x16x32_bf16 v[18:21], v[156:159], v[132:135], v[18:21]
	s_waitcnt vmcnt(6) lgkmcnt(0)
	s_barrier
	ds_read_b128 v[84:87], v8 offset:49152
	ds_read_b128 v[88:91], v8 offset:51200
	ds_read_b128 v[128:131], v8 offset:53248
	ds_read_b128 v[132:135], v8 offset:55296
	ds_read_b128 v[138:141], v12
	ds_read_b128 v[142:145], v12 offset:2048
	ds_read_b128 v[152:155], v12 offset:4096
	ds_read_b128 v[156:159], v12 offset:6144
	v_mfma_f32_16x16x32_bf16 v[70:73], v[116:119], v[92:95], v[70:73]
	v_mfma_f32_16x16x32_bf16 v[74:77], v[120:123], v[92:95], v[74:77]
	v_mfma_f32_16x16x32_bf16 v[78:81], v[124:127], v[92:95], v[78:81]
	v_mfma_f32_16x16x32_bf16 v[22:25], v[160:163], v[92:95], v[22:25]
	v_mfma_f32_16x16x32_bf16 v[38:41], v[116:119], v[102:105], v[38:41]
	v_mfma_f32_16x16x32_bf16 v[46:49], v[120:123], v[102:105], v[46:49]
	v_mfma_f32_16x16x32_bf16 v[58:61], v[124:127], v[102:105], v[58:61]
	v_mfma_f32_16x16x32_bf16 v[50:53], v[160:163], v[102:105], v[50:53]
	v_mfma_f32_16x16x32_bf16 v[42:45], v[116:119], v[106:109], v[42:45]
	v_mfma_f32_16x16x32_bf16 v[62:65], v[120:123], v[106:109], v[62:65]
	v_mfma_f32_16x16x32_bf16 v[66:69], v[124:127], v[106:109], v[66:69]
	v_mfma_f32_16x16x32_bf16 v[54:57], v[160:163], v[106:109], v[54:57]
	v_mfma_f32_16x16x32_bf16 v[34:37], v[116:119], v[112:115], v[34:37]
	v_mfma_f32_16x16x32_bf16 v[30:33], v[120:123], v[112:115], v[30:33]
	v_mfma_f32_16x16x32_bf16 v[26:29], v[124:127], v[112:115], v[26:29]
	v_mfma_f32_16x16x32_bf16 v[18:21], v[160:163], v[112:115], v[18:21]
	s_mov_b64 s[8:9], 0x780
	s_mov_b32 m0, s56
	v_lshl_add_u64 v[2:3], v[2:3], 0, s[8:9]
	global_load_lds_dwordx4 v[2:3], off
	v_lshl_add_u64 v[2:3], v[4:5], 0, s[8:9]
	s_mov_b32 m0, s4
	s_nop 0
	global_load_lds_dwordx4 v[2:3], off
	v_lshl_add_u64 v[2:3], v[6:7], 0, s[8:9]
	s_mov_b32 m0, s5
	s_mov_b64 s[4:5], 0x20780
	global_load_lds_dwordx4 v[2:3], off
	v_lshl_add_u64 v[2:3], v[6:7], 0, s[4:5]
	s_mov_b32 m0, s33
	s_mov_b64 s[4:5], 0x40780
	global_load_lds_dwordx4 v[2:3], off
	v_lshl_add_u64 v[2:3], v[6:7], 0, s[4:5]
	s_mov_b32 m0, s38
	s_mov_b64 s[4:5], 0x60780
	global_load_lds_dwordx4 v[2:3], off
	v_lshl_add_u64 v[2:3], v[6:7], 0, s[4:5]
	s_mov_b32 m0, s39
	s_nop 0
	global_load_lds_dwordx4 v[2:3], off
	ds_read_b128 v[2:5], v10 offset:49152
	ds_read_b128 v[92:95], v10 offset:51200
	ds_read_b128 v[102:105], v10 offset:53248
	ds_read_b128 v[106:109], v10 offset:55296
	ds_read_b128 v[112:115], v13
	ds_read_b128 v[116:119], v13 offset:2048
	ds_read_b128 v[120:123], v13 offset:4096
	ds_read_b128 v[124:127], v13 offset:6144
	s_waitcnt lgkmcnt(8)
	v_mfma_f32_16x16x32_bf16 v[70:73], v[138:141], v[84:87], v[70:73]
	v_mfma_f32_16x16x32_bf16 v[74:77], v[142:145], v[84:87], v[74:77]
	v_mfma_f32_16x16x32_bf16 v[78:81], v[152:155], v[84:87], v[78:81]
	v_mfma_f32_16x16x32_bf16 v[22:25], v[156:159], v[84:87], v[22:25]
	v_mfma_f32_16x16x32_bf16 v[38:41], v[138:141], v[88:91], v[38:41]
	v_mfma_f32_16x16x32_bf16 v[46:49], v[142:145], v[88:91], v[46:49]
	v_mfma_f32_16x16x32_bf16 v[58:61], v[152:155], v[88:91], v[58:61]
	v_mfma_f32_16x16x32_bf16 v[50:53], v[156:159], v[88:91], v[50:53]
	v_mfma_f32_16x16x32_bf16 v[42:45], v[138:141], v[128:131], v[42:45]
	v_mfma_f32_16x16x32_bf16 v[62:65], v[142:145], v[128:131], v[62:65]
	v_mfma_f32_16x16x32_bf16 v[66:69], v[152:155], v[128:131], v[66:69]
	v_mfma_f32_16x16x32_bf16 v[54:57], v[156:159], v[128:131], v[54:57]
	v_mfma_f32_16x16x32_bf16 v[34:37], v[138:141], v[132:135], v[34:37]
	v_mfma_f32_16x16x32_bf16 v[30:33], v[142:145], v[132:135], v[30:33]
	v_mfma_f32_16x16x32_bf16 v[26:29], v[152:155], v[132:135], v[26:29]
	v_mfma_f32_16x16x32_bf16 v[18:21], v[156:159], v[132:135], v[18:21]
	s_waitcnt vmcnt(6) lgkmcnt(0)
	s_barrier
	ds_read_b128 v[84:87], v14
	ds_read_b128 v[88:91], v14 offset:2048
	ds_read_b128 v[128:131], v14 offset:4096
	ds_read_b128 v[132:135], v14 offset:6144
	ds_read_b128 v[138:141], v15
	ds_read_b128 v[142:145], v15 offset:2048
	ds_read_b128 v[152:155], v15 offset:4096
	ds_read_b128 v[12:15], v15 offset:6144
	v_mfma_f32_16x16x32_bf16 v[70:73], v[112:115], v[2:5], v[70:73]
	v_mfma_f32_16x16x32_bf16 v[74:77], v[116:119], v[2:5], v[74:77]
	v_mfma_f32_16x16x32_bf16 v[78:81], v[120:123], v[2:5], v[78:81]
	v_mfma_f32_16x16x32_bf16 v[2:5], v[124:127], v[2:5], v[22:25]
	v_mfma_f32_16x16x32_bf16 v[22:25], v[112:115], v[92:95], v[38:41]
	v_mfma_f32_16x16x32_bf16 v[38:41], v[116:119], v[92:95], v[46:49]
	v_mfma_f32_16x16x32_bf16 v[46:49], v[120:123], v[92:95], v[58:61]
	v_mfma_f32_16x16x32_bf16 v[50:53], v[124:127], v[92:95], v[50:53]
	v_mfma_f32_16x16x32_bf16 v[42:45], v[112:115], v[102:105], v[42:45]
	v_mfma_f32_16x16x32_bf16 v[58:61], v[116:119], v[102:105], v[62:65]
	v_mfma_f32_16x16x32_bf16 v[62:65], v[120:123], v[102:105], v[66:69]
	v_mfma_f32_16x16x32_bf16 v[54:57], v[124:127], v[102:105], v[54:57]
	v_mfma_f32_16x16x32_bf16 v[34:37], v[112:115], v[106:109], v[34:37]
	v_mfma_f32_16x16x32_bf16 v[30:33], v[116:119], v[106:109], v[30:33]
	v_mfma_f32_16x16x32_bf16 v[26:29], v[120:123], v[106:109], v[26:29]
	v_mfma_f32_16x16x32_bf16 v[18:21], v[124:127], v[106:109], v[18:21]
	ds_read_b128 v[66:69], v16
	ds_read_b128 v[92:95], v16 offset:2048
	ds_read_b128 v[102:105], v16 offset:4096
	ds_read_b128 v[106:109], v16 offset:6144
	ds_read_b128 v[112:115], v17
	ds_read_b128 v[116:119], v17 offset:2048
	ds_read_b128 v[120:123], v17 offset:4096
	ds_read_b128 v[124:127], v17 offset:6144
	s_waitcnt lgkmcnt(8)
	v_mfma_f32_16x16x32_bf16 v[70:73], v[138:141], v[84:87], v[70:73]
	v_mfma_f32_16x16x32_bf16 v[74:77], v[142:145], v[84:87], v[74:77]
	v_mfma_f32_16x16x32_bf16 v[78:81], v[152:155], v[84:87], v[78:81]
	v_mfma_f32_16x16x32_bf16 v[2:5], v[12:15], v[84:87], v[2:5]
	v_mfma_f32_16x16x32_bf16 v[22:25], v[138:141], v[88:91], v[22:25]
	v_mfma_f32_16x16x32_bf16 v[38:41], v[142:145], v[88:91], v[38:41]
	v_mfma_f32_16x16x32_bf16 v[46:49], v[152:155], v[88:91], v[46:49]
	v_mfma_f32_16x16x32_bf16 v[50:53], v[12:15], v[88:91], v[50:53]
	v_mfma_f32_16x16x32_bf16 v[42:45], v[138:141], v[128:131], v[42:45]
	v_mfma_f32_16x16x32_bf16 v[58:61], v[142:145], v[128:131], v[58:61]
	v_mfma_f32_16x16x32_bf16 v[62:65], v[152:155], v[128:131], v[62:65]
	v_mfma_f32_16x16x32_bf16 v[54:57], v[12:15], v[128:131], v[54:57]
	v_mfma_f32_16x16x32_bf16 v[34:37], v[138:141], v[132:135], v[34:37]
	v_mfma_f32_16x16x32_bf16 v[30:33], v[142:145], v[132:135], v[30:33]
	v_mfma_f32_16x16x32_bf16 v[26:29], v[152:155], v[132:135], v[26:29]
	v_mfma_f32_16x16x32_bf16 v[12:15], v[12:15], v[132:135], v[18:21]
	s_waitcnt vmcnt(0) lgkmcnt(0)
	s_barrier
	s_nop 1
	ds_read_b128 v[16:19], v8
	ds_read_b128 v[84:87], v8 offset:2048
	ds_read_b128 v[88:91], v8 offset:4096
	ds_read_b128 v[128:131], v8 offset:6144
	ds_read_b128 v[132:135], v9 offset:16384
	ds_read_b128 v[138:141], v9 offset:18432
	ds_read_b128 v[142:145], v9 offset:20480
	ds_read_b128 v[6:9], v9 offset:22528
	v_mfma_f32_16x16x32_bf16 v[70:73], v[112:115], v[66:69], v[70:73]
	v_mfma_f32_16x16x32_bf16 v[74:77], v[116:119], v[66:69], v[74:77]
	v_mfma_f32_16x16x32_bf16 v[78:81], v[120:123], v[66:69], v[78:81]
	v_mfma_f32_16x16x32_bf16 v[2:5], v[124:127], v[66:69], v[2:5]
	v_mfma_f32_16x16x32_bf16 v[20:23], v[112:115], v[92:95], v[22:25]
	v_mfma_f32_16x16x32_bf16 v[38:41], v[116:119], v[92:95], v[38:41]
	v_mfma_f32_16x16x32_bf16 v[46:49], v[120:123], v[92:95], v[46:49]
	v_mfma_f32_16x16x32_bf16 v[50:53], v[124:127], v[92:95], v[50:53]
	v_mfma_f32_16x16x32_bf16 v[42:45], v[112:115], v[102:105], v[42:45]
	v_mfma_f32_16x16x32_bf16 v[58:61], v[116:119], v[102:105], v[58:61]
	v_mfma_f32_16x16x32_bf16 v[62:65], v[120:123], v[102:105], v[62:65]
	v_mfma_f32_16x16x32_bf16 v[54:57], v[124:127], v[102:105], v[54:57]
	v_mfma_f32_16x16x32_bf16 v[34:37], v[112:115], v[106:109], v[34:37]
	v_mfma_f32_16x16x32_bf16 v[30:33], v[116:119], v[106:109], v[30:33]
	v_mfma_f32_16x16x32_bf16 v[24:27], v[120:123], v[106:109], v[26:29]
	v_mfma_f32_16x16x32_bf16 v[12:15], v[124:127], v[106:109], v[12:15]
	ds_read_b128 v[66:69], v10
	ds_read_b128 v[92:95], v10 offset:2048
	ds_read_b128 v[102:105], v10 offset:4096
	ds_read_b128 v[106:109], v10 offset:6144
	ds_read_b128 v[112:115], v11 offset:16384
	ds_read_b128 v[116:119], v11 offset:18432
	ds_read_b128 v[120:123], v11 offset:20480
	ds_read_b128 v[124:127], v11 offset:22528
	s_waitcnt lgkmcnt(8)
	v_mfma_f32_16x16x32_bf16 v[70:73], v[132:135], v[16:19], v[70:73]
	v_mfma_f32_16x16x32_bf16 v[74:77], v[138:141], v[16:19], v[74:77]
	v_mfma_f32_16x16x32_bf16 v[152:155], v[142:145], v[16:19], v[78:81]
	v_mfma_f32_16x16x32_bf16 v[2:5], v[6:9], v[16:19], v[2:5]
	v_mfma_f32_16x16x32_bf16 v[16:19], v[132:135], v[84:87], v[20:23]
	v_mfma_f32_16x16x32_bf16 v[20:23], v[138:141], v[84:87], v[38:41]
	v_mfma_f32_16x16x32_bf16 v[38:41], v[142:145], v[84:87], v[46:49]
	v_mfma_f32_16x16x32_bf16 v[46:49], v[6:9], v[84:87], v[50:53]
	v_mfma_f32_16x16x32_bf16 v[42:45], v[132:135], v[88:91], v[42:45]
	v_mfma_f32_16x16x32_bf16 v[84:87], v[138:141], v[88:91], v[58:61]
	v_mfma_f32_16x16x32_bf16 v[156:159], v[142:145], v[88:91], v[62:65]
	v_mfma_f32_16x16x32_bf16 v[88:91], v[6:9], v[88:91], v[54:57]
	v_mfma_f32_16x16x32_bf16 v[28:31], v[138:141], v[128:131], v[30:33]
	v_mfma_f32_16x16x32_bf16 v[24:27], v[142:145], v[128:131], v[24:27]
	v_mfma_f32_16x16x32_bf16 v[132:135], v[132:135], v[128:131], v[34:37]
	v_mfma_f32_16x16x32_bf16 v[128:131], v[6:9], v[128:131], v[12:15]
	s_waitcnt vmcnt(0) lgkmcnt(0)
	s_barrier
	v_mfma_f32_16x16x32_bf16 v[78:81], v[112:115], v[66:69], v[70:73]
	v_mfma_f32_16x16x32_bf16 v[74:77], v[116:119], v[66:69], v[74:77]
	v_mfma_f32_16x16x32_bf16 v[70:73], v[120:123], v[66:69], v[152:155]
	v_mfma_f32_16x16x32_bf16 v[66:69], v[124:127], v[66:69], v[2:5]
	v_mfma_f32_16x16x32_bf16 v[62:65], v[112:115], v[92:95], v[16:19]
	v_mfma_f32_16x16x32_bf16 v[58:61], v[116:119], v[92:95], v[20:23]
	v_mfma_f32_16x16x32_bf16 v[54:57], v[120:123], v[92:95], v[38:41]
	v_mfma_f32_16x16x32_bf16 v[50:53], v[124:127], v[92:95], v[46:49]
	v_mfma_f32_16x16x32_bf16 v[46:49], v[112:115], v[102:105], v[42:45]
	v_mfma_f32_16x16x32_bf16 v[42:45], v[116:119], v[102:105], v[84:87]
	v_mfma_f32_16x16x32_bf16 v[38:41], v[120:123], v[102:105], v[156:159]
	v_mfma_f32_16x16x32_bf16 v[34:37], v[124:127], v[102:105], v[88:91]
	v_mfma_f32_16x16x32_bf16 v[14:17], v[112:115], v[106:109], v[132:135]
	v_mfma_f32_16x16x32_bf16 v[10:13], v[116:119], v[106:109], v[28:31]
	v_mfma_f32_16x16x32_bf16 v[6:9], v[120:123], v[106:109], v[24:27]
	v_mfma_f32_16x16x32_bf16 v[2:5], v[124:127], v[106:109], v[128:131]
	v_readlane_b32 s8, v197, 2
	v_lshl_or_b32 v100, v83, 6, s1
	v_readlane_b32 s11, v197, 5
	v_readlane_b32 s13, v197, 7
	s_movk_i32 s1, 0x300
	v_readlane_b32 s10, v197, 4
	v_readlane_b32 s12, v197, 6
	v_mov_b32_e32 v18, s13
	v_mov_b32_e32 v19, s11
	v_cmp_gt_i32_e32 vcc, s1, v100
	v_lshl_add_u32 v98, v82, 6, s0
	v_mov_b32_e32 v20, s10
	v_cndmask_b32_e32 v19, v18, v19, vcc
	v_mov_b32_e32 v18, s12
	v_and_b32_e32 v82, 0xfc0, v98
	v_mov_b32_e32 v83, v99
	v_cndmask_b32_e32 v18, v18, v20, vcc
	v_lshlrev_b32_e32 v84, 4, v110
	v_mov_b32_e32 v85, v99
	v_lshl_add_u64 v[86:87], s[46:47], 0, v[82:83]
	v_lshl_add_u64 v[82:83], s[34:35], 0, v[82:83]
	s_waitcnt lgkmcnt(0)
	s_barrier
	v_lshl_add_u64 v[18:19], v[18:19], 0, v[84:85]
	v_lshl_add_u64 v[106:107], v[82:83], 0, v[84:85]
	v_lshlrev_b32_e32 v82, 6, v101
	v_mov_b32_e32 v83, v99
	global_load_dwordx4 v[30:33], v[18:19], off
	global_load_dwordx4 v[26:29], v[18:19], off offset:64
	global_load_dwordx4 v[22:25], v[18:19], off offset:128
	s_nop 0
	global_load_dwordx4 v[18:21], v[18:19], off offset:192
	v_lshl_add_u64 v[104:105], v[86:87], 0, v[84:85]
	v_lshl_add_u64 v[86:87], s[46:47], 0, v[82:83]
	v_lshl_add_u64 v[82:83], s[34:35], 0, v[82:83]
	v_lshl_add_u64 v[86:87], v[86:87], 0, v[84:85]
	v_lshl_add_u64 v[82:83], v[82:83], 0, v[84:85]
	global_load_dwordx4 v[90:93], v[104:105], off
	global_load_dwordx4 v[94:97], v[106:107], off
	s_nop 0
	global_load_dwordx4 v[86:89], v[86:87], off
	s_nop 0
	global_load_dwordx4 v[82:85], v[82:83], off
	v_and_b32_e32 v102, 64, v150
	v_mov_b32_e32 v108, v79
	v_mov_b32_e32 v109, v75
	v_add_u32_e32 v112, 64, v102
	v_mov_b32_e32 v102, v78
	v_mov_b32_e32 v103, v74
	v_pk_mul_f32 v[108:109], v[108:109], v[108:109]
	v_mov_b32_e32 v114, v71
	v_pk_fma_f32 v[102:103], v[102:103], v[102:103], v[108:109]
	v_mov_b32_e32 v108, v80
	v_mov_b32_e32 v109, v76
	v_pk_fma_f32 v[102:103], v[108:109], v[108:109], v[102:103]
	v_mov_b32_e32 v108, v81
	v_mov_b32_e32 v109, v77
	v_mov_b32_e32 v115, v67
	s_movk_i32 s0, 0x2ff
	v_or_b32_e32 v113, v98, v101
	v_xor_b32_e32 v101, 16, v150
	v_pk_fma_f32 v[102:103], v[108:109], v[108:109], v[102:103]
	v_mov_b32_e32 v108, v70
	v_mov_b32_e32 v109, v66
	v_pk_mul_f32 v[114:115], v[114:115], v[114:115]
	v_cmp_lt_i32_e32 vcc, s0, v100
	v_cmp_lt_i32_e64 s[0:1], v101, v112
	v_pk_fma_f32 v[108:109], v[108:109], v[108:109], v[114:115]
	v_mov_b32_e32 v114, v72
	v_mov_b32_e32 v115, v68
	v_cndmask_b32_e64 v101, v150, v101, s[0:1]
	v_pk_fma_f32 v[108:109], v[114:115], v[114:115], v[108:109]
	v_mov_b32_e32 v114, v73
	v_mov_b32_e32 v115, v69
	v_lshlrev_b32_e32 v111, 2, v101
	v_pk_fma_f32 v[108:109], v[114:115], v[114:115], v[108:109]
	v_add_f32_e32 v101, v102, v103
	v_add_f32_e32 v101, v101, v108
	v_add_f32_e32 v101, v101, v109
	ds_bpermute_b32 v102, v111, v101
	v_xor_b32_e32 v103, 32, v150
	v_cmp_lt_i32_e64 s[0:1], v103, v112
	v_ashrrev_i32_e32 v98, 12, v98
	v_readlane_b32 s9, v197, 3
	v_cndmask_b32_e64 v103, v150, v103, s[0:1]
	v_lshlrev_b32_e32 v112, 2, v103
	s_waitcnt lgkmcnt(0)
	v_add_f32_e32 v101, v101, v102
	ds_bpermute_b32 v108, v112, v101
	v_mul_hi_i32_i24_e32 v103, 0x1100, v98
	v_mul_i32_i24_e32 v102, 0x1100, v98
	v_mov_b32_e32 v98, v100
	v_readlane_b32 s14, v197, 8
	s_waitcnt lgkmcnt(0)
	v_add_f32_e32 v101, v101, v108
	v_fmamk_f32 v101, v101, 0x3c800000, v137
	v_cmp_gt_f32_e64 s[0:1], s83, v101
	v_readlane_b32 s15, v197, 9
	v_readlane_b32 s16, v197, 10
	v_readlane_b32 s17, v197, 11
	v_readlane_b32 s18, v197, 12
	v_readlane_b32 s19, v197, 13
	v_readlane_b32 s20, v197, 14
	v_readlane_b32 s21, v197, 15
	v_readlane_b32 s22, v197, 16
	v_readlane_b32 s23, v197, 17
	s_and_saveexec_b64 s[4:5], vcc
	s_xor_b64 s[4:5], exec, s[4:5]
	s_cbranch_execz .LBB0_318
	v_readlane_b32 s8, v196, 6
	v_and_b32_e32 v108, 0xfcf, v113
	v_mov_b32_e32 v109, v99
	v_readlane_b32 s14, v196, 12
	v_readlane_b32 s15, v196, 13
	v_lshl_add_u64 v[108:109], v[102:103], 0, v[108:109]
	v_readlane_b32 s9, v196, 7
	v_mov_b64_e32 v[114:115], s[14:15]
	v_mad_u64_u32 v[114:115], s[38:39], v108, s82, v[114:115]
	v_mov_b32_e32 v108, v115
	v_mad_u64_u32 v[108:109], s[38:39], v109, s82, v[108:109]
	v_mov_b32_e32 v115, v108
	v_lshl_add_u64 v[108:109], v[98:99], 1, v[114:115]
	v_readlane_b32 s10, v196, 8
	v_readlane_b32 s11, v196, 9
	v_readlane_b32 s12, v196, 10
	v_readlane_b32 s13, v196, 11
	v_readlane_b32 s16, v196, 14
	v_readlane_b32 s17, v196, 15
	v_readlane_b32 s18, v196, 16
	v_readlane_b32 s19, v196, 17
	v_readlane_b32 s20, v196, 18
	v_readlane_b32 s21, v196, 19
	v_readlane_b32 s22, v196, 20
	v_readlane_b32 s23, v196, 21
	v_lshl_add_u64 v[108:109], v[108:109], 0, s[84:85]
